# prep_dn_chunk moved onto the waves that idle during prep_gla k-channel body (waves 4-7, 6 passes of 8 rows), all-wave version removed
# speedup vs baseline: 1.0346x; 1.0038x over previous
; __device__ __forceinline__ unsigned pk2(float lo, float hi) { const f32v2_t v = {lo, hi}; const bf16v2_t b = __builtin_convertvector(v, bf16v2_t); return __builtin_bit_cast(unsigned, b); }
; __device__ __forceinline__ void prep_dn_finish(const float* cw, bf16_t* dq, bf16_t* dk, bf16_t* dv, const u32x4 (&raw)[4], int t, int ch) {
;     float a[8];
; #pragma unroll
;     for (int e = 0; e < 8; ++e) a[e] = 0.f;
; #pragma unroll
;     for (int k = 0; k < 4; ++k) {
;         const f32x4 w0 = *(const f32x4*)(cw + k * 3072 + ch), w1 = *(const f32x4*)(cw + k * 3072 + ch + 4);
;         a[0] += w0[0] * lo16(raw[k].x); a[1] += w0[1] * hi16(raw[k].x); a[2] += w0[2] * lo16(raw[k].y); a[3] += w0[3] * hi16(raw[k].y);
;         a[4] += w1[0] * lo16(raw[k].z); a[5] += w1[1] * hi16(raw[k].z); a[6] += w1[2] * lo16(raw[k].w); a[7] += w1[3] * hi16(raw[k].w); }
;     float ss = 0.f;
; #pragma unroll
;     for (int e = 0; e < 8; ++e) { a[e] = siluf_(a[e]); ss += a[e] * a[e]; }
;     ss += __shfl_xor(ss, 1); ss += __shfl_xor(ss, 2); ss += __shfl_xor(ss, 4); ss += __shfl_xor(ss, 8);
;     float sc = 1.0f;
;     if (ch < 2048) { sc = rsqrtf(ss + EPS); if (ch < 1024) sc *= 0.08838834764831845f; }
;     u32x4 w; w.x = pk2(a[0] * sc, a[1] * sc); w.y = pk2(a[2] * sc, a[3] * sc); w.z = pk2(a[4] * sc, a[5] * sc); w.w = pk2(a[6] * sc, a[7] * sc);
;     bf16_t* dst = (ch < 1024) ? dq : (ch < 2048 ? dk : dv);
;     *(u32x4*)(dst + (size_t)t * 1024 + (ch & 1023)) = w;
; }
; __device__ void prep_dn_chunk(const Ctx& c, int ck, int half) {
;     const bf16_t* proj = c.W<bf16_t>(WS_PROJ);
;     const float* cw = c.in(I_DNCONV) + (size_t)c.layer * 4 * 3072;
;     bf16_t* dq = c.W<bf16_t>(WS_DQ); bf16_t* dk = c.W<bf16_t>(WS_DK); bf16_t* dv = c.W<bf16_t>(WS_DV);
;     for (int it = c.tid; it < 64 * 192; it += 1024) {
;         u32x4 r0[4], r1[4]; int t0, c0, t1, c1;
;         { const int l = it / 192, j = it - l * 192; t0 = ck * 64 + l; c0 = (j >> 6) * 1024 + half * 512 + (j & 63) * 8; }
;         { const int i2 = it + 512, l = i2 / 192, j = i2 - l * 192; t1 = ck * 64 + l; c1 = (j >> 6) * 1024 + half * 512 + (j & 63) * 8; }
;         prep_dn_load(proj, cw, -1, r0, t0, c0);
;         prep_dn_load(proj, cw, -1, r1, t1, c1);
;         prep_dn_finish(cw, dq, dk, dv, r0, t0, c0);
;         prep_dn_finish(cw, dq, dk, dv, r1, t1, c1);
;     }
.LBB0_613:
	s_or_saveexec_b64 s[0:1], s[0:1]
	s_ashr_i32 s4, s18, 1
	s_mov_b32 s2, s4
	v_writelane_b32 v249, s2, 38
	s_lshl_b32 s20, s4, 6
	s_nop 0
	v_writelane_b32 v249, s3, 39
	s_xor_b64 exec, exec, s[0:1]
	s_cbranch_execz .LBB0_637
	v_and_b32_e32 v49, 64, v237
	v_xor_b32_e32 v0, 1, v237
	v_add_u32_e32 v1, 64, v49
	v_cmp_lt_i32_e32 vcc, v0, v1
	s_load_dwordx2 s[2:3], s[94:95], 0x20
	v_readlane_b32 s4, v248, 40
	v_cndmask_b32_e32 v0, v237, v0, vcc
	v_lshlrev_b32_e32 v55, 2, v0
	v_xor_b32_e32 v0, 2, v237
	v_cmp_lt_i32_e32 vcc, v0, v1
	s_waitcnt lgkmcnt(0)
	s_add_u32 s4, s2, s4
	v_readlane_b32 s2, v248, 39
	v_cndmask_b32_e32 v0, v237, v0, vcc
	v_lshlrev_b32_e32 v64, 2, v0
	v_xor_b32_e32 v0, 4, v237
	v_cmp_lt_i32_e32 vcc, v0, v1
	s_addc_u32 s5, s3, s2
	v_readlane_b32 s2, v249, 37
	v_cndmask_b32_e32 v0, v237, v0, vcc
	v_lshlrev_b32_e32 v65, 2, v0
	v_xor_b32_e32 v0, 8, v237
	v_cmp_lt_i32_e32 vcc, v0, v1
	v_readlane_b32 s14, v248, 41
	s_lshl_b32 s2, s2, 9
	v_cndmask_b32_e32 v0, v237, v0, vcc
	v_lshlrev_b32_e32 v66, 2, v0
	v_lshlrev_b32_e32 v48, 4, v144
	v_lshlrev_b32_e32 v67, 3, v144
	s_mov_b64 s[6:7], 0
	v_mov_b32_e32 v68, v144
	v_readlane_b32 s15, v248, 42
	s_mov_b64 s[6:7], exec

; #define PIN16(a, o) asm volatile("" : "+v"(a[(o)+0]), "+v"(a[(o)+1]), "+v"(a[(o)+2]), "+v"(a[(o)+3]), "+v"(a[(o)+4]), "+v"(a[(o)+5]), "+v"(a[(o)+6]), "+v"(a[(o)+7]), \
;     "+v"(a[(o)+8]), "+v"(a[(o)+9]), "+v"(a[(o)+10]), "+v"(a[(o)+11]), "+v"(a[(o)+12]), "+v"(a[(o)+13]), "+v"(a[(o)+14]), "+v"(a[(o)+15]))
; __device__ void prep_gla(const Ctx& c, int ck, int blk) {
;     ...
;         for (int lh = 0; lh < 64; lh += 32) {
;             float qr[32], kr[32];
;             { unsigned qw[32], kw[32];
; #pragma unroll
;               for (int l = 0; l < 32; ++l) { const size_t rb = (size_t)(t0 + lh + l) * NP; qw[l] = proj[rb + C_GQ + ch]; kw[l] = proj[rb + C_GK + ch]; }
;               PIN16(qw, 0); PIN16(kw, 0); PIN16(qw, 16); PIN16(kw, 16);
; #pragma unroll
;               for (int l = 0; l < 32; ++l) { qr[l] = __uint_as_float(qw[l] << 16); kr[l] = __uint_as_float(kw[l] << 16); } }
.LBB0_662:
	v_cndmask_b32_e64 v0, 0, 1, s[0:1]
	v_readlane_b32 s0, v253, 27
	s_or_b32 s0, s88, s0
	v_readlane_b32 s1, v253, 28
	s_mul_i32 s2, s0, 0x7e00
	s_mul_hi_i32 s1, s0, 0x7e00
	s_add_u32 s4, s28, s2
	s_addc_u32 s5, s29, s1
	s_or_b32 s1, s0, 1
	s_mul_hi_i32 s2, s1, 0x7e00
	s_mulk_i32 s1, 0x7e00
	s_add_u32 s82, s28, s1
	s_addc_u32 s83, s29, s2
	s_or_b32 s1, s0, 2
	s_mul_hi_i32 s2, s1, 0x7e00
	s_mulk_i32 s1, 0x7e00
	s_add_u32 s80, s28, s1
	v_cmp_ne_u32_e32 vcc, 1, v0
	v_lshlrev_b64 v[0:1], 1, v[22:23]
	s_addc_u32 s81, s29, s2
	s_or_b32 s1, s0, 3
	v_lshl_add_u64 v[2:3], s[4:5], 0, v[0:1]
	s_mul_hi_i32 s2, s1, 0x7e00
	s_mulk_i32 s1, 0x7e00
	v_add_co_u32_e64 v4, s[4:5], s91, v2
	s_add_u32 s78, s28, s1
	s_nop 0
	v_addc_co_u32_e64 v5, s[4:5], 0, v3, s[4:5]
	v_lshl_add_u64 v[6:7], s[82:83], 0, v[0:1]
	s_addc_u32 s79, s29, s2
	s_or_b32 s1, s0, 4
	v_add_co_u32_e64 v6, s[4:5], s91, v6
	s_mul_hi_i32 s2, s1, 0x7e00
	s_mulk_i32 s1, 0x7e00
	v_addc_co_u32_e64 v7, s[4:5], 0, v7, s[4:5]
	s_add_u32 s76, s28, s1
	global_load_ushort v2, v[4:5], off offset:1088
	s_nop 0
	global_load_ushort v4, v[4:5], off offset:2112
	s_nop 0
	global_load_ushort v3, v[6:7], off offset:1088
	global_load_ushort v5, v[6:7], off offset:2112
	v_lshl_add_u64 v[6:7], s[80:81], 0, v[0:1]
	s_addc_u32 s77, s29, s2
	s_or_b32 s1, s0, 5
	v_add_co_u32_e64 v6, s[4:5], s91, v6
	s_mul_hi_i32 s2, s1, 0x7e00
	s_mulk_i32 s1, 0x7e00
	v_addc_co_u32_e64 v7, s[4:5], 0, v7, s[4:5]
	v_lshl_add_u64 v[8:9], s[78:79], 0, v[0:1]
	s_add_u32 s74, s28, s1
	v_add_co_u32_e64 v8, s[4:5], s91, v8
	s_addc_u32 s75, s29, s2
	s_or_b32 s1, s0, 6
	v_addc_co_u32_e64 v9, s[4:5], 0, v9, s[4:5]
	s_mul_hi_i32 s2, s1, 0x7e00
	s_mulk_i32 s1, 0x7e00
	global_load_ushort v12, v[6:7], off offset:1088
	s_nop 0
	global_load_ushort v6, v[6:7], off offset:2112
	s_nop 0
	global_load_ushort v13, v[8:9], off offset:1088
	global_load_ushort v7, v[8:9], off offset:2112
	v_lshl_add_u64 v[8:9], s[76:77], 0, v[0:1]
	s_add_u32 s72, s28, s1
	v_add_co_u32_e64 v8, s[4:5], s91, v8
	s_addc_u32 s73, s29, s2
	s_or_b32 s1, s0, 7
	v_addc_co_u32_e64 v9, s[4:5], 0, v9, s[4:5]
	v_lshl_add_u64 v[10:11], s[74:75], 0, v[0:1]
	s_mul_hi_i32 s2, s1, 0x7e00
	s_mulk_i32 s1, 0x7e00
	v_add_co_u32_e64 v10, s[4:5], s91, v10
	s_add_u32 s70, s28, s1
	s_nop 0
	v_addc_co_u32_e64 v11, s[4:5], 0, v11, s[4:5]
	s_addc_u32 s71, s29, s2
	s_or_b32 s1, s0, 8
	global_load_ushort v14, v[8:9], off offset:1088
	s_nop 0
	global_load_ushort v8, v[8:9], off offset:2112
	s_nop 0
	global_load_ushort v15, v[10:11], off offset:1088
	global_load_ushort v9, v[10:11], off offset:2112
	v_lshl_add_u64 v[10:11], s[72:73], 0, v[0:1]
	s_mul_hi_i32 s2, s1, 0x7e00
	s_mulk_i32 s1, 0x7e00
	v_add_co_u32_e64 v10, s[4:5], s91, v10
	s_add_u32 s68, s28, s1
	s_nop 0
	v_addc_co_u32_e64 v11, s[4:5], 0, v11, s[4:5]
	v_lshl_add_u64 v[46:47], s[70:71], 0, v[0:1]
	s_addc_u32 s69, s29, s2
	s_or_b32 s1, s0, 9
	v_add_co_u32_e64 v46, s[4:5], s91, v46
	s_mul_hi_i32 s2, s1, 0x7e00
	s_mulk_i32 s1, 0x7e00
	v_addc_co_u32_e64 v47, s[4:5], 0, v47, s[4:5]
	s_add_u32 s66, s28, s1
	global_load_ushort v44, v[10:11], off offset:1088
	s_nop 0
	global_load_ushort v10, v[10:11], off offset:2112
	s_nop 0
	global_load_ushort v45, v[46:47], off offset:1088
	global_load_ushort v11, v[46:47], off offset:2112
	v_lshl_add_u64 v[46:47], s[68:69], 0, v[0:1]
	s_addc_u32 s67, s29, s2
	s_or_b32 s1, s0, 10
	v_add_co_u32_e64 v46, s[4:5], s91, v46
	s_mul_hi_i32 s2, s1, 0x7e00
	s_mulk_i32 s1, 0x7e00
	v_addc_co_u32_e64 v47, s[4:5], 0, v47, s[4:5]
	s_add_u32 s64, s28, s1
	global_load_ushort v49, v[46:47], off offset:1088
	global_load_ushort v95, v[46:47], off offset:2112
	v_lshl_add_u64 v[46:47], s[66:67], 0, v[0:1]
	s_addc_u32 s65, s29, s2
	s_or_b32 s1, s0, 11
	v_add_co_u32_e64 v46, s[4:5], s91, v46
	s_mul_hi_i32 s2, s1, 0x7e00
	s_mulk_i32 s1, 0x7e00
	v_addc_co_u32_e64 v47, s[4:5], 0, v47, s[4:5]
	s_add_u32 s60, s28, s1
	global_load_ushort v52, v[46:47], off offset:1088
	global_load_ushort v96, v[46:47], off offset:2112
	v_lshl_add_u64 v[46:47], s[64:65], 0, v[0:1]
	s_addc_u32 s61, s29, s2
	s_or_b32 s1, s0, 12
	v_add_co_u32_e64 v46, s[4:5], s91, v46
	s_mul_hi_i32 s2, s1, 0x7e00
	s_mulk_i32 s1, 0x7e00
	v_addc_co_u32_e64 v47, s[4:5], 0, v47, s[4:5]
	s_add_u32 s58, s28, s1
	global_load_ushort v53, v[46:47], off offset:1088
	global_load_ushort v91, v[46:47], off offset:2112
	v_lshl_add_u64 v[46:47], s[60:61], 0, v[0:1]
	s_addc_u32 s59, s29, s2
	s_or_b32 s1, s0, 13
	v_add_co_u32_e64 v46, s[4:5], s91, v46
	s_mul_hi_i32 s2, s1, 0x7e00
	s_mulk_i32 s1, 0x7e00
	v_addc_co_u32_e64 v47, s[4:5], 0, v47, s[4:5]
	s_add_u32 s52, s28, s1
	global_load_ushort v56, v[46:47], off offset:1088
	global_load_ushort v92, v[46:47], off offset:2112
	v_lshl_add_u64 v[46:47], s[58:59], 0, v[0:1]
	s_addc_u32 s53, s29, s2
	s_or_b32 s1, s0, 14
	v_add_co_u32_e64 v46, s[4:5], s91, v46
	s_mul_hi_i32 s2, s1, 0x7e00
	s_mulk_i32 s1, 0x7e00
	v_addc_co_u32_e64 v47, s[4:5], 0, v47, s[4:5]
	s_add_u32 s50, s28, s1
	global_load_ushort v57, v[46:47], off offset:1088
	global_load_ushort v87, v[46:47], off offset:2112
	v_lshl_add_u64 v[46:47], s[52:53], 0, v[0:1]
	s_addc_u32 s51, s29, s2
	s_or_b32 s1, s0, 15
	v_add_co_u32_e64 v46, s[4:5], s91, v46
	s_mul_hi_i32 s2, s1, 0x7e00
	s_mulk_i32 s1, 0x7e00
	v_addc_co_u32_e64 v47, s[4:5], 0, v47, s[4:5]
	s_add_u32 s46, s28, s1
	global_load_ushort v61, v[46:47], off offset:1088
	global_load_ushort v88, v[46:47], off offset:2112
	v_lshl_add_u64 v[46:47], s[50:51], 0, v[0:1]
	s_addc_u32 s47, s29, s2
	s_or_b32 s1, s0, 16
	v_add_co_u32_e64 v46, s[4:5], s91, v46
	s_mul_hi_i32 s2, s1, 0x7e00
	s_mulk_i32 s1, 0x7e00
	v_addc_co_u32_e64 v47, s[4:5], 0, v47, s[4:5]
; #define PIN16(a, o) asm volatile("" : "+v"(a[(o)+0]), "+v"(a[(o)+1]), "+v"(a[(o)+2]), "+v"(a[(o)+3]), "+v"(a[(o)+4]), "+v"(a[(o)+5]), "+v"(a[(o)+6]), "+v"(a[(o)+7]), \
;     "+v"(a[(o)+8]), "+v"(a[(o)+9]), "+v"(a[(o)+10]), "+v"(a[(o)+11]), "+v"(a[(o)+12]), "+v"(a[(o)+13]), "+v"(a[(o)+14]), "+v"(a[(o)+15]))
; __device__ void prep_gla(const Ctx& c, int ck, int blk) {
;     ...
;         for (int lh = 0; lh < 64; lh += 32) {
;             float qr[32], kr[32];
;             { unsigned qw[32], kw[32];
; #pragma unroll
;               for (int l = 0; l < 32; ++l) { const size_t rb = (size_t)(t0 + lh + l) * NP; qw[l] = proj[rb + C_GQ + ch]; kw[l] = proj[rb + C_GK + ch]; }
;               PIN16(qw, 0); PIN16(kw, 0); PIN16(qw, 16); PIN16(kw, 16);
; #pragma unroll
;               for (int l = 0; l < 32; ++l) { qr[l] = __uint_as_float(qw[l] << 16); kr[l] = __uint_as_float(kw[l] << 16); } }
	s_add_u32 s42, s28, s1
	global_load_ushort v65, v[46:47], off offset:1088
	global_load_ushort v84, v[46:47], off offset:2112
	v_lshl_add_u64 v[46:47], s[46:47], 0, v[0:1]
	s_addc_u32 s43, s29, s2
	s_or_b32 s1, s0, 17
	v_add_co_u32_e64 v46, s[4:5], s91, v46
	s_mul_hi_i32 s2, s1, 0x7e00
	s_mulk_i32 s1, 0x7e00
	v_addc_co_u32_e64 v47, s[4:5], 0, v47, s[4:5]
	s_add_u32 s40, s28, s1
	global_load_ushort v67, v[46:47], off offset:1088
	global_load_ushort v85, v[46:47], off offset:2112
	v_lshl_add_u64 v[46:47], s[42:43], 0, v[0:1]
	s_addc_u32 s41, s29, s2
	s_or_b32 s1, s0, 18
	v_add_co_u32_e64 v46, s[4:5], s91, v46
	s_mul_hi_i32 s2, s1, 0x7e00
	s_mulk_i32 s1, 0x7e00
	v_addc_co_u32_e64 v47, s[4:5], 0, v47, s[4:5]
	s_add_u32 s38, s28, s1
	global_load_ushort v69, v[46:47], off offset:1088
	global_load_ushort v80, v[46:47], off offset:2112
	v_lshl_add_u64 v[46:47], s[40:41], 0, v[0:1]
	s_addc_u32 s39, s29, s2
	s_or_b32 s1, s0, 19
	v_add_co_u32_e64 v46, s[4:5], s91, v46
	s_mul_hi_i32 s2, s1, 0x7e00
	s_mulk_i32 s1, 0x7e00
	v_addc_co_u32_e64 v47, s[4:5], 0, v47, s[4:5]
	s_add_u32 s36, s28, s1
	global_load_ushort v71, v[46:47], off offset:1088
	global_load_ushort v81, v[46:47], off offset:2112
	v_lshl_add_u64 v[46:47], s[38:39], 0, v[0:1]
	s_addc_u32 s37, s29, s2
	s_or_b32 s1, s0, 20
	v_add_co_u32_e64 v46, s[4:5], s91, v46
	s_mul_hi_i32 s2, s1, 0x7e00
	s_mulk_i32 s1, 0x7e00
	v_addc_co_u32_e64 v47, s[4:5], 0, v47, s[4:5]
	s_add_u32 s26, s28, s1
	global_load_ushort v74, v[46:47], off offset:1088
	global_load_ushort v76, v[46:47], off offset:2112
	v_lshl_add_u64 v[46:47], s[36:37], 0, v[0:1]
	s_addc_u32 s27, s29, s2
	s_or_b32 s1, s0, 21
	v_add_co_u32_e64 v46, s[4:5], s91, v46
	s_mul_hi_i32 s2, s1, 0x7e00
	s_mulk_i32 s1, 0x7e00
	v_addc_co_u32_e64 v47, s[4:5], 0, v47, s[4:5]
	s_add_u32 s24, s28, s1
	global_load_ushort v75, v[46:47], off offset:1088
	global_load_ushort v77, v[46:47], off offset:2112
	v_lshl_add_u64 v[46:47], s[26:27], 0, v[0:1]
	s_addc_u32 s25, s29, s2
	s_or_b32 s1, s0, 22
	v_add_co_u32_e64 v46, s[4:5], s91, v46
	s_mul_hi_i32 s2, s1, 0x7e00
	s_mulk_i32 s1, 0x7e00
	v_addc_co_u32_e64 v47, s[4:5], 0, v47, s[4:5]
	s_add_u32 s22, s28, s1
	global_load_ushort v78, v[46:47], off offset:1088
	global_load_ushort v72, v[46:47], off offset:2112
	v_lshl_add_u64 v[46:47], s[24:25], 0, v[0:1]
	s_addc_u32 s23, s29, s2
	s_or_b32 s1, s0, 23
	v_add_co_u32_e64 v46, s[4:5], s91, v46
	s_mul_hi_i32 s2, s1, 0x7e00
	s_mulk_i32 s1, 0x7e00
	v_addc_co_u32_e64 v47, s[4:5], 0, v47, s[4:5]
	s_add_u32 s20, s28, s1
	global_load_ushort v99, v[46:47], off offset:1088
	global_load_ushort v73, v[46:47], off offset:2112
	v_lshl_add_u64 v[46:47], s[22:23], 0, v[0:1]
	s_addc_u32 s21, s29, s2
	s_or_b32 s1, s0, 24
	v_add_co_u32_e64 v46, s[4:5], s91, v46
	s_mul_hi_i32 s2, s1, 0x7e00
	s_mulk_i32 s1, 0x7e00
	v_addc_co_u32_e64 v47, s[4:5], 0, v47, s[4:5]
	s_add_u32 s18, s28, s1
	global_load_ushort v100, v[46:47], off offset:1088
	global_load_ushort v68, v[46:47], off offset:2112
	v_lshl_add_u64 v[46:47], s[20:21], 0, v[0:1]
	s_addc_u32 s19, s29, s2
	s_or_b32 s1, s0, 25
	v_add_co_u32_e64 v46, s[4:5], s91, v46
	s_mul_hi_i32 s2, s1, 0x7e00
	s_mulk_i32 s1, 0x7e00
	v_addc_co_u32_e64 v47, s[4:5], 0, v47, s[4:5]
	s_add_u32 s16, s28, s1
	global_load_ushort v101, v[46:47], off offset:1088
	global_load_ushort v70, v[46:47], off offset:2112
	v_lshl_add_u64 v[46:47], s[18:19], 0, v[0:1]
	s_addc_u32 s17, s29, s2
	s_or_b32 s1, s0, 26
	v_add_co_u32_e64 v46, s[4:5], s91, v46
	s_mul_hi_i32 s2, s1, 0x7e00
	s_mulk_i32 s1, 0x7e00
	v_addc_co_u32_e64 v47, s[4:5], 0, v47, s[4:5]
	s_add_u32 s14, s28, s1
	global_load_ushort v102, v[46:47], off offset:1088
	global_load_ushort v63, v[46:47], off offset:2112
	v_lshl_add_u64 v[46:47], s[16:17], 0, v[0:1]
	s_addc_u32 s15, s29, s2
	s_or_b32 s1, s0, 27
	v_add_co_u32_e64 v46, s[4:5], s91, v46
	s_mul_hi_i32 s2, s1, 0x7e00
	s_mulk_i32 s1, 0x7e00
	v_addc_co_u32_e64 v47, s[4:5], 0, v47, s[4:5]
	s_add_u32 s12, s28, s1
	global_load_ushort v103, v[46:47], off offset:1088
	global_load_ushort v66, v[46:47], off offset:2112
	v_lshl_add_u64 v[46:47], s[14:15], 0, v[0:1]
	s_addc_u32 s13, s29, s2
	s_or_b32 s1, s0, 28
	v_add_co_u32_e64 v46, s[4:5], s91, v46
	s_mul_hi_i32 s2, s1, 0x7e00
	s_mulk_i32 s1, 0x7e00
	v_addc_co_u32_e64 v47, s[4:5], 0, v47, s[4:5]
	s_add_u32 s10, s28, s1
	global_load_ushort v104, v[46:47], off offset:1088
	global_load_ushort v58, v[46:47], off offset:2112
	v_lshl_add_u64 v[46:47], s[12:13], 0, v[0:1]
	s_addc_u32 s11, s29, s2
	s_or_b32 s1, s0, 29
	v_add_co_u32_e64 v46, s[4:5], s91, v46
	s_mul_hi_i32 s2, s1, 0x7e00
	s_mulk_i32 s1, 0x7e00
	v_addc_co_u32_e64 v47, s[4:5], 0, v47, s[4:5]
	s_add_u32 s8, s28, s1
	global_load_ushort v105, v[46:47], off offset:1088
	global_load_ushort v59, v[46:47], off offset:2112
	v_lshl_add_u64 v[46:47], s[10:11], 0, v[0:1]
	s_addc_u32 s9, s29, s2
	s_or_b32 s1, s0, 30
	v_add_co_u32_e64 v46, s[4:5], s91, v46
	s_mul_hi_i32 s2, s1, 0x7e00
	s_mulk_i32 s1, 0x7e00
	v_addc_co_u32_e64 v47, s[4:5], 0, v47, s[4:5]
	s_add_u32 s6, s28, s1
	global_load_ushort v106, v[46:47], off offset:1088
	global_load_ushort v54, v[46:47], off offset:2112
	v_lshl_add_u64 v[46:47], s[8:9], 0, v[0:1]
	s_addc_u32 s7, s29, s2
	s_or_b32 s0, s0, 31
	v_add_co_u32_e64 v46, s[4:5], s91, v46
	s_mul_hi_i32 s1, s0, 0x7e00
	s_mulk_i32 s0, 0x7e00
	v_addc_co_u32_e64 v47, s[4:5], 0, v47, s[4:5]
	s_add_u32 s0, s28, s0
	global_load_ushort v107, v[46:47], off offset:1088
	global_load_ushort v55, v[46:47], off offset:2112
	v_lshl_add_u64 v[46:47], s[6:7], 0, v[0:1]
	s_addc_u32 s1, s29, s1
	v_add_co_u32_e64 v46, s[4:5], s91, v46
	v_lshl_add_u64 v[0:1], s[0:1], 0, v[0:1]
	s_nop 0
; #define PIN16(a, o) asm volatile("" : "+v"(a[(o)+0]), "+v"(a[(o)+1]), "+v"(a[(o)+2]), "+v"(a[(o)+3]), "+v"(a[(o)+4]), "+v"(a[(o)+5]), "+v"(a[(o)+6]), "+v"(a[(o)+7]), \
;     "+v"(a[(o)+8]), "+v"(a[(o)+9]), "+v"(a[(o)+10]), "+v"(a[(o)+11]), "+v"(a[(o)+12]), "+v"(a[(o)+13]), "+v"(a[(o)+14]), "+v"(a[(o)+15]))
; __device__ void prep_gla(const Ctx& c, int ck, int blk) {
;     ...
;               for (int l = 0; l < 32; ++l) { const size_t rb = (size_t)(t0 + lh + l) * NP; qw[l] = proj[rb + C_GQ + ch]; kw[l] = proj[rb + C_GK + ch]; }
;               PIN16(qw, 0); PIN16(kw, 0); PIN16(qw, 16); PIN16(kw, 16);
; #pragma unroll
;               for (int l = 0; l < 32; ++l) { qr[l] = __uint_as_float(qw[l] << 16); kr[l] = __uint_as_float(kw[l] << 16); } }
; #pragma unroll
;             for (int l0 = 0; l0 < 32; l0 += 8) {
;                 float kn[8];
; #pragma unroll
;                 for (int j = 0; j < 8; ++j) { const int l = lh + l0 + j;
;                     float x = b2;
; #pragma unroll
;                     for (int r4 = 0; r4 < 16; r4 += 4) { const f32x4 lv = *(const f32x4*)(lr_s + l * 16 + r4); x += lv[0] * w2r[r4] + lv[1] * w2r[r4 + 1] + lv[2] * w2r[r4 + 2] + lv[3] * w2r[r4 + 3]; }
	v_addc_co_u32_e64 v47, s[4:5], 0, v47, s[4:5]
	v_add_co_u32_e64 v0, s[4:5], s91, v0
	global_load_ushort v108, v[46:47], off offset:1088
	global_load_ushort v50, v[46:47], off offset:2112
	v_addc_co_u32_e64 v1, s[4:5], 0, v1, s[4:5]
	global_load_ushort v109, v[0:1], off offset:1088
	global_load_ushort v51, v[0:1], off offset:2112
	s_lshl_b32 s2, s88, 6
	s_or_b32 s30, s88, 1
	s_add_i32 s56, s2, 0
	s_lshl_b32 s2, s30, 6
	s_or_b32 s44, s88, 2
	s_add_i32 s31, s2, 0
	s_lshl_b32 s2, s44, 6
	s_or_b32 s94, s88, 3
	s_add_i32 s34, s2, 0
	s_lshl_b32 s2, s94, 6
	s_or_b32 s48, s88, 4
	s_add_i32 s92, s2, 0
	s_lshl_b32 s2, s48, 6
	s_or_b32 s96, s88, 5
	s_add_i32 s3, s2, 0
	s_lshl_b32 s2, s96, 6
	s_or_b32 s62, s88, 6
	s_add_i32 s33, s2, 0
	s_lshl_b32 s2, s62, 6
	s_or_b32 s54, s88, 7
	s_add_i32 s49, s2, 0
	s_lshl_b32 s2, s54, 6
	s_add_i32 s63, s2, 0
	s_or_b32 s2, s88, 8
	s_lshl_b32 s35, s2, 6
	s_add_i32 s35, s35, 0
	v_writelane_b32 v253, s35, 49
	s_or_b32 s35, s88, 9
	s_lshl_b32 s45, s35, 6
	s_add_i32 s45, s45, 0
	v_writelane_b32 v255, s45, 7
	s_or_b32 s45, s88, 10
	s_lshl_b32 s55, s45, 6
	s_add_i32 s55, s55, 0
	v_writelane_b32 v253, s55, 51
	s_or_b32 s55, s88, 11
	s_lshl_b32 s57, s55, 6
	s_add_i32 s57, s57, 0
	s_or_b32 s93, s88, 12
	v_writelane_b32 v255, s57, 5
	s_lshl_b32 s57, s93, 6
	s_add_i32 s57, s57, 0
	s_or_b32 s95, s88, 13
	v_writelane_b32 v253, s57, 53
	s_lshl_b32 s57, s95, 6
	s_add_i32 s57, s57, 0
	s_or_b32 s90, s88, 14
	v_writelane_b32 v253, s57, 61
	s_lshl_b32 s57, s90, 6
	s_add_i32 s57, s57, 0
	s_or_b32 s97, s88, 15
	v_writelane_b32 v253, s57, 59
	s_lshl_b32 s57, s97, 6
	s_add_i32 s57, s57, 0
	v_writelane_b32 v253, s57, 57
	s_or_b32 s57, s88, 16
	v_writelane_b32 v255, s57, 1
	s_lshl_b32 s57, s57, 6
	s_add_i32 s57, s57, 0
	v_writelane_b32 v255, s57, 3
	s_or_b32 s57, s88, 17
	v_writelane_b32 v253, s57, 55
	s_lshl_b32 s57, s57, 6
	s_add_i32 s57, s57, 0
	v_writelane_b32 v253, s57, 63
	s_or_b32 s57, s88, 18
	v_writelane_b32 v249, s57, 49
	s_lshl_b32 s57, s57, 6
	s_add_i32 s57, s57, 0
	v_writelane_b32 v253, s57, 31
	s_or_b32 s57, s88, 19
	v_writelane_b32 v253, s57, 29
	s_lshl_b32 s57, s57, 6
	s_add_i32 s57, s57, 0
	v_writelane_b32 v253, s57, 33
	s_or_b32 s57, s88, 20
	v_writelane_b32 v253, s57, 39
	s_lshl_b32 s57, s57, 6
	s_add_i32 s57, s57, 0
	v_writelane_b32 v253, s57, 41
	s_or_b32 s57, s88, 21
	v_writelane_b32 v253, s57, 35
	s_lshl_b32 s57, s57, 6
	s_add_i32 s57, s57, 0
	v_writelane_b32 v253, s57, 37
	s_or_b32 s57, s88, 22
	v_writelane_b32 v254, s57, 33
	s_lshl_b32 s57, s57, 6
	s_add_i32 s57, s57, 0
	v_writelane_b32 v249, s57, 47
	s_or_b32 s57, s88, 23
	v_writelane_b32 v252, s57, 23
	s_lshl_b32 s57, s57, 6
	s_add_i32 s57, s57, 0
	v_writelane_b32 v252, s57, 29
	s_or_b32 s57, s88, 24
	v_writelane_b32 v251, s57, 47
	s_lshl_b32 s57, s57, 6
	s_add_i32 s57, s57, 0
	v_writelane_b32 v251, s57, 59
	s_or_b32 s57, s88, 25
	v_writelane_b32 v252, s57, 17
	s_lshl_b32 s57, s57, 6
	s_add_i32 s57, s57, 0
	v_writelane_b32 v251, s57, 35
	s_or_b32 s57, s88, 26
	v_writelane_b32 v253, s57, 21
	s_lshl_b32 s57, s57, 6
	s_waitcnt vmcnt(33)
	s_add_i32 s57, s57, 0
	s_waitcnt vmcnt(32)
	s_waitcnt vmcnt(1)
	v_lshlrev_b32_e32 v0, 16, v2
	v_mov_b32_e32 v2, s56
	v_writelane_b32 v252, s57, 11
	s_or_b32 s57, s88, 27
	s_waitcnt vmcnt(0)
	v_lshlrev_b32_e32 v48, 16, v12
	v_lshlrev_b32_e32 v12, 16, v49
	v_lshlrev_b32_e32 v49, 16, v52
	v_lshlrev_b32_e32 v98, 16, v53
	v_lshlrev_b32_e32 v97, 16, v56
	v_lshlrev_b32_e32 v94, 16, v57
	v_lshlrev_b32_e32 v93, 16, v61
	v_lshlrev_b32_e32 v90, 16, v65
	v_lshlrev_b32_e32 v89, 16, v67
	v_lshlrev_b32_e32 v86, 16, v69
	v_lshlrev_b32_e32 v83, 16, v71
	v_lshlrev_b32_e32 v82, 16, v74
	v_lshlrev_b32_e32 v74, 16, v100
	v_lshlrev_b32_e32 v71, 16, v101
	v_lshlrev_b32_e32 v69, 16, v102
	v_lshlrev_b32_e32 v67, 16, v103
	v_lshlrev_b32_e32 v65, 16, v104
	v_lshlrev_b32_e32 v61, 16, v105
	v_lshlrev_b32_e32 v57, 16, v106
	v_lshlrev_b32_e32 v56, 16, v107
	v_lshlrev_b32_e32 v53, 16, v108
	v_lshlrev_b32_e32 v52, 16, v109
	ds_read_b128 v[100:103], v2
	ds_read_b128 v[104:107], v2 offset:16
	ds_read_b128 v[108:111], v2 offset:32
	ds_read_b128 v[112:115], v2 offset:48
	v_writelane_b32 v253, s57, 9
	s_lshl_b32 s57, s57, 6
	s_add_i32 s57, s57, 0
	v_writelane_b32 v253, s57, 15
	s_or_b32 s57, s88, 28
	v_lshlrev_b32_e32 v1, 16, v3
	s_waitcnt lgkmcnt(2)
	v_mov_b32_e32 v3, v104
	v_mov_b32_e32 v104, v101
	v_writelane_b32 v252, s57, 61
	s_lshl_b32 s57, s57, 6
	v_mov_b32_e32 v2, v100
	v_pk_mul_f32 v[100:101], v[34:35], v[104:105]
	s_add_i32 s57, s57, 0
	v_pk_fma_f32 v[2:3], v[26:27], v[2:3], v[100:101]
	v_mov_b32_e32 v100, v102
	v_mov_b32_e32 v101, v106
	v_writelane_b32 v253, s57, 3
	s_or_b32 s57, s88, 29
	v_pk_fma_f32 v[2:3], v[24:25], v[100:101], v[2:3]
	v_mov_b32_e32 v106, v103
	v_writelane_b32 v249, s57, 43
	s_lshl_b32 s57, s57, 6
	v_pk_fma_f32 v[2:3], v[36:37], v[106:107], v[2:3]
	s_add_i32 s57, s57, 0
	v_add_f32_e32 v2, v17, v2
	v_writelane_b32 v252, s57, 55
	s_or_b32 s57, s88, 30
	v_lshlrev_b32_e32 v79, 16, v75
	v_lshlrev_b32_e32 v75, 16, v99
	v_add_f32_e32 v99, v2, v3
	s_waitcnt lgkmcnt(0)
; __device__ __forceinline__ unsigned pk2(float lo, float hi) { const f32v2_t v = {lo, hi}; const bf16v2_t b = __builtin_convertvector(v, bf16v2_t); return __builtin_bit_cast(unsigned, b); }
; __device__ __forceinline__ float softplusf_(float x) { return fmaxf(x, 0.f) + __logf(1.0f + __expf(-fabsf(x))); }
; __device__ void prep_gla(const Ctx& c, int ck, int blk) {
;     ...
;                 for (int j = 0; j < 8; ++j) { const int l = lh + l0 + j;
;                     float x = b2;
; #pragma unroll
;                     for (int r4 = 0; r4 < 16; r4 += 4) { const f32x4 lv = *(const f32x4*)(lr_s + l * 16 + r4); x += lv[0] * w2r[r4] + lv[1] * w2r[r4 + 1] + lv[2] * w2r[r4 + 2] + lv[3] * w2r[r4 + 3]; }
;                     G += -softplusf_(-x) * (1.0f / 16.0f);
;                     const float qv = qr[l0 + j] * 0.08838834764831845f, kv = kr[l0 + j];
;                     const size_t o = ((size_t)(ck * 4 + h) * 64 + l) * 128 + k;
;                     gQg[o] = f2bf(qv * __expf(G)); const float kneg = kv * __expf(-G); gKn[o] = f2bf(kneg); kn[j] = kneg; }
;                 u32x4 a; a.x = pk2(kn[0], kn[1]); a.y = pk2(kn[2], kn[3]); a.z = pk2(kn[4], kn[5]); a.w = pk2(kn[6], kn[7]);
	v_mov_b32_e32 v3, v112
	v_mov_b32_e32 v112, v109
	v_writelane_b32 v252, s57, 5
	s_lshl_b32 s57, s57, 6
	v_mov_b32_e32 v2, v108
	v_pk_mul_f32 v[100:101], v[30:31], v[112:113]
	s_add_i32 s57, s57, 0
	v_pk_fma_f32 v[2:3], v[28:29], v[2:3], v[100:101]
	v_mov_b32_e32 v100, v110
	v_mov_b32_e32 v101, v114
	v_writelane_b32 v251, s57, 53
	s_or_b32 s57, s88, 31
	v_pk_fma_f32 v[2:3], v[32:33], v[100:101], v[2:3]
	v_mov_b32_e32 v114, v111
	v_writelane_b32 v250, s57, 63
	s_lshl_b32 s57, s57, 6
	v_pk_fma_f32 v[2:3], v[38:39], v[114:115], v[2:3]
	s_add_i32 s57, s57, 0
	v_add_f32_e32 v2, v99, v2
	v_writelane_b32 v251, s57, 41
	s_mov_b32 s57, 0xbfb8aa3b
	v_add_f32_e32 v2, v2, v3
	v_max_f32_e64 v3, -v2, 0
	v_mul_f32_e64 v2, |v2|, s57
	v_exp_f32_e32 v2, v2
	s_mov_b32 s59, 0x800000
	s_mov_b32 s60, 0x3f317217
	s_mov_b32 s61, 0x7f800000
	v_add_f32_e32 v2, 1.0, v2
	v_cmp_gt_f32_e64 s[4:5], s59, v2
	v_mul_f32_e32 v0, 0x3db504f3, v0
	v_mul_f32_e32 v1, 0x3db504f3, v1
	v_cndmask_b32_e64 v99, 0, 32, s[4:5]
	v_ldexp_f32 v2, v2, v99
	v_log_f32_e32 v2, v2
	v_lshlrev_b32_e32 v5, 16, v5
	v_lshlrev_b32_e32 v4, 16, v4
	v_lshlrev_b32_e32 v47, 16, v13
	v_mul_f32_e32 v99, 0x3f317217, v2
	v_fma_f32 v99, v2, s60, -v99
	v_fmac_f32_e32 v99, 0x3377d1cf, v2
	v_fmac_f32_e32 v99, 0x3f317217, v2
	v_cmp_lt_f32_e64 s[6:7], |v2|, s61
	v_lshlrev_b32_e32 v7, 16, v7
	v_lshlrev_b32_e32 v6, 16, v6
	v_cndmask_b32_e64 v2, v2, v99, s[6:7]
	v_cndmask_b32_e64 v99, 0, v240, s[4:5]
	v_sub_f32_e32 v2, v2, v99
	v_add_f32_e32 v2, v3, v2
	v_fmac_f32_e32 v21, 0xbd800000, v2
	v_mul_f32_e32 v99, 0x3fb8aa3b, v21
	v_exp_f32_e32 v99, v99
	v_lshl_or_b32 v2, s88, 7, v40
	v_mov_b32_e32 v3, v41
	v_lshlrev_b64 v[2:3], 1, v[2:3]
	v_mul_f32_e32 v0, v0, v99
	v_cvt_pk_bf16_f32 v0, v0, s0
	v_lshl_add_u64 v[100:101], s[86:87], 0, v[2:3]
	global_store_short v[100:101], v0, off
	v_mov_b32_e32 v99, s31
	ds_read_b128 v[100:103], v99
	ds_read_b128 v[104:107], v99 offset:16
	ds_read_b128 v[108:111], v99 offset:32
	ds_read_b128 v[112:115], v99 offset:48
	v_mul_f32_e32 v0, 0xbfb8aa3b, v21
	s_waitcnt lgkmcnt(3)
	v_mov_b32_e32 v116, v100
	s_waitcnt lgkmcnt(2)
	v_mov_b32_e32 v117, v104
	v_mov_b32_e32 v104, v101
	v_pk_mul_f32 v[100:101], v[34:35], v[104:105]
	v_mov_b32_e32 v104, v102
	v_pk_fma_f32 v[100:101], v[26:27], v[116:117], v[100:101]
	v_mov_b32_e32 v105, v106
	v_pk_fma_f32 v[100:101], v[24:25], v[104:105], v[100:101]
	v_mov_b32_e32 v106, v103
	v_pk_fma_f32 v[100:101], v[36:37], v[106:107], v[100:101]
	v_exp_f32_e32 v0, v0
	v_add_f32_e32 v99, v17, v100
	v_add_f32_e32 v99, v99, v101
	s_waitcnt lgkmcnt(0)
	v_mov_b32_e32 v101, v112
	v_mov_b32_e32 v112, v109
	v_mov_b32_e32 v100, v108
	v_pk_mul_f32 v[102:103], v[30:31], v[112:113]
	v_lshl_add_u64 v[2:3], s[84:85], 0, v[2:3]
	v_pk_fma_f32 v[100:101], v[28:29], v[100:101], v[102:103]
	v_mov_b32_e32 v102, v110
	v_mov_b32_e32 v103, v114
	v_pk_fma_f32 v[100:101], v[32:33], v[102:103], v[100:101]
	v_mov_b32_e32 v114, v111
	v_pk_fma_f32 v[100:101], v[38:39], v[114:115], v[100:101]
	v_lshlrev_b32_e32 v46, 16, v14
	v_add_f32_e32 v99, v99, v100
	v_add_f32_e32 v99, v99, v101
	v_max_f32_e64 v100, -v99, 0
	v_mul_f32_e64 v99, |v99|, s57
	v_exp_f32_e32 v99, v99
	v_lshlrev_b32_e32 v15, 16, v15
	v_lshlrev_b32_e32 v9, 16, v9
	v_lshlrev_b32_e32 v8, 16, v8
	v_add_f32_e32 v99, 1.0, v99
	v_cmp_gt_f32_e64 s[4:5], s59, v99
	v_lshlrev_b32_e32 v14, 16, v44
	v_lshlrev_b32_e32 v13, 16, v45
	v_cndmask_b32_e64 v101, 0, 32, s[4:5]
	v_ldexp_f32 v99, v99, v101
	v_log_f32_e32 v99, v99
	v_lshlrev_b32_e32 v11, 16, v11
	v_lshlrev_b32_e32 v10, 16, v10
	v_lshl_add_u64 v[44:45], s[88:89], 1, v[42:43]
	v_mul_f32_e32 v101, 0x3f317217, v99
	v_fma_f32 v101, v99, s60, -v101
	v_fmac_f32_e32 v101, 0x3377d1cf, v99
	v_fmac_f32_e32 v101, 0x3f317217, v99
	v_cmp_lt_f32_e64 s[6:7], |v99|, s61
	v_lshlrev_b32_e32 v78, 16, v78
	v_writelane_b32 v251, vcc_lo, 29
	v_cndmask_b32_e64 v99, v99, v101, s[6:7]
	v_cndmask_b32_e64 v101, 0, v240, s[4:5]
	v_sub_f32_e32 v99, v99, v101
	v_add_f32_e32 v99, v100, v99
	v_fmac_f32_e32 v21, 0xbd800000, v99
	v_mul_f32_e32 v99, 0x3fb8aa3b, v21
	v_exp_f32_e32 v99, v99
	v_lshl_or_b32 v100, s30, 7, v40
	v_mov_b32_e32 v101, v41
	v_lshlrev_b64 v[100:101], 1, v[100:101]
	v_mul_f32_e32 v1, v1, v99
	v_cvt_pk_bf16_f32 v99, v1, s0
	v_mul_f32_e32 v1, 0xbfb8aa3b, v21
	v_exp_f32_e32 v1, v1
	v_lshl_add_u64 v[102:103], s[86:87], 0, v[100:101]
	v_writelane_b32 v251, vcc_hi, 30
	s_mov_b32 s8, 32
	v_pk_mul_f32 v[0:1], v[0:1], v[4:5]
	s_mov_b32 s88, s8
	v_cvt_pk_bf16_f32 v4, v0, s0
	global_store_short v[2:3], v4, off
	global_store_short v[102:103], v99, off
	v_cvt_pk_bf16_f32 v4, v1, s0
	v_lshl_add_u64 v[2:3], s[84:85], 0, v[100:101]
	global_store_short v[2:3], v4, off
	v_mov_b32_e32 v99, s34
	ds_read_b128 v[2:5], v99
	ds_read_b128 v[100:103], v99 offset:16
	ds_read_b128 v[104:107], v99 offset:32
	ds_read_b128 v[108:111], v99 offset:48
	v_cvt_pk_bf16_f32 v0, v0, v1
	s_waitcnt lgkmcnt(3)
	v_mov_b32_e32 v112, v2
	s_waitcnt lgkmcnt(2)
	v_mov_b32_e32 v113, v100
	v_mov_b32_e32 v100, v3
	v_pk_mul_f32 v[2:3], v[34:35], v[100:101]
	v_mov_b32_e32 v100, v4
	v_pk_fma_f32 v[2:3], v[26:27], v[112:113], v[2:3]
	v_mov_b32_e32 v101, v102
	v_pk_fma_f32 v[2:3], v[24:25], v[100:101], v[2:3]
	v_mov_b32_e32 v102, v5
	v_pk_fma_f32 v[2:3], v[36:37], v[102:103], v[2:3]
	s_nop 0
	v_add_f32_e32 v2, v17, v2
	v_add_f32_e32 v99, v2, v3
	s_waitcnt lgkmcnt(0)
; __device__ __forceinline__ unsigned pk2(float lo, float hi) { const f32v2_t v = {lo, hi}; const bf16v2_t b = __builtin_convertvector(v, bf16v2_t); return __builtin_bit_cast(unsigned, b); }
; __device__ __forceinline__ float softplusf_(float x) { return fmaxf(x, 0.f) + __logf(1.0f + __expf(-fabsf(x))); }
; __device__ void prep_gla(const Ctx& c, int ck, int blk) {
;     ...
;                 for (int j = 0; j < 8; ++j) { const int l = lh + l0 + j;
;                     float x = b2;
; #pragma unroll
;                     for (int r4 = 0; r4 < 16; r4 += 4) { const f32x4 lv = *(const f32x4*)(lr_s + l * 16 + r4); x += lv[0] * w2r[r4] + lv[1] * w2r[r4 + 1] + lv[2] * w2r[r4 + 2] + lv[3] * w2r[r4 + 3]; }
;                     G += -softplusf_(-x) * (1.0f / 16.0f);
;                     const float qv = qr[l0 + j] * 0.08838834764831845f, kv = kr[l0 + j];
;                     const size_t o = ((size_t)(ck * 4 + h) * 64 + l) * 128 + k;
;                     gQg[o] = f2bf(qv * __expf(G)); const float kneg = kv * __expf(-G); gKn[o] = f2bf(kneg); kn[j] = kneg; }
;                 u32x4 a; a.x = pk2(kn[0], kn[1]); a.y = pk2(kn[2], kn[3]); a.z = pk2(kn[4], kn[5]); a.w = pk2(kn[6], kn[7]);
	v_mov_b32_e32 v3, v108
	v_mov_b32_e32 v108, v105
	v_mov_b32_e32 v2, v104
	v_pk_mul_f32 v[4:5], v[30:31], v[108:109]
	s_nop 0
	v_pk_fma_f32 v[2:3], v[28:29], v[2:3], v[4:5]
	v_mov_b32_e32 v4, v106
	v_mov_b32_e32 v5, v110
	v_pk_fma_f32 v[2:3], v[32:33], v[4:5], v[2:3]
	v_mov_b32_e32 v110, v107
	v_pk_fma_f32 v[2:3], v[38:39], v[110:111], v[2:3]
	s_nop 0
	v_add_f32_e32 v2, v99, v2
	v_add_f32_e32 v2, v2, v3
	v_max_f32_e64 v3, -v2, 0
	v_mul_f32_e64 v2, |v2|, s57
	v_exp_f32_e32 v2, v2
	s_nop 0
	v_add_f32_e32 v2, 1.0, v2
	v_cmp_gt_f32_e64 s[4:5], s59, v2
	s_nop 1
	v_cndmask_b32_e64 v4, 0, 32, s[4:5]
	v_ldexp_f32 v2, v2, v4
	v_log_f32_e32 v2, v2
	s_nop 0
	v_mul_f32_e32 v4, 0x3f317217, v2
	v_fma_f32 v4, v2, s60, -v4
	v_fmac_f32_e32 v4, 0x3377d1cf, v2
	v_fmac_f32_e32 v4, 0x3f317217, v2
	v_cmp_lt_f32_e64 s[6:7], |v2|, s61
	s_nop 1
	v_cndmask_b32_e64 v2, v2, v4, s[6:7]
	v_cndmask_b32_e64 v4, 0, v240, s[4:5]
	v_sub_f32_e32 v2, v2, v4
	v_add_f32_e32 v2, v3, v2
	v_fmac_f32_e32 v21, 0xbd800000, v2
	v_mul_f32_e32 v5, 0x3fb8aa3b, v21
	v_exp_f32_e32 v5, v5
	v_mul_f32_e32 v4, 0x3db504f3, v48
	v_lshl_or_b32 v2, s44, 7, v40
	v_mov_b32_e32 v3, v41
	v_mul_f32_e32 v4, v4, v5
	v_cvt_pk_bf16_f32 v48, v4, s0
	v_lshlrev_b64 v[4:5], 1, v[2:3]
	v_lshl_add_u64 v[2:3], s[86:87], 0, v[4:5]
	global_store_short v[2:3], v48, off
	v_mov_b32_e32 v3, s92
	ds_read_b128 v[100:103], v3
	ds_read_b128 v[104:107], v3 offset:16
	ds_read_b128 v[108:111], v3 offset:32
	ds_read_b128 v[112:115], v3 offset:48
	v_mul_f32_e32 v2, 0xbfb8aa3b, v21
	s_waitcnt lgkmcnt(3)
	v_mov_b32_e32 v116, v100
	s_waitcnt lgkmcnt(2)
	v_mov_b32_e32 v117, v104
	v_mov_b32_e32 v104, v101
	v_pk_mul_f32 v[100:101], v[34:35], v[104:105]
	v_mov_b32_e32 v104, v102
	v_pk_fma_f32 v[100:101], v[26:27], v[116:117], v[100:101]
	v_mov_b32_e32 v105, v106
	v_pk_fma_f32 v[100:101], v[24:25], v[104:105], v[100:101]
	v_mov_b32_e32 v106, v103
	v_pk_fma_f32 v[100:101], v[36:37], v[106:107], v[100:101]
	v_exp_f32_e32 v2, v2
	v_add_f32_e32 v3, v17, v100
	v_add_f32_e32 v3, v3, v101
	s_waitcnt lgkmcnt(0)
	v_mov_b32_e32 v101, v112
	v_mov_b32_e32 v112, v109
	v_mov_b32_e32 v100, v108
	v_pk_mul_f32 v[102:103], v[30:31], v[112:113]
	v_lshl_add_u64 v[4:5], s[84:85], 0, v[4:5]
	v_pk_fma_f32 v[100:101], v[28:29], v[100:101], v[102:103]
	v_mov_b32_e32 v102, v110
	v_mov_b32_e32 v103, v114
	v_pk_fma_f32 v[100:101], v[32:33], v[102:103], v[100:101]
	v_mov_b32_e32 v114, v111
	v_pk_fma_f32 v[100:101], v[38:39], v[114:115], v[100:101]
	s_nop 0
	v_add_f32_e32 v3, v3, v100
	v_add_f32_e32 v3, v3, v101
	v_max_f32_e64 v48, -v3, 0
	v_mul_f32_e64 v3, |v3|, s57
	v_exp_f32_e32 v3, v3
	v_lshl_or_b32 v100, s94, 7, v40
	v_mov_b32_e32 v101, v41
	v_lshlrev_b64 v[100:101], 1, v[100:101]
	v_add_f32_e32 v3, 1.0, v3
	v_cmp_gt_f32_e64 s[4:5], s59, v3
	v_lshl_add_u64 v[102:103], s[86:87], 0, v[100:101]
	s_nop 0
	v_cndmask_b32_e64 v99, 0, 32, s[4:5]
	v_ldexp_f32 v3, v3, v99
	v_log_f32_e32 v3, v3
	s_nop 0
	v_mul_f32_e32 v99, 0x3f317217, v3
	v_fma_f32 v99, v3, s60, -v99
	v_fmac_f32_e32 v99, 0x3377d1cf, v3
	v_fmac_f32_e32 v99, 0x3f317217, v3
	v_cmp_lt_f32_e64 s[6:7], |v3|, s61
	s_nop 1
	v_cndmask_b32_e64 v3, v3, v99, s[6:7]
	v_cndmask_b32_e64 v99, 0, v240, s[4:5]
	v_sub_f32_e32 v3, v3, v99
	v_add_f32_e32 v3, v48, v3
	v_fmac_f32_e32 v21, 0xbd800000, v3
	v_mul_f32_e32 v3, 0x3db504f3, v47
	v_mul_f32_e32 v47, 0x3fb8aa3b, v21
	v_exp_f32_e32 v47, v47
	s_nop 0
	v_mul_f32_e32 v3, v3, v47
	v_cvt_pk_bf16_f32 v47, v3, s0
	v_mul_f32_e32 v3, 0xbfb8aa3b, v21
	v_exp_f32_e32 v3, v3
	s_nop 0
	v_pk_mul_f32 v[2:3], v[2:3], v[6:7]
	s_nop 0
	v_cvt_pk_bf16_f32 v6, v2, s0
	global_store_short v[4:5], v6, off
	global_store_short v[102:103], v47, off
	v_cvt_pk_bf16_f32 v6, v3, s0
	v_lshl_add_u64 v[4:5], s[84:85], 0, v[100:101]
	global_store_short v[4:5], v6, off
	v_mov_b32_e32 v47, s3
	ds_read_b128 v[4:7], v47
	ds_read_b128 v[100:103], v47 offset:16
	ds_read_b128 v[104:107], v47 offset:32
	ds_read_b128 v[108:111], v47 offset:48
	v_cvt_pk_bf16_f32 v1, v2, v3
	s_waitcnt lgkmcnt(3)
	v_mov_b32_e32 v112, v4
	s_waitcnt lgkmcnt(2)
	v_mov_b32_e32 v113, v100
	v_mov_b32_e32 v100, v5
	v_pk_mul_f32 v[4:5], v[34:35], v[100:101]
	v_mov_b32_e32 v100, v6
	v_pk_fma_f32 v[4:5], v[26:27], v[112:113], v[4:5]
	v_mov_b32_e32 v101, v102
	v_pk_fma_f32 v[4:5], v[24:25], v[100:101], v[4:5]
	v_mov_b32_e32 v102, v7
	v_pk_fma_f32 v[4:5], v[36:37], v[102:103], v[4:5]
	s_nop 0
	v_add_f32_e32 v4, v17, v4
	v_add_f32_e32 v47, v4, v5
	s_waitcnt lgkmcnt(0)
	v_mov_b32_e32 v5, v108
	v_mov_b32_e32 v108, v105
	v_mov_b32_e32 v4, v104
	v_pk_mul_f32 v[6:7], v[30:31], v[108:109]
	s_nop 0
	v_pk_fma_f32 v[4:5], v[28:29], v[4:5], v[6:7]
	v_mov_b32_e32 v6, v106
	v_mov_b32_e32 v7, v110
	v_pk_fma_f32 v[4:5], v[32:33], v[6:7], v[4:5]
	v_mov_b32_e32 v110, v107
	v_pk_fma_f32 v[4:5], v[38:39], v[110:111], v[4:5]
	s_nop 0
	v_add_f32_e32 v4, v47, v4
	v_add_f32_e32 v4, v4, v5
	v_max_f32_e64 v5, -v4, 0
	v_mul_f32_e64 v4, |v4|, s57
	v_exp_f32_e32 v4, v4
	s_nop 0
	v_add_f32_e32 v4, 1.0, v4
	v_cmp_gt_f32_e64 s[4:5], s59, v4
	s_nop 1
	v_cndmask_b32_e64 v6, 0, 32, s[4:5]
	v_ldexp_f32 v4, v4, v6
	v_log_f32_e32 v4, v4
	s_nop 0
	v_mul_f32_e32 v6, 0x3f317217, v4
	v_fma_f32 v6, v4, s60, -v6
	v_fmac_f32_e32 v6, 0x3377d1cf, v4
	v_fmac_f32_e32 v6, 0x3f317217, v4
	v_cmp_lt_f32_e64 s[6:7], |v4|, s61
	s_nop 1
	v_cndmask_b32_e64 v4, v4, v6, s[6:7]
	v_cndmask_b32_e64 v6, 0, v240, s[4:5]
	v_sub_f32_e32 v4, v4, v6
	v_add_f32_e32 v4, v5, v4
	v_fmac_f32_e32 v21, 0xbd800000, v4
	v_mul_f32_e32 v7, 0x3fb8aa3b, v21
	v_exp_f32_e32 v7, v7
	v_mul_f32_e32 v6, 0x3db504f3, v46
	v_lshl_or_b32 v4, s48, 7, v40
	v_mov_b32_e32 v5, v41
	v_mul_f32_e32 v6, v6, v7
	v_cvt_pk_bf16_f32 v46, v6, s0
	v_lshlrev_b64 v[6:7], 1, v[4:5]
	v_lshl_add_u64 v[4:5], s[86:87], 0, v[6:7]
	global_store_short v[4:5], v46, off
	v_mov_b32_e32 v5, s33
	ds_read_b128 v[100:103], v5
	ds_read_b128 v[104:107], v5 offset:16
	ds_read_b128 v[108:111], v5 offset:32
	ds_read_b128 v[112:115], v5 offset:48
	v_mul_f32_e32 v4, 0xbfb8aa3b, v21
	s_waitcnt lgkmcnt(3)
; __device__ __forceinline__ unsigned pk2(float lo, float hi) { const f32v2_t v = {lo, hi}; const bf16v2_t b = __builtin_convertvector(v, bf16v2_t); return __builtin_bit_cast(unsigned, b); }
; __device__ __forceinline__ float softplusf_(float x) { return fmaxf(x, 0.f) + __logf(1.0f + __expf(-fabsf(x))); }
; __device__ void prep_gla(const Ctx& c, int ck, int blk) {
;     ...
;                 for (int j = 0; j < 8; ++j) { const int l = lh + l0 + j;
;                     float x = b2;
; #pragma unroll
;                     for (int r4 = 0; r4 < 16; r4 += 4) { const f32x4 lv = *(const f32x4*)(lr_s + l * 16 + r4); x += lv[0] * w2r[r4] + lv[1] * w2r[r4 + 1] + lv[2] * w2r[r4 + 2] + lv[3] * w2r[r4 + 3]; }
;                     G += -softplusf_(-x) * (1.0f / 16.0f);
;                     const float qv = qr[l0 + j] * 0.08838834764831845f, kv = kr[l0 + j];
;                     const size_t o = ((size_t)(ck * 4 + h) * 64 + l) * 128 + k;
;                     gQg[o] = f2bf(qv * __expf(G)); const float kneg = kv * __expf(-G); gKn[o] = f2bf(kneg); kn[j] = kneg; }
;                 u32x4 a; a.x = pk2(kn[0], kn[1]); a.y = pk2(kn[2], kn[3]); a.z = pk2(kn[4], kn[5]); a.w = pk2(kn[6], kn[7]);
	v_mov_b32_e32 v46, v100
	s_waitcnt lgkmcnt(2)
	v_mov_b32_e32 v47, v104
	v_mov_b32_e32 v104, v101
	v_pk_mul_f32 v[100:101], v[34:35], v[104:105]
	v_exp_f32_e32 v4, v4
	v_pk_fma_f32 v[46:47], v[26:27], v[46:47], v[100:101]
	v_mov_b32_e32 v100, v102
	v_mov_b32_e32 v101, v106
	v_pk_fma_f32 v[46:47], v[24:25], v[100:101], v[46:47]
	v_mov_b32_e32 v106, v103
	v_pk_fma_f32 v[46:47], v[36:37], v[106:107], v[46:47]
	v_lshl_add_u64 v[6:7], s[84:85], 0, v[6:7]
	v_add_f32_e32 v5, v17, v46
	v_add_f32_e32 v5, v5, v47
	s_waitcnt lgkmcnt(0)
	v_mov_b32_e32 v47, v112
	v_mov_b32_e32 v112, v109
	v_mov_b32_e32 v46, v108
	v_pk_mul_f32 v[100:101], v[30:31], v[112:113]
	s_nop 0
	v_pk_fma_f32 v[46:47], v[28:29], v[46:47], v[100:101]
	v_mov_b32_e32 v100, v110
	v_mov_b32_e32 v101, v114
	v_pk_fma_f32 v[46:47], v[32:33], v[100:101], v[46:47]
	v_mov_b32_e32 v114, v111
	v_pk_fma_f32 v[46:47], v[38:39], v[114:115], v[46:47]
	s_nop 0
	v_add_f32_e32 v5, v5, v46
	v_add_f32_e32 v5, v5, v47
	v_max_f32_e64 v46, -v5, 0
	v_mul_f32_e64 v5, |v5|, s57
	v_exp_f32_e32 v5, v5
	s_nop 0
	v_add_f32_e32 v5, 1.0, v5
	v_cmp_gt_f32_e64 s[4:5], s59, v5
	s_nop 1
	v_cndmask_b32_e64 v47, 0, 32, s[4:5]
	v_ldexp_f32 v5, v5, v47
	v_log_f32_e32 v5, v5
	s_nop 0
	v_mul_f32_e32 v47, 0x3f317217, v5
	v_fma_f32 v47, v5, s60, -v47
	v_fmac_f32_e32 v47, 0x3377d1cf, v5
	v_fmac_f32_e32 v47, 0x3f317217, v5
	v_cmp_lt_f32_e64 s[6:7], |v5|, s61
	s_nop 1
	v_cndmask_b32_e64 v5, v5, v47, s[6:7]
	v_cndmask_b32_e64 v47, 0, v240, s[4:5]
	v_sub_f32_e32 v5, v5, v47
	v_add_f32_e32 v5, v46, v5
	v_fmac_f32_e32 v21, 0xbd800000, v5
	v_mul_f32_e32 v5, 0x3db504f3, v15
	v_mul_f32_e32 v15, 0x3fb8aa3b, v21
	v_exp_f32_e32 v15, v15
	v_lshl_or_b32 v46, s96, 7, v40
	v_mov_b32_e32 v47, v41
	v_lshlrev_b64 v[46:47], 1, v[46:47]
	v_mul_f32_e32 v5, v5, v15
	v_cvt_pk_bf16_f32 v15, v5, s0
	v_mul_f32_e32 v5, 0xbfb8aa3b, v21
	v_exp_f32_e32 v5, v5
	v_lshl_add_u64 v[100:101], s[86:87], 0, v[46:47]
	v_pk_mul_f32 v[4:5], v[4:5], v[8:9]
	s_nop 0
	v_cvt_pk_bf16_f32 v8, v4, s0
	global_store_short v[6:7], v8, off
	global_store_short v[100:101], v15, off
	v_cvt_pk_bf16_f32 v8, v5, s0
	v_lshl_add_u64 v[6:7], s[84:85], 0, v[46:47]
	global_store_short v[6:7], v8, off
	v_mov_b32_e32 v15, s49
	ds_read_b128 v[6:9], v15
	ds_read_b128 v[100:103], v15 offset:16
	ds_read_b128 v[104:107], v15 offset:32
	ds_read_b128 v[108:111], v15 offset:48
	v_cvt_pk_bf16_f32 v2, v4, v5
	s_waitcnt lgkmcnt(3)
	v_mov_b32_e32 v46, v6
	s_waitcnt lgkmcnt(2)
	v_mov_b32_e32 v47, v100
	v_mov_b32_e32 v100, v7
	v_pk_mul_f32 v[6:7], v[34:35], v[100:101]
	s_nop 0
	v_pk_fma_f32 v[6:7], v[26:27], v[46:47], v[6:7]
	v_mov_b32_e32 v46, v8
	v_mov_b32_e32 v47, v102
	v_pk_fma_f32 v[6:7], v[24:25], v[46:47], v[6:7]
	v_mov_b32_e32 v102, v9
	v_pk_fma_f32 v[6:7], v[36:37], v[102:103], v[6:7]
	s_nop 0
	v_add_f32_e32 v6, v17, v6
	v_add_f32_e32 v15, v6, v7
	s_waitcnt lgkmcnt(0)
	v_mov_b32_e32 v7, v108
	v_mov_b32_e32 v108, v105
	v_mov_b32_e32 v6, v104
	v_pk_mul_f32 v[8:9], v[30:31], v[108:109]
	s_nop 0
	v_pk_fma_f32 v[6:7], v[28:29], v[6:7], v[8:9]
	v_mov_b32_e32 v8, v106
	v_mov_b32_e32 v9, v110
	v_pk_fma_f32 v[6:7], v[32:33], v[8:9], v[6:7]
	v_mov_b32_e32 v110, v107
	v_pk_fma_f32 v[6:7], v[38:39], v[110:111], v[6:7]
	s_nop 0
	v_add_f32_e32 v6, v15, v6
	v_add_f32_e32 v6, v6, v7
	v_max_f32_e64 v7, -v6, 0
	v_mul_f32_e64 v6, |v6|, s57
	v_exp_f32_e32 v6, v6
	s_nop 0
	v_add_f32_e32 v6, 1.0, v6
	v_cmp_gt_f32_e64 s[4:5], s59, v6
	s_nop 1
	v_cndmask_b32_e64 v8, 0, 32, s[4:5]
	v_ldexp_f32 v6, v6, v8
	v_log_f32_e32 v6, v6
	s_nop 0
	v_mul_f32_e32 v8, 0x3f317217, v6
	v_fma_f32 v8, v6, s60, -v8
	v_fmac_f32_e32 v8, 0x3377d1cf, v6
	v_fmac_f32_e32 v8, 0x3f317217, v6
	v_cmp_lt_f32_e64 s[6:7], |v6|, s61
	s_nop 1
	v_cndmask_b32_e64 v6, v6, v8, s[6:7]
	v_cndmask_b32_e64 v8, 0, v240, s[4:5]
	v_sub_f32_e32 v6, v6, v8
	v_add_f32_e32 v6, v7, v6
	v_fmac_f32_e32 v21, 0xbd800000, v6
	v_mul_f32_e32 v9, 0x3fb8aa3b, v21
	v_exp_f32_e32 v9, v9
	v_mul_f32_e32 v8, 0x3db504f3, v14
	v_lshl_or_b32 v6, s62, 7, v40
	v_mov_b32_e32 v7, v41
	v_mul_f32_e32 v8, v8, v9
	v_lshlrev_b64 v[6:7], 1, v[6:7]
	v_cvt_pk_bf16_f32 v14, v8, s0
	v_lshl_add_u64 v[8:9], s[86:87], 0, v[6:7]
	global_store_short v[8:9], v14, off
	v_mov_b32_e32 v9, s63
	ds_read_b128 v[100:103], v9
	ds_read_b128 v[104:107], v9 offset:16
	ds_read_b128 v[108:111], v9 offset:32
	ds_read_b128 v[112:115], v9 offset:48
	v_mul_f32_e32 v8, 0xbfb8aa3b, v21
	s_waitcnt lgkmcnt(3)
	v_mov_b32_e32 v14, v100
	s_waitcnt lgkmcnt(2)
	v_mov_b32_e32 v15, v104
	v_mov_b32_e32 v104, v101
	v_pk_mul_f32 v[46:47], v[34:35], v[104:105]
	v_exp_f32_e32 v8, v8
	v_pk_fma_f32 v[14:15], v[26:27], v[14:15], v[46:47]
	v_mov_b32_e32 v46, v102
	v_mov_b32_e32 v47, v106
	v_pk_fma_f32 v[14:15], v[24:25], v[46:47], v[14:15]
	v_mov_b32_e32 v106, v103
	v_pk_fma_f32 v[14:15], v[36:37], v[106:107], v[14:15]
	v_lshl_add_u64 v[6:7], s[84:85], 0, v[6:7]
	v_add_f32_e32 v9, v17, v14
	v_add_f32_e32 v9, v9, v15
	s_waitcnt lgkmcnt(0)
; __device__ __forceinline__ unsigned pk2(float lo, float hi) { const f32v2_t v = {lo, hi}; const bf16v2_t b = __builtin_convertvector(v, bf16v2_t); return __builtin_bit_cast(unsigned, b); }
; __device__ __forceinline__ float softplusf_(float x) { return fmaxf(x, 0.f) + __logf(1.0f + __expf(-fabsf(x))); }
; __device__ void prep_gla(const Ctx& c, int ck, int blk) {
;     ...
;                 for (int j = 0; j < 8; ++j) { const int l = lh + l0 + j;
;                     float x = b2;
; #pragma unroll
;                     for (int r4 = 0; r4 < 16; r4 += 4) { const f32x4 lv = *(const f32x4*)(lr_s + l * 16 + r4); x += lv[0] * w2r[r4] + lv[1] * w2r[r4 + 1] + lv[2] * w2r[r4 + 2] + lv[3] * w2r[r4 + 3]; }
;                     G += -softplusf_(-x) * (1.0f / 16.0f);
;                     const float qv = qr[l0 + j] * 0.08838834764831845f, kv = kr[l0 + j];
;                     const size_t o = ((size_t)(ck * 4 + h) * 64 + l) * 128 + k;
;                     gQg[o] = f2bf(qv * __expf(G)); const float kneg = kv * __expf(-G); gKn[o] = f2bf(kneg); kn[j] = kneg; }
;                 u32x4 a; a.x = pk2(kn[0], kn[1]); a.y = pk2(kn[2], kn[3]); a.z = pk2(kn[4], kn[5]); a.w = pk2(kn[6], kn[7]);
;                 *(u32x4*)(gKnT + ((size_t)(ck * 4 + h) * 128 + k) * 64 + lh + l0) = a;
	v_mov_b32_e32 v15, v112
	v_mov_b32_e32 v112, v109
	v_mov_b32_e32 v14, v108
	v_pk_mul_f32 v[46:47], v[30:31], v[112:113]
	s_nop 0
	v_pk_fma_f32 v[14:15], v[28:29], v[14:15], v[46:47]
	v_mov_b32_e32 v46, v110
	v_mov_b32_e32 v47, v114
	v_pk_fma_f32 v[14:15], v[32:33], v[46:47], v[14:15]
	v_mov_b32_e32 v114, v111
	v_pk_fma_f32 v[14:15], v[38:39], v[114:115], v[14:15]
	s_nop 0
	v_add_f32_e32 v9, v9, v14
	v_add_f32_e32 v9, v9, v15
	v_max_f32_e64 v14, -v9, 0
	v_mul_f32_e64 v9, |v9|, s57
	v_exp_f32_e32 v9, v9
	s_nop 0
	v_add_f32_e32 v9, 1.0, v9
	v_cmp_gt_f32_e64 s[4:5], s59, v9
	s_nop 1
	v_cndmask_b32_e64 v15, 0, 32, s[4:5]
	v_ldexp_f32 v9, v9, v15
	v_log_f32_e32 v9, v9
	s_nop 0
	v_mul_f32_e32 v15, 0x3f317217, v9
	v_fma_f32 v15, v9, s60, -v15
	v_fmac_f32_e32 v15, 0x3377d1cf, v9
	v_fmac_f32_e32 v15, 0x3f317217, v9
	v_cmp_lt_f32_e64 s[6:7], |v9|, s61
	s_nop 1
	v_cndmask_b32_e64 v9, v9, v15, s[6:7]
	v_cndmask_b32_e64 v15, 0, v240, s[4:5]
	v_sub_f32_e32 v9, v9, v15
	v_add_f32_e32 v9, v14, v9
	v_fmac_f32_e32 v21, 0xbd800000, v9
	v_mul_f32_e32 v9, 0x3db504f3, v13
	v_mul_f32_e32 v13, 0x3fb8aa3b, v21
	v_exp_f32_e32 v13, v13
	v_lshl_or_b32 v14, s54, 7, v40
	v_mov_b32_e32 v15, v41
	v_lshlrev_b64 v[14:15], 1, v[14:15]
	v_mul_f32_e32 v9, v9, v13
	v_cvt_pk_bf16_f32 v13, v9, s0
	v_mul_f32_e32 v9, 0xbfb8aa3b, v21
	v_exp_f32_e32 v9, v9
	v_lshl_add_u64 v[46:47], s[86:87], 0, v[14:15]
	v_pk_mul_f32 v[8:9], v[8:9], v[10:11]
	s_nop 0
	v_cvt_pk_bf16_f32 v10, v8, s0
	global_store_short v[6:7], v10, off
	global_store_short v[46:47], v13, off
	v_cvt_pk_bf16_f32 v10, v9, s0
	v_lshl_add_u64 v[6:7], s[84:85], 0, v[14:15]
	v_cvt_pk_bf16_f32 v3, v8, v9
	v_readlane_b32 s0, v253, 49
	global_store_short v[6:7], v10, off
	global_store_dwordx4 v[44:45], v[0:3], off
	v_mov_b32_e32 v13, s0
	ds_read_b128 v[0:3], v13
	ds_read_b128 v[4:7], v13 offset:16
	ds_read_b128 v[8:11], v13 offset:32
	ds_read_b128 v[100:103], v13 offset:48
	s_waitcnt lgkmcnt(3)
	v_mov_b32_e32 v14, v0
	s_waitcnt lgkmcnt(2)
	v_mov_b32_e32 v15, v4
	v_mov_b32_e32 v4, v1
	v_pk_mul_f32 v[0:1], v[34:35], v[4:5]
	v_mov_b32_e32 v4, v2
	v_pk_fma_f32 v[0:1], v[26:27], v[14:15], v[0:1]
	v_mov_b32_e32 v5, v6
	v_pk_fma_f32 v[0:1], v[24:25], v[4:5], v[0:1]
	v_mov_b32_e32 v6, v3
	v_pk_fma_f32 v[0:1], v[36:37], v[6:7], v[0:1]
	s_nop 0
	v_add_f32_e32 v0, v17, v0
	v_add_f32_e32 v4, v0, v1
	s_waitcnt lgkmcnt(0)
	v_mov_b32_e32 v1, v100
	v_mov_b32_e32 v100, v9
	v_mov_b32_e32 v0, v8
	v_pk_mul_f32 v[2:3], v[30:31], v[100:101]
	s_nop 0
	v_pk_fma_f32 v[0:1], v[28:29], v[0:1], v[2:3]
	v_mov_b32_e32 v2, v10
	v_mov_b32_e32 v3, v102
	v_pk_fma_f32 v[0:1], v[32:33], v[2:3], v[0:1]
	v_mov_b32_e32 v102, v11
	v_pk_fma_f32 v[0:1], v[38:39], v[102:103], v[0:1]
	s_nop 0
	v_add_f32_e32 v0, v4, v0
	v_add_f32_e32 v0, v0, v1
	v_max_f32_e64 v1, -v0, 0
	v_mul_f32_e64 v0, |v0|, s57
	v_exp_f32_e32 v0, v0
	s_nop 0
	v_add_f32_e32 v0, 1.0, v0
	v_cmp_gt_f32_e64 s[4:5], s59, v0
	s_nop 1
	v_cndmask_b32_e64 v2, 0, 32, s[4:5]
	v_ldexp_f32 v0, v0, v2
	v_log_f32_e32 v0, v0
	s_nop 0
	v_mul_f32_e32 v2, 0x3f317217, v0
	v_fma_f32 v2, v0, s60, -v2
	v_fmac_f32_e32 v2, 0x3377d1cf, v0
	v_fmac_f32_e32 v2, 0x3f317217, v0
	v_cmp_lt_f32_e64 s[6:7], |v0|, s61
	s_nop 1
	v_cndmask_b32_e64 v0, v0, v2, s[6:7]
	v_cndmask_b32_e64 v2, 0, v240, s[4:5]
	v_sub_f32_e32 v0, v0, v2
	v_add_f32_e32 v0, v1, v0
	v_fmac_f32_e32 v21, 0xbd800000, v0
	v_mul_f32_e32 v3, 0x3fb8aa3b, v21
	v_exp_f32_e32 v3, v3
	v_mul_f32_e32 v2, 0x3db504f3, v12
	v_lshl_or_b32 v0, s2, 7, v40
	v_mov_b32_e32 v1, v41
	v_mul_f32_e32 v2, v2, v3
	v_lshlrev_b64 v[0:1], 1, v[0:1]
	v_cvt_pk_bf16_f32 v4, v2, s0
	v_lshl_add_u64 v[2:3], s[86:87], 0, v[0:1]
	v_readlane_b32 s0, v255, 7
	global_store_short v[2:3], v4, off
	v_mul_f32_e32 v2, 0xbfb8aa3b, v21
	v_mov_b32_e32 v8, s0
	v_exp_f32_e32 v48, v2
	v_lshl_add_u64 v[46:47], s[84:85], 0, v[0:1]
	ds_read_b128 v[0:3], v8
	ds_read_b128 v[12:15], v8 offset:16
	ds_read_b128 v[4:7], v8 offset:32
	ds_read_b128 v[8:11], v8 offset:48
	v_readlane_b32 s2, v251, 29
	s_waitcnt lgkmcnt(3)
	v_mov_b32_e32 v100, v0
	s_waitcnt lgkmcnt(2)
	v_mov_b32_e32 v101, v12
	v_mov_b32_e32 v12, v1
	v_pk_mul_f32 v[0:1], v[34:35], v[12:13]
	v_mov_b32_e32 v12, v2
	v_pk_fma_f32 v[0:1], v[26:27], v[100:101], v[0:1]
	v_mov_b32_e32 v13, v14
	v_pk_fma_f32 v[0:1], v[24:25], v[12:13], v[0:1]
	v_mov_b32_e32 v14, v3
	v_pk_fma_f32 v[0:1], v[36:37], v[14:15], v[0:1]
	v_readlane_b32 s3, v251, 30
	v_add_f32_e32 v0, v17, v0
	v_add_f32_e32 v12, v0, v1
	s_waitcnt lgkmcnt(0)
	v_mov_b32_e32 v1, v8
	v_mov_b32_e32 v8, v5
	v_mov_b32_e32 v0, v4
	v_pk_mul_f32 v[2:3], v[30:31], v[8:9]
	s_and_b64 vcc, exec, s[2:3]
	v_pk_fma_f32 v[0:1], v[28:29], v[0:1], v[2:3]
	v_mov_b32_e32 v2, v6
	v_mov_b32_e32 v3, v10
	v_pk_fma_f32 v[0:1], v[32:33], v[2:3], v[0:1]
	v_mov_b32_e32 v10, v7
	v_pk_fma_f32 v[0:1], v[38:39], v[10:11], v[0:1]
	s_nop 0
	v_add_f32_e32 v0, v12, v0
	v_add_f32_e32 v0, v0, v1
	v_max_f32_e64 v1, -v0, 0
	v_mul_f32_e64 v0, |v0|, s57
	v_exp_f32_e32 v0, v0
	s_nop 0
	v_add_f32_e32 v0, 1.0, v0
	v_cmp_gt_f32_e64 s[4:5], s59, v0
	s_nop 1
	v_cndmask_b32_e64 v2, 0, 32, s[4:5]
	v_ldexp_f32 v0, v0, v2
	v_log_f32_e32 v0, v0
	s_nop 0
	v_mul_f32_e32 v2, 0x3f317217, v0
	v_fma_f32 v2, v0, s60, -v2
	v_fmac_f32_e32 v2, 0x3377d1cf, v0
	v_fmac_f32_e32 v2, 0x3f317217, v0
	v_cmp_lt_f32_e64 s[6:7], |v0|, s61
	s_nop 1
	v_cndmask_b32_e64 v0, v0, v2, s[6:7]
	v_cndmask_b32_e64 v2, 0, v240, s[4:5]
	v_sub_f32_e32 v0, v0, v2
	v_add_f32_e32 v0, v1, v0
	v_fmac_f32_e32 v21, 0xbd800000, v0
	v_mul_f32_e32 v3, 0x3fb8aa3b, v21
	v_exp_f32_e32 v3, v3
	v_mul_f32_e32 v2, 0x3db504f3, v49
	v_lshl_or_b32 v0, s35, 7, v40
	v_mov_b32_e32 v1, v41
	v_mul_f32_e32 v2, v2, v3
	v_cvt_pk_bf16_f32 v6, v2, s0
	v_lshlrev_b64 v[2:3], 1, v[0:1]
	v_mul_f32_e32 v0, 0xbfb8aa3b, v21
	v_exp_f32_e32 v49, v0
	v_lshlrev_b32_e32 v1, 16, v96
	v_lshlrev_b32_e32 v0, 16, v95
	v_lshl_add_u64 v[4:5], s[86:87], 0, v[2:3]
	v_pk_mul_f32 v[0:1], v[48:49], v[0:1]
	v_lshl_add_u64 v[2:3], s[84:85], 0, v[2:3]
	v_cvt_pk_bf16_f32 v7, v0, s0
	global_store_short v[46:47], v7, off
	global_store_short v[4:5], v6, off
	v_cvt_pk_bf16_f32 v4, v1, s0
	v_readlane_b32 s0, v253, 51
	global_store_short v[2:3], v4, off
	v_cvt_pk_bf16_f32 v0, v0, v1
	v_mov_b32_e32 v14, s0
	ds_read_b128 v[2:5], v14
	ds_read_b128 v[6:9], v14 offset:16
	ds_read_b128 v[10:13], v14 offset:32
	ds_read_b128 v[46:49], v14 offset:48
	s_waitcnt lgkmcnt(3)
; __device__ __forceinline__ unsigned pk2(float lo, float hi) { const f32v2_t v = {lo, hi}; const bf16v2_t b = __builtin_convertvector(v, bf16v2_t); return __builtin_bit_cast(unsigned, b); }
; __device__ __forceinline__ float softplusf_(float x) { return fmaxf(x, 0.f) + __logf(1.0f + __expf(-fabsf(x))); }
; __device__ void prep_gla(const Ctx& c, int ck, int blk) {
;     ...
;                 for (int j = 0; j < 8; ++j) { const int l = lh + l0 + j;
;                     float x = b2;
; #pragma unroll
;                     for (int r4 = 0; r4 < 16; r4 += 4) { const f32x4 lv = *(const f32x4*)(lr_s + l * 16 + r4); x += lv[0] * w2r[r4] + lv[1] * w2r[r4 + 1] + lv[2] * w2r[r4 + 2] + lv[3] * w2r[r4 + 3]; }
;                     G += -softplusf_(-x) * (1.0f / 16.0f);
;                     const float qv = qr[l0 + j] * 0.08838834764831845f, kv = kr[l0 + j];
;                     const size_t o = ((size_t)(ck * 4 + h) * 64 + l) * 128 + k;
;                     gQg[o] = f2bf(qv * __expf(G)); const float kneg = kv * __expf(-G); gKn[o] = f2bf(kneg); kn[j] = kneg; }
;                 u32x4 a; a.x = pk2(kn[0], kn[1]); a.y = pk2(kn[2], kn[3]); a.z = pk2(kn[4], kn[5]); a.w = pk2(kn[6], kn[7]);
	v_mov_b32_e32 v14, v2
	s_waitcnt lgkmcnt(2)
	v_mov_b32_e32 v15, v6
	v_mov_b32_e32 v6, v3
	v_pk_mul_f32 v[2:3], v[34:35], v[6:7]
	v_mov_b32_e32 v6, v4
	v_pk_fma_f32 v[2:3], v[26:27], v[14:15], v[2:3]
	v_mov_b32_e32 v7, v8
	v_pk_fma_f32 v[2:3], v[24:25], v[6:7], v[2:3]
	v_mov_b32_e32 v8, v5
	v_pk_fma_f32 v[2:3], v[36:37], v[8:9], v[2:3]
	s_nop 0
	v_add_f32_e32 v2, v17, v2
	v_add_f32_e32 v6, v2, v3
	s_waitcnt lgkmcnt(0)
	v_mov_b32_e32 v3, v46
	v_mov_b32_e32 v46, v11
	v_mov_b32_e32 v2, v10
	v_pk_mul_f32 v[4:5], v[30:31], v[46:47]
	s_nop 0
	v_pk_fma_f32 v[2:3], v[28:29], v[2:3], v[4:5]
	v_mov_b32_e32 v4, v12
	v_mov_b32_e32 v5, v48
	v_pk_fma_f32 v[2:3], v[32:33], v[4:5], v[2:3]
	v_mov_b32_e32 v48, v13
	v_pk_fma_f32 v[2:3], v[38:39], v[48:49], v[2:3]
	s_nop 0
	v_add_f32_e32 v2, v6, v2
	v_add_f32_e32 v2, v2, v3
	v_max_f32_e64 v3, -v2, 0
	v_mul_f32_e64 v2, |v2|, s57
	v_exp_f32_e32 v2, v2
	s_nop 0
	v_add_f32_e32 v2, 1.0, v2
	v_cmp_gt_f32_e64 s[4:5], s59, v2
	s_nop 1
	v_cndmask_b32_e64 v4, 0, 32, s[4:5]
	v_ldexp_f32 v2, v2, v4
	v_log_f32_e32 v2, v2
	s_nop 0
	v_mul_f32_e32 v4, 0x3f317217, v2
	v_fma_f32 v4, v2, s60, -v4
	v_fmac_f32_e32 v4, 0x3377d1cf, v2
	v_fmac_f32_e32 v4, 0x3f317217, v2
	v_cmp_lt_f32_e64 s[6:7], |v2|, s61
	s_nop 1
	v_cndmask_b32_e64 v2, v2, v4, s[6:7]
	v_cndmask_b32_e64 v4, 0, v240, s[4:5]
	v_sub_f32_e32 v2, v2, v4
	v_add_f32_e32 v2, v3, v2
	v_fmac_f32_e32 v21, 0xbd800000, v2
	v_mul_f32_e32 v5, 0x3fb8aa3b, v21
	v_exp_f32_e32 v5, v5
	v_mul_f32_e32 v4, 0x3db504f3, v98
	v_lshl_or_b32 v2, s45, 7, v40
	v_mov_b32_e32 v3, v41
	v_mul_f32_e32 v4, v4, v5
	v_cvt_pk_bf16_f32 v6, v4, s0
	v_lshlrev_b64 v[4:5], 1, v[2:3]
	v_lshl_add_u64 v[2:3], s[86:87], 0, v[4:5]
	v_readlane_b32 s0, v255, 5
	global_store_short v[2:3], v6, off
	v_mul_f32_e32 v2, 0xbfb8aa3b, v21
	v_mov_b32_e32 v3, s0
	ds_read_b128 v[6:9], v3
	ds_read_b128 v[10:13], v3 offset:16
	ds_read_b128 v[46:49], v3 offset:32
	ds_read_b128 v[98:101], v3 offset:48
	v_exp_f32_e32 v2, v2
	s_waitcnt lgkmcnt(3)
	v_mov_b32_e32 v14, v6
	s_waitcnt lgkmcnt(2)
	v_mov_b32_e32 v15, v10
	v_mov_b32_e32 v10, v7
	v_pk_mul_f32 v[6:7], v[34:35], v[10:11]
	v_mov_b32_e32 v10, v8
	v_pk_fma_f32 v[6:7], v[26:27], v[14:15], v[6:7]
	v_mov_b32_e32 v11, v12
	v_pk_fma_f32 v[6:7], v[24:25], v[10:11], v[6:7]
	v_mov_b32_e32 v12, v9
	v_pk_fma_f32 v[6:7], v[36:37], v[12:13], v[6:7]
	v_lshlrev_b32_e32 v11, 16, v92
	v_add_f32_e32 v3, v17, v6
	v_add_f32_e32 v3, v3, v7
	s_waitcnt lgkmcnt(0)
	v_mov_b32_e32 v7, v98
	v_mov_b32_e32 v98, v47
	v_mov_b32_e32 v6, v46
	v_pk_mul_f32 v[8:9], v[30:31], v[98:99]
	v_lshlrev_b32_e32 v10, 16, v91
	v_pk_fma_f32 v[6:7], v[28:29], v[6:7], v[8:9]
	v_mov_b32_e32 v8, v48
	v_mov_b32_e32 v9, v100
	v_pk_fma_f32 v[6:7], v[32:33], v[8:9], v[6:7]
	v_mov_b32_e32 v100, v49
	v_pk_fma_f32 v[6:7], v[38:39], v[100:101], v[6:7]
	v_lshl_add_u64 v[4:5], s[84:85], 0, v[4:5]
	v_add_f32_e32 v3, v3, v6
	v_add_f32_e32 v3, v3, v7
	v_max_f32_e64 v6, -v3, 0
	v_mul_f32_e64 v3, |v3|, s57
	v_exp_f32_e32 v3, v3
	s_nop 0
	v_add_f32_e32 v3, 1.0, v3
	v_cmp_gt_f32_e64 s[4:5], s59, v3
	s_nop 1
	v_cndmask_b32_e64 v7, 0, 32, s[4:5]
	v_ldexp_f32 v3, v3, v7
	v_log_f32_e32 v3, v3
	s_nop 0
	v_mul_f32_e32 v7, 0x3f317217, v3
	v_fma_f32 v7, v3, s60, -v7
	v_fmac_f32_e32 v7, 0x3377d1cf, v3
	v_fmac_f32_e32 v7, 0x3f317217, v3
	v_cmp_lt_f32_e64 s[6:7], |v3|, s61
	s_nop 1
	v_cndmask_b32_e64 v3, v3, v7, s[6:7]
	v_cndmask_b32_e64 v7, 0, v240, s[4:5]
	v_sub_f32_e32 v3, v3, v7
	v_add_f32_e32 v3, v6, v3
	v_fmac_f32_e32 v21, 0xbd800000, v3
	v_mul_f32_e32 v8, 0x3fb8aa3b, v21
	v_exp_f32_e32 v8, v8
	v_mul_f32_e32 v3, 0x3db504f3, v97
	v_lshl_or_b32 v6, s55, 7, v40
	v_mov_b32_e32 v7, v41
	v_mul_f32_e32 v3, v3, v8
	v_cvt_pk_bf16_f32 v12, v3, s0
	v_mul_f32_e32 v3, 0xbfb8aa3b, v21
	v_exp_f32_e32 v3, v3
	v_lshlrev_b64 v[6:7], 1, v[6:7]
	v_lshl_add_u64 v[8:9], s[86:87], 0, v[6:7]
	v_pk_mul_f32 v[2:3], v[2:3], v[10:11]
	s_nop 0
	v_cvt_pk_bf16_f32 v10, v2, s0
	global_store_short v[4:5], v10, off
	global_store_short v[8:9], v12, off
	v_cvt_pk_bf16_f32 v8, v3, s0
	v_lshl_add_u64 v[4:5], s[84:85], 0, v[6:7]
	v_readlane_b32 s0, v253, 53
	global_store_short v[4:5], v8, off
	v_cvt_pk_bf16_f32 v1, v2, v3
	v_mov_b32_e32 v46, s0
	ds_read_b128 v[4:7], v46
	ds_read_b128 v[8:11], v46 offset:16
	ds_read_b128 v[12:15], v46 offset:32
	ds_read_b128 v[46:49], v46 offset:48
	s_waitcnt lgkmcnt(3)
	v_mov_b32_e32 v96, v4
	s_waitcnt lgkmcnt(2)
	v_mov_b32_e32 v97, v8
	v_mov_b32_e32 v8, v5
	v_pk_mul_f32 v[4:5], v[34:35], v[8:9]
	v_mov_b32_e32 v8, v6
	v_pk_fma_f32 v[4:5], v[26:27], v[96:97], v[4:5]
	v_mov_b32_e32 v9, v10
	v_pk_fma_f32 v[4:5], v[24:25], v[8:9], v[4:5]
	v_mov_b32_e32 v10, v7
	v_pk_fma_f32 v[4:5], v[36:37], v[10:11], v[4:5]
	s_nop 0
	v_add_f32_e32 v4, v17, v4
	v_add_f32_e32 v8, v4, v5
	s_waitcnt lgkmcnt(0)
	v_mov_b32_e32 v5, v46
	v_mov_b32_e32 v46, v13
	v_mov_b32_e32 v4, v12
	v_pk_mul_f32 v[6:7], v[30:31], v[46:47]
	s_nop 0
	v_pk_fma_f32 v[4:5], v[28:29], v[4:5], v[6:7]
	v_mov_b32_e32 v6, v14
	v_mov_b32_e32 v7, v48
	v_pk_fma_f32 v[4:5], v[32:33], v[6:7], v[4:5]
	v_mov_b32_e32 v48, v15
	v_pk_fma_f32 v[4:5], v[38:39], v[48:49], v[4:5]
	s_nop 0
	v_add_f32_e32 v4, v8, v4
	v_add_f32_e32 v4, v4, v5
	v_max_f32_e64 v5, -v4, 0
	v_mul_f32_e64 v4, |v4|, s57
	v_exp_f32_e32 v4, v4
	s_nop 0
	v_add_f32_e32 v4, 1.0, v4
	v_cmp_gt_f32_e64 s[4:5], s59, v4
	s_nop 1
	v_cndmask_b32_e64 v6, 0, 32, s[4:5]
	v_ldexp_f32 v4, v4, v6
	v_log_f32_e32 v4, v4
	s_nop 0
	v_mul_f32_e32 v6, 0x3f317217, v4
	v_fma_f32 v6, v4, s60, -v6
	v_fmac_f32_e32 v6, 0x3377d1cf, v4
	v_fmac_f32_e32 v6, 0x3f317217, v4
	v_cmp_lt_f32_e64 s[6:7], |v4|, s61
	s_nop 1
	v_cndmask_b32_e64 v4, v4, v6, s[6:7]
	v_cndmask_b32_e64 v6, 0, v240, s[4:5]
	v_sub_f32_e32 v4, v4, v6
	v_add_f32_e32 v4, v5, v4
	v_fmac_f32_e32 v21, 0xbd800000, v4
	v_mul_f32_e32 v7, 0x3fb8aa3b, v21
	v_exp_f32_e32 v7, v7
	v_mul_f32_e32 v6, 0x3db504f3, v94
	v_lshl_or_b32 v4, s93, 7, v40
	v_mov_b32_e32 v5, v41
	v_mul_f32_e32 v6, v6, v7
	v_cvt_pk_bf16_f32 v8, v6, s0
	v_lshlrev_b64 v[6:7], 1, v[4:5]
	v_lshl_add_u64 v[4:5], s[86:87], 0, v[6:7]
	v_readlane_b32 s0, v253, 61
	global_store_short v[4:5], v8, off
	v_mul_f32_e32 v4, 0xbfb8aa3b, v21
	v_mov_b32_e32 v5, s0
	ds_read_b128 v[8:11], v5
	ds_read_b128 v[12:15], v5 offset:16
	ds_read_b128 v[46:49], v5 offset:32
	ds_read_b128 v[94:97], v5 offset:48
	v_exp_f32_e32 v4, v4
	s_waitcnt lgkmcnt(3)
; __device__ __forceinline__ unsigned pk2(float lo, float hi) { const f32v2_t v = {lo, hi}; const bf16v2_t b = __builtin_convertvector(v, bf16v2_t); return __builtin_bit_cast(unsigned, b); }
; __device__ __forceinline__ float softplusf_(float x) { return fmaxf(x, 0.f) + __logf(1.0f + __expf(-fabsf(x))); }
; __device__ void prep_gla(const Ctx& c, int ck, int blk) {
;     ...
;                 for (int j = 0; j < 8; ++j) { const int l = lh + l0 + j;
;                     float x = b2;
; #pragma unroll
;                     for (int r4 = 0; r4 < 16; r4 += 4) { const f32x4 lv = *(const f32x4*)(lr_s + l * 16 + r4); x += lv[0] * w2r[r4] + lv[1] * w2r[r4 + 1] + lv[2] * w2r[r4 + 2] + lv[3] * w2r[r4 + 3]; }
;                     G += -softplusf_(-x) * (1.0f / 16.0f);
;                     const float qv = qr[l0 + j] * 0.08838834764831845f, kv = kr[l0 + j];
;                     const size_t o = ((size_t)(ck * 4 + h) * 64 + l) * 128 + k;
;                     gQg[o] = f2bf(qv * __expf(G)); const float kneg = kv * __expf(-G); gKn[o] = f2bf(kneg); kn[j] = kneg; }
;                 u32x4 a; a.x = pk2(kn[0], kn[1]); a.y = pk2(kn[2], kn[3]); a.z = pk2(kn[4], kn[5]); a.w = pk2(kn[6], kn[7]);
	v_mov_b32_e32 v98, v8
	s_waitcnt lgkmcnt(2)
	v_mov_b32_e32 v99, v12
	v_mov_b32_e32 v12, v9
	v_pk_mul_f32 v[8:9], v[34:35], v[12:13]
	v_mov_b32_e32 v12, v10
	v_pk_fma_f32 v[8:9], v[26:27], v[98:99], v[8:9]
	v_mov_b32_e32 v13, v14
	v_pk_fma_f32 v[8:9], v[24:25], v[12:13], v[8:9]
	v_mov_b32_e32 v14, v11
	v_pk_fma_f32 v[8:9], v[36:37], v[14:15], v[8:9]
	v_lshlrev_b32_e32 v13, 16, v88
	v_add_f32_e32 v5, v17, v8
	v_add_f32_e32 v5, v5, v9
	s_waitcnt lgkmcnt(0)
	v_mov_b32_e32 v9, v94
	v_mov_b32_e32 v94, v47
	v_mov_b32_e32 v8, v46
	v_pk_mul_f32 v[10:11], v[30:31], v[94:95]
	v_lshlrev_b32_e32 v12, 16, v87
	v_pk_fma_f32 v[8:9], v[28:29], v[8:9], v[10:11]
	v_mov_b32_e32 v10, v48
	v_mov_b32_e32 v11, v96
	v_pk_fma_f32 v[8:9], v[32:33], v[10:11], v[8:9]
	v_mov_b32_e32 v96, v49
	v_pk_fma_f32 v[8:9], v[38:39], v[96:97], v[8:9]
	v_lshl_add_u64 v[6:7], s[84:85], 0, v[6:7]
	v_add_f32_e32 v5, v5, v8
	v_add_f32_e32 v5, v5, v9
	v_max_f32_e64 v8, -v5, 0
	v_mul_f32_e64 v5, |v5|, s57
	v_exp_f32_e32 v5, v5
	s_nop 0
	v_add_f32_e32 v5, 1.0, v5
	v_cmp_gt_f32_e64 s[4:5], s59, v5
	s_nop 1
	v_cndmask_b32_e64 v9, 0, 32, s[4:5]
	v_ldexp_f32 v5, v5, v9
	v_log_f32_e32 v5, v5
	s_nop 0
	v_mul_f32_e32 v9, 0x3f317217, v5
	v_fma_f32 v9, v5, s60, -v9
	v_fmac_f32_e32 v9, 0x3377d1cf, v5
	v_fmac_f32_e32 v9, 0x3f317217, v5
	v_cmp_lt_f32_e64 s[6:7], |v5|, s61
	s_nop 1
	v_cndmask_b32_e64 v5, v5, v9, s[6:7]
	v_cndmask_b32_e64 v9, 0, v240, s[4:5]
	v_sub_f32_e32 v5, v5, v9
	v_add_f32_e32 v5, v8, v5
	v_fmac_f32_e32 v21, 0xbd800000, v5
	v_mul_f32_e32 v10, 0x3fb8aa3b, v21
	v_exp_f32_e32 v10, v10
	v_mul_f32_e32 v5, 0x3db504f3, v93
	v_lshl_or_b32 v8, s95, 7, v40
	v_mov_b32_e32 v9, v41
	v_mul_f32_e32 v5, v5, v10
	v_cvt_pk_bf16_f32 v14, v5, s0
	v_mul_f32_e32 v5, 0xbfb8aa3b, v21
	v_exp_f32_e32 v5, v5
	v_lshlrev_b64 v[8:9], 1, v[8:9]
	v_lshl_add_u64 v[10:11], s[86:87], 0, v[8:9]
	v_pk_mul_f32 v[4:5], v[4:5], v[12:13]
	s_nop 0
	v_cvt_pk_bf16_f32 v12, v4, s0
	global_store_short v[6:7], v12, off
	global_store_short v[10:11], v14, off
	v_cvt_pk_bf16_f32 v10, v5, s0
	v_lshl_add_u64 v[6:7], s[84:85], 0, v[8:9]
	v_readlane_b32 s0, v253, 59
	global_store_short v[6:7], v10, off
	v_cvt_pk_bf16_f32 v2, v4, v5
	v_mov_b32_e32 v14, s0
	ds_read_b128 v[6:9], v14
	ds_read_b128 v[10:13], v14 offset:16
	ds_read_b128 v[46:49], v14 offset:32
	ds_read_b128 v[92:95], v14 offset:48
	s_waitcnt lgkmcnt(3)
	v_mov_b32_e32 v14, v6
	s_waitcnt lgkmcnt(2)
	v_mov_b32_e32 v15, v10
	v_mov_b32_e32 v10, v7
	v_pk_mul_f32 v[6:7], v[34:35], v[10:11]
	v_mov_b32_e32 v10, v8
	v_pk_fma_f32 v[6:7], v[26:27], v[14:15], v[6:7]
	v_mov_b32_e32 v11, v12
	v_pk_fma_f32 v[6:7], v[24:25], v[10:11], v[6:7]
	v_mov_b32_e32 v12, v9
	v_pk_fma_f32 v[6:7], v[36:37], v[12:13], v[6:7]
	s_nop 0
	v_add_f32_e32 v6, v17, v6
	v_add_f32_e32 v10, v6, v7
	s_waitcnt lgkmcnt(0)
	v_mov_b32_e32 v7, v92
	v_mov_b32_e32 v92, v47
	v_mov_b32_e32 v6, v46
	v_pk_mul_f32 v[8:9], v[30:31], v[92:93]
	s_nop 0
	v_pk_fma_f32 v[6:7], v[28:29], v[6:7], v[8:9]
	v_mov_b32_e32 v8, v48
	v_mov_b32_e32 v9, v94
	v_pk_fma_f32 v[6:7], v[32:33], v[8:9], v[6:7]
	v_mov_b32_e32 v94, v49
	v_pk_fma_f32 v[6:7], v[38:39], v[94:95], v[6:7]
	s_nop 0
	v_add_f32_e32 v6, v10, v6
	v_add_f32_e32 v6, v6, v7
	v_max_f32_e64 v7, -v6, 0
	v_mul_f32_e64 v6, |v6|, s57
	v_exp_f32_e32 v6, v6
	s_nop 0
	v_add_f32_e32 v6, 1.0, v6
	v_cmp_gt_f32_e64 s[4:5], s59, v6
	s_nop 1
	v_cndmask_b32_e64 v8, 0, 32, s[4:5]
	v_ldexp_f32 v6, v6, v8
	v_log_f32_e32 v6, v6
	s_nop 0
	v_mul_f32_e32 v8, 0x3f317217, v6
	v_fma_f32 v8, v6, s60, -v8
	v_fmac_f32_e32 v8, 0x3377d1cf, v6
	v_fmac_f32_e32 v8, 0x3f317217, v6
	v_cmp_lt_f32_e64 s[6:7], |v6|, s61
	s_nop 1
	v_cndmask_b32_e64 v6, v6, v8, s[6:7]
	v_cndmask_b32_e64 v8, 0, v240, s[4:5]
	v_sub_f32_e32 v6, v6, v8
	v_add_f32_e32 v6, v7, v6
	v_fmac_f32_e32 v21, 0xbd800000, v6
	v_mul_f32_e32 v9, 0x3fb8aa3b, v21
	v_exp_f32_e32 v9, v9
	v_mul_f32_e32 v8, 0x3db504f3, v90
	v_lshl_or_b32 v6, s90, 7, v40
	v_mov_b32_e32 v7, v41
	v_mul_f32_e32 v8, v8, v9
	v_lshlrev_b64 v[6:7], 1, v[6:7]
	v_cvt_pk_bf16_f32 v10, v8, s0
	v_lshl_add_u64 v[8:9], s[86:87], 0, v[6:7]
	v_readlane_b32 s0, v253, 57
	global_store_short v[8:9], v10, off
	v_mul_f32_e32 v8, 0xbfb8aa3b, v21
	v_mov_b32_e32 v9, s0
	ds_read_b128 v[10:13], v9
	ds_read_b128 v[46:49], v9 offset:16
	ds_read_b128 v[90:93], v9 offset:32
	ds_read_b128 v[94:97], v9 offset:48
	v_exp_f32_e32 v8, v8
	s_waitcnt lgkmcnt(3)
	v_mov_b32_e32 v14, v10
	s_waitcnt lgkmcnt(2)
	v_mov_b32_e32 v15, v46
	v_mov_b32_e32 v46, v11
	v_pk_mul_f32 v[10:11], v[34:35], v[46:47]
	v_lshl_add_u64 v[6:7], s[84:85], 0, v[6:7]
	v_pk_fma_f32 v[10:11], v[26:27], v[14:15], v[10:11]
	v_mov_b32_e32 v14, v12
	v_mov_b32_e32 v15, v48
	v_pk_fma_f32 v[10:11], v[24:25], v[14:15], v[10:11]
	v_mov_b32_e32 v48, v13
	v_pk_fma_f32 v[10:11], v[36:37], v[48:49], v[10:11]
	v_lshlrev_b32_e32 v15, 16, v85
	v_add_f32_e32 v9, v17, v10
	v_add_f32_e32 v9, v9, v11
	s_waitcnt lgkmcnt(0)
; __device__ __forceinline__ unsigned pk2(float lo, float hi) { const f32v2_t v = {lo, hi}; const bf16v2_t b = __builtin_convertvector(v, bf16v2_t); return __builtin_bit_cast(unsigned, b); }
; __device__ __forceinline__ float softplusf_(float x) { return fmaxf(x, 0.f) + __logf(1.0f + __expf(-fabsf(x))); }
; __device__ void prep_gla(const Ctx& c, int ck, int blk) {
;     ...
;                 for (int j = 0; j < 8; ++j) { const int l = lh + l0 + j;
;                     float x = b2;
; #pragma unroll
;                     for (int r4 = 0; r4 < 16; r4 += 4) { const f32x4 lv = *(const f32x4*)(lr_s + l * 16 + r4); x += lv[0] * w2r[r4] + lv[1] * w2r[r4 + 1] + lv[2] * w2r[r4 + 2] + lv[3] * w2r[r4 + 3]; }
;                     G += -softplusf_(-x) * (1.0f / 16.0f);
;                     const float qv = qr[l0 + j] * 0.08838834764831845f, kv = kr[l0 + j];
;                     const size_t o = ((size_t)(ck * 4 + h) * 64 + l) * 128 + k;
;                     gQg[o] = f2bf(qv * __expf(G)); const float kneg = kv * __expf(-G); gKn[o] = f2bf(kneg); kn[j] = kneg; }
;                 u32x4 a; a.x = pk2(kn[0], kn[1]); a.y = pk2(kn[2], kn[3]); a.z = pk2(kn[4], kn[5]); a.w = pk2(kn[6], kn[7]);
;                 *(u32x4*)(gKnT + ((size_t)(ck * 4 + h) * 128 + k) * 64 + lh + l0) = a;
	v_mov_b32_e32 v11, v94
	v_mov_b32_e32 v94, v91
	v_mov_b32_e32 v10, v90
	v_pk_mul_f32 v[12:13], v[30:31], v[94:95]
	v_lshlrev_b32_e32 v14, 16, v84
	v_pk_fma_f32 v[10:11], v[28:29], v[10:11], v[12:13]
	v_mov_b32_e32 v12, v92
	v_mov_b32_e32 v13, v96
	v_pk_fma_f32 v[10:11], v[32:33], v[12:13], v[10:11]
	v_mov_b32_e32 v96, v93
	v_pk_fma_f32 v[10:11], v[38:39], v[96:97], v[10:11]
	s_nop 0
	v_add_f32_e32 v9, v9, v10
	v_add_f32_e32 v9, v9, v11
	v_max_f32_e64 v10, -v9, 0
	v_mul_f32_e64 v9, |v9|, s57
	v_exp_f32_e32 v9, v9
	s_nop 0
	v_add_f32_e32 v9, 1.0, v9
	v_cmp_gt_f32_e64 s[4:5], s59, v9
	s_nop 1
	v_cndmask_b32_e64 v11, 0, 32, s[4:5]
	v_ldexp_f32 v9, v9, v11
	v_log_f32_e32 v9, v9
	s_nop 0
	v_mul_f32_e32 v11, 0x3f317217, v9
	v_fma_f32 v11, v9, s60, -v11
	v_fmac_f32_e32 v11, 0x3377d1cf, v9
	v_fmac_f32_e32 v11, 0x3f317217, v9
	v_cmp_lt_f32_e64 s[6:7], |v9|, s61
	s_nop 1
	v_cndmask_b32_e64 v9, v9, v11, s[6:7]
	v_cndmask_b32_e64 v11, 0, v240, s[4:5]
	v_sub_f32_e32 v9, v9, v11
	v_add_f32_e32 v9, v10, v9
	v_fmac_f32_e32 v21, 0xbd800000, v9
	v_mul_f32_e32 v12, 0x3fb8aa3b, v21
	v_exp_f32_e32 v12, v12
	v_mul_f32_e32 v9, 0x3db504f3, v89
	v_lshl_or_b32 v10, s97, 7, v40
	v_mov_b32_e32 v11, v41
	v_mul_f32_e32 v9, v9, v12
	v_cvt_pk_bf16_f32 v46, v9, s0
	v_mul_f32_e32 v9, 0xbfb8aa3b, v21
	v_exp_f32_e32 v9, v9
	v_lshlrev_b64 v[10:11], 1, v[10:11]
	v_lshl_add_u64 v[12:13], s[86:87], 0, v[10:11]
	v_pk_mul_f32 v[8:9], v[8:9], v[14:15]
	s_nop 0
	v_cvt_pk_bf16_f32 v14, v8, s0
	global_store_short v[6:7], v14, off
	global_store_short v[12:13], v46, off
	v_cvt_pk_bf16_f32 v12, v9, s0
	v_lshl_add_u64 v[6:7], s[84:85], 0, v[10:11]
	v_cvt_pk_bf16_f32 v3, v8, v9
	v_readlane_b32 s0, v255, 3
	global_store_short v[6:7], v12, off
	global_store_dwordx4 v[44:45], v[0:3], off offset:16
	v_mov_b32_e32 v12, s0
	ds_read_b128 v[0:3], v12
	ds_read_b128 v[4:7], v12 offset:16
	ds_read_b128 v[8:11], v12 offset:32
	ds_read_b128 v[12:15], v12 offset:48
	v_readlane_b32 s0, v255, 1
	s_waitcnt lgkmcnt(3)
	v_mov_b32_e32 v46, v0
	s_waitcnt lgkmcnt(2)
	v_mov_b32_e32 v47, v4
	v_mov_b32_e32 v4, v1
	v_pk_mul_f32 v[0:1], v[34:35], v[4:5]
	v_mov_b32_e32 v4, v2
	v_pk_fma_f32 v[0:1], v[26:27], v[46:47], v[0:1]
	v_mov_b32_e32 v5, v6
	v_pk_fma_f32 v[0:1], v[24:25], v[4:5], v[0:1]
	v_mov_b32_e32 v6, v3
	v_pk_fma_f32 v[0:1], v[36:37], v[6:7], v[0:1]
	s_nop 0
	v_add_f32_e32 v0, v17, v0
	v_add_f32_e32 v4, v0, v1
	s_waitcnt lgkmcnt(0)
	v_mov_b32_e32 v1, v12
	v_mov_b32_e32 v12, v9
	v_mov_b32_e32 v0, v8
	v_pk_mul_f32 v[2:3], v[30:31], v[12:13]
	s_nop 0
	v_pk_fma_f32 v[0:1], v[28:29], v[0:1], v[2:3]
	v_mov_b32_e32 v2, v10
	v_mov_b32_e32 v3, v14
	v_pk_fma_f32 v[0:1], v[32:33], v[2:3], v[0:1]
	v_mov_b32_e32 v14, v11
	v_pk_fma_f32 v[0:1], v[38:39], v[14:15], v[0:1]
	s_nop 0
	v_add_f32_e32 v0, v4, v0
	v_add_f32_e32 v0, v0, v1
	v_max_f32_e64 v1, -v0, 0
	v_mul_f32_e64 v0, |v0|, s57
	v_exp_f32_e32 v0, v0
	s_nop 0
	v_add_f32_e32 v0, 1.0, v0
	v_cmp_gt_f32_e64 s[4:5], s59, v0
	s_nop 1
	v_cndmask_b32_e64 v2, 0, 32, s[4:5]
	v_ldexp_f32 v0, v0, v2
	v_log_f32_e32 v0, v0
	s_nop 0
	v_mul_f32_e32 v2, 0x3f317217, v0
	v_fma_f32 v2, v0, s60, -v2
	v_fmac_f32_e32 v2, 0x3377d1cf, v0
	v_fmac_f32_e32 v2, 0x3f317217, v0
	v_cmp_lt_f32_e64 s[6:7], |v0|, s61
	s_nop 1
	v_cndmask_b32_e64 v0, v0, v2, s[6:7]
	v_cndmask_b32_e64 v2, 0, v240, s[4:5]
	v_sub_f32_e32 v0, v0, v2
	v_add_f32_e32 v0, v1, v0
	v_fmac_f32_e32 v21, 0xbd800000, v0
	v_mul_f32_e32 v3, 0x3fb8aa3b, v21
	v_exp_f32_e32 v3, v3
	v_mul_f32_e32 v2, 0x3db504f3, v86
	v_lshl_or_b32 v0, s0, 7, v40
	v_mov_b32_e32 v1, v41
	v_mul_f32_e32 v2, v2, v3
	v_cvt_pk_bf16_f32 v4, v2, s0
	v_lshlrev_b64 v[2:3], 1, v[0:1]
	v_lshl_add_u64 v[0:1], s[86:87], 0, v[2:3]
	v_readlane_b32 s0, v253, 63
	global_store_short v[0:1], v4, off
	v_mul_f32_e32 v0, 0xbfb8aa3b, v21
	v_mov_b32_e32 v1, s0
	ds_read_b128 v[4:7], v1
	ds_read_b128 v[8:11], v1 offset:16
	ds_read_b128 v[12:15], v1 offset:32
	ds_read_b128 v[46:49], v1 offset:48
	v_readlane_b32 s0, v253, 55
	s_waitcnt lgkmcnt(3)
	v_mov_b32_e32 v84, v4
	s_waitcnt lgkmcnt(2)
	v_mov_b32_e32 v85, v8
	v_mov_b32_e32 v8, v5
	v_pk_mul_f32 v[4:5], v[34:35], v[8:9]
	v_mov_b32_e32 v8, v6
	v_pk_fma_f32 v[4:5], v[26:27], v[84:85], v[4:5]
	v_mov_b32_e32 v9, v10
	v_pk_fma_f32 v[4:5], v[24:25], v[8:9], v[4:5]
	v_mov_b32_e32 v10, v7
	v_pk_fma_f32 v[4:5], v[36:37], v[10:11], v[4:5]
	v_exp_f32_e32 v0, v0
	v_add_f32_e32 v1, v17, v4
	v_add_f32_e32 v1, v1, v5
	s_waitcnt lgkmcnt(0)
	v_mov_b32_e32 v5, v46
	v_mov_b32_e32 v46, v13
	v_mov_b32_e32 v4, v12
	v_pk_mul_f32 v[6:7], v[30:31], v[46:47]
	v_lshlrev_b32_e32 v9, 16, v81
	v_pk_fma_f32 v[4:5], v[28:29], v[4:5], v[6:7]
	v_mov_b32_e32 v6, v14
	v_mov_b32_e32 v7, v48
	v_pk_fma_f32 v[4:5], v[32:33], v[6:7], v[4:5]
	v_mov_b32_e32 v48, v15
	v_pk_fma_f32 v[4:5], v[38:39], v[48:49], v[4:5]
	v_lshlrev_b32_e32 v8, 16, v80
	v_add_f32_e32 v1, v1, v4
	v_add_f32_e32 v1, v1, v5
	v_max_f32_e64 v4, -v1, 0
	v_mul_f32_e64 v1, |v1|, s57
	v_exp_f32_e32 v1, v1
	v_lshl_add_u64 v[2:3], s[84:85], 0, v[2:3]
	v_add_f32_e32 v1, 1.0, v1
	v_cmp_gt_f32_e64 s[4:5], s59, v1
	s_nop 1
	v_cndmask_b32_e64 v5, 0, 32, s[4:5]
	v_ldexp_f32 v1, v1, v5
	v_log_f32_e32 v1, v1
	s_nop 0
	v_mul_f32_e32 v5, 0x3f317217, v1
	v_fma_f32 v5, v1, s60, -v5
	v_fmac_f32_e32 v5, 0x3377d1cf, v1
	v_fmac_f32_e32 v5, 0x3f317217, v1
	v_cmp_lt_f32_e64 s[6:7], |v1|, s61
	s_nop 1
	v_cndmask_b32_e64 v1, v1, v5, s[6:7]
	v_cndmask_b32_e64 v5, 0, v240, s[4:5]
	v_sub_f32_e32 v1, v1, v5
	v_add_f32_e32 v1, v4, v1
	v_fmac_f32_e32 v21, 0xbd800000, v1
	v_mul_f32_e32 v6, 0x3fb8aa3b, v21
	v_exp_f32_e32 v6, v6
	v_mul_f32_e32 v1, 0x3db504f3, v83
	v_lshl_or_b32 v4, s0, 7, v40
	v_mov_b32_e32 v5, v41
	v_mul_f32_e32 v1, v1, v6
	v_cvt_pk_bf16_f32 v10, v1, s0
	v_mul_f32_e32 v1, 0xbfb8aa3b, v21
	v_exp_f32_e32 v1, v1
	v_lshlrev_b64 v[4:5], 1, v[4:5]
	v_lshl_add_u64 v[6:7], s[86:87], 0, v[4:5]
	v_pk_mul_f32 v[0:1], v[0:1], v[8:9]
	s_nop 0
	v_cvt_pk_bf16_f32 v8, v0, s0
	global_store_short v[2:3], v8, off
	global_store_short v[6:7], v10, off
	v_cvt_pk_bf16_f32 v6, v1, s0
	v_lshl_add_u64 v[2:3], s[84:85], 0, v[4:5]
	v_readlane_b32 s0, v253, 31
	global_store_short v[2:3], v6, off
	v_cvt_pk_bf16_f32 v0, v0, v1
	v_mov_b32_e32 v14, s0
	ds_read_b128 v[2:5], v14
	ds_read_b128 v[6:9], v14 offset:16
	ds_read_b128 v[10:13], v14 offset:32
	ds_read_b128 v[46:49], v14 offset:48
	v_readlane_b32 s0, v249, 49
	s_waitcnt lgkmcnt(3)
; __device__ __forceinline__ unsigned pk2(float lo, float hi) { const f32v2_t v = {lo, hi}; const bf16v2_t b = __builtin_convertvector(v, bf16v2_t); return __builtin_bit_cast(unsigned, b); }
; __device__ __forceinline__ float softplusf_(float x) { return fmaxf(x, 0.f) + __logf(1.0f + __expf(-fabsf(x))); }
; __device__ void prep_gla(const Ctx& c, int ck, int blk) {
;     ...
;                 for (int j = 0; j < 8; ++j) { const int l = lh + l0 + j;
;                     float x = b2;
; #pragma unroll
;                     for (int r4 = 0; r4 < 16; r4 += 4) { const f32x4 lv = *(const f32x4*)(lr_s + l * 16 + r4); x += lv[0] * w2r[r4] + lv[1] * w2r[r4 + 1] + lv[2] * w2r[r4 + 2] + lv[3] * w2r[r4 + 3]; }
;                     G += -softplusf_(-x) * (1.0f / 16.0f);
;                     const float qv = qr[l0 + j] * 0.08838834764831845f, kv = kr[l0 + j];
;                     const size_t o = ((size_t)(ck * 4 + h) * 64 + l) * 128 + k;
;                     gQg[o] = f2bf(qv * __expf(G)); const float kneg = kv * __expf(-G); gKn[o] = f2bf(kneg); kn[j] = kneg; }
;                 u32x4 a; a.x = pk2(kn[0], kn[1]); a.y = pk2(kn[2], kn[3]); a.z = pk2(kn[4], kn[5]); a.w = pk2(kn[6], kn[7]);
	v_mov_b32_e32 v14, v2
	s_waitcnt lgkmcnt(2)
	v_mov_b32_e32 v15, v6
	v_mov_b32_e32 v6, v3
	v_pk_mul_f32 v[2:3], v[34:35], v[6:7]
	v_mov_b32_e32 v6, v4
	v_pk_fma_f32 v[2:3], v[26:27], v[14:15], v[2:3]
	v_mov_b32_e32 v7, v8
	v_pk_fma_f32 v[2:3], v[24:25], v[6:7], v[2:3]
	v_mov_b32_e32 v8, v5
	v_pk_fma_f32 v[2:3], v[36:37], v[8:9], v[2:3]
	s_nop 0
	v_add_f32_e32 v2, v17, v2
	v_add_f32_e32 v6, v2, v3
	s_waitcnt lgkmcnt(0)
	v_mov_b32_e32 v3, v46
	v_mov_b32_e32 v46, v11
	v_mov_b32_e32 v2, v10
	v_pk_mul_f32 v[4:5], v[30:31], v[46:47]
	s_nop 0
	v_pk_fma_f32 v[2:3], v[28:29], v[2:3], v[4:5]
	v_mov_b32_e32 v4, v12
	v_mov_b32_e32 v5, v48
	v_pk_fma_f32 v[2:3], v[32:33], v[4:5], v[2:3]
	v_mov_b32_e32 v48, v13
	v_pk_fma_f32 v[2:3], v[38:39], v[48:49], v[2:3]
	s_nop 0
	v_add_f32_e32 v2, v6, v2
	v_add_f32_e32 v2, v2, v3
	v_max_f32_e64 v3, -v2, 0
	v_mul_f32_e64 v2, |v2|, s57
	v_exp_f32_e32 v2, v2
	s_nop 0
	v_add_f32_e32 v2, 1.0, v2
	v_cmp_gt_f32_e64 s[4:5], s59, v2
	s_nop 1
	v_cndmask_b32_e64 v4, 0, 32, s[4:5]
	v_ldexp_f32 v2, v2, v4
	v_log_f32_e32 v2, v2
	s_nop 0
	v_mul_f32_e32 v4, 0x3f317217, v2
	v_fma_f32 v4, v2, s60, -v4
	v_fmac_f32_e32 v4, 0x3377d1cf, v2
	v_fmac_f32_e32 v4, 0x3f317217, v2
	v_cmp_lt_f32_e64 s[6:7], |v2|, s61
	s_nop 1
	v_cndmask_b32_e64 v2, v2, v4, s[6:7]
	v_cndmask_b32_e64 v4, 0, v240, s[4:5]
	v_sub_f32_e32 v2, v2, v4
	v_add_f32_e32 v2, v3, v2
	v_fmac_f32_e32 v21, 0xbd800000, v2
	v_mul_f32_e32 v5, 0x3fb8aa3b, v21
	v_exp_f32_e32 v5, v5
	v_mul_f32_e32 v4, 0x3db504f3, v82
	v_lshl_or_b32 v2, s0, 7, v40
	v_mov_b32_e32 v3, v41
	v_mul_f32_e32 v4, v4, v5
	v_cvt_pk_bf16_f32 v6, v4, s0
	v_lshlrev_b64 v[4:5], 1, v[2:3]
	v_lshl_add_u64 v[2:3], s[86:87], 0, v[4:5]
	v_readlane_b32 s0, v253, 33
	global_store_short v[2:3], v6, off
	v_mul_f32_e32 v2, 0xbfb8aa3b, v21
	v_mov_b32_e32 v3, s0
	ds_read_b128 v[6:9], v3
	ds_read_b128 v[10:13], v3 offset:16
	ds_read_b128 v[46:49], v3 offset:32
	ds_read_b128 v[80:83], v3 offset:48
	v_readlane_b32 s0, v253, 29
	s_waitcnt lgkmcnt(3)
	v_mov_b32_e32 v14, v6
	s_waitcnt lgkmcnt(2)
	v_mov_b32_e32 v15, v10
	v_mov_b32_e32 v10, v7
	v_pk_mul_f32 v[6:7], v[34:35], v[10:11]
	v_mov_b32_e32 v10, v8
	v_pk_fma_f32 v[6:7], v[26:27], v[14:15], v[6:7]
	v_mov_b32_e32 v11, v12
	v_pk_fma_f32 v[6:7], v[24:25], v[10:11], v[6:7]
	v_mov_b32_e32 v12, v9
	v_pk_fma_f32 v[6:7], v[36:37], v[12:13], v[6:7]
	v_exp_f32_e32 v2, v2
	v_add_f32_e32 v3, v17, v6
	v_add_f32_e32 v3, v3, v7
	s_waitcnt lgkmcnt(0)
	v_mov_b32_e32 v7, v80
	v_mov_b32_e32 v80, v47
	v_mov_b32_e32 v6, v46
	v_pk_mul_f32 v[8:9], v[30:31], v[80:81]
	v_lshlrev_b32_e32 v11, 16, v77
	v_pk_fma_f32 v[6:7], v[28:29], v[6:7], v[8:9]
	v_mov_b32_e32 v8, v48
	v_mov_b32_e32 v9, v82
	v_pk_fma_f32 v[6:7], v[32:33], v[8:9], v[6:7]
	v_mov_b32_e32 v82, v49
	v_pk_fma_f32 v[6:7], v[38:39], v[82:83], v[6:7]
	v_lshlrev_b32_e32 v10, 16, v76
	v_add_f32_e32 v3, v3, v6
	v_add_f32_e32 v3, v3, v7
	v_max_f32_e64 v6, -v3, 0
	v_mul_f32_e64 v3, |v3|, s57
	v_exp_f32_e32 v3, v3
	v_lshl_add_u64 v[4:5], s[84:85], 0, v[4:5]
	v_add_f32_e32 v3, 1.0, v3
	v_cmp_gt_f32_e64 s[4:5], s59, v3
	s_nop 1
	v_cndmask_b32_e64 v7, 0, 32, s[4:5]
	v_ldexp_f32 v3, v3, v7
	v_log_f32_e32 v3, v3
	s_nop 0
	v_mul_f32_e32 v7, 0x3f317217, v3
	v_fma_f32 v7, v3, s60, -v7
	v_fmac_f32_e32 v7, 0x3377d1cf, v3
	v_fmac_f32_e32 v7, 0x3f317217, v3
	v_cmp_lt_f32_e64 s[6:7], |v3|, s61
	s_nop 1
	v_cndmask_b32_e64 v3, v3, v7, s[6:7]
	v_cndmask_b32_e64 v7, 0, v240, s[4:5]
	v_sub_f32_e32 v3, v3, v7
	v_add_f32_e32 v3, v6, v3
	v_fmac_f32_e32 v21, 0xbd800000, v3
	v_mul_f32_e32 v8, 0x3fb8aa3b, v21
	v_exp_f32_e32 v8, v8
	v_mul_f32_e32 v3, 0x3db504f3, v79
	v_lshl_or_b32 v6, s0, 7, v40
	v_mov_b32_e32 v7, v41
	v_mul_f32_e32 v3, v3, v8
	v_cvt_pk_bf16_f32 v12, v3, s0
	v_mul_f32_e32 v3, 0xbfb8aa3b, v21
	v_exp_f32_e32 v3, v3
	v_lshlrev_b64 v[6:7], 1, v[6:7]
	v_lshl_add_u64 v[8:9], s[86:87], 0, v[6:7]
	v_pk_mul_f32 v[2:3], v[2:3], v[10:11]
	s_nop 0
	v_cvt_pk_bf16_f32 v10, v2, s0
	global_store_short v[4:5], v10, off
	global_store_short v[8:9], v12, off
	v_cvt_pk_bf16_f32 v8, v3, s0
	v_lshl_add_u64 v[4:5], s[84:85], 0, v[6:7]
	v_readlane_b32 s0, v253, 41
	global_store_short v[4:5], v8, off
	v_cvt_pk_bf16_f32 v1, v2, v3
	v_mov_b32_e32 v46, s0
	ds_read_b128 v[4:7], v46
	ds_read_b128 v[8:11], v46 offset:16
	ds_read_b128 v[12:15], v46 offset:32
	ds_read_b128 v[46:49], v46 offset:48
	v_readlane_b32 s0, v253, 39
	s_waitcnt lgkmcnt(3)
	v_mov_b32_e32 v76, v4
	s_waitcnt lgkmcnt(2)
	v_mov_b32_e32 v77, v8
	v_mov_b32_e32 v8, v5
	v_pk_mul_f32 v[4:5], v[34:35], v[8:9]
	v_mov_b32_e32 v8, v6
	v_pk_fma_f32 v[4:5], v[26:27], v[76:77], v[4:5]
	v_mov_b32_e32 v9, v10
	v_pk_fma_f32 v[4:5], v[24:25], v[8:9], v[4:5]
	v_mov_b32_e32 v10, v7
	v_pk_fma_f32 v[4:5], v[36:37], v[10:11], v[4:5]
	s_nop 0
	v_add_f32_e32 v4, v17, v4
	v_add_f32_e32 v8, v4, v5
	s_waitcnt lgkmcnt(0)
	v_mov_b32_e32 v5, v46
	v_mov_b32_e32 v46, v13
	v_mov_b32_e32 v4, v12
	v_pk_mul_f32 v[6:7], v[30:31], v[46:47]
	s_nop 0
	v_pk_fma_f32 v[4:5], v[28:29], v[4:5], v[6:7]
	v_mov_b32_e32 v6, v14
	v_mov_b32_e32 v7, v48
	v_pk_fma_f32 v[4:5], v[32:33], v[6:7], v[4:5]
	v_mov_b32_e32 v48, v15
	v_pk_fma_f32 v[4:5], v[38:39], v[48:49], v[4:5]
	s_nop 0
	v_add_f32_e32 v4, v8, v4
	v_add_f32_e32 v4, v4, v5
	v_max_f32_e64 v5, -v4, 0
	v_mul_f32_e64 v4, |v4|, s57
	v_exp_f32_e32 v4, v4
	s_nop 0
	v_add_f32_e32 v4, 1.0, v4
	v_cmp_gt_f32_e64 s[4:5], s59, v4
	s_nop 1
	v_cndmask_b32_e64 v6, 0, 32, s[4:5]
	v_ldexp_f32 v4, v4, v6
	v_log_f32_e32 v4, v4
	s_nop 0
	v_mul_f32_e32 v6, 0x3f317217, v4
	v_fma_f32 v6, v4, s60, -v6
	v_fmac_f32_e32 v6, 0x3377d1cf, v4
	v_fmac_f32_e32 v6, 0x3f317217, v4
	v_cmp_lt_f32_e64 s[6:7], |v4|, s61
	s_nop 1
	v_cndmask_b32_e64 v4, v4, v6, s[6:7]
	v_cndmask_b32_e64 v6, 0, v240, s[4:5]
	v_sub_f32_e32 v4, v4, v6
	v_add_f32_e32 v4, v5, v4
	v_fmac_f32_e32 v21, 0xbd800000, v4
	v_mul_f32_e32 v7, 0x3fb8aa3b, v21
	v_exp_f32_e32 v7, v7
	v_mul_f32_e32 v6, 0x3db504f3, v78
	v_lshl_or_b32 v4, s0, 7, v40
	v_mov_b32_e32 v5, v41
	v_mul_f32_e32 v6, v6, v7
	v_cvt_pk_bf16_f32 v8, v6, s0
	v_lshlrev_b64 v[6:7], 1, v[4:5]
	v_lshl_add_u64 v[4:5], s[86:87], 0, v[6:7]
	v_readlane_b32 s0, v253, 37
	global_store_short v[4:5], v8, off
	v_mul_f32_e32 v4, 0xbfb8aa3b, v21
	v_mov_b32_e32 v5, s0
	ds_read_b128 v[8:11], v5
	ds_read_b128 v[12:15], v5 offset:16
	ds_read_b128 v[46:49], v5 offset:32
	ds_read_b128 v[76:79], v5 offset:48
	v_readlane_b32 s0, v253, 35
	s_waitcnt lgkmcnt(3)
; __device__ __forceinline__ unsigned pk2(float lo, float hi) { const f32v2_t v = {lo, hi}; const bf16v2_t b = __builtin_convertvector(v, bf16v2_t); return __builtin_bit_cast(unsigned, b); }
; __device__ __forceinline__ float softplusf_(float x) { return fmaxf(x, 0.f) + __logf(1.0f + __expf(-fabsf(x))); }
; __device__ void prep_gla(const Ctx& c, int ck, int blk) {
;     ...
;                 for (int j = 0; j < 8; ++j) { const int l = lh + l0 + j;
;                     float x = b2;
; #pragma unroll
;                     for (int r4 = 0; r4 < 16; r4 += 4) { const f32x4 lv = *(const f32x4*)(lr_s + l * 16 + r4); x += lv[0] * w2r[r4] + lv[1] * w2r[r4 + 1] + lv[2] * w2r[r4 + 2] + lv[3] * w2r[r4 + 3]; }
;                     G += -softplusf_(-x) * (1.0f / 16.0f);
;                     const float qv = qr[l0 + j] * 0.08838834764831845f, kv = kr[l0 + j];
;                     const size_t o = ((size_t)(ck * 4 + h) * 64 + l) * 128 + k;
;                     gQg[o] = f2bf(qv * __expf(G)); const float kneg = kv * __expf(-G); gKn[o] = f2bf(kneg); kn[j] = kneg; }
;                 u32x4 a; a.x = pk2(kn[0], kn[1]); a.y = pk2(kn[2], kn[3]); a.z = pk2(kn[4], kn[5]); a.w = pk2(kn[6], kn[7]);
	v_mov_b32_e32 v80, v8
	s_waitcnt lgkmcnt(2)
	v_mov_b32_e32 v81, v12
	v_mov_b32_e32 v12, v9
	v_pk_mul_f32 v[8:9], v[34:35], v[12:13]
	v_mov_b32_e32 v12, v10
	v_pk_fma_f32 v[8:9], v[26:27], v[80:81], v[8:9]
	v_mov_b32_e32 v13, v14
	v_pk_fma_f32 v[8:9], v[24:25], v[12:13], v[8:9]
	v_mov_b32_e32 v14, v11
	v_pk_fma_f32 v[8:9], v[36:37], v[14:15], v[8:9]
	v_exp_f32_e32 v4, v4
	v_add_f32_e32 v5, v17, v8
	v_add_f32_e32 v5, v5, v9
	s_waitcnt lgkmcnt(0)
	v_mov_b32_e32 v9, v76
	v_mov_b32_e32 v76, v47
	v_mov_b32_e32 v8, v46
	v_pk_mul_f32 v[10:11], v[30:31], v[76:77]
	v_lshlrev_b32_e32 v13, 16, v73
	v_pk_fma_f32 v[8:9], v[28:29], v[8:9], v[10:11]
	v_mov_b32_e32 v10, v48
	v_mov_b32_e32 v11, v78
	v_pk_fma_f32 v[8:9], v[32:33], v[10:11], v[8:9]
	v_mov_b32_e32 v78, v49
	v_pk_fma_f32 v[8:9], v[38:39], v[78:79], v[8:9]
	v_lshlrev_b32_e32 v12, 16, v72
	v_add_f32_e32 v5, v5, v8
	v_add_f32_e32 v5, v5, v9
	v_max_f32_e64 v8, -v5, 0
	v_mul_f32_e64 v5, |v5|, s57
	v_exp_f32_e32 v5, v5
	v_lshl_add_u64 v[6:7], s[84:85], 0, v[6:7]
	v_add_f32_e32 v5, 1.0, v5
	v_cmp_gt_f32_e64 s[4:5], s59, v5
	s_nop 1
	v_cndmask_b32_e64 v9, 0, 32, s[4:5]
	v_ldexp_f32 v5, v5, v9
	v_log_f32_e32 v5, v5
	s_nop 0
	v_mul_f32_e32 v9, 0x3f317217, v5
	v_fma_f32 v9, v5, s60, -v9
	v_fmac_f32_e32 v9, 0x3377d1cf, v5
	v_fmac_f32_e32 v9, 0x3f317217, v5
	v_cmp_lt_f32_e64 s[6:7], |v5|, s61
	s_nop 1
	v_cndmask_b32_e64 v5, v5, v9, s[6:7]
	v_cndmask_b32_e64 v9, 0, v240, s[4:5]
	v_sub_f32_e32 v5, v5, v9
	v_add_f32_e32 v5, v8, v5
	v_fmac_f32_e32 v21, 0xbd800000, v5
	v_mul_f32_e32 v10, 0x3fb8aa3b, v21
	v_exp_f32_e32 v10, v10
	v_mul_f32_e32 v5, 0x3db504f3, v75
	v_lshl_or_b32 v8, s0, 7, v40
	v_mov_b32_e32 v9, v41
	v_mul_f32_e32 v5, v5, v10
	v_cvt_pk_bf16_f32 v14, v5, s0
	v_mul_f32_e32 v5, 0xbfb8aa3b, v21
	v_exp_f32_e32 v5, v5
	v_lshlrev_b64 v[8:9], 1, v[8:9]
	v_lshl_add_u64 v[10:11], s[86:87], 0, v[8:9]
	v_pk_mul_f32 v[4:5], v[4:5], v[12:13]
	s_nop 0
	v_cvt_pk_bf16_f32 v12, v4, s0
	global_store_short v[6:7], v12, off
	global_store_short v[10:11], v14, off
	v_cvt_pk_bf16_f32 v10, v5, s0
	v_lshl_add_u64 v[6:7], s[84:85], 0, v[8:9]
	v_readlane_b32 s0, v249, 47
	global_store_short v[6:7], v10, off
	v_cvt_pk_bf16_f32 v2, v4, v5
	v_mov_b32_e32 v14, s0
	ds_read_b128 v[6:9], v14
	ds_read_b128 v[10:13], v14 offset:16
	ds_read_b128 v[46:49], v14 offset:32
	ds_read_b128 v[76:79], v14 offset:48
	v_readlane_b32 s0, v254, 33
	s_waitcnt lgkmcnt(3)
	v_mov_b32_e32 v14, v6
	s_waitcnt lgkmcnt(2)
	v_mov_b32_e32 v15, v10
	v_mov_b32_e32 v10, v7
	v_pk_mul_f32 v[6:7], v[34:35], v[10:11]
	v_mov_b32_e32 v10, v8
	v_pk_fma_f32 v[6:7], v[26:27], v[14:15], v[6:7]
	v_mov_b32_e32 v11, v12
	v_pk_fma_f32 v[6:7], v[24:25], v[10:11], v[6:7]
	v_mov_b32_e32 v12, v9
	v_pk_fma_f32 v[6:7], v[36:37], v[12:13], v[6:7]
	s_nop 0
	v_add_f32_e32 v6, v17, v6
	v_add_f32_e32 v10, v6, v7
	s_waitcnt lgkmcnt(0)
	v_mov_b32_e32 v7, v76
	v_mov_b32_e32 v76, v47
	v_mov_b32_e32 v6, v46
	v_pk_mul_f32 v[8:9], v[30:31], v[76:77]
	s_nop 0
	v_pk_fma_f32 v[6:7], v[28:29], v[6:7], v[8:9]
	v_mov_b32_e32 v8, v48
	v_mov_b32_e32 v9, v78
	v_pk_fma_f32 v[6:7], v[32:33], v[8:9], v[6:7]
	v_mov_b32_e32 v78, v49
	v_pk_fma_f32 v[6:7], v[38:39], v[78:79], v[6:7]
	s_nop 0
	v_add_f32_e32 v6, v10, v6
	v_add_f32_e32 v6, v6, v7
	v_max_f32_e64 v7, -v6, 0
	v_mul_f32_e64 v6, |v6|, s57
	v_exp_f32_e32 v6, v6
	s_nop 0
	v_add_f32_e32 v6, 1.0, v6
	v_cmp_gt_f32_e64 s[4:5], s59, v6
	s_nop 1
	v_cndmask_b32_e64 v8, 0, 32, s[4:5]
	v_ldexp_f32 v6, v6, v8
	v_log_f32_e32 v6, v6
	s_nop 0
	v_mul_f32_e32 v8, 0x3f317217, v6
	v_fma_f32 v8, v6, s60, -v8
	v_fmac_f32_e32 v8, 0x3377d1cf, v6
	v_fmac_f32_e32 v8, 0x3f317217, v6
	v_cmp_lt_f32_e64 s[6:7], |v6|, s61
	s_nop 1
	v_cndmask_b32_e64 v6, v6, v8, s[6:7]
	v_cndmask_b32_e64 v8, 0, v240, s[4:5]
	v_sub_f32_e32 v6, v6, v8
	v_add_f32_e32 v6, v7, v6
	v_fmac_f32_e32 v21, 0xbd800000, v6
	v_mul_f32_e32 v9, 0x3fb8aa3b, v21
	v_exp_f32_e32 v9, v9
	v_mul_f32_e32 v8, 0x3db504f3, v74
	v_lshl_or_b32 v6, s0, 7, v40
	v_mov_b32_e32 v7, v41
	v_mul_f32_e32 v8, v8, v9
	v_lshlrev_b64 v[6:7], 1, v[6:7]
	v_cvt_pk_bf16_f32 v10, v8, s0
	v_lshl_add_u64 v[8:9], s[86:87], 0, v[6:7]
	v_readlane_b32 s0, v252, 29
	global_store_short v[8:9], v10, off
	v_mul_f32_e32 v8, 0xbfb8aa3b, v21
	v_mov_b32_e32 v9, s0
	ds_read_b128 v[10:13], v9
	ds_read_b128 v[46:49], v9 offset:16
	ds_read_b128 v[72:75], v9 offset:32
	ds_read_b128 v[76:79], v9 offset:48
	v_readlane_b32 s0, v252, 23
	s_waitcnt lgkmcnt(3)
	v_mov_b32_e32 v14, v10
	s_waitcnt lgkmcnt(2)
	v_mov_b32_e32 v15, v46
	v_mov_b32_e32 v46, v11
	v_pk_mul_f32 v[10:11], v[34:35], v[46:47]
	v_exp_f32_e32 v8, v8
	v_pk_fma_f32 v[10:11], v[26:27], v[14:15], v[10:11]
	v_mov_b32_e32 v14, v12
	v_mov_b32_e32 v15, v48
	v_pk_fma_f32 v[10:11], v[24:25], v[14:15], v[10:11]
	v_mov_b32_e32 v48, v13
	v_pk_fma_f32 v[10:11], v[36:37], v[48:49], v[10:11]
	v_lshlrev_b32_e32 v15, 16, v70
	v_add_f32_e32 v9, v17, v10
	v_add_f32_e32 v9, v9, v11
	s_waitcnt lgkmcnt(0)
; __device__ __forceinline__ unsigned pk2(float lo, float hi) { const f32v2_t v = {lo, hi}; const bf16v2_t b = __builtin_convertvector(v, bf16v2_t); return __builtin_bit_cast(unsigned, b); }
; __device__ __forceinline__ float softplusf_(float x) { return fmaxf(x, 0.f) + __logf(1.0f + __expf(-fabsf(x))); }
; __device__ void prep_gla(const Ctx& c, int ck, int blk) {
;     ...
;                 for (int j = 0; j < 8; ++j) { const int l = lh + l0 + j;
;                     float x = b2;
; #pragma unroll
;                     for (int r4 = 0; r4 < 16; r4 += 4) { const f32x4 lv = *(const f32x4*)(lr_s + l * 16 + r4); x += lv[0] * w2r[r4] + lv[1] * w2r[r4 + 1] + lv[2] * w2r[r4 + 2] + lv[3] * w2r[r4 + 3]; }
;                     G += -softplusf_(-x) * (1.0f / 16.0f);
;                     const float qv = qr[l0 + j] * 0.08838834764831845f, kv = kr[l0 + j];
;                     const size_t o = ((size_t)(ck * 4 + h) * 64 + l) * 128 + k;
;                     gQg[o] = f2bf(qv * __expf(G)); const float kneg = kv * __expf(-G); gKn[o] = f2bf(kneg); kn[j] = kneg; }
;                 u32x4 a; a.x = pk2(kn[0], kn[1]); a.y = pk2(kn[2], kn[3]); a.z = pk2(kn[4], kn[5]); a.w = pk2(kn[6], kn[7]);
;                 *(u32x4*)(gKnT + ((size_t)(ck * 4 + h) * 128 + k) * 64 + lh + l0) = a;
	v_mov_b32_e32 v11, v76
	v_mov_b32_e32 v76, v73
	v_mov_b32_e32 v10, v72
	v_pk_mul_f32 v[12:13], v[30:31], v[76:77]
	v_lshlrev_b32_e32 v14, 16, v68
	v_pk_fma_f32 v[10:11], v[28:29], v[10:11], v[12:13]
	v_mov_b32_e32 v12, v74
	v_mov_b32_e32 v13, v78
	v_pk_fma_f32 v[10:11], v[32:33], v[12:13], v[10:11]
	v_mov_b32_e32 v78, v75
	v_pk_fma_f32 v[10:11], v[38:39], v[78:79], v[10:11]
	v_lshl_add_u64 v[6:7], s[84:85], 0, v[6:7]
	v_add_f32_e32 v9, v9, v10
	v_add_f32_e32 v9, v9, v11
	v_max_f32_e64 v10, -v9, 0
	v_mul_f32_e64 v9, |v9|, s57
	v_exp_f32_e32 v9, v9
	s_nop 0
	v_add_f32_e32 v9, 1.0, v9
	v_cmp_gt_f32_e64 s[4:5], s59, v9
	s_nop 1
	v_cndmask_b32_e64 v11, 0, 32, s[4:5]
	v_ldexp_f32 v9, v9, v11
	v_log_f32_e32 v9, v9
	s_nop 0
	v_mul_f32_e32 v11, 0x3f317217, v9
	v_fma_f32 v11, v9, s60, -v11
	v_fmac_f32_e32 v11, 0x3377d1cf, v9
	v_fmac_f32_e32 v11, 0x3f317217, v9
	v_cmp_lt_f32_e64 s[6:7], |v9|, s61
	s_nop 1
	v_cndmask_b32_e64 v9, v9, v11, s[6:7]
	v_cndmask_b32_e64 v11, 0, v240, s[4:5]
	v_sub_f32_e32 v9, v9, v11
	v_add_f32_e32 v9, v10, v9
	v_fmac_f32_e32 v21, 0xbd800000, v9
	v_mul_f32_e32 v12, 0x3fb8aa3b, v21
	v_exp_f32_e32 v12, v12
	v_mul_f32_e32 v9, 0x3db504f3, v71
	v_lshl_or_b32 v10, s0, 7, v40
	v_mov_b32_e32 v11, v41
	v_mul_f32_e32 v9, v9, v12
	v_cvt_pk_bf16_f32 v46, v9, s0
	v_mul_f32_e32 v9, 0xbfb8aa3b, v21
	v_exp_f32_e32 v9, v9
	v_lshlrev_b64 v[10:11], 1, v[10:11]
	v_lshl_add_u64 v[12:13], s[86:87], 0, v[10:11]
	v_pk_mul_f32 v[8:9], v[8:9], v[14:15]
	s_nop 0
	v_cvt_pk_bf16_f32 v14, v8, s0
	global_store_short v[6:7], v14, off
	global_store_short v[12:13], v46, off
	v_cvt_pk_bf16_f32 v12, v9, s0
	v_lshl_add_u64 v[6:7], s[84:85], 0, v[10:11]
	v_cvt_pk_bf16_f32 v3, v8, v9
	v_readlane_b32 s0, v251, 59
	global_store_short v[6:7], v12, off
	global_store_dwordx4 v[44:45], v[0:3], off offset:32
	v_mov_b32_e32 v12, s0
	ds_read_b128 v[0:3], v12
	ds_read_b128 v[4:7], v12 offset:16
	ds_read_b128 v[8:11], v12 offset:32
	ds_read_b128 v[12:15], v12 offset:48
	v_readlane_b32 s0, v251, 47
	s_waitcnt lgkmcnt(3)
	v_mov_b32_e32 v46, v0
	s_waitcnt lgkmcnt(2)
	v_mov_b32_e32 v47, v4
	v_mov_b32_e32 v4, v1
	v_pk_mul_f32 v[0:1], v[34:35], v[4:5]
	v_mov_b32_e32 v4, v2
	v_pk_fma_f32 v[0:1], v[26:27], v[46:47], v[0:1]
	v_mov_b32_e32 v5, v6
	v_pk_fma_f32 v[0:1], v[24:25], v[4:5], v[0:1]
	v_mov_b32_e32 v6, v3
	v_pk_fma_f32 v[0:1], v[36:37], v[6:7], v[0:1]
	s_nop 0
	v_add_f32_e32 v0, v17, v0
	v_add_f32_e32 v4, v0, v1
	s_waitcnt lgkmcnt(0)
	v_mov_b32_e32 v1, v12
	v_mov_b32_e32 v12, v9
	v_mov_b32_e32 v0, v8
	v_pk_mul_f32 v[2:3], v[30:31], v[12:13]
	s_nop 0
	v_pk_fma_f32 v[0:1], v[28:29], v[0:1], v[2:3]
	v_mov_b32_e32 v2, v10
	v_mov_b32_e32 v3, v14
	v_pk_fma_f32 v[0:1], v[32:33], v[2:3], v[0:1]
	v_mov_b32_e32 v14, v11
	v_pk_fma_f32 v[0:1], v[38:39], v[14:15], v[0:1]
	s_nop 0
	v_add_f32_e32 v0, v4, v0
	v_add_f32_e32 v0, v0, v1
	v_max_f32_e64 v1, -v0, 0
	v_mul_f32_e64 v0, |v0|, s57
	v_exp_f32_e32 v0, v0
	s_nop 0
	v_add_f32_e32 v0, 1.0, v0
	v_cmp_gt_f32_e64 s[4:5], s59, v0
	s_nop 1
	v_cndmask_b32_e64 v2, 0, 32, s[4:5]
	v_ldexp_f32 v0, v0, v2
	v_log_f32_e32 v0, v0
	s_nop 0
	v_mul_f32_e32 v2, 0x3f317217, v0
	v_fma_f32 v2, v0, s60, -v2
	v_fmac_f32_e32 v2, 0x3377d1cf, v0
	v_fmac_f32_e32 v2, 0x3f317217, v0
	v_cmp_lt_f32_e64 s[6:7], |v0|, s61
	s_nop 1
	v_cndmask_b32_e64 v0, v0, v2, s[6:7]
	v_cndmask_b32_e64 v2, 0, v240, s[4:5]
	v_sub_f32_e32 v0, v0, v2
	v_add_f32_e32 v0, v1, v0
	v_fmac_f32_e32 v21, 0xbd800000, v0
	v_mul_f32_e32 v3, 0x3fb8aa3b, v21
	v_exp_f32_e32 v3, v3
	v_mul_f32_e32 v2, 0x3db504f3, v69
	v_lshl_or_b32 v0, s0, 7, v40
	v_mov_b32_e32 v1, v41
	v_mul_f32_e32 v2, v2, v3
	v_lshlrev_b64 v[0:1], 1, v[0:1]
	v_cvt_pk_bf16_f32 v4, v2, s0
	v_lshl_add_u64 v[2:3], s[86:87], 0, v[0:1]
	v_readlane_b32 s0, v251, 35
	global_store_short v[2:3], v4, off
	v_mul_f32_e32 v2, 0xbfb8aa3b, v21
	v_mov_b32_e32 v3, s0
	ds_read_b128 v[4:7], v3
	ds_read_b128 v[8:11], v3 offset:16
	ds_read_b128 v[12:15], v3 offset:32
	ds_read_b128 v[46:49], v3 offset:48
	v_readlane_b32 s0, v252, 17
	s_waitcnt lgkmcnt(3)
	v_mov_b32_e32 v68, v4
	s_waitcnt lgkmcnt(2)
	v_mov_b32_e32 v69, v8
	v_mov_b32_e32 v8, v5
	v_pk_mul_f32 v[4:5], v[34:35], v[8:9]
	v_mov_b32_e32 v8, v6
	v_pk_fma_f32 v[4:5], v[26:27], v[68:69], v[4:5]
	v_mov_b32_e32 v9, v10
	v_pk_fma_f32 v[4:5], v[24:25], v[8:9], v[4:5]
	v_mov_b32_e32 v10, v7
	v_pk_fma_f32 v[4:5], v[36:37], v[10:11], v[4:5]
	v_exp_f32_e32 v2, v2
	v_add_f32_e32 v3, v17, v4
	v_add_f32_e32 v3, v3, v5
	s_waitcnt lgkmcnt(0)
	v_mov_b32_e32 v5, v46
	v_mov_b32_e32 v46, v13
	v_mov_b32_e32 v4, v12
	v_pk_mul_f32 v[6:7], v[30:31], v[46:47]
	v_lshl_add_u64 v[0:1], s[84:85], 0, v[0:1]
	v_pk_fma_f32 v[4:5], v[28:29], v[4:5], v[6:7]
	v_mov_b32_e32 v6, v14
	v_mov_b32_e32 v7, v48
	v_pk_fma_f32 v[4:5], v[32:33], v[6:7], v[4:5]
	v_mov_b32_e32 v48, v15
	v_pk_fma_f32 v[4:5], v[38:39], v[48:49], v[4:5]
	s_nop 0
	v_add_f32_e32 v3, v3, v4
	v_add_f32_e32 v3, v3, v5
	v_max_f32_e64 v4, -v3, 0
	v_mul_f32_e64 v3, |v3|, s57
	v_exp_f32_e32 v3, v3
	s_nop 0
	v_add_f32_e32 v3, 1.0, v3
	v_cmp_gt_f32_e64 s[4:5], s59, v3
	s_nop 1
	v_cndmask_b32_e64 v5, 0, 32, s[4:5]
	v_ldexp_f32 v3, v3, v5
	v_log_f32_e32 v3, v3
	s_nop 0
	v_mul_f32_e32 v5, 0x3f317217, v3
	v_fma_f32 v5, v3, s60, -v5
	v_fmac_f32_e32 v5, 0x3377d1cf, v3
	v_fmac_f32_e32 v5, 0x3f317217, v3
	v_cmp_lt_f32_e64 s[6:7], |v3|, s61
	s_nop 1
	v_cndmask_b32_e64 v3, v3, v5, s[6:7]
	v_cndmask_b32_e64 v5, 0, v240, s[4:5]
	v_sub_f32_e32 v3, v3, v5
	v_add_f32_e32 v3, v4, v3
	v_fmac_f32_e32 v21, 0xbd800000, v3
	v_mul_f32_e32 v6, 0x3fb8aa3b, v21
	v_exp_f32_e32 v6, v6
	v_mul_f32_e32 v3, 0x3db504f3, v67
	v_lshl_or_b32 v4, s0, 7, v40
	v_mov_b32_e32 v5, v41
	v_mul_f32_e32 v3, v3, v6
	v_cvt_pk_bf16_f32 v10, v3, s0
	v_mul_f32_e32 v3, 0xbfb8aa3b, v21
	v_exp_f32_e32 v3, v3
	v_lshlrev_b64 v[6:7], 1, v[4:5]
	v_lshlrev_b32_e32 v5, 16, v66
	v_lshlrev_b32_e32 v4, 16, v63
	v_pk_mul_f32 v[4:5], v[2:3], v[4:5]
	v_lshl_add_u64 v[8:9], s[86:87], 0, v[6:7]
	v_cvt_pk_bf16_f32 v2, v4, s0
	global_store_short v[0:1], v2, off
	global_store_short v[8:9], v10, off
	v_cvt_pk_bf16_f32 v2, v5, s0
	v_lshl_add_u64 v[0:1], s[84:85], 0, v[6:7]
	v_readlane_b32 s0, v252, 11
	global_store_short v[0:1], v2, off
	s_nop 0
	v_mov_b32_e32 v14, s0
	ds_read_b128 v[0:3], v14
	ds_read_b128 v[6:9], v14 offset:16
	ds_read_b128 v[10:13], v14 offset:32
	ds_read_b128 v[46:49], v14 offset:48
	v_readlane_b32 s0, v253, 21
	s_waitcnt lgkmcnt(3)
; __device__ __forceinline__ unsigned pk2(float lo, float hi) { const f32v2_t v = {lo, hi}; const bf16v2_t b = __builtin_convertvector(v, bf16v2_t); return __builtin_bit_cast(unsigned, b); }
; __device__ __forceinline__ float softplusf_(float x) { return fmaxf(x, 0.f) + __logf(1.0f + __expf(-fabsf(x))); }
; __device__ void prep_gla(const Ctx& c, int ck, int blk) {
;     ...
;                 for (int j = 0; j < 8; ++j) { const int l = lh + l0 + j;
;                     float x = b2;
; #pragma unroll
;                     for (int r4 = 0; r4 < 16; r4 += 4) { const f32x4 lv = *(const f32x4*)(lr_s + l * 16 + r4); x += lv[0] * w2r[r4] + lv[1] * w2r[r4 + 1] + lv[2] * w2r[r4 + 2] + lv[3] * w2r[r4 + 3]; }
;                     G += -softplusf_(-x) * (1.0f / 16.0f);
;                     const float qv = qr[l0 + j] * 0.08838834764831845f, kv = kr[l0 + j];
;                     const size_t o = ((size_t)(ck * 4 + h) * 64 + l) * 128 + k;
;                     gQg[o] = f2bf(qv * __expf(G)); const float kneg = kv * __expf(-G); gKn[o] = f2bf(kneg); kn[j] = kneg; }
;                 u32x4 a; a.x = pk2(kn[0], kn[1]); a.y = pk2(kn[2], kn[3]); a.z = pk2(kn[4], kn[5]); a.w = pk2(kn[6], kn[7]);
	v_mov_b32_e32 v14, v0
	s_waitcnt lgkmcnt(2)
	v_mov_b32_e32 v15, v6
	v_mov_b32_e32 v6, v1
	v_pk_mul_f32 v[0:1], v[34:35], v[6:7]
	v_mov_b32_e32 v6, v2
	v_pk_fma_f32 v[0:1], v[26:27], v[14:15], v[0:1]
	v_mov_b32_e32 v7, v8
	v_pk_fma_f32 v[0:1], v[24:25], v[6:7], v[0:1]
	v_mov_b32_e32 v8, v3
	v_pk_fma_f32 v[0:1], v[36:37], v[8:9], v[0:1]
	s_nop 0
	v_add_f32_e32 v0, v17, v0
	v_add_f32_e32 v6, v0, v1
	s_waitcnt lgkmcnt(0)
	v_mov_b32_e32 v1, v46
	v_mov_b32_e32 v46, v11
	v_mov_b32_e32 v0, v10
	v_pk_mul_f32 v[2:3], v[30:31], v[46:47]
	s_nop 0
	v_pk_fma_f32 v[0:1], v[28:29], v[0:1], v[2:3]
	v_mov_b32_e32 v2, v12
	v_mov_b32_e32 v3, v48
	v_pk_fma_f32 v[0:1], v[32:33], v[2:3], v[0:1]
	v_mov_b32_e32 v48, v13
	v_pk_fma_f32 v[0:1], v[38:39], v[48:49], v[0:1]
	s_nop 0
	v_add_f32_e32 v0, v6, v0
	v_add_f32_e32 v0, v0, v1
	v_max_f32_e64 v1, -v0, 0
	v_mul_f32_e64 v0, |v0|, s57
	v_exp_f32_e32 v0, v0
	s_nop 0
	v_add_f32_e32 v0, 1.0, v0
	v_cmp_gt_f32_e64 s[4:5], s59, v0
	s_nop 1
	v_cndmask_b32_e64 v2, 0, 32, s[4:5]
	v_ldexp_f32 v0, v0, v2
	v_log_f32_e32 v0, v0
	s_nop 0
	v_mul_f32_e32 v2, 0x3f317217, v0
	v_fma_f32 v2, v0, s60, -v2
	v_fmac_f32_e32 v2, 0x3377d1cf, v0
	v_fmac_f32_e32 v2, 0x3f317217, v0
	v_cmp_lt_f32_e64 s[6:7], |v0|, s61
	s_nop 1
	v_cndmask_b32_e64 v0, v0, v2, s[6:7]
	v_cndmask_b32_e64 v2, 0, v240, s[4:5]
	v_sub_f32_e32 v0, v0, v2
	v_add_f32_e32 v0, v1, v0
	v_fmac_f32_e32 v21, 0xbd800000, v0
	v_mul_f32_e32 v3, 0x3fb8aa3b, v21
	v_exp_f32_e32 v3, v3
	v_mul_f32_e32 v2, 0x3db504f3, v65
	v_lshl_or_b32 v0, s0, 7, v40
	v_mov_b32_e32 v1, v41
	v_mul_f32_e32 v2, v2, v3
	v_lshlrev_b64 v[0:1], 1, v[0:1]
	v_cvt_pk_bf16_f32 v6, v2, s0
	v_lshl_add_u64 v[2:3], s[86:87], 0, v[0:1]
	v_readlane_b32 s0, v253, 15
	global_store_short v[2:3], v6, off
	v_mul_f32_e32 v2, 0xbfb8aa3b, v21
	v_mov_b32_e32 v3, s0
	ds_read_b128 v[6:9], v3
	ds_read_b128 v[10:13], v3 offset:16
	ds_read_b128 v[46:49], v3 offset:32
	ds_read_b128 v[66:69], v3 offset:48
	v_readlane_b32 s0, v253, 9
	s_waitcnt lgkmcnt(3)
	v_mov_b32_e32 v14, v6
	s_waitcnt lgkmcnt(2)
	v_mov_b32_e32 v15, v10
	v_mov_b32_e32 v10, v7
	v_pk_mul_f32 v[6:7], v[34:35], v[10:11]
	v_mov_b32_e32 v10, v8
	v_pk_fma_f32 v[6:7], v[26:27], v[14:15], v[6:7]
	v_mov_b32_e32 v11, v12
	v_pk_fma_f32 v[6:7], v[24:25], v[10:11], v[6:7]
	v_mov_b32_e32 v12, v9
	v_pk_fma_f32 v[6:7], v[36:37], v[12:13], v[6:7]
	v_exp_f32_e32 v2, v2
	v_add_f32_e32 v3, v17, v6
	v_add_f32_e32 v3, v3, v7
	s_waitcnt lgkmcnt(0)
	v_mov_b32_e32 v7, v66
	v_mov_b32_e32 v66, v47
	v_mov_b32_e32 v6, v46
	v_pk_mul_f32 v[8:9], v[30:31], v[66:67]
	v_lshl_add_u64 v[0:1], s[84:85], 0, v[0:1]
	v_pk_fma_f32 v[6:7], v[28:29], v[6:7], v[8:9]
	v_mov_b32_e32 v8, v48
	v_mov_b32_e32 v9, v68
	v_pk_fma_f32 v[6:7], v[32:33], v[8:9], v[6:7]
	v_mov_b32_e32 v68, v49
	v_pk_fma_f32 v[6:7], v[38:39], v[68:69], v[6:7]
	s_nop 0
	v_add_f32_e32 v3, v3, v6
	v_add_f32_e32 v3, v3, v7
	v_max_f32_e64 v6, -v3, 0
	v_mul_f32_e64 v3, |v3|, s57
	v_exp_f32_e32 v3, v3
	s_nop 0
	v_add_f32_e32 v3, 1.0, v3
	v_cmp_gt_f32_e64 s[4:5], s59, v3
	s_nop 1
	v_cndmask_b32_e64 v7, 0, 32, s[4:5]
	v_ldexp_f32 v3, v3, v7
	v_log_f32_e32 v3, v3
	s_nop 0
	v_mul_f32_e32 v7, 0x3f317217, v3
	v_fma_f32 v7, v3, s60, -v7
	v_fmac_f32_e32 v7, 0x3377d1cf, v3
	v_fmac_f32_e32 v7, 0x3f317217, v3
	v_cmp_lt_f32_e64 s[6:7], |v3|, s61
	s_nop 1
	v_cndmask_b32_e64 v3, v3, v7, s[6:7]
	v_cndmask_b32_e64 v7, 0, v240, s[4:5]
	v_sub_f32_e32 v3, v3, v7
	v_add_f32_e32 v3, v6, v3
	v_fmac_f32_e32 v21, 0xbd800000, v3
	v_mul_f32_e32 v8, 0x3fb8aa3b, v21
	v_exp_f32_e32 v8, v8
	v_mul_f32_e32 v3, 0x3db504f3, v61
	v_lshl_or_b32 v6, s0, 7, v40
	v_mov_b32_e32 v7, v41
	v_mul_f32_e32 v3, v3, v8
	v_cvt_pk_bf16_f32 v12, v3, s0
	v_mul_f32_e32 v3, 0xbfb8aa3b, v21
	v_exp_f32_e32 v3, v3
	v_lshlrev_b64 v[8:9], 1, v[6:7]
	v_lshlrev_b32_e32 v7, 16, v59
	v_lshlrev_b32_e32 v6, 16, v58
	v_pk_mul_f32 v[6:7], v[2:3], v[6:7]
	v_lshl_add_u64 v[10:11], s[86:87], 0, v[8:9]
	v_cvt_pk_bf16_f32 v2, v6, s0
	global_store_short v[0:1], v2, off
	global_store_short v[10:11], v12, off
	v_cvt_pk_bf16_f32 v2, v7, s0
	v_lshl_add_u64 v[0:1], s[84:85], 0, v[8:9]
	v_readlane_b32 s0, v253, 3
	global_store_short v[0:1], v2, off
	s_nop 0
	v_mov_b32_e32 v46, s0
	ds_read_b128 v[0:3], v46
	ds_read_b128 v[8:11], v46 offset:16
	ds_read_b128 v[12:15], v46 offset:32
	ds_read_b128 v[46:49], v46 offset:48
	v_readlane_b32 s0, v252, 61
	s_waitcnt lgkmcnt(3)
	v_mov_b32_e32 v58, v0
	s_waitcnt lgkmcnt(2)
	v_mov_b32_e32 v59, v8
	v_mov_b32_e32 v8, v1
	v_pk_mul_f32 v[0:1], v[34:35], v[8:9]
	v_mov_b32_e32 v8, v2
	v_pk_fma_f32 v[0:1], v[26:27], v[58:59], v[0:1]
	v_mov_b32_e32 v9, v10
	v_pk_fma_f32 v[0:1], v[24:25], v[8:9], v[0:1]
	v_mov_b32_e32 v10, v3
	v_pk_fma_f32 v[0:1], v[36:37], v[10:11], v[0:1]
	s_nop 0
	v_add_f32_e32 v0, v17, v0
	v_add_f32_e32 v8, v0, v1
	s_waitcnt lgkmcnt(0)
	v_mov_b32_e32 v1, v46
	v_mov_b32_e32 v46, v13
	v_mov_b32_e32 v0, v12
	v_pk_mul_f32 v[2:3], v[30:31], v[46:47]
	s_nop 0
	v_pk_fma_f32 v[0:1], v[28:29], v[0:1], v[2:3]
	v_mov_b32_e32 v2, v14
	v_mov_b32_e32 v3, v48
	v_pk_fma_f32 v[0:1], v[32:33], v[2:3], v[0:1]
	v_mov_b32_e32 v48, v15
	v_pk_fma_f32 v[0:1], v[38:39], v[48:49], v[0:1]
	s_nop 0
	v_add_f32_e32 v0, v8, v0
	v_add_f32_e32 v0, v0, v1
	v_max_f32_e64 v1, -v0, 0
	v_mul_f32_e64 v0, |v0|, s57
	v_exp_f32_e32 v0, v0
	s_nop 0
	v_add_f32_e32 v0, 1.0, v0
	v_cmp_gt_f32_e64 s[4:5], s59, v0
	s_nop 1
	v_cndmask_b32_e64 v2, 0, 32, s[4:5]
	v_ldexp_f32 v0, v0, v2
	v_log_f32_e32 v0, v0
	s_nop 0
	v_mul_f32_e32 v2, 0x3f317217, v0
	v_fma_f32 v2, v0, s60, -v2
	v_fmac_f32_e32 v2, 0x3377d1cf, v0
	v_fmac_f32_e32 v2, 0x3f317217, v0
	v_cmp_lt_f32_e64 s[6:7], |v0|, s61
	s_nop 1
	v_cndmask_b32_e64 v0, v0, v2, s[6:7]
	v_cndmask_b32_e64 v2, 0, v240, s[4:5]
	v_sub_f32_e32 v0, v0, v2
	v_add_f32_e32 v0, v1, v0
	v_fmac_f32_e32 v21, 0xbd800000, v0
	v_mul_f32_e32 v3, 0x3fb8aa3b, v21
	v_exp_f32_e32 v3, v3
	v_mul_f32_e32 v2, 0x3db504f3, v57
	v_lshl_or_b32 v0, s0, 7, v40
	v_mov_b32_e32 v1, v41
	v_mul_f32_e32 v2, v2, v3
	v_lshlrev_b64 v[0:1], 1, v[0:1]
	v_cvt_pk_bf16_f32 v8, v2, s0
	v_lshl_add_u64 v[2:3], s[86:87], 0, v[0:1]
	v_readlane_b32 s0, v252, 55
	global_store_short v[2:3], v8, off
	v_mul_f32_e32 v2, 0xbfb8aa3b, v21
	v_mov_b32_e32 v3, s0
	ds_read_b128 v[8:11], v3
	ds_read_b128 v[12:15], v3 offset:16
	ds_read_b128 v[46:49], v3 offset:32
	ds_read_b128 v[66:69], v3 offset:48
	v_readlane_b32 s0, v249, 43
	s_waitcnt lgkmcnt(3)
; __device__ __forceinline__ unsigned pk2(float lo, float hi) { const f32v2_t v = {lo, hi}; const bf16v2_t b = __builtin_convertvector(v, bf16v2_t); return __builtin_bit_cast(unsigned, b); }
; __device__ __forceinline__ float softplusf_(float x) { return fmaxf(x, 0.f) + __logf(1.0f + __expf(-fabsf(x))); }
; __device__ void prep_gla(const Ctx& c, int ck, int blk) {
;     ...
;                 for (int j = 0; j < 8; ++j) { const int l = lh + l0 + j;
;                     float x = b2;
; #pragma unroll
;                     for (int r4 = 0; r4 < 16; r4 += 4) { const f32x4 lv = *(const f32x4*)(lr_s + l * 16 + r4); x += lv[0] * w2r[r4] + lv[1] * w2r[r4 + 1] + lv[2] * w2r[r4 + 2] + lv[3] * w2r[r4 + 3]; }
;                     G += -softplusf_(-x) * (1.0f / 16.0f);
;                     const float qv = qr[l0 + j] * 0.08838834764831845f, kv = kr[l0 + j];
;                     const size_t o = ((size_t)(ck * 4 + h) * 64 + l) * 128 + k;
;                     gQg[o] = f2bf(qv * __expf(G)); const float kneg = kv * __expf(-G); gKn[o] = f2bf(kneg); kn[j] = kneg; }
;                 u32x4 a; a.x = pk2(kn[0], kn[1]); a.y = pk2(kn[2], kn[3]); a.z = pk2(kn[4], kn[5]); a.w = pk2(kn[6], kn[7]);
;                 *(u32x4*)(gKnT + ((size_t)(ck * 4 + h) * 128 + k) * 64 + lh + l0) = a;
	v_mov_b32_e32 v58, v8
	s_waitcnt lgkmcnt(2)
	v_mov_b32_e32 v59, v12
	v_mov_b32_e32 v12, v9
	v_pk_mul_f32 v[8:9], v[34:35], v[12:13]
	v_mov_b32_e32 v12, v10
	v_pk_fma_f32 v[8:9], v[26:27], v[58:59], v[8:9]
	v_mov_b32_e32 v13, v14
	v_pk_fma_f32 v[8:9], v[24:25], v[12:13], v[8:9]
	v_mov_b32_e32 v14, v11
	v_pk_fma_f32 v[8:9], v[36:37], v[14:15], v[8:9]
	v_exp_f32_e32 v2, v2
	v_add_f32_e32 v3, v17, v8
	v_add_f32_e32 v3, v3, v9
	s_waitcnt lgkmcnt(0)
	v_mov_b32_e32 v9, v66
	v_mov_b32_e32 v66, v47
	v_mov_b32_e32 v8, v46
	v_pk_mul_f32 v[10:11], v[30:31], v[66:67]
	v_lshl_add_u64 v[0:1], s[84:85], 0, v[0:1]
	v_pk_fma_f32 v[8:9], v[28:29], v[8:9], v[10:11]
	v_mov_b32_e32 v10, v48
	v_mov_b32_e32 v11, v68
	v_pk_fma_f32 v[8:9], v[32:33], v[10:11], v[8:9]
	v_mov_b32_e32 v68, v49
	v_pk_fma_f32 v[8:9], v[38:39], v[68:69], v[8:9]
	s_nop 0
	v_add_f32_e32 v3, v3, v8
	v_add_f32_e32 v3, v3, v9
	v_max_f32_e64 v8, -v3, 0
	v_mul_f32_e64 v3, |v3|, s57
	v_exp_f32_e32 v3, v3
	s_nop 0
	v_add_f32_e32 v3, 1.0, v3
	v_cmp_gt_f32_e64 s[4:5], s59, v3
	s_nop 1
	v_cndmask_b32_e64 v9, 0, 32, s[4:5]
	v_ldexp_f32 v3, v3, v9
	v_log_f32_e32 v3, v3
	s_nop 0
	v_mul_f32_e32 v9, 0x3f317217, v3
	v_fma_f32 v9, v3, s60, -v9
	v_fmac_f32_e32 v9, 0x3377d1cf, v3
	v_fmac_f32_e32 v9, 0x3f317217, v3
	v_cmp_lt_f32_e64 s[6:7], |v3|, s61
	s_nop 1
	v_cndmask_b32_e64 v3, v3, v9, s[6:7]
	v_cndmask_b32_e64 v9, 0, v240, s[4:5]
	v_sub_f32_e32 v3, v3, v9
	v_add_f32_e32 v3, v8, v3
	v_fmac_f32_e32 v21, 0xbd800000, v3
	v_mul_f32_e32 v10, 0x3fb8aa3b, v21
	v_exp_f32_e32 v10, v10
	v_mul_f32_e32 v3, 0x3db504f3, v56
	v_lshl_or_b32 v8, s0, 7, v40
	v_mov_b32_e32 v9, v41
	v_mul_f32_e32 v3, v3, v10
	v_cvt_pk_bf16_f32 v14, v3, s0
	v_mul_f32_e32 v3, 0xbfb8aa3b, v21
	v_exp_f32_e32 v3, v3
	v_lshlrev_b64 v[10:11], 1, v[8:9]
	v_lshlrev_b32_e32 v9, 16, v55
	v_lshlrev_b32_e32 v8, 16, v54
	v_pk_mul_f32 v[8:9], v[2:3], v[8:9]
	v_lshl_add_u64 v[12:13], s[86:87], 0, v[10:11]
	v_cvt_pk_bf16_f32 v2, v8, s0
	global_store_short v[0:1], v2, off
	global_store_short v[12:13], v14, off
	v_cvt_pk_bf16_f32 v2, v9, s0
	v_lshl_add_u64 v[0:1], s[84:85], 0, v[10:11]
	v_readlane_b32 s0, v251, 53
	global_store_short v[0:1], v2, off
	s_nop 0
	v_mov_b32_e32 v14, s0
	ds_read_b128 v[0:3], v14
	ds_read_b128 v[10:13], v14 offset:16
	ds_read_b128 v[46:49], v14 offset:32
	ds_read_b128 v[54:57], v14 offset:48
	v_readlane_b32 s0, v252, 5
	s_waitcnt lgkmcnt(3)
	v_mov_b32_e32 v14, v0
	s_waitcnt lgkmcnt(2)
	v_mov_b32_e32 v15, v10
	v_mov_b32_e32 v10, v1
	v_pk_mul_f32 v[0:1], v[34:35], v[10:11]
	v_mov_b32_e32 v10, v2
	v_pk_fma_f32 v[0:1], v[26:27], v[14:15], v[0:1]
	v_mov_b32_e32 v11, v12
	v_pk_fma_f32 v[0:1], v[24:25], v[10:11], v[0:1]
	v_mov_b32_e32 v12, v3
	v_pk_fma_f32 v[0:1], v[36:37], v[12:13], v[0:1]
	s_nop 0
	v_add_f32_e32 v0, v17, v0
	v_add_f32_e32 v10, v0, v1
	s_waitcnt lgkmcnt(0)
	v_mov_b32_e32 v1, v54
	v_mov_b32_e32 v54, v47
	v_mov_b32_e32 v0, v46
	v_pk_mul_f32 v[2:3], v[30:31], v[54:55]
	s_nop 0
	v_pk_fma_f32 v[0:1], v[28:29], v[0:1], v[2:3]
	v_mov_b32_e32 v2, v48
	v_mov_b32_e32 v3, v56
	v_pk_fma_f32 v[0:1], v[32:33], v[2:3], v[0:1]
	v_mov_b32_e32 v56, v49
	v_pk_fma_f32 v[0:1], v[38:39], v[56:57], v[0:1]
	s_nop 0
	v_add_f32_e32 v0, v10, v0
	v_add_f32_e32 v0, v0, v1
	v_max_f32_e64 v1, -v0, 0
	v_mul_f32_e64 v0, |v0|, s57
	v_exp_f32_e32 v0, v0
	s_nop 0
	v_add_f32_e32 v0, 1.0, v0
	v_cmp_gt_f32_e64 s[4:5], s59, v0
	s_nop 1
	v_cndmask_b32_e64 v2, 0, 32, s[4:5]
	v_ldexp_f32 v0, v0, v2
	v_log_f32_e32 v0, v0
	s_nop 0
	v_mul_f32_e32 v2, 0x3f317217, v0
	v_fma_f32 v2, v0, s60, -v2
	v_fmac_f32_e32 v2, 0x3377d1cf, v0
	v_fmac_f32_e32 v2, 0x3f317217, v0
	v_cmp_lt_f32_e64 s[6:7], |v0|, s61
	s_nop 1
	v_cndmask_b32_e64 v0, v0, v2, s[6:7]
	v_cndmask_b32_e64 v2, 0, v240, s[4:5]
	v_sub_f32_e32 v0, v0, v2
	v_add_f32_e32 v0, v1, v0
	v_fmac_f32_e32 v21, 0xbd800000, v0
	v_mul_f32_e32 v3, 0x3fb8aa3b, v21
	v_exp_f32_e32 v3, v3
	v_mul_f32_e32 v2, 0x3db504f3, v53
	v_lshl_or_b32 v0, s0, 7, v40
	v_mov_b32_e32 v1, v41
	v_mul_f32_e32 v2, v2, v3
	v_lshlrev_b64 v[0:1], 1, v[0:1]
	v_cvt_pk_bf16_f32 v10, v2, s0
	v_lshl_add_u64 v[2:3], s[86:87], 0, v[0:1]
	v_readlane_b32 s0, v251, 41
	global_store_short v[2:3], v10, off
	v_mul_f32_e32 v2, 0xbfb8aa3b, v21
	v_lshl_add_u64 v[10:11], s[84:85], 0, v[0:1]
	v_mov_b32_e32 v0, s0
	v_exp_f32_e32 v12, v2
	ds_read_b128 v[46:49], v0
	ds_read_b128 v[54:57], v0 offset:16
	ds_read_b128 v[66:69], v0 offset:32
	ds_read_b128 v[0:3], v0 offset:48
	v_readlane_b32 s0, v250, 63
	s_waitcnt lgkmcnt(3)
	v_mov_b32_e32 v14, v46
	s_waitcnt lgkmcnt(2)
	v_mov_b32_e32 v15, v54
	v_mov_b32_e32 v54, v47
	v_pk_mul_f32 v[46:47], v[34:35], v[54:55]
	s_nop 0
	v_pk_fma_f32 v[14:15], v[26:27], v[14:15], v[46:47]
	v_mov_b32_e32 v46, v48
	v_mov_b32_e32 v47, v56
	v_pk_fma_f32 v[14:15], v[24:25], v[46:47], v[14:15]
	v_mov_b32_e32 v56, v49
	v_pk_fma_f32 v[14:15], v[36:37], v[56:57], v[14:15]
	v_lshlrev_b32_e32 v47, 16, v51
	v_add_f32_e32 v13, v17, v14
	v_add_f32_e32 v13, v13, v15
	s_waitcnt lgkmcnt(0)
	v_mov_b32_e32 v15, v0
	v_mov_b32_e32 v0, v67
	v_mov_b32_e32 v14, v66
	v_pk_mul_f32 v[0:1], v[30:31], v[0:1]
	v_lshlrev_b32_e32 v46, 16, v50
	v_pk_fma_f32 v[0:1], v[28:29], v[14:15], v[0:1]
	v_mov_b32_e32 v14, v68
	v_mov_b32_e32 v15, v2
	v_pk_fma_f32 v[0:1], v[32:33], v[14:15], v[0:1]
	v_mov_b32_e32 v2, v69
	v_pk_fma_f32 v[0:1], v[38:39], v[2:3], v[0:1]
	v_mov_b32_e32 v3, v41
	v_add_f32_e32 v0, v13, v0
	v_add_f32_e32 v0, v0, v1
	v_max_f32_e64 v1, -v0, 0
	v_mul_f32_e64 v0, |v0|, s57
	v_exp_f32_e32 v0, v0
	s_nop 0
	v_add_f32_e32 v0, 1.0, v0
	v_cmp_gt_f32_e64 s[4:5], s59, v0
	s_nop 1
	v_cndmask_b32_e64 v2, 0, 32, s[4:5]
	v_ldexp_f32 v0, v0, v2
	v_log_f32_e32 v0, v0
	s_nop 0
	v_mul_f32_e32 v2, 0x3f317217, v0
	v_fma_f32 v2, v0, s60, -v2
	v_fmac_f32_e32 v2, 0x3377d1cf, v0
	v_fmac_f32_e32 v2, 0x3f317217, v0
	v_cmp_lt_f32_e64 s[6:7], |v0|, s61
	s_nop 1
	v_cndmask_b32_e64 v0, v0, v2, s[6:7]
	v_cndmask_b32_e64 v2, 0, v240, s[4:5]
	v_sub_f32_e32 v0, v0, v2
	v_add_f32_e32 v0, v1, v0
	v_fmac_f32_e32 v21, 0xbd800000, v0
	v_mul_f32_e32 v0, 0x3fb8aa3b, v21
	v_mul_f32_e32 v13, 0xbfb8aa3b, v21
	v_exp_f32_e32 v0, v0
	v_exp_f32_e32 v13, v13
	v_mul_f32_e32 v1, 0x3db504f3, v52
	v_lshl_or_b32 v2, s0, 7, v40
	v_mul_f32_e32 v1, v1, v0
	v_pk_mul_f32 v[12:13], v[12:13], v[46:47]
	v_cvt_pk_bf16_f32 v1, v1, s0
	v_lshlrev_b64 v[2:3], 1, v[2:3]
	v_cvt_pk_bf16_f32 v46, v12, s0
	v_lshl_add_u64 v[14:15], s[86:87], 0, v[2:3]
	global_store_short v[10:11], v46, off
	global_store_short v[14:15], v1, off
	v_cvt_pk_bf16_f32 v1, v13, s0
	v_lshl_add_u64 v[2:3], s[84:85], 0, v[2:3]
	global_store_short v[2:3], v1, off
	v_cvt_pk_bf16_f32 v2, v4, v5
	v_cvt_pk_bf16_f32 v3, v6, v7
	v_cvt_pk_bf16_f32 v4, v8, v9
	v_cvt_pk_bf16_f32 v5, v12, v13
	s_mov_b64 s[0:1], 0
	global_store_dwordx4 v[44:45], v[2:5], off offset:48
	s_cbranch_vccz .LBB0_662
;     template <class Tp> __device__ __forceinline__ Tp* W(size_t off) const { return (Tp*)(ws + off); }
; __device__ __forceinline__ void prep_dn_load(const bf16_t* proj, const float* cw, int idx, u32x4 (&raw)[4], int& t, int& ch) {
;     if (idx >= 0) { t = idx / 384; const int j = idx - t * 384; ch = j * 8; }
; #pragma unroll
;     for (int k = 0; k < 4; ++k) { const int tt = t - 3 + k; raw[k] = (u32x4){0u, 0u, 0u, 0u};
;         if (tt >= 0) raw[k] = *(const u32x4*)(proj + (size_t)tt * NP + C_DNQ + ch); }
; }
; __device__ void prep_gla(const Ctx& c, int ck, int blk) {
;     ...
;         c.W<float>(WS_GDEC)[(size_t)ck * 512 + ch] = __expf(G);
	v_readlane_b32 s0, v249, 38
	v_readlane_b32 s1, v249, 39
	s_mov_b32 s2, s0
	s_ashr_i32 s3, s0, 31
	v_writelane_b32 v249, s0, 38
	s_movk_i32 s56, 0x2000
	s_movk_i32 s43, 0x6000
	v_writelane_b32 v249, s1, 39
	s_lshl_b64 s[0:1], s[2:3], 11
	v_readlane_b32 s2, v249, 3
	s_add_u32 s0, s2, s0
	v_readlane_b32 s2, v249, 4
	s_addc_u32 s1, s2, s1
	v_lshl_add_u64 v[2:3], v[22:23], 2, s[0:1]
	v_readlane_b32 s94, v249, 32
	v_readlane_b32 s0, v253, 47
	s_movk_i32 s6, 0x7e00
	s_movk_i32 s62, 0x3000
	v_readlane_b32 s92, v249, 30
	v_readlane_b32 s95, v249, 33
	v_readlane_b32 s58, v249, 42
	v_readlane_b32 s1, v253, 48
	v_readlane_b32 s7, v253, 45
	global_store_dword v[2:3], v0, off
	v_readlane_b32 s93, v249, 31
	s_branch .LBB0_664
.Ldnc2_entry:
	s_mov_b64 exec, -1
	s_load_dwordx2 s[8:9], s[94:95], 0xe8
	s_load_dwordx2 s[2:3], s[94:95], 0x20
	v_lshrrev_b32_e32 v7, 6, v144
	v_readlane_b32 s21, v249, 38
	v_readlane_b32 s22, v249, 37
	v_readfirstlane_b32 s11, v7
	s_mov_b32 s12, 0xbfb8aa3b
	s_mov_b32 s13, 0xbfb8aa3b
	s_mov_b32 s14, 1.0
	s_mov_b32 s15, 1.0
	s_lshl_b32 s21, s21, 6
	s_lshl_b32 s22, s22, 9
	s_sub_u32 s11, s11, 4
	v_lshlrev_b32_e32 v7, 3, v237
	v_add_u32_e32 v7, s22, v7
	v_lshlrev_b32_e32 v0, 1, v7
	v_lshlrev_b32_e32 v3, 2, v7
	v_add_u32_e32 v1, 0x800, v0
	v_add_u32_e32 v2, 0x1000, v0
	v_add_u32_e32 v4, 0x1f100000, v0
	v_add_u32_e32 v5, 0x20100000, v0
	v_add_u32_e32 v6, 0x21100000, v0
	s_lshl_b32 s20, s11, 3
	s_add_u32 s20, s20, s21
	s_add_i32 s10, s20, -3
	s_lshl_b32 s20, s20, 11
	v_readlane_b32 s23, v248, 40
	v_readlane_b32 s24, v248, 39
	s_waitcnt lgkmcnt(0)
	s_add_u32 s4, s2, s23
	s_addc_u32 s5, s3, s24
	s_add_u32 s18, s8, s20
	s_addc_u32 s19, s9, 0
	s_mul_i32 s20, s10, 0x7e00
	s_ashr_i32 vcc_lo, s20, 31
	s_add_u32 s16, s8, s20
	s_addc_u32 s17, s9, vcc_lo
	s_add_u32 s16, s16, 0x9c00000
	s_addc_u32 s17, s17, 0
	global_load_dwordx4 v[22:25], v3, s[4:5]
	global_load_dwordx4 v[26:29], v3, s[4:5] offset:16
	s_add_u32 vcc_lo, s4, 0x3000
	s_addc_u32 vcc_hi, s5, 0
	global_load_dwordx4 v[30:33], v3, vcc
	global_load_dwordx4 v[34:37], v3, vcc offset:16
	s_add_u32 vcc_lo, s4, 0x6000
	s_addc_u32 vcc_hi, s5, 0
	global_load_dwordx4 v[38:41], v3, vcc
	global_load_dwordx4 v[42:45], v3, vcc offset:16
	s_add_u32 vcc_lo, s4, 0x9000
	s_addc_u32 vcc_hi, s5, 0
	global_load_dwordx4 v[46:49], v3, vcc
	global_load_dwordx4 v[50:53], v3, vcc offset:16
	global_load_dwordx4 v[66:69], v0, s[16:17]
	s_add_u32 s16, s16, 0x7e00
	s_addc_u32 s17, s17, 0
	global_load_dwordx4 v[70:73], v0, s[16:17]
	s_add_u32 s16, s16, 0x7e00
	s_addc_u32 s17, s17, 0
	global_load_dwordx4 v[74:77], v0, s[16:17]
	s_add_u32 s16, s16, 0x7e00
	s_addc_u32 s17, s17, 0
	global_load_dwordx4 v[78:81], v0, s[16:17]
	s_add_u32 s16, s16, 0x7e00
	s_addc_u32 s17, s17, 0
	global_load_dwordx4 v[82:85], v0, s[16:17]
	s_add_u32 s16, s16, 0x7e00
	s_addc_u32 s17, s17, 0
	global_load_dwordx4 v[86:89], v0, s[16:17]
	s_add_u32 s16, s16, 0x7e00
	s_addc_u32 s17, s17, 0
	global_load_dwordx4 v[90:93], v0, s[16:17]
	s_add_u32 s16, s16, 0x7e00
	s_addc_u32 s17, s17, 0
	global_load_dwordx4 v[94:97], v0, s[16:17]
	s_add_u32 s16, s16, 0x7e00
	s_addc_u32 s17, s17, 0
	global_load_dwordx4 v[98:101], v0, s[16:17]
	s_add_u32 s16, s16, 0x7e00
	s_addc_u32 s17, s17, 0
	global_load_dwordx4 v[102:105], v0, s[16:17]
	s_add_u32 s16, s16, 0x7e00
	s_addc_u32 s17, s17, 0
	global_load_dwordx4 v[106:109], v0, s[16:17]
	s_add_u32 s16, s16, 0xad400
	s_addc_u32 s17, s17, 0
	s_waitcnt vmcnt(8)
	s_cmp_lt_i32 s10, 0
	s_cbranch_scc0 .Ldnc2_nz0
	v_mov_b32_e32 v66, 0
	v_mov_b32_e32 v67, 0
	v_mov_b32_e32 v68, 0
	v_mov_b32_e32 v69, 0
	v_mov_b32_e32 v70, 0
	v_mov_b32_e32 v71, 0
	v_mov_b32_e32 v72, 0
	v_mov_b32_e32 v73, 0
	v_mov_b32_e32 v74, 0
	v_mov_b32_e32 v75, 0
	v_mov_b32_e32 v76, 0
	v_mov_b32_e32 v77, 0
.Ldnc2_nz0:
	v_lshlrev_b32_e32 v110, 16, v66
	v_and_b32_e32 v111, 0xffff0000, v66
	v_lshlrev_b32_e32 v112, 16, v67
	v_and_b32_e32 v113, 0xffff0000, v67
	v_lshlrev_b32_e32 v114, 16, v68
	v_and_b32_e32 v115, 0xffff0000, v68
	v_lshlrev_b32_e32 v116, 16, v69
	v_and_b32_e32 v117, 0xffff0000, v69
	v_lshlrev_b32_e32 v118, 16, v70
	v_and_b32_e32 v119, 0xffff0000, v70
	v_lshlrev_b32_e32 v120, 16, v71
	v_and_b32_e32 v121, 0xffff0000, v71
	v_lshlrev_b32_e32 v122, 16, v72
	v_and_b32_e32 v123, 0xffff0000, v72
	v_lshlrev_b32_e32 v124, 16, v73
	v_and_b32_e32 v125, 0xffff0000, v73
	v_lshlrev_b32_e32 v126, 16, v74
	v_and_b32_e32 v127, 0xffff0000, v74
	v_lshlrev_b32_e32 v128, 16, v75
	v_and_b32_e32 v129, 0xffff0000, v75
	v_lshlrev_b32_e32 v130, 16, v76
	v_and_b32_e32 v131, 0xffff0000, v76
	v_lshlrev_b32_e32 v132, 16, v77
	v_and_b32_e32 v133, 0xffff0000, v77
	global_load_dwordx4 v[66:69], v0, s[16:17]
	s_add_u32 s16, s16, 0x7e00
	s_addc_u32 s17, s17, 0
	global_load_dwordx4 v[70:73], v0, s[16:17]
	s_add_u32 s16, s16, 0x7e00
	s_addc_u32 s17, s17, 0
	global_load_dwordx4 v[74:77], v0, s[16:17]
	s_add_u32 s16, s16, 0x7e00
	s_addc_u32 s17, s17, 0
	s_waitcnt vmcnt(10)
; __device__ __forceinline__ unsigned pk2(float lo, float hi) { const f32v2_t v = {lo, hi}; const bf16v2_t b = __builtin_convertvector(v, bf16v2_t); return __builtin_bit_cast(unsigned, b); }
; __device__ __forceinline__ float lo16(unsigned u) { return __uint_as_float(u << 16); }
; __device__ __forceinline__ float hi16(unsigned u) { return __uint_as_float(u & 0xffff0000u); }
; __device__ __forceinline__ float siluf_(float x) { return x * __builtin_amdgcn_rcpf(1.0f + __expf(-x)); }
; __device__ __forceinline__ void prep_dn_finish(const float* cw, bf16_t* dq, bf16_t* dk, bf16_t* dv, const u32x4 (&raw)[4], int t, int ch) {
;     float a[8];
; #pragma unroll
;     for (int e = 0; e < 8; ++e) a[e] = 0.f;
; #pragma unroll
;     for (int k = 0; k < 4; ++k) {
;         const f32x4 w0 = *(const f32x4*)(cw + k * 3072 + ch), w1 = *(const f32x4*)(cw + k * 3072 + ch + 4);
;         a[0] += w0[0] * lo16(raw[k].x); a[1] += w0[1] * hi16(raw[k].x); a[2] += w0[2] * lo16(raw[k].y); a[3] += w0[3] * hi16(raw[k].y);
;         a[4] += w1[0] * lo16(raw[k].z); a[5] += w1[1] * hi16(raw[k].z); a[6] += w1[2] * lo16(raw[k].w); a[7] += w1[3] * hi16(raw[k].w); }
;     float ss = 0.f;
; #pragma unroll
;     for (int e = 0; e < 8; ++e) { a[e] = siluf_(a[e]); ss += a[e] * a[e]; }
;     ss += __shfl_xor(ss, 1); ss += __shfl_xor(ss, 2); ss += __shfl_xor(ss, 4); ss += __shfl_xor(ss, 8);
;     float sc = 1.0f;
;     if (ch < 2048) { sc = rsqrtf(ss + EPS); if (ch < 1024) sc *= 0.08838834764831845f; }
;     u32x4 w; w.x = pk2(a[0] * sc, a[1] * sc); w.y = pk2(a[2] * sc, a[3] * sc); w.z = pk2(a[4] * sc, a[5] * sc); w.w = pk2(a[6] * sc, a[7] * sc);
;     bf16_t* dst = (ch < 1024) ? dq : (ch < 2048 ? dk : dv);
;     *(u32x4*)(dst + (size_t)t * 1024 + (ch & 1023)) = w;
; }
	v_lshlrev_b32_e32 v134, 16, v78
	v_and_b32_e32 v135, 0xffff0000, v78
	v_lshlrev_b32_e32 v136, 16, v79
	v_and_b32_e32 v137, 0xffff0000, v79
	v_lshlrev_b32_e32 v138, 16, v80
	v_and_b32_e32 v139, 0xffff0000, v80
	v_lshlrev_b32_e32 v140, 16, v81
	v_and_b32_e32 v141, 0xffff0000, v81
	global_load_dwordx4 v[78:81], v0, s[16:17]
	s_add_u32 s16, s16, 0x7e00
	s_addc_u32 s17, s17, 0
	v_pk_mul_f32 v[152:153], v[22:23], v[110:111]
	v_pk_mul_f32 v[154:155], v[24:25], v[112:113]
	v_pk_mul_f32 v[156:157], v[26:27], v[114:115]
	v_pk_mul_f32 v[158:159], v[28:29], v[116:117]
	v_pk_fma_f32 v[152:153], v[30:31], v[118:119], v[152:153]
	v_pk_fma_f32 v[154:155], v[32:33], v[120:121], v[154:155]
	v_pk_fma_f32 v[156:157], v[34:35], v[122:123], v[156:157]
	v_pk_fma_f32 v[158:159], v[36:37], v[124:125], v[158:159]
	v_pk_fma_f32 v[152:153], v[38:39], v[126:127], v[152:153]
	v_pk_fma_f32 v[154:155], v[40:41], v[128:129], v[154:155]
	v_pk_fma_f32 v[156:157], v[42:43], v[130:131], v[156:157]
	v_pk_fma_f32 v[158:159], v[44:45], v[132:133], v[158:159]
	v_pk_fma_f32 v[152:153], v[46:47], v[134:135], v[152:153]
	v_pk_fma_f32 v[154:155], v[48:49], v[136:137], v[154:155]
	v_pk_fma_f32 v[156:157], v[50:51], v[138:139], v[156:157]
	v_pk_fma_f32 v[158:159], v[52:53], v[140:141], v[158:159]
	v_pk_mul_f32 v[8:9], v[152:153], s[12:13]
	v_pk_mul_f32 v[10:11], v[154:155], s[12:13]
	v_pk_mul_f32 v[12:13], v[156:157], s[12:13]
	v_pk_mul_f32 v[14:15], v[158:159], s[12:13]
	v_exp_f32_e32 v8, v8
	v_exp_f32_e32 v9, v9
	v_exp_f32_e32 v10, v10
	v_exp_f32_e32 v11, v11
	v_exp_f32_e32 v12, v12
	v_exp_f32_e32 v13, v13
	v_exp_f32_e32 v14, v14
	v_exp_f32_e32 v15, v15
	v_pk_add_f32 v[8:9], v[8:9], s[14:15]
	v_pk_add_f32 v[10:11], v[10:11], s[14:15]
	v_pk_add_f32 v[12:13], v[12:13], s[14:15]
	v_pk_add_f32 v[14:15], v[14:15], s[14:15]
	v_rcp_f32_e32 v8, v8
	v_rcp_f32_e32 v9, v9
	v_rcp_f32_e32 v10, v10
	v_rcp_f32_e32 v11, v11
	v_rcp_f32_e32 v12, v12
	v_rcp_f32_e32 v13, v13
	v_rcp_f32_e32 v14, v14
	v_rcp_f32_e32 v15, v15
	v_pk_mul_f32 v[152:153], v[152:153], v[8:9]
	v_pk_mul_f32 v[154:155], v[154:155], v[10:11]
	v_pk_mul_f32 v[156:157], v[156:157], v[12:13]
	v_pk_mul_f32 v[158:159], v[158:159], v[14:15]
	v_pk_mul_f32 v[8:9], v[152:153], v[152:153]
	v_pk_fma_f32 v[8:9], v[154:155], v[154:155], v[8:9]
	v_pk_fma_f32 v[8:9], v[156:157], v[156:157], v[8:9]
	v_pk_fma_f32 v[8:9], v[158:159], v[158:159], v[8:9]
	s_nop 0
	v_add_f32_e32 v54, v8, v9
	s_nop 1
	v_add_f32_dpp v54, v54, v54 quad_perm:[1,0,3,2] row_mask:0xf bank_mask:0xf
	s_nop 1
	v_add_f32_dpp v54, v54, v54 quad_perm:[2,3,0,1] row_mask:0xf bank_mask:0xf
	s_nop 1
	v_add_f32_dpp v54, v54, v54 row_half_mirror row_mask:0xf bank_mask:0xf
	s_nop 1
	v_add_f32_dpp v54, v54, v54 row_mirror row_mask:0xf bank_mask:0xf
	v_add_f32_e32 v54, 0x358637bd, v54
	v_rsq_f32_e32 v54, v54
	s_nop 0
	v_mul_f32_e32 v54, 0x3db504f3, v54
	v_pk_mul_f32 v[152:153], v[152:153], v[54:55] op_sel_hi:[1,0]
	v_pk_mul_f32 v[154:155], v[154:155], v[54:55] op_sel_hi:[1,0]
	v_pk_mul_f32 v[156:157], v[156:157], v[54:55] op_sel_hi:[1,0]
	v_pk_mul_f32 v[158:159], v[158:159], v[54:55] op_sel_hi:[1,0]
	v_cvt_pk_bf16_f32 v56, v152, v153
	v_cvt_pk_bf16_f32 v57, v154, v155
	v_cvt_pk_bf16_f32 v58, v156, v157
	v_cvt_pk_bf16_f32 v59, v158, v159
	global_store_dwordx4 v4, v[56:59], s[18:19]
	s_add_u32 s18, s18, 0x800
	s_addc_u32 s19, s19, 0
	s_waitcnt vmcnt(11)
	v_lshlrev_b32_e32 v110, 16, v82
	v_and_b32_e32 v111, 0xffff0000, v82
	v_lshlrev_b32_e32 v112, 16, v83
	v_and_b32_e32 v113, 0xffff0000, v83
	v_lshlrev_b32_e32 v114, 16, v84
	v_and_b32_e32 v115, 0xffff0000, v84
	v_lshlrev_b32_e32 v116, 16, v85
	v_and_b32_e32 v117, 0xffff0000, v85
	global_load_dwordx4 v[82:85], v0, s[16:17]
	s_add_u32 s16, s16, 0x7e00
	s_addc_u32 s17, s17, 0
	v_pk_mul_f32 v[152:153], v[22:23], v[118:119]
	v_pk_mul_f32 v[154:155], v[24:25], v[120:121]
	v_pk_mul_f32 v[156:157], v[26:27], v[122:123]
	v_pk_mul_f32 v[158:159], v[28:29], v[124:125]
	v_pk_fma_f32 v[152:153], v[30:31], v[126:127], v[152:153]
	v_pk_fma_f32 v[154:155], v[32:33], v[128:129], v[154:155]
	v_pk_fma_f32 v[156:157], v[34:35], v[130:131], v[156:157]
	v_pk_fma_f32 v[158:159], v[36:37], v[132:133], v[158:159]
	v_pk_fma_f32 v[152:153], v[38:39], v[134:135], v[152:153]
	v_pk_fma_f32 v[154:155], v[40:41], v[136:137], v[154:155]
	v_pk_fma_f32 v[156:157], v[42:43], v[138:139], v[156:157]
	v_pk_fma_f32 v[158:159], v[44:45], v[140:141], v[158:159]
	v_pk_fma_f32 v[152:153], v[46:47], v[110:111], v[152:153]
	v_pk_fma_f32 v[154:155], v[48:49], v[112:113], v[154:155]
	v_pk_fma_f32 v[156:157], v[50:51], v[114:115], v[156:157]
	v_pk_fma_f32 v[158:159], v[52:53], v[116:117], v[158:159]
	v_pk_mul_f32 v[8:9], v[152:153], s[12:13]
	v_pk_mul_f32 v[10:11], v[154:155], s[12:13]
	v_pk_mul_f32 v[12:13], v[156:157], s[12:13]
	v_pk_mul_f32 v[14:15], v[158:159], s[12:13]
	v_exp_f32_e32 v8, v8
	v_exp_f32_e32 v9, v9
	v_exp_f32_e32 v10, v10
	v_exp_f32_e32 v11, v11
	v_exp_f32_e32 v12, v12
	v_exp_f32_e32 v13, v13
	v_exp_f32_e32 v14, v14
	v_exp_f32_e32 v15, v15
	v_pk_add_f32 v[8:9], v[8:9], s[14:15]
	v_pk_add_f32 v[10:11], v[10:11], s[14:15]
	v_pk_add_f32 v[12:13], v[12:13], s[14:15]
	v_pk_add_f32 v[14:15], v[14:15], s[14:15]
	v_rcp_f32_e32 v8, v8
	v_rcp_f32_e32 v9, v9
	v_rcp_f32_e32 v10, v10
	v_rcp_f32_e32 v11, v11
	v_rcp_f32_e32 v12, v12
	v_rcp_f32_e32 v13, v13
	v_rcp_f32_e32 v14, v14
	v_rcp_f32_e32 v15, v15
	v_pk_mul_f32 v[152:153], v[152:153], v[8:9]
	v_pk_mul_f32 v[154:155], v[154:155], v[10:11]
	v_pk_mul_f32 v[156:157], v[156:157], v[12:13]
	v_pk_mul_f32 v[158:159], v[158:159], v[14:15]
	v_pk_mul_f32 v[8:9], v[152:153], v[152:153]
	v_pk_fma_f32 v[8:9], v[154:155], v[154:155], v[8:9]
	v_pk_fma_f32 v[8:9], v[156:157], v[156:157], v[8:9]
	v_pk_fma_f32 v[8:9], v[158:159], v[158:159], v[8:9]
	s_nop 0
	v_add_f32_e32 v54, v8, v9
	s_nop 1
	v_add_f32_dpp v54, v54, v54 quad_perm:[1,0,3,2] row_mask:0xf bank_mask:0xf
	s_nop 1
	v_add_f32_dpp v54, v54, v54 quad_perm:[2,3,0,1] row_mask:0xf bank_mask:0xf
	s_nop 1
	v_add_f32_dpp v54, v54, v54 row_half_mirror row_mask:0xf bank_mask:0xf
	s_nop 1
	v_add_f32_dpp v54, v54, v54 row_mirror row_mask:0xf bank_mask:0xf
	v_add_f32_e32 v54, 0x358637bd, v54
	v_rsq_f32_e32 v54, v54
	s_nop 0
	v_mul_f32_e32 v54, 0x3db504f3, v54
	v_pk_mul_f32 v[152:153], v[152:153], v[54:55] op_sel_hi:[1,0]
	v_pk_mul_f32 v[154:155], v[154:155], v[54:55] op_sel_hi:[1,0]
	v_pk_mul_f32 v[156:157], v[156:157], v[54:55] op_sel_hi:[1,0]
	v_pk_mul_f32 v[158:159], v[158:159], v[54:55] op_sel_hi:[1,0]
	v_cvt_pk_bf16_f32 v56, v152, v153
	v_cvt_pk_bf16_f32 v57, v154, v155
	v_cvt_pk_bf16_f32 v58, v156, v157
	v_cvt_pk_bf16_f32 v59, v158, v159
	global_store_dwordx4 v4, v[56:59], s[18:19]
	s_add_u32 s18, s18, 0x800
	s_addc_u32 s19, s19, 0
	s_waitcnt vmcnt(12)
; __device__ __forceinline__ unsigned pk2(float lo, float hi) { const f32v2_t v = {lo, hi}; const bf16v2_t b = __builtin_convertvector(v, bf16v2_t); return __builtin_bit_cast(unsigned, b); }
; __device__ __forceinline__ float lo16(unsigned u) { return __uint_as_float(u << 16); }
; __device__ __forceinline__ float hi16(unsigned u) { return __uint_as_float(u & 0xffff0000u); }
; __device__ __forceinline__ float siluf_(float x) { return x * __builtin_amdgcn_rcpf(1.0f + __expf(-x)); }
; __device__ __forceinline__ void prep_dn_finish(const float* cw, bf16_t* dq, bf16_t* dk, bf16_t* dv, const u32x4 (&raw)[4], int t, int ch) {
;     float a[8];
; #pragma unroll
;     for (int e = 0; e < 8; ++e) a[e] = 0.f;
; #pragma unroll
;     for (int k = 0; k < 4; ++k) {
;         const f32x4 w0 = *(const f32x4*)(cw + k * 3072 + ch), w1 = *(const f32x4*)(cw + k * 3072 + ch + 4);
;         a[0] += w0[0] * lo16(raw[k].x); a[1] += w0[1] * hi16(raw[k].x); a[2] += w0[2] * lo16(raw[k].y); a[3] += w0[3] * hi16(raw[k].y);
;         a[4] += w1[0] * lo16(raw[k].z); a[5] += w1[1] * hi16(raw[k].z); a[6] += w1[2] * lo16(raw[k].w); a[7] += w1[3] * hi16(raw[k].w); }
;     float ss = 0.f;
; #pragma unroll
;     for (int e = 0; e < 8; ++e) { a[e] = siluf_(a[e]); ss += a[e] * a[e]; }
;     ss += __shfl_xor(ss, 1); ss += __shfl_xor(ss, 2); ss += __shfl_xor(ss, 4); ss += __shfl_xor(ss, 8);
;     float sc = 1.0f;
;     if (ch < 2048) { sc = rsqrtf(ss + EPS); if (ch < 1024) sc *= 0.08838834764831845f; }
;     u32x4 w; w.x = pk2(a[0] * sc, a[1] * sc); w.y = pk2(a[2] * sc, a[3] * sc); w.z = pk2(a[4] * sc, a[5] * sc); w.w = pk2(a[6] * sc, a[7] * sc);
;     bf16_t* dst = (ch < 1024) ? dq : (ch < 2048 ? dk : dv);
;     *(u32x4*)(dst + (size_t)t * 1024 + (ch & 1023)) = w;
; }
	v_lshlrev_b32_e32 v118, 16, v86
	v_and_b32_e32 v119, 0xffff0000, v86
	v_lshlrev_b32_e32 v120, 16, v87
	v_and_b32_e32 v121, 0xffff0000, v87
	v_lshlrev_b32_e32 v122, 16, v88
	v_and_b32_e32 v123, 0xffff0000, v88
	v_lshlrev_b32_e32 v124, 16, v89
	v_and_b32_e32 v125, 0xffff0000, v89
	global_load_dwordx4 v[86:89], v0, s[16:17]
	s_add_u32 s16, s16, 0x7e00
	s_addc_u32 s17, s17, 0
	v_pk_mul_f32 v[152:153], v[22:23], v[126:127]
	v_pk_mul_f32 v[154:155], v[24:25], v[128:129]
	v_pk_mul_f32 v[156:157], v[26:27], v[130:131]
	v_pk_mul_f32 v[158:159], v[28:29], v[132:133]
	v_pk_fma_f32 v[152:153], v[30:31], v[134:135], v[152:153]
	v_pk_fma_f32 v[154:155], v[32:33], v[136:137], v[154:155]
	v_pk_fma_f32 v[156:157], v[34:35], v[138:139], v[156:157]
	v_pk_fma_f32 v[158:159], v[36:37], v[140:141], v[158:159]
	v_pk_fma_f32 v[152:153], v[38:39], v[110:111], v[152:153]
	v_pk_fma_f32 v[154:155], v[40:41], v[112:113], v[154:155]
	v_pk_fma_f32 v[156:157], v[42:43], v[114:115], v[156:157]
	v_pk_fma_f32 v[158:159], v[44:45], v[116:117], v[158:159]
	v_pk_fma_f32 v[152:153], v[46:47], v[118:119], v[152:153]
	v_pk_fma_f32 v[154:155], v[48:49], v[120:121], v[154:155]
	v_pk_fma_f32 v[156:157], v[50:51], v[122:123], v[156:157]
	v_pk_fma_f32 v[158:159], v[52:53], v[124:125], v[158:159]
	v_pk_mul_f32 v[8:9], v[152:153], s[12:13]
	v_pk_mul_f32 v[10:11], v[154:155], s[12:13]
	v_pk_mul_f32 v[12:13], v[156:157], s[12:13]
	v_pk_mul_f32 v[14:15], v[158:159], s[12:13]
	v_exp_f32_e32 v8, v8
	v_exp_f32_e32 v9, v9
	v_exp_f32_e32 v10, v10
	v_exp_f32_e32 v11, v11
	v_exp_f32_e32 v12, v12
	v_exp_f32_e32 v13, v13
	v_exp_f32_e32 v14, v14
	v_exp_f32_e32 v15, v15
	v_pk_add_f32 v[8:9], v[8:9], s[14:15]
	v_pk_add_f32 v[10:11], v[10:11], s[14:15]
	v_pk_add_f32 v[12:13], v[12:13], s[14:15]
	v_pk_add_f32 v[14:15], v[14:15], s[14:15]
	v_rcp_f32_e32 v8, v8
	v_rcp_f32_e32 v9, v9
	v_rcp_f32_e32 v10, v10
	v_rcp_f32_e32 v11, v11
	v_rcp_f32_e32 v12, v12
	v_rcp_f32_e32 v13, v13
	v_rcp_f32_e32 v14, v14
	v_rcp_f32_e32 v15, v15
	v_pk_mul_f32 v[152:153], v[152:153], v[8:9]
	v_pk_mul_f32 v[154:155], v[154:155], v[10:11]
	v_pk_mul_f32 v[156:157], v[156:157], v[12:13]
	v_pk_mul_f32 v[158:159], v[158:159], v[14:15]
	v_pk_mul_f32 v[8:9], v[152:153], v[152:153]
	v_pk_fma_f32 v[8:9], v[154:155], v[154:155], v[8:9]
	v_pk_fma_f32 v[8:9], v[156:157], v[156:157], v[8:9]
	v_pk_fma_f32 v[8:9], v[158:159], v[158:159], v[8:9]
	s_nop 0
	v_add_f32_e32 v54, v8, v9
	s_nop 1
	v_add_f32_dpp v54, v54, v54 quad_perm:[1,0,3,2] row_mask:0xf bank_mask:0xf
	s_nop 1
	v_add_f32_dpp v54, v54, v54 quad_perm:[2,3,0,1] row_mask:0xf bank_mask:0xf
	s_nop 1
	v_add_f32_dpp v54, v54, v54 row_half_mirror row_mask:0xf bank_mask:0xf
	s_nop 1
	v_add_f32_dpp v54, v54, v54 row_mirror row_mask:0xf bank_mask:0xf
	v_add_f32_e32 v54, 0x358637bd, v54
	v_rsq_f32_e32 v54, v54
	s_nop 0
	v_mul_f32_e32 v54, 0x3db504f3, v54
	v_pk_mul_f32 v[152:153], v[152:153], v[54:55] op_sel_hi:[1,0]
	v_pk_mul_f32 v[154:155], v[154:155], v[54:55] op_sel_hi:[1,0]
	v_pk_mul_f32 v[156:157], v[156:157], v[54:55] op_sel_hi:[1,0]
	v_pk_mul_f32 v[158:159], v[158:159], v[54:55] op_sel_hi:[1,0]
	v_cvt_pk_bf16_f32 v56, v152, v153
	v_cvt_pk_bf16_f32 v57, v154, v155
	v_cvt_pk_bf16_f32 v58, v156, v157
	v_cvt_pk_bf16_f32 v59, v158, v159
	global_store_dwordx4 v4, v[56:59], s[18:19]
	s_add_u32 s18, s18, 0x800
	s_addc_u32 s19, s19, 0
	s_waitcnt vmcnt(13)
	v_lshlrev_b32_e32 v126, 16, v90
	v_and_b32_e32 v127, 0xffff0000, v90
	v_lshlrev_b32_e32 v128, 16, v91
	v_and_b32_e32 v129, 0xffff0000, v91
	v_lshlrev_b32_e32 v130, 16, v92
	v_and_b32_e32 v131, 0xffff0000, v92
	v_lshlrev_b32_e32 v132, 16, v93
	v_and_b32_e32 v133, 0xffff0000, v93
	global_load_dwordx4 v[90:93], v0, s[16:17]
	s_add_u32 s16, s16, 0x7e00
	s_addc_u32 s17, s17, 0
	v_pk_mul_f32 v[152:153], v[22:23], v[134:135]
	v_pk_mul_f32 v[154:155], v[24:25], v[136:137]
	v_pk_mul_f32 v[156:157], v[26:27], v[138:139]
	v_pk_mul_f32 v[158:159], v[28:29], v[140:141]
	v_pk_fma_f32 v[152:153], v[30:31], v[110:111], v[152:153]
	v_pk_fma_f32 v[154:155], v[32:33], v[112:113], v[154:155]
	v_pk_fma_f32 v[156:157], v[34:35], v[114:115], v[156:157]
	v_pk_fma_f32 v[158:159], v[36:37], v[116:117], v[158:159]
	v_pk_fma_f32 v[152:153], v[38:39], v[118:119], v[152:153]
	v_pk_fma_f32 v[154:155], v[40:41], v[120:121], v[154:155]
	v_pk_fma_f32 v[156:157], v[42:43], v[122:123], v[156:157]
	v_pk_fma_f32 v[158:159], v[44:45], v[124:125], v[158:159]
	v_pk_fma_f32 v[152:153], v[46:47], v[126:127], v[152:153]
	v_pk_fma_f32 v[154:155], v[48:49], v[128:129], v[154:155]
	v_pk_fma_f32 v[156:157], v[50:51], v[130:131], v[156:157]
	v_pk_fma_f32 v[158:159], v[52:53], v[132:133], v[158:159]
	v_pk_mul_f32 v[8:9], v[152:153], s[12:13]
	v_pk_mul_f32 v[10:11], v[154:155], s[12:13]
	v_pk_mul_f32 v[12:13], v[156:157], s[12:13]
	v_pk_mul_f32 v[14:15], v[158:159], s[12:13]
	v_exp_f32_e32 v8, v8
	v_exp_f32_e32 v9, v9
	v_exp_f32_e32 v10, v10
	v_exp_f32_e32 v11, v11
	v_exp_f32_e32 v12, v12
	v_exp_f32_e32 v13, v13
	v_exp_f32_e32 v14, v14
	v_exp_f32_e32 v15, v15
	v_pk_add_f32 v[8:9], v[8:9], s[14:15]
	v_pk_add_f32 v[10:11], v[10:11], s[14:15]
	v_pk_add_f32 v[12:13], v[12:13], s[14:15]
	v_pk_add_f32 v[14:15], v[14:15], s[14:15]
	v_rcp_f32_e32 v8, v8
	v_rcp_f32_e32 v9, v9
	v_rcp_f32_e32 v10, v10
	v_rcp_f32_e32 v11, v11
	v_rcp_f32_e32 v12, v12
	v_rcp_f32_e32 v13, v13
	v_rcp_f32_e32 v14, v14
	v_rcp_f32_e32 v15, v15
	v_pk_mul_f32 v[152:153], v[152:153], v[8:9]
	v_pk_mul_f32 v[154:155], v[154:155], v[10:11]
	v_pk_mul_f32 v[156:157], v[156:157], v[12:13]
	v_pk_mul_f32 v[158:159], v[158:159], v[14:15]
	v_pk_mul_f32 v[8:9], v[152:153], v[152:153]
	v_pk_fma_f32 v[8:9], v[154:155], v[154:155], v[8:9]
	v_pk_fma_f32 v[8:9], v[156:157], v[156:157], v[8:9]
	v_pk_fma_f32 v[8:9], v[158:159], v[158:159], v[8:9]
	s_nop 0
	v_add_f32_e32 v54, v8, v9
	s_nop 1
	v_add_f32_dpp v54, v54, v54 quad_perm:[1,0,3,2] row_mask:0xf bank_mask:0xf
	s_nop 1
	v_add_f32_dpp v54, v54, v54 quad_perm:[2,3,0,1] row_mask:0xf bank_mask:0xf
	s_nop 1
	v_add_f32_dpp v54, v54, v54 row_half_mirror row_mask:0xf bank_mask:0xf
	s_nop 1
	v_add_f32_dpp v54, v54, v54 row_mirror row_mask:0xf bank_mask:0xf
	v_add_f32_e32 v54, 0x358637bd, v54
	v_rsq_f32_e32 v54, v54
	s_nop 0
	v_mul_f32_e32 v54, 0x3db504f3, v54
	v_pk_mul_f32 v[152:153], v[152:153], v[54:55] op_sel_hi:[1,0]
	v_pk_mul_f32 v[154:155], v[154:155], v[54:55] op_sel_hi:[1,0]
	v_pk_mul_f32 v[156:157], v[156:157], v[54:55] op_sel_hi:[1,0]
	v_pk_mul_f32 v[158:159], v[158:159], v[54:55] op_sel_hi:[1,0]
	v_cvt_pk_bf16_f32 v56, v152, v153
	v_cvt_pk_bf16_f32 v57, v154, v155
	v_cvt_pk_bf16_f32 v58, v156, v157
	v_cvt_pk_bf16_f32 v59, v158, v159
	global_store_dwordx4 v4, v[56:59], s[18:19]
	s_add_u32 s18, s18, 0x800
	s_addc_u32 s19, s19, 0
	s_waitcnt vmcnt(14)
; __device__ __forceinline__ unsigned pk2(float lo, float hi) { const f32v2_t v = {lo, hi}; const bf16v2_t b = __builtin_convertvector(v, bf16v2_t); return __builtin_bit_cast(unsigned, b); }
; __device__ __forceinline__ float lo16(unsigned u) { return __uint_as_float(u << 16); }
; __device__ __forceinline__ float hi16(unsigned u) { return __uint_as_float(u & 0xffff0000u); }
; __device__ __forceinline__ float siluf_(float x) { return x * __builtin_amdgcn_rcpf(1.0f + __expf(-x)); }
; __device__ __forceinline__ void prep_dn_finish(const float* cw, bf16_t* dq, bf16_t* dk, bf16_t* dv, const u32x4 (&raw)[4], int t, int ch) {
;     float a[8];
; #pragma unroll
;     for (int e = 0; e < 8; ++e) a[e] = 0.f;
; #pragma unroll
;     for (int k = 0; k < 4; ++k) {
;         const f32x4 w0 = *(const f32x4*)(cw + k * 3072 + ch), w1 = *(const f32x4*)(cw + k * 3072 + ch + 4);
;         a[0] += w0[0] * lo16(raw[k].x); a[1] += w0[1] * hi16(raw[k].x); a[2] += w0[2] * lo16(raw[k].y); a[3] += w0[3] * hi16(raw[k].y);
;         a[4] += w1[0] * lo16(raw[k].z); a[5] += w1[1] * hi16(raw[k].z); a[6] += w1[2] * lo16(raw[k].w); a[7] += w1[3] * hi16(raw[k].w); }
;     float ss = 0.f;
; #pragma unroll
;     for (int e = 0; e < 8; ++e) { a[e] = siluf_(a[e]); ss += a[e] * a[e]; }
;     ss += __shfl_xor(ss, 1); ss += __shfl_xor(ss, 2); ss += __shfl_xor(ss, 4); ss += __shfl_xor(ss, 8);
;     float sc = 1.0f;
;     if (ch < 2048) { sc = rsqrtf(ss + EPS); if (ch < 1024) sc *= 0.08838834764831845f; }
;     u32x4 w; w.x = pk2(a[0] * sc, a[1] * sc); w.y = pk2(a[2] * sc, a[3] * sc); w.z = pk2(a[4] * sc, a[5] * sc); w.w = pk2(a[6] * sc, a[7] * sc);
;     bf16_t* dst = (ch < 1024) ? dq : (ch < 2048 ? dk : dv);
;     *(u32x4*)(dst + (size_t)t * 1024 + (ch & 1023)) = w;
; }
	v_lshlrev_b32_e32 v134, 16, v94
	v_and_b32_e32 v135, 0xffff0000, v94
	v_lshlrev_b32_e32 v136, 16, v95
	v_and_b32_e32 v137, 0xffff0000, v95
	v_lshlrev_b32_e32 v138, 16, v96
	v_and_b32_e32 v139, 0xffff0000, v96
	v_lshlrev_b32_e32 v140, 16, v97
	v_and_b32_e32 v141, 0xffff0000, v97
	global_load_dwordx4 v[94:97], v0, s[16:17]
	s_add_u32 s16, s16, 0x7e00
	s_addc_u32 s17, s17, 0
	v_pk_mul_f32 v[152:153], v[22:23], v[110:111]
	v_pk_mul_f32 v[154:155], v[24:25], v[112:113]
	v_pk_mul_f32 v[156:157], v[26:27], v[114:115]
	v_pk_mul_f32 v[158:159], v[28:29], v[116:117]
	v_pk_fma_f32 v[152:153], v[30:31], v[118:119], v[152:153]
	v_pk_fma_f32 v[154:155], v[32:33], v[120:121], v[154:155]
	v_pk_fma_f32 v[156:157], v[34:35], v[122:123], v[156:157]
	v_pk_fma_f32 v[158:159], v[36:37], v[124:125], v[158:159]
	v_pk_fma_f32 v[152:153], v[38:39], v[126:127], v[152:153]
	v_pk_fma_f32 v[154:155], v[40:41], v[128:129], v[154:155]
	v_pk_fma_f32 v[156:157], v[42:43], v[130:131], v[156:157]
	v_pk_fma_f32 v[158:159], v[44:45], v[132:133], v[158:159]
	v_pk_fma_f32 v[152:153], v[46:47], v[134:135], v[152:153]
	v_pk_fma_f32 v[154:155], v[48:49], v[136:137], v[154:155]
	v_pk_fma_f32 v[156:157], v[50:51], v[138:139], v[156:157]
	v_pk_fma_f32 v[158:159], v[52:53], v[140:141], v[158:159]
	v_pk_mul_f32 v[8:9], v[152:153], s[12:13]
	v_pk_mul_f32 v[10:11], v[154:155], s[12:13]
	v_pk_mul_f32 v[12:13], v[156:157], s[12:13]
	v_pk_mul_f32 v[14:15], v[158:159], s[12:13]
	v_exp_f32_e32 v8, v8
	v_exp_f32_e32 v9, v9
	v_exp_f32_e32 v10, v10
	v_exp_f32_e32 v11, v11
	v_exp_f32_e32 v12, v12
	v_exp_f32_e32 v13, v13
	v_exp_f32_e32 v14, v14
	v_exp_f32_e32 v15, v15
	v_pk_add_f32 v[8:9], v[8:9], s[14:15]
	v_pk_add_f32 v[10:11], v[10:11], s[14:15]
	v_pk_add_f32 v[12:13], v[12:13], s[14:15]
	v_pk_add_f32 v[14:15], v[14:15], s[14:15]
	v_rcp_f32_e32 v8, v8
	v_rcp_f32_e32 v9, v9
	v_rcp_f32_e32 v10, v10
	v_rcp_f32_e32 v11, v11
	v_rcp_f32_e32 v12, v12
	v_rcp_f32_e32 v13, v13
	v_rcp_f32_e32 v14, v14
	v_rcp_f32_e32 v15, v15
	v_pk_mul_f32 v[152:153], v[152:153], v[8:9]
	v_pk_mul_f32 v[154:155], v[154:155], v[10:11]
	v_pk_mul_f32 v[156:157], v[156:157], v[12:13]
	v_pk_mul_f32 v[158:159], v[158:159], v[14:15]
	v_pk_mul_f32 v[8:9], v[152:153], v[152:153]
	v_pk_fma_f32 v[8:9], v[154:155], v[154:155], v[8:9]
	v_pk_fma_f32 v[8:9], v[156:157], v[156:157], v[8:9]
	v_pk_fma_f32 v[8:9], v[158:159], v[158:159], v[8:9]
	s_nop 0
	v_add_f32_e32 v54, v8, v9
	s_nop 1
	v_add_f32_dpp v54, v54, v54 quad_perm:[1,0,3,2] row_mask:0xf bank_mask:0xf
	s_nop 1
	v_add_f32_dpp v54, v54, v54 quad_perm:[2,3,0,1] row_mask:0xf bank_mask:0xf
	s_nop 1
	v_add_f32_dpp v54, v54, v54 row_half_mirror row_mask:0xf bank_mask:0xf
	s_nop 1
	v_add_f32_dpp v54, v54, v54 row_mirror row_mask:0xf bank_mask:0xf
	v_add_f32_e32 v54, 0x358637bd, v54
	v_rsq_f32_e32 v54, v54
	s_nop 0
	v_mul_f32_e32 v54, 0x3db504f3, v54
	v_pk_mul_f32 v[152:153], v[152:153], v[54:55] op_sel_hi:[1,0]
	v_pk_mul_f32 v[154:155], v[154:155], v[54:55] op_sel_hi:[1,0]
	v_pk_mul_f32 v[156:157], v[156:157], v[54:55] op_sel_hi:[1,0]
	v_pk_mul_f32 v[158:159], v[158:159], v[54:55] op_sel_hi:[1,0]
	v_cvt_pk_bf16_f32 v56, v152, v153
	v_cvt_pk_bf16_f32 v57, v154, v155
	v_cvt_pk_bf16_f32 v58, v156, v157
	v_cvt_pk_bf16_f32 v59, v158, v159
	global_store_dwordx4 v4, v[56:59], s[18:19]
	s_add_u32 s18, s18, 0x800
	s_addc_u32 s19, s19, 0
	s_waitcnt vmcnt(15)
	v_lshlrev_b32_e32 v110, 16, v98
	v_and_b32_e32 v111, 0xffff0000, v98
	v_lshlrev_b32_e32 v112, 16, v99
	v_and_b32_e32 v113, 0xffff0000, v99
	v_lshlrev_b32_e32 v114, 16, v100
	v_and_b32_e32 v115, 0xffff0000, v100
	v_lshlrev_b32_e32 v116, 16, v101
	v_and_b32_e32 v117, 0xffff0000, v101
	global_load_dwordx4 v[98:101], v0, s[16:17]
	s_add_u32 s16, s16, 0x7e00
	s_addc_u32 s17, s17, 0
	v_pk_mul_f32 v[152:153], v[22:23], v[118:119]
	v_pk_mul_f32 v[154:155], v[24:25], v[120:121]
	v_pk_mul_f32 v[156:157], v[26:27], v[122:123]
	v_pk_mul_f32 v[158:159], v[28:29], v[124:125]
	v_pk_fma_f32 v[152:153], v[30:31], v[126:127], v[152:153]
	v_pk_fma_f32 v[154:155], v[32:33], v[128:129], v[154:155]
	v_pk_fma_f32 v[156:157], v[34:35], v[130:131], v[156:157]
	v_pk_fma_f32 v[158:159], v[36:37], v[132:133], v[158:159]
	v_pk_fma_f32 v[152:153], v[38:39], v[134:135], v[152:153]
	v_pk_fma_f32 v[154:155], v[40:41], v[136:137], v[154:155]
	v_pk_fma_f32 v[156:157], v[42:43], v[138:139], v[156:157]
	v_pk_fma_f32 v[158:159], v[44:45], v[140:141], v[158:159]
	v_pk_fma_f32 v[152:153], v[46:47], v[110:111], v[152:153]
	v_pk_fma_f32 v[154:155], v[48:49], v[112:113], v[154:155]
	v_pk_fma_f32 v[156:157], v[50:51], v[114:115], v[156:157]
	v_pk_fma_f32 v[158:159], v[52:53], v[116:117], v[158:159]
	v_pk_mul_f32 v[8:9], v[152:153], s[12:13]
	v_pk_mul_f32 v[10:11], v[154:155], s[12:13]
	v_pk_mul_f32 v[12:13], v[156:157], s[12:13]
	v_pk_mul_f32 v[14:15], v[158:159], s[12:13]
	v_exp_f32_e32 v8, v8
	v_exp_f32_e32 v9, v9
	v_exp_f32_e32 v10, v10
	v_exp_f32_e32 v11, v11
	v_exp_f32_e32 v12, v12
	v_exp_f32_e32 v13, v13
	v_exp_f32_e32 v14, v14
	v_exp_f32_e32 v15, v15
	v_pk_add_f32 v[8:9], v[8:9], s[14:15]
	v_pk_add_f32 v[10:11], v[10:11], s[14:15]
	v_pk_add_f32 v[12:13], v[12:13], s[14:15]
	v_pk_add_f32 v[14:15], v[14:15], s[14:15]
	v_rcp_f32_e32 v8, v8
	v_rcp_f32_e32 v9, v9
	v_rcp_f32_e32 v10, v10
	v_rcp_f32_e32 v11, v11
	v_rcp_f32_e32 v12, v12
	v_rcp_f32_e32 v13, v13
	v_rcp_f32_e32 v14, v14
	v_rcp_f32_e32 v15, v15
	v_pk_mul_f32 v[152:153], v[152:153], v[8:9]
	v_pk_mul_f32 v[154:155], v[154:155], v[10:11]
	v_pk_mul_f32 v[156:157], v[156:157], v[12:13]
	v_pk_mul_f32 v[158:159], v[158:159], v[14:15]
	v_pk_mul_f32 v[8:9], v[152:153], v[152:153]
	v_pk_fma_f32 v[8:9], v[154:155], v[154:155], v[8:9]
	v_pk_fma_f32 v[8:9], v[156:157], v[156:157], v[8:9]
	v_pk_fma_f32 v[8:9], v[158:159], v[158:159], v[8:9]
	s_nop 0
	v_add_f32_e32 v54, v8, v9
	s_nop 1
	v_add_f32_dpp v54, v54, v54 quad_perm:[1,0,3,2] row_mask:0xf bank_mask:0xf
	s_nop 1
	v_add_f32_dpp v54, v54, v54 quad_perm:[2,3,0,1] row_mask:0xf bank_mask:0xf
	s_nop 1
	v_add_f32_dpp v54, v54, v54 row_half_mirror row_mask:0xf bank_mask:0xf
	s_nop 1
	v_add_f32_dpp v54, v54, v54 row_mirror row_mask:0xf bank_mask:0xf
	v_add_f32_e32 v54, 0x358637bd, v54
	v_rsq_f32_e32 v54, v54
	s_nop 0
	v_mul_f32_e32 v54, 0x3db504f3, v54
	v_pk_mul_f32 v[152:153], v[152:153], v[54:55] op_sel_hi:[1,0]
	v_pk_mul_f32 v[154:155], v[154:155], v[54:55] op_sel_hi:[1,0]
	v_pk_mul_f32 v[156:157], v[156:157], v[54:55] op_sel_hi:[1,0]
	v_pk_mul_f32 v[158:159], v[158:159], v[54:55] op_sel_hi:[1,0]
	v_cvt_pk_bf16_f32 v56, v152, v153
	v_cvt_pk_bf16_f32 v57, v154, v155
	v_cvt_pk_bf16_f32 v58, v156, v157
	v_cvt_pk_bf16_f32 v59, v158, v159
	global_store_dwordx4 v4, v[56:59], s[18:19]
	s_add_u32 s18, s18, 0x800
	s_addc_u32 s19, s19, 0
	s_waitcnt vmcnt(16)
; __device__ __forceinline__ unsigned pk2(float lo, float hi) { const f32v2_t v = {lo, hi}; const bf16v2_t b = __builtin_convertvector(v, bf16v2_t); return __builtin_bit_cast(unsigned, b); }
; __device__ __forceinline__ float lo16(unsigned u) { return __uint_as_float(u << 16); }
; __device__ __forceinline__ float hi16(unsigned u) { return __uint_as_float(u & 0xffff0000u); }
; __device__ __forceinline__ float siluf_(float x) { return x * __builtin_amdgcn_rcpf(1.0f + __expf(-x)); }
; __device__ __forceinline__ void prep_dn_finish(const float* cw, bf16_t* dq, bf16_t* dk, bf16_t* dv, const u32x4 (&raw)[4], int t, int ch) {
;     float a[8];
; #pragma unroll
;     for (int e = 0; e < 8; ++e) a[e] = 0.f;
; #pragma unroll
;     for (int k = 0; k < 4; ++k) {
;         const f32x4 w0 = *(const f32x4*)(cw + k * 3072 + ch), w1 = *(const f32x4*)(cw + k * 3072 + ch + 4);
;         a[0] += w0[0] * lo16(raw[k].x); a[1] += w0[1] * hi16(raw[k].x); a[2] += w0[2] * lo16(raw[k].y); a[3] += w0[3] * hi16(raw[k].y);
;         a[4] += w1[0] * lo16(raw[k].z); a[5] += w1[1] * hi16(raw[k].z); a[6] += w1[2] * lo16(raw[k].w); a[7] += w1[3] * hi16(raw[k].w); }
;     float ss = 0.f;
; #pragma unroll
;     for (int e = 0; e < 8; ++e) { a[e] = siluf_(a[e]); ss += a[e] * a[e]; }
;     ss += __shfl_xor(ss, 1); ss += __shfl_xor(ss, 2); ss += __shfl_xor(ss, 4); ss += __shfl_xor(ss, 8);
;     float sc = 1.0f;
;     if (ch < 2048) { sc = rsqrtf(ss + EPS); if (ch < 1024) sc *= 0.08838834764831845f; }
;     u32x4 w; w.x = pk2(a[0] * sc, a[1] * sc); w.y = pk2(a[2] * sc, a[3] * sc); w.z = pk2(a[4] * sc, a[5] * sc); w.w = pk2(a[6] * sc, a[7] * sc);
;     bf16_t* dst = (ch < 1024) ? dq : (ch < 2048 ? dk : dv);
;     *(u32x4*)(dst + (size_t)t * 1024 + (ch & 1023)) = w;
; }
	v_lshlrev_b32_e32 v118, 16, v102
	v_and_b32_e32 v119, 0xffff0000, v102
	v_lshlrev_b32_e32 v120, 16, v103
	v_and_b32_e32 v121, 0xffff0000, v103
	v_lshlrev_b32_e32 v122, 16, v104
	v_and_b32_e32 v123, 0xffff0000, v104
	v_lshlrev_b32_e32 v124, 16, v105
	v_and_b32_e32 v125, 0xffff0000, v105
	global_load_dwordx4 v[102:105], v0, s[16:17]
	s_add_u32 s16, s16, 0x7e00
	s_addc_u32 s17, s17, 0
	v_pk_mul_f32 v[152:153], v[22:23], v[126:127]
	v_pk_mul_f32 v[154:155], v[24:25], v[128:129]
	v_pk_mul_f32 v[156:157], v[26:27], v[130:131]
	v_pk_mul_f32 v[158:159], v[28:29], v[132:133]
	v_pk_fma_f32 v[152:153], v[30:31], v[134:135], v[152:153]
	v_pk_fma_f32 v[154:155], v[32:33], v[136:137], v[154:155]
	v_pk_fma_f32 v[156:157], v[34:35], v[138:139], v[156:157]
	v_pk_fma_f32 v[158:159], v[36:37], v[140:141], v[158:159]
	v_pk_fma_f32 v[152:153], v[38:39], v[110:111], v[152:153]
	v_pk_fma_f32 v[154:155], v[40:41], v[112:113], v[154:155]
	v_pk_fma_f32 v[156:157], v[42:43], v[114:115], v[156:157]
	v_pk_fma_f32 v[158:159], v[44:45], v[116:117], v[158:159]
	v_pk_fma_f32 v[152:153], v[46:47], v[118:119], v[152:153]
	v_pk_fma_f32 v[154:155], v[48:49], v[120:121], v[154:155]
	v_pk_fma_f32 v[156:157], v[50:51], v[122:123], v[156:157]
	v_pk_fma_f32 v[158:159], v[52:53], v[124:125], v[158:159]
	v_pk_mul_f32 v[8:9], v[152:153], s[12:13]
	v_pk_mul_f32 v[10:11], v[154:155], s[12:13]
	v_pk_mul_f32 v[12:13], v[156:157], s[12:13]
	v_pk_mul_f32 v[14:15], v[158:159], s[12:13]
	v_exp_f32_e32 v8, v8
	v_exp_f32_e32 v9, v9
	v_exp_f32_e32 v10, v10
	v_exp_f32_e32 v11, v11
	v_exp_f32_e32 v12, v12
	v_exp_f32_e32 v13, v13
	v_exp_f32_e32 v14, v14
	v_exp_f32_e32 v15, v15
	v_pk_add_f32 v[8:9], v[8:9], s[14:15]
	v_pk_add_f32 v[10:11], v[10:11], s[14:15]
	v_pk_add_f32 v[12:13], v[12:13], s[14:15]
	v_pk_add_f32 v[14:15], v[14:15], s[14:15]
	v_rcp_f32_e32 v8, v8
	v_rcp_f32_e32 v9, v9
	v_rcp_f32_e32 v10, v10
	v_rcp_f32_e32 v11, v11
	v_rcp_f32_e32 v12, v12
	v_rcp_f32_e32 v13, v13
	v_rcp_f32_e32 v14, v14
	v_rcp_f32_e32 v15, v15
	v_pk_mul_f32 v[152:153], v[152:153], v[8:9]
	v_pk_mul_f32 v[154:155], v[154:155], v[10:11]
	v_pk_mul_f32 v[156:157], v[156:157], v[12:13]
	v_pk_mul_f32 v[158:159], v[158:159], v[14:15]
	v_pk_mul_f32 v[8:9], v[152:153], v[152:153]
	v_pk_fma_f32 v[8:9], v[154:155], v[154:155], v[8:9]
	v_pk_fma_f32 v[8:9], v[156:157], v[156:157], v[8:9]
	v_pk_fma_f32 v[8:9], v[158:159], v[158:159], v[8:9]
	s_nop 0
	v_add_f32_e32 v54, v8, v9
	s_nop 1
	v_add_f32_dpp v54, v54, v54 quad_perm:[1,0,3,2] row_mask:0xf bank_mask:0xf
	s_nop 1
	v_add_f32_dpp v54, v54, v54 quad_perm:[2,3,0,1] row_mask:0xf bank_mask:0xf
	s_nop 1
	v_add_f32_dpp v54, v54, v54 row_half_mirror row_mask:0xf bank_mask:0xf
	s_nop 1
	v_add_f32_dpp v54, v54, v54 row_mirror row_mask:0xf bank_mask:0xf
	v_add_f32_e32 v54, 0x358637bd, v54
	v_rsq_f32_e32 v54, v54
	s_nop 0
	v_mul_f32_e32 v54, 0x3db504f3, v54
	v_pk_mul_f32 v[152:153], v[152:153], v[54:55] op_sel_hi:[1,0]
	v_pk_mul_f32 v[154:155], v[154:155], v[54:55] op_sel_hi:[1,0]
	v_pk_mul_f32 v[156:157], v[156:157], v[54:55] op_sel_hi:[1,0]
	v_pk_mul_f32 v[158:159], v[158:159], v[54:55] op_sel_hi:[1,0]
	v_cvt_pk_bf16_f32 v56, v152, v153
	v_cvt_pk_bf16_f32 v57, v154, v155
	v_cvt_pk_bf16_f32 v58, v156, v157
	v_cvt_pk_bf16_f32 v59, v158, v159
	global_store_dwordx4 v4, v[56:59], s[18:19]
	s_add_u32 s18, s18, 0x800
	s_addc_u32 s19, s19, 0
	s_waitcnt vmcnt(17)
	v_lshlrev_b32_e32 v126, 16, v106
	v_and_b32_e32 v127, 0xffff0000, v106
	v_lshlrev_b32_e32 v128, 16, v107
	v_and_b32_e32 v129, 0xffff0000, v107
	v_lshlrev_b32_e32 v130, 16, v108
	v_and_b32_e32 v131, 0xffff0000, v108
	v_lshlrev_b32_e32 v132, 16, v109
	v_and_b32_e32 v133, 0xffff0000, v109
	global_load_dwordx4 v[106:109], v0, s[16:17]
	s_sub_u32 s16, s16, 0x14ac00
	s_subb_u32 s17, s17, 0
	v_pk_mul_f32 v[152:153], v[22:23], v[134:135]
	v_pk_mul_f32 v[154:155], v[24:25], v[136:137]
	v_pk_mul_f32 v[156:157], v[26:27], v[138:139]
	v_pk_mul_f32 v[158:159], v[28:29], v[140:141]
	v_pk_fma_f32 v[152:153], v[30:31], v[110:111], v[152:153]
	v_pk_fma_f32 v[154:155], v[32:33], v[112:113], v[154:155]
	v_pk_fma_f32 v[156:157], v[34:35], v[114:115], v[156:157]
	v_pk_fma_f32 v[158:159], v[36:37], v[116:117], v[158:159]
	v_pk_fma_f32 v[152:153], v[38:39], v[118:119], v[152:153]
	v_pk_fma_f32 v[154:155], v[40:41], v[120:121], v[154:155]
	v_pk_fma_f32 v[156:157], v[42:43], v[122:123], v[156:157]
	v_pk_fma_f32 v[158:159], v[44:45], v[124:125], v[158:159]
	v_pk_fma_f32 v[152:153], v[46:47], v[126:127], v[152:153]
	v_pk_fma_f32 v[154:155], v[48:49], v[128:129], v[154:155]
	v_pk_fma_f32 v[156:157], v[50:51], v[130:131], v[156:157]
	v_pk_fma_f32 v[158:159], v[52:53], v[132:133], v[158:159]
	v_pk_mul_f32 v[8:9], v[152:153], s[12:13]
	v_pk_mul_f32 v[10:11], v[154:155], s[12:13]
	v_pk_mul_f32 v[12:13], v[156:157], s[12:13]
	v_pk_mul_f32 v[14:15], v[158:159], s[12:13]
	v_exp_f32_e32 v8, v8
	v_exp_f32_e32 v9, v9
	v_exp_f32_e32 v10, v10
	v_exp_f32_e32 v11, v11
	v_exp_f32_e32 v12, v12
	v_exp_f32_e32 v13, v13
	v_exp_f32_e32 v14, v14
	v_exp_f32_e32 v15, v15
	v_pk_add_f32 v[8:9], v[8:9], s[14:15]
	v_pk_add_f32 v[10:11], v[10:11], s[14:15]
	v_pk_add_f32 v[12:13], v[12:13], s[14:15]
	v_pk_add_f32 v[14:15], v[14:15], s[14:15]
	v_rcp_f32_e32 v8, v8
	v_rcp_f32_e32 v9, v9
	v_rcp_f32_e32 v10, v10
	v_rcp_f32_e32 v11, v11
	v_rcp_f32_e32 v12, v12
	v_rcp_f32_e32 v13, v13
	v_rcp_f32_e32 v14, v14
	v_rcp_f32_e32 v15, v15
	v_pk_mul_f32 v[152:153], v[152:153], v[8:9]
	v_pk_mul_f32 v[154:155], v[154:155], v[10:11]
	v_pk_mul_f32 v[156:157], v[156:157], v[12:13]
	v_pk_mul_f32 v[158:159], v[158:159], v[14:15]
	v_pk_mul_f32 v[8:9], v[152:153], v[152:153]
	v_pk_fma_f32 v[8:9], v[154:155], v[154:155], v[8:9]
	v_pk_fma_f32 v[8:9], v[156:157], v[156:157], v[8:9]
	v_pk_fma_f32 v[8:9], v[158:159], v[158:159], v[8:9]
	s_nop 0
	v_add_f32_e32 v54, v8, v9
	s_nop 1
	v_add_f32_dpp v54, v54, v54 quad_perm:[1,0,3,2] row_mask:0xf bank_mask:0xf
	s_nop 1
	v_add_f32_dpp v54, v54, v54 quad_perm:[2,3,0,1] row_mask:0xf bank_mask:0xf
	s_nop 1
	v_add_f32_dpp v54, v54, v54 row_half_mirror row_mask:0xf bank_mask:0xf
	s_nop 1
	v_add_f32_dpp v54, v54, v54 row_mirror row_mask:0xf bank_mask:0xf
	v_add_f32_e32 v54, 0x358637bd, v54
	v_rsq_f32_e32 v54, v54
	s_nop 0
	v_mul_f32_e32 v54, 0x3db504f3, v54
	v_pk_mul_f32 v[152:153], v[152:153], v[54:55] op_sel_hi:[1,0]
	v_pk_mul_f32 v[154:155], v[154:155], v[54:55] op_sel_hi:[1,0]
	v_pk_mul_f32 v[156:157], v[156:157], v[54:55] op_sel_hi:[1,0]
	v_pk_mul_f32 v[158:159], v[158:159], v[54:55] op_sel_hi:[1,0]
	v_cvt_pk_bf16_f32 v56, v152, v153
	v_cvt_pk_bf16_f32 v57, v154, v155
	v_cvt_pk_bf16_f32 v58, v156, v157
	v_cvt_pk_bf16_f32 v59, v158, v159
	global_store_dwordx4 v4, v[56:59], s[18:19]
	s_add_u32 s18, s18, 0xc800
	s_addc_u32 s19, s19, 0
	s_waitcnt vmcnt(16)
; __device__ __forceinline__ unsigned pk2(float lo, float hi) { const f32v2_t v = {lo, hi}; const bf16v2_t b = __builtin_convertvector(v, bf16v2_t); return __builtin_bit_cast(unsigned, b); }
; __device__ __forceinline__ float lo16(unsigned u) { return __uint_as_float(u << 16); }
; __device__ __forceinline__ float hi16(unsigned u) { return __uint_as_float(u & 0xffff0000u); }
; __device__ __forceinline__ float siluf_(float x) { return x * __builtin_amdgcn_rcpf(1.0f + __expf(-x)); }
; __device__ __forceinline__ void prep_dn_load(const bf16_t* proj, const float* cw, int idx, u32x4 (&raw)[4], int& t, int& ch) {
;     if (idx >= 0) { t = idx / 384; const int j = idx - t * 384; ch = j * 8; }
; #pragma unroll
;     for (int k = 0; k < 4; ++k) { const int tt = t - 3 + k; raw[k] = (u32x4){0u, 0u, 0u, 0u};
;         if (tt >= 0) raw[k] = *(const u32x4*)(proj + (size_t)tt * NP + C_DNQ + ch); }
; }
; __device__ __forceinline__ void prep_dn_finish(const float* cw, bf16_t* dq, bf16_t* dk, bf16_t* dv, const u32x4 (&raw)[4], int t, int ch) {
;     float a[8];
; #pragma unroll
;     for (int e = 0; e < 8; ++e) a[e] = 0.f;
; #pragma unroll
;     for (int k = 0; k < 4; ++k) {
;         const f32x4 w0 = *(const f32x4*)(cw + k * 3072 + ch), w1 = *(const f32x4*)(cw + k * 3072 + ch + 4);
;         a[0] += w0[0] * lo16(raw[k].x); a[1] += w0[1] * hi16(raw[k].x); a[2] += w0[2] * lo16(raw[k].y); a[3] += w0[3] * hi16(raw[k].y);
;         a[4] += w1[0] * lo16(raw[k].z); a[5] += w1[1] * hi16(raw[k].z); a[6] += w1[2] * lo16(raw[k].w); a[7] += w1[3] * hi16(raw[k].w); }
;     float ss = 0.f;
; #pragma unroll
;     for (int e = 0; e < 8; ++e) { a[e] = siluf_(a[e]); ss += a[e] * a[e]; }
;     ss += __shfl_xor(ss, 1); ss += __shfl_xor(ss, 2); ss += __shfl_xor(ss, 4); ss += __shfl_xor(ss, 8);
;     float sc = 1.0f;
;     if (ch < 2048) { sc = rsqrtf(ss + EPS); if (ch < 1024) sc *= 0.08838834764831845f; }
;     u32x4 w; w.x = pk2(a[0] * sc, a[1] * sc); w.y = pk2(a[2] * sc, a[3] * sc); w.z = pk2(a[4] * sc, a[5] * sc); w.w = pk2(a[6] * sc, a[7] * sc);
;     bf16_t* dst = (ch < 1024) ? dq : (ch < 2048 ? dk : dv);
;     *(u32x4*)(dst + (size_t)t * 1024 + (ch & 1023)) = w;
; }
	v_lshlrev_b32_e32 v110, 16, v66
	v_and_b32_e32 v111, 0xffff0000, v66
	v_lshlrev_b32_e32 v112, 16, v67
	v_and_b32_e32 v113, 0xffff0000, v67
	v_lshlrev_b32_e32 v114, 16, v68
	v_and_b32_e32 v115, 0xffff0000, v68
	v_lshlrev_b32_e32 v116, 16, v69
	v_and_b32_e32 v117, 0xffff0000, v69
	v_lshlrev_b32_e32 v118, 16, v70
	v_and_b32_e32 v119, 0xffff0000, v70
	v_lshlrev_b32_e32 v120, 16, v71
	v_and_b32_e32 v121, 0xffff0000, v71
	v_lshlrev_b32_e32 v122, 16, v72
	v_and_b32_e32 v123, 0xffff0000, v72
	v_lshlrev_b32_e32 v124, 16, v73
	v_and_b32_e32 v125, 0xffff0000, v73
	v_lshlrev_b32_e32 v126, 16, v74
	v_and_b32_e32 v127, 0xffff0000, v74
	v_lshlrev_b32_e32 v128, 16, v75
	v_and_b32_e32 v129, 0xffff0000, v75
	v_lshlrev_b32_e32 v130, 16, v76
	v_and_b32_e32 v131, 0xffff0000, v76
	v_lshlrev_b32_e32 v132, 16, v77
	v_and_b32_e32 v133, 0xffff0000, v77
	global_load_dwordx4 v[66:69], v1, s[16:17]
	s_add_u32 s16, s16, 0x7e00
	s_addc_u32 s17, s17, 0
	global_load_dwordx4 v[70:73], v1, s[16:17]
	s_add_u32 s16, s16, 0x7e00
	s_addc_u32 s17, s17, 0
	global_load_dwordx4 v[74:77], v1, s[16:17]
	s_add_u32 s16, s16, 0x7e00
	s_addc_u32 s17, s17, 0
	s_waitcnt vmcnt(18)
	v_lshlrev_b32_e32 v134, 16, v78
	v_and_b32_e32 v135, 0xffff0000, v78
	v_lshlrev_b32_e32 v136, 16, v79
	v_and_b32_e32 v137, 0xffff0000, v79
	v_lshlrev_b32_e32 v138, 16, v80
	v_and_b32_e32 v139, 0xffff0000, v80
	v_lshlrev_b32_e32 v140, 16, v81
	v_and_b32_e32 v141, 0xffff0000, v81
	global_load_dwordx4 v[78:81], v1, s[16:17]
	s_add_u32 s16, s16, 0x7e00
	s_addc_u32 s17, s17, 0
	v_pk_mul_f32 v[152:153], v[22:23], v[110:111]
	v_pk_mul_f32 v[154:155], v[24:25], v[112:113]
	v_pk_mul_f32 v[156:157], v[26:27], v[114:115]
	v_pk_mul_f32 v[158:159], v[28:29], v[116:117]
	v_pk_fma_f32 v[152:153], v[30:31], v[118:119], v[152:153]
	v_pk_fma_f32 v[154:155], v[32:33], v[120:121], v[154:155]
	v_pk_fma_f32 v[156:157], v[34:35], v[122:123], v[156:157]
	v_pk_fma_f32 v[158:159], v[36:37], v[124:125], v[158:159]
	v_pk_fma_f32 v[152:153], v[38:39], v[126:127], v[152:153]
	v_pk_fma_f32 v[154:155], v[40:41], v[128:129], v[154:155]
	v_pk_fma_f32 v[156:157], v[42:43], v[130:131], v[156:157]
	v_pk_fma_f32 v[158:159], v[44:45], v[132:133], v[158:159]
	v_pk_fma_f32 v[152:153], v[46:47], v[134:135], v[152:153]
	v_pk_fma_f32 v[154:155], v[48:49], v[136:137], v[154:155]
	v_pk_fma_f32 v[156:157], v[50:51], v[138:139], v[156:157]
	v_pk_fma_f32 v[158:159], v[52:53], v[140:141], v[158:159]
	v_pk_mul_f32 v[8:9], v[152:153], s[12:13]
	v_pk_mul_f32 v[10:11], v[154:155], s[12:13]
	v_pk_mul_f32 v[12:13], v[156:157], s[12:13]
	v_pk_mul_f32 v[14:15], v[158:159], s[12:13]
	v_exp_f32_e32 v8, v8
	v_exp_f32_e32 v9, v9
	v_exp_f32_e32 v10, v10
	v_exp_f32_e32 v11, v11
	v_exp_f32_e32 v12, v12
	v_exp_f32_e32 v13, v13
	v_exp_f32_e32 v14, v14
	v_exp_f32_e32 v15, v15
	v_pk_add_f32 v[8:9], v[8:9], s[14:15]
	v_pk_add_f32 v[10:11], v[10:11], s[14:15]
	v_pk_add_f32 v[12:13], v[12:13], s[14:15]
	v_pk_add_f32 v[14:15], v[14:15], s[14:15]
	v_rcp_f32_e32 v8, v8
	v_rcp_f32_e32 v9, v9
	v_rcp_f32_e32 v10, v10
	v_rcp_f32_e32 v11, v11
	v_rcp_f32_e32 v12, v12
	v_rcp_f32_e32 v13, v13
	v_rcp_f32_e32 v14, v14
	v_rcp_f32_e32 v15, v15
	v_pk_mul_f32 v[152:153], v[152:153], v[8:9]
	v_pk_mul_f32 v[154:155], v[154:155], v[10:11]
	v_pk_mul_f32 v[156:157], v[156:157], v[12:13]
	v_pk_mul_f32 v[158:159], v[158:159], v[14:15]
	v_pk_mul_f32 v[8:9], v[152:153], v[152:153]
	v_pk_fma_f32 v[8:9], v[154:155], v[154:155], v[8:9]
	v_pk_fma_f32 v[8:9], v[156:157], v[156:157], v[8:9]
	v_pk_fma_f32 v[8:9], v[158:159], v[158:159], v[8:9]
	s_nop 0
	v_add_f32_e32 v54, v8, v9
	s_nop 1
	v_add_f32_dpp v54, v54, v54 quad_perm:[1,0,3,2] row_mask:0xf bank_mask:0xf
	s_nop 1
	v_add_f32_dpp v54, v54, v54 quad_perm:[2,3,0,1] row_mask:0xf bank_mask:0xf
	s_nop 1
	v_add_f32_dpp v54, v54, v54 row_half_mirror row_mask:0xf bank_mask:0xf
	s_nop 1
	v_add_f32_dpp v54, v54, v54 row_mirror row_mask:0xf bank_mask:0xf
	v_add_f32_e32 v54, 0x358637bd, v54
	v_rsq_f32_e32 v54, v54
	s_nop 0
	v_mul_f32_e32 v54, 0x3db504f3, v54
	v_pk_mul_f32 v[152:153], v[152:153], v[54:55] op_sel_hi:[1,0]
	v_pk_mul_f32 v[154:155], v[154:155], v[54:55] op_sel_hi:[1,0]
	v_pk_mul_f32 v[156:157], v[156:157], v[54:55] op_sel_hi:[1,0]
	v_pk_mul_f32 v[158:159], v[158:159], v[54:55] op_sel_hi:[1,0]
	v_cvt_pk_bf16_f32 v56, v152, v153
	v_cvt_pk_bf16_f32 v57, v154, v155
	v_cvt_pk_bf16_f32 v58, v156, v157
	v_cvt_pk_bf16_f32 v59, v158, v159
	global_store_dwordx4 v4, v[56:59], s[18:19]
	s_add_u32 s18, s18, 0x800
	s_addc_u32 s19, s19, 0
	s_waitcnt vmcnt(18)
; __device__ __forceinline__ unsigned pk2(float lo, float hi) { const f32v2_t v = {lo, hi}; const bf16v2_t b = __builtin_convertvector(v, bf16v2_t); return __builtin_bit_cast(unsigned, b); }
; __device__ __forceinline__ float lo16(unsigned u) { return __uint_as_float(u << 16); }
; __device__ __forceinline__ float hi16(unsigned u) { return __uint_as_float(u & 0xffff0000u); }
; __device__ __forceinline__ float siluf_(float x) { return x * __builtin_amdgcn_rcpf(1.0f + __expf(-x)); }
; __device__ __forceinline__ void prep_dn_finish(const float* cw, bf16_t* dq, bf16_t* dk, bf16_t* dv, const u32x4 (&raw)[4], int t, int ch) {
;     float a[8];
; #pragma unroll
;     for (int e = 0; e < 8; ++e) a[e] = 0.f;
; #pragma unroll
;     for (int k = 0; k < 4; ++k) {
;         const f32x4 w0 = *(const f32x4*)(cw + k * 3072 + ch), w1 = *(const f32x4*)(cw + k * 3072 + ch + 4);
;         a[0] += w0[0] * lo16(raw[k].x); a[1] += w0[1] * hi16(raw[k].x); a[2] += w0[2] * lo16(raw[k].y); a[3] += w0[3] * hi16(raw[k].y);
;         a[4] += w1[0] * lo16(raw[k].z); a[5] += w1[1] * hi16(raw[k].z); a[6] += w1[2] * lo16(raw[k].w); a[7] += w1[3] * hi16(raw[k].w); }
;     float ss = 0.f;
; #pragma unroll
;     for (int e = 0; e < 8; ++e) { a[e] = siluf_(a[e]); ss += a[e] * a[e]; }
;     ss += __shfl_xor(ss, 1); ss += __shfl_xor(ss, 2); ss += __shfl_xor(ss, 4); ss += __shfl_xor(ss, 8);
;     float sc = 1.0f;
;     if (ch < 2048) { sc = rsqrtf(ss + EPS); if (ch < 1024) sc *= 0.08838834764831845f; }
;     u32x4 w; w.x = pk2(a[0] * sc, a[1] * sc); w.y = pk2(a[2] * sc, a[3] * sc); w.z = pk2(a[4] * sc, a[5] * sc); w.w = pk2(a[6] * sc, a[7] * sc);
;     bf16_t* dst = (ch < 1024) ? dq : (ch < 2048 ? dk : dv);
;     *(u32x4*)(dst + (size_t)t * 1024 + (ch & 1023)) = w;
; }
	v_lshlrev_b32_e32 v110, 16, v82
	v_and_b32_e32 v111, 0xffff0000, v82
	v_lshlrev_b32_e32 v112, 16, v83
	v_and_b32_e32 v113, 0xffff0000, v83
	v_lshlrev_b32_e32 v114, 16, v84
	v_and_b32_e32 v115, 0xffff0000, v84
	v_lshlrev_b32_e32 v116, 16, v85
	v_and_b32_e32 v117, 0xffff0000, v85
	global_load_dwordx4 v[82:85], v1, s[16:17]
	s_add_u32 s16, s16, 0x7e00
	s_addc_u32 s17, s17, 0
	v_pk_mul_f32 v[152:153], v[22:23], v[118:119]
	v_pk_mul_f32 v[154:155], v[24:25], v[120:121]
	v_pk_mul_f32 v[156:157], v[26:27], v[122:123]
	v_pk_mul_f32 v[158:159], v[28:29], v[124:125]
	v_pk_fma_f32 v[152:153], v[30:31], v[126:127], v[152:153]
	v_pk_fma_f32 v[154:155], v[32:33], v[128:129], v[154:155]
	v_pk_fma_f32 v[156:157], v[34:35], v[130:131], v[156:157]
	v_pk_fma_f32 v[158:159], v[36:37], v[132:133], v[158:159]
	v_pk_fma_f32 v[152:153], v[38:39], v[134:135], v[152:153]
	v_pk_fma_f32 v[154:155], v[40:41], v[136:137], v[154:155]
	v_pk_fma_f32 v[156:157], v[42:43], v[138:139], v[156:157]
	v_pk_fma_f32 v[158:159], v[44:45], v[140:141], v[158:159]
	v_pk_fma_f32 v[152:153], v[46:47], v[110:111], v[152:153]
	v_pk_fma_f32 v[154:155], v[48:49], v[112:113], v[154:155]
	v_pk_fma_f32 v[156:157], v[50:51], v[114:115], v[156:157]
	v_pk_fma_f32 v[158:159], v[52:53], v[116:117], v[158:159]
	v_pk_mul_f32 v[8:9], v[152:153], s[12:13]
	v_pk_mul_f32 v[10:11], v[154:155], s[12:13]
	v_pk_mul_f32 v[12:13], v[156:157], s[12:13]
	v_pk_mul_f32 v[14:15], v[158:159], s[12:13]
	v_exp_f32_e32 v8, v8
	v_exp_f32_e32 v9, v9
	v_exp_f32_e32 v10, v10
	v_exp_f32_e32 v11, v11
	v_exp_f32_e32 v12, v12
	v_exp_f32_e32 v13, v13
	v_exp_f32_e32 v14, v14
	v_exp_f32_e32 v15, v15
	v_pk_add_f32 v[8:9], v[8:9], s[14:15]
	v_pk_add_f32 v[10:11], v[10:11], s[14:15]
	v_pk_add_f32 v[12:13], v[12:13], s[14:15]
	v_pk_add_f32 v[14:15], v[14:15], s[14:15]
	v_rcp_f32_e32 v8, v8
	v_rcp_f32_e32 v9, v9
	v_rcp_f32_e32 v10, v10
	v_rcp_f32_e32 v11, v11
	v_rcp_f32_e32 v12, v12
	v_rcp_f32_e32 v13, v13
	v_rcp_f32_e32 v14, v14
	v_rcp_f32_e32 v15, v15
	v_pk_mul_f32 v[152:153], v[152:153], v[8:9]
	v_pk_mul_f32 v[154:155], v[154:155], v[10:11]
	v_pk_mul_f32 v[156:157], v[156:157], v[12:13]
	v_pk_mul_f32 v[158:159], v[158:159], v[14:15]
	v_pk_mul_f32 v[8:9], v[152:153], v[152:153]
	v_pk_fma_f32 v[8:9], v[154:155], v[154:155], v[8:9]
	v_pk_fma_f32 v[8:9], v[156:157], v[156:157], v[8:9]
	v_pk_fma_f32 v[8:9], v[158:159], v[158:159], v[8:9]
	s_nop 0
	v_add_f32_e32 v54, v8, v9
	s_nop 1
	v_add_f32_dpp v54, v54, v54 quad_perm:[1,0,3,2] row_mask:0xf bank_mask:0xf
	s_nop 1
	v_add_f32_dpp v54, v54, v54 quad_perm:[2,3,0,1] row_mask:0xf bank_mask:0xf
	s_nop 1
	v_add_f32_dpp v54, v54, v54 row_half_mirror row_mask:0xf bank_mask:0xf
	s_nop 1
	v_add_f32_dpp v54, v54, v54 row_mirror row_mask:0xf bank_mask:0xf
	v_add_f32_e32 v54, 0x358637bd, v54
	v_rsq_f32_e32 v54, v54
	s_nop 0
	v_mul_f32_e32 v54, 0x3db504f3, v54
	v_pk_mul_f32 v[152:153], v[152:153], v[54:55] op_sel_hi:[1,0]
	v_pk_mul_f32 v[154:155], v[154:155], v[54:55] op_sel_hi:[1,0]
	v_pk_mul_f32 v[156:157], v[156:157], v[54:55] op_sel_hi:[1,0]
	v_pk_mul_f32 v[158:159], v[158:159], v[54:55] op_sel_hi:[1,0]
	v_cvt_pk_bf16_f32 v56, v152, v153
	v_cvt_pk_bf16_f32 v57, v154, v155
	v_cvt_pk_bf16_f32 v58, v156, v157
	v_cvt_pk_bf16_f32 v59, v158, v159
	global_store_dwordx4 v4, v[56:59], s[18:19]
	s_add_u32 s18, s18, 0x800
	s_addc_u32 s19, s19, 0
	s_waitcnt vmcnt(18)
	v_lshlrev_b32_e32 v118, 16, v86
	v_and_b32_e32 v119, 0xffff0000, v86
	v_lshlrev_b32_e32 v120, 16, v87
	v_and_b32_e32 v121, 0xffff0000, v87
	v_lshlrev_b32_e32 v122, 16, v88
	v_and_b32_e32 v123, 0xffff0000, v88
	v_lshlrev_b32_e32 v124, 16, v89
	v_and_b32_e32 v125, 0xffff0000, v89
	global_load_dwordx4 v[86:89], v1, s[16:17]
	s_add_u32 s16, s16, 0x7e00
	s_addc_u32 s17, s17, 0
	v_pk_mul_f32 v[152:153], v[22:23], v[126:127]
	v_pk_mul_f32 v[154:155], v[24:25], v[128:129]
	v_pk_mul_f32 v[156:157], v[26:27], v[130:131]
	v_pk_mul_f32 v[158:159], v[28:29], v[132:133]
	v_pk_fma_f32 v[152:153], v[30:31], v[134:135], v[152:153]
	v_pk_fma_f32 v[154:155], v[32:33], v[136:137], v[154:155]
	v_pk_fma_f32 v[156:157], v[34:35], v[138:139], v[156:157]
	v_pk_fma_f32 v[158:159], v[36:37], v[140:141], v[158:159]
	v_pk_fma_f32 v[152:153], v[38:39], v[110:111], v[152:153]
	v_pk_fma_f32 v[154:155], v[40:41], v[112:113], v[154:155]
	v_pk_fma_f32 v[156:157], v[42:43], v[114:115], v[156:157]
	v_pk_fma_f32 v[158:159], v[44:45], v[116:117], v[158:159]
	v_pk_fma_f32 v[152:153], v[46:47], v[118:119], v[152:153]
	v_pk_fma_f32 v[154:155], v[48:49], v[120:121], v[154:155]
	v_pk_fma_f32 v[156:157], v[50:51], v[122:123], v[156:157]
	v_pk_fma_f32 v[158:159], v[52:53], v[124:125], v[158:159]
	v_pk_mul_f32 v[8:9], v[152:153], s[12:13]
	v_pk_mul_f32 v[10:11], v[154:155], s[12:13]
	v_pk_mul_f32 v[12:13], v[156:157], s[12:13]
	v_pk_mul_f32 v[14:15], v[158:159], s[12:13]
	v_exp_f32_e32 v8, v8
	v_exp_f32_e32 v9, v9
	v_exp_f32_e32 v10, v10
	v_exp_f32_e32 v11, v11
	v_exp_f32_e32 v12, v12
	v_exp_f32_e32 v13, v13
	v_exp_f32_e32 v14, v14
	v_exp_f32_e32 v15, v15
	v_pk_add_f32 v[8:9], v[8:9], s[14:15]
	v_pk_add_f32 v[10:11], v[10:11], s[14:15]
	v_pk_add_f32 v[12:13], v[12:13], s[14:15]
	v_pk_add_f32 v[14:15], v[14:15], s[14:15]
	v_rcp_f32_e32 v8, v8
	v_rcp_f32_e32 v9, v9
	v_rcp_f32_e32 v10, v10
	v_rcp_f32_e32 v11, v11
	v_rcp_f32_e32 v12, v12
	v_rcp_f32_e32 v13, v13
	v_rcp_f32_e32 v14, v14
	v_rcp_f32_e32 v15, v15
	v_pk_mul_f32 v[152:153], v[152:153], v[8:9]
	v_pk_mul_f32 v[154:155], v[154:155], v[10:11]
	v_pk_mul_f32 v[156:157], v[156:157], v[12:13]
	v_pk_mul_f32 v[158:159], v[158:159], v[14:15]
	v_pk_mul_f32 v[8:9], v[152:153], v[152:153]
	v_pk_fma_f32 v[8:9], v[154:155], v[154:155], v[8:9]
	v_pk_fma_f32 v[8:9], v[156:157], v[156:157], v[8:9]
	v_pk_fma_f32 v[8:9], v[158:159], v[158:159], v[8:9]
	s_nop 0
	v_add_f32_e32 v54, v8, v9
	s_nop 1
	v_add_f32_dpp v54, v54, v54 quad_perm:[1,0,3,2] row_mask:0xf bank_mask:0xf
	s_nop 1
	v_add_f32_dpp v54, v54, v54 quad_perm:[2,3,0,1] row_mask:0xf bank_mask:0xf
	s_nop 1
	v_add_f32_dpp v54, v54, v54 row_half_mirror row_mask:0xf bank_mask:0xf
	s_nop 1
	v_add_f32_dpp v54, v54, v54 row_mirror row_mask:0xf bank_mask:0xf
	v_add_f32_e32 v54, 0x358637bd, v54
	v_rsq_f32_e32 v54, v54
	s_nop 0
	v_mul_f32_e32 v54, 0x3db504f3, v54
	v_pk_mul_f32 v[152:153], v[152:153], v[54:55] op_sel_hi:[1,0]
	v_pk_mul_f32 v[154:155], v[154:155], v[54:55] op_sel_hi:[1,0]
	v_pk_mul_f32 v[156:157], v[156:157], v[54:55] op_sel_hi:[1,0]
	v_pk_mul_f32 v[158:159], v[158:159], v[54:55] op_sel_hi:[1,0]
	v_cvt_pk_bf16_f32 v56, v152, v153
	v_cvt_pk_bf16_f32 v57, v154, v155
	v_cvt_pk_bf16_f32 v58, v156, v157
	v_cvt_pk_bf16_f32 v59, v158, v159
	global_store_dwordx4 v4, v[56:59], s[18:19]
	s_add_u32 s18, s18, 0x800
	s_addc_u32 s19, s19, 0
	s_waitcnt vmcnt(18)
; __device__ __forceinline__ unsigned pk2(float lo, float hi) { const f32v2_t v = {lo, hi}; const bf16v2_t b = __builtin_convertvector(v, bf16v2_t); return __builtin_bit_cast(unsigned, b); }
; __device__ __forceinline__ float lo16(unsigned u) { return __uint_as_float(u << 16); }
; __device__ __forceinline__ float hi16(unsigned u) { return __uint_as_float(u & 0xffff0000u); }
; __device__ __forceinline__ float siluf_(float x) { return x * __builtin_amdgcn_rcpf(1.0f + __expf(-x)); }
; __device__ __forceinline__ void prep_dn_finish(const float* cw, bf16_t* dq, bf16_t* dk, bf16_t* dv, const u32x4 (&raw)[4], int t, int ch) {
;     float a[8];
; #pragma unroll
;     for (int e = 0; e < 8; ++e) a[e] = 0.f;
; #pragma unroll
;     for (int k = 0; k < 4; ++k) {
;         const f32x4 w0 = *(const f32x4*)(cw + k * 3072 + ch), w1 = *(const f32x4*)(cw + k * 3072 + ch + 4);
;         a[0] += w0[0] * lo16(raw[k].x); a[1] += w0[1] * hi16(raw[k].x); a[2] += w0[2] * lo16(raw[k].y); a[3] += w0[3] * hi16(raw[k].y);
;         a[4] += w1[0] * lo16(raw[k].z); a[5] += w1[1] * hi16(raw[k].z); a[6] += w1[2] * lo16(raw[k].w); a[7] += w1[3] * hi16(raw[k].w); }
;     float ss = 0.f;
; #pragma unroll
;     for (int e = 0; e < 8; ++e) { a[e] = siluf_(a[e]); ss += a[e] * a[e]; }
;     ss += __shfl_xor(ss, 1); ss += __shfl_xor(ss, 2); ss += __shfl_xor(ss, 4); ss += __shfl_xor(ss, 8);
;     float sc = 1.0f;
;     if (ch < 2048) { sc = rsqrtf(ss + EPS); if (ch < 1024) sc *= 0.08838834764831845f; }
;     u32x4 w; w.x = pk2(a[0] * sc, a[1] * sc); w.y = pk2(a[2] * sc, a[3] * sc); w.z = pk2(a[4] * sc, a[5] * sc); w.w = pk2(a[6] * sc, a[7] * sc);
;     bf16_t* dst = (ch < 1024) ? dq : (ch < 2048 ? dk : dv);
;     *(u32x4*)(dst + (size_t)t * 1024 + (ch & 1023)) = w;
; }
	v_lshlrev_b32_e32 v126, 16, v90
	v_and_b32_e32 v127, 0xffff0000, v90
	v_lshlrev_b32_e32 v128, 16, v91
	v_and_b32_e32 v129, 0xffff0000, v91
	v_lshlrev_b32_e32 v130, 16, v92
	v_and_b32_e32 v131, 0xffff0000, v92
	v_lshlrev_b32_e32 v132, 16, v93
	v_and_b32_e32 v133, 0xffff0000, v93
	global_load_dwordx4 v[90:93], v1, s[16:17]
	s_add_u32 s16, s16, 0x7e00
	s_addc_u32 s17, s17, 0
	v_pk_mul_f32 v[152:153], v[22:23], v[134:135]
	v_pk_mul_f32 v[154:155], v[24:25], v[136:137]
	v_pk_mul_f32 v[156:157], v[26:27], v[138:139]
	v_pk_mul_f32 v[158:159], v[28:29], v[140:141]
	v_pk_fma_f32 v[152:153], v[30:31], v[110:111], v[152:153]
	v_pk_fma_f32 v[154:155], v[32:33], v[112:113], v[154:155]
	v_pk_fma_f32 v[156:157], v[34:35], v[114:115], v[156:157]
	v_pk_fma_f32 v[158:159], v[36:37], v[116:117], v[158:159]
	v_pk_fma_f32 v[152:153], v[38:39], v[118:119], v[152:153]
	v_pk_fma_f32 v[154:155], v[40:41], v[120:121], v[154:155]
	v_pk_fma_f32 v[156:157], v[42:43], v[122:123], v[156:157]
	v_pk_fma_f32 v[158:159], v[44:45], v[124:125], v[158:159]
	v_pk_fma_f32 v[152:153], v[46:47], v[126:127], v[152:153]
	v_pk_fma_f32 v[154:155], v[48:49], v[128:129], v[154:155]
	v_pk_fma_f32 v[156:157], v[50:51], v[130:131], v[156:157]
	v_pk_fma_f32 v[158:159], v[52:53], v[132:133], v[158:159]
	v_pk_mul_f32 v[8:9], v[152:153], s[12:13]
	v_pk_mul_f32 v[10:11], v[154:155], s[12:13]
	v_pk_mul_f32 v[12:13], v[156:157], s[12:13]
	v_pk_mul_f32 v[14:15], v[158:159], s[12:13]
	v_exp_f32_e32 v8, v8
	v_exp_f32_e32 v9, v9
	v_exp_f32_e32 v10, v10
	v_exp_f32_e32 v11, v11
	v_exp_f32_e32 v12, v12
	v_exp_f32_e32 v13, v13
	v_exp_f32_e32 v14, v14
	v_exp_f32_e32 v15, v15
	v_pk_add_f32 v[8:9], v[8:9], s[14:15]
	v_pk_add_f32 v[10:11], v[10:11], s[14:15]
	v_pk_add_f32 v[12:13], v[12:13], s[14:15]
	v_pk_add_f32 v[14:15], v[14:15], s[14:15]
	v_rcp_f32_e32 v8, v8
	v_rcp_f32_e32 v9, v9
	v_rcp_f32_e32 v10, v10
	v_rcp_f32_e32 v11, v11
	v_rcp_f32_e32 v12, v12
	v_rcp_f32_e32 v13, v13
	v_rcp_f32_e32 v14, v14
	v_rcp_f32_e32 v15, v15
	v_pk_mul_f32 v[152:153], v[152:153], v[8:9]
	v_pk_mul_f32 v[154:155], v[154:155], v[10:11]
	v_pk_mul_f32 v[156:157], v[156:157], v[12:13]
	v_pk_mul_f32 v[158:159], v[158:159], v[14:15]
	v_pk_mul_f32 v[8:9], v[152:153], v[152:153]
	v_pk_fma_f32 v[8:9], v[154:155], v[154:155], v[8:9]
	v_pk_fma_f32 v[8:9], v[156:157], v[156:157], v[8:9]
	v_pk_fma_f32 v[8:9], v[158:159], v[158:159], v[8:9]
	s_nop 0
	v_add_f32_e32 v54, v8, v9
	s_nop 1
	v_add_f32_dpp v54, v54, v54 quad_perm:[1,0,3,2] row_mask:0xf bank_mask:0xf
	s_nop 1
	v_add_f32_dpp v54, v54, v54 quad_perm:[2,3,0,1] row_mask:0xf bank_mask:0xf
	s_nop 1
	v_add_f32_dpp v54, v54, v54 row_half_mirror row_mask:0xf bank_mask:0xf
	s_nop 1
	v_add_f32_dpp v54, v54, v54 row_mirror row_mask:0xf bank_mask:0xf
	v_add_f32_e32 v54, 0x358637bd, v54
	v_rsq_f32_e32 v54, v54
	s_nop 0
	v_mul_f32_e32 v54, 0x3db504f3, v54
	v_pk_mul_f32 v[152:153], v[152:153], v[54:55] op_sel_hi:[1,0]
	v_pk_mul_f32 v[154:155], v[154:155], v[54:55] op_sel_hi:[1,0]
	v_pk_mul_f32 v[156:157], v[156:157], v[54:55] op_sel_hi:[1,0]
	v_pk_mul_f32 v[158:159], v[158:159], v[54:55] op_sel_hi:[1,0]
	v_cvt_pk_bf16_f32 v56, v152, v153
	v_cvt_pk_bf16_f32 v57, v154, v155
	v_cvt_pk_bf16_f32 v58, v156, v157
	v_cvt_pk_bf16_f32 v59, v158, v159
	global_store_dwordx4 v4, v[56:59], s[18:19]
	s_add_u32 s18, s18, 0x800
	s_addc_u32 s19, s19, 0
	s_waitcnt vmcnt(18)
	v_lshlrev_b32_e32 v134, 16, v94
	v_and_b32_e32 v135, 0xffff0000, v94
	v_lshlrev_b32_e32 v136, 16, v95
	v_and_b32_e32 v137, 0xffff0000, v95
	v_lshlrev_b32_e32 v138, 16, v96
	v_and_b32_e32 v139, 0xffff0000, v96
	v_lshlrev_b32_e32 v140, 16, v97
	v_and_b32_e32 v141, 0xffff0000, v97
	global_load_dwordx4 v[94:97], v1, s[16:17]
	s_add_u32 s16, s16, 0x7e00
	s_addc_u32 s17, s17, 0
	v_pk_mul_f32 v[152:153], v[22:23], v[110:111]
	v_pk_mul_f32 v[154:155], v[24:25], v[112:113]
	v_pk_mul_f32 v[156:157], v[26:27], v[114:115]
	v_pk_mul_f32 v[158:159], v[28:29], v[116:117]
	v_pk_fma_f32 v[152:153], v[30:31], v[118:119], v[152:153]
	v_pk_fma_f32 v[154:155], v[32:33], v[120:121], v[154:155]
	v_pk_fma_f32 v[156:157], v[34:35], v[122:123], v[156:157]
	v_pk_fma_f32 v[158:159], v[36:37], v[124:125], v[158:159]
	v_pk_fma_f32 v[152:153], v[38:39], v[126:127], v[152:153]
	v_pk_fma_f32 v[154:155], v[40:41], v[128:129], v[154:155]
	v_pk_fma_f32 v[156:157], v[42:43], v[130:131], v[156:157]
	v_pk_fma_f32 v[158:159], v[44:45], v[132:133], v[158:159]
	v_pk_fma_f32 v[152:153], v[46:47], v[134:135], v[152:153]
	v_pk_fma_f32 v[154:155], v[48:49], v[136:137], v[154:155]
	v_pk_fma_f32 v[156:157], v[50:51], v[138:139], v[156:157]
	v_pk_fma_f32 v[158:159], v[52:53], v[140:141], v[158:159]
	v_pk_mul_f32 v[8:9], v[152:153], s[12:13]
	v_pk_mul_f32 v[10:11], v[154:155], s[12:13]
	v_pk_mul_f32 v[12:13], v[156:157], s[12:13]
	v_pk_mul_f32 v[14:15], v[158:159], s[12:13]
	v_exp_f32_e32 v8, v8
	v_exp_f32_e32 v9, v9
	v_exp_f32_e32 v10, v10
	v_exp_f32_e32 v11, v11
	v_exp_f32_e32 v12, v12
	v_exp_f32_e32 v13, v13
	v_exp_f32_e32 v14, v14
	v_exp_f32_e32 v15, v15
	v_pk_add_f32 v[8:9], v[8:9], s[14:15]
	v_pk_add_f32 v[10:11], v[10:11], s[14:15]
	v_pk_add_f32 v[12:13], v[12:13], s[14:15]
	v_pk_add_f32 v[14:15], v[14:15], s[14:15]
	v_rcp_f32_e32 v8, v8
	v_rcp_f32_e32 v9, v9
	v_rcp_f32_e32 v10, v10
	v_rcp_f32_e32 v11, v11
	v_rcp_f32_e32 v12, v12
	v_rcp_f32_e32 v13, v13
	v_rcp_f32_e32 v14, v14
	v_rcp_f32_e32 v15, v15
	v_pk_mul_f32 v[152:153], v[152:153], v[8:9]
	v_pk_mul_f32 v[154:155], v[154:155], v[10:11]
	v_pk_mul_f32 v[156:157], v[156:157], v[12:13]
	v_pk_mul_f32 v[158:159], v[158:159], v[14:15]
	v_pk_mul_f32 v[8:9], v[152:153], v[152:153]
	v_pk_fma_f32 v[8:9], v[154:155], v[154:155], v[8:9]
	v_pk_fma_f32 v[8:9], v[156:157], v[156:157], v[8:9]
	v_pk_fma_f32 v[8:9], v[158:159], v[158:159], v[8:9]
	s_nop 0
	v_add_f32_e32 v54, v8, v9
	s_nop 1
	v_add_f32_dpp v54, v54, v54 quad_perm:[1,0,3,2] row_mask:0xf bank_mask:0xf
	s_nop 1
	v_add_f32_dpp v54, v54, v54 quad_perm:[2,3,0,1] row_mask:0xf bank_mask:0xf
	s_nop 1
	v_add_f32_dpp v54, v54, v54 row_half_mirror row_mask:0xf bank_mask:0xf
	s_nop 1
	v_add_f32_dpp v54, v54, v54 row_mirror row_mask:0xf bank_mask:0xf
	v_add_f32_e32 v54, 0x358637bd, v54
	v_rsq_f32_e32 v54, v54
	s_nop 0
	v_mul_f32_e32 v54, 0x3db504f3, v54
	v_pk_mul_f32 v[152:153], v[152:153], v[54:55] op_sel_hi:[1,0]
	v_pk_mul_f32 v[154:155], v[154:155], v[54:55] op_sel_hi:[1,0]
	v_pk_mul_f32 v[156:157], v[156:157], v[54:55] op_sel_hi:[1,0]
	v_pk_mul_f32 v[158:159], v[158:159], v[54:55] op_sel_hi:[1,0]
	v_cvt_pk_bf16_f32 v56, v152, v153
	v_cvt_pk_bf16_f32 v57, v154, v155
	v_cvt_pk_bf16_f32 v58, v156, v157
	v_cvt_pk_bf16_f32 v59, v158, v159
	global_store_dwordx4 v4, v[56:59], s[18:19]
	s_add_u32 s18, s18, 0x800
	s_addc_u32 s19, s19, 0
	s_waitcnt vmcnt(18)
; __device__ __forceinline__ unsigned pk2(float lo, float hi) { const f32v2_t v = {lo, hi}; const bf16v2_t b = __builtin_convertvector(v, bf16v2_t); return __builtin_bit_cast(unsigned, b); }
; __device__ __forceinline__ float lo16(unsigned u) { return __uint_as_float(u << 16); }
; __device__ __forceinline__ float hi16(unsigned u) { return __uint_as_float(u & 0xffff0000u); }
; __device__ __forceinline__ float siluf_(float x) { return x * __builtin_amdgcn_rcpf(1.0f + __expf(-x)); }
; __device__ __forceinline__ void prep_dn_finish(const float* cw, bf16_t* dq, bf16_t* dk, bf16_t* dv, const u32x4 (&raw)[4], int t, int ch) {
;     float a[8];
; #pragma unroll
;     for (int e = 0; e < 8; ++e) a[e] = 0.f;
; #pragma unroll
;     for (int k = 0; k < 4; ++k) {
;         const f32x4 w0 = *(const f32x4*)(cw + k * 3072 + ch), w1 = *(const f32x4*)(cw + k * 3072 + ch + 4);
;         a[0] += w0[0] * lo16(raw[k].x); a[1] += w0[1] * hi16(raw[k].x); a[2] += w0[2] * lo16(raw[k].y); a[3] += w0[3] * hi16(raw[k].y);
;         a[4] += w1[0] * lo16(raw[k].z); a[5] += w1[1] * hi16(raw[k].z); a[6] += w1[2] * lo16(raw[k].w); a[7] += w1[3] * hi16(raw[k].w); }
;     float ss = 0.f;
; #pragma unroll
;     for (int e = 0; e < 8; ++e) { a[e] = siluf_(a[e]); ss += a[e] * a[e]; }
;     ss += __shfl_xor(ss, 1); ss += __shfl_xor(ss, 2); ss += __shfl_xor(ss, 4); ss += __shfl_xor(ss, 8);
;     float sc = 1.0f;
;     if (ch < 2048) { sc = rsqrtf(ss + EPS); if (ch < 1024) sc *= 0.08838834764831845f; }
;     u32x4 w; w.x = pk2(a[0] * sc, a[1] * sc); w.y = pk2(a[2] * sc, a[3] * sc); w.z = pk2(a[4] * sc, a[5] * sc); w.w = pk2(a[6] * sc, a[7] * sc);
;     bf16_t* dst = (ch < 1024) ? dq : (ch < 2048 ? dk : dv);
;     *(u32x4*)(dst + (size_t)t * 1024 + (ch & 1023)) = w;
; }
	v_lshlrev_b32_e32 v110, 16, v98
	v_and_b32_e32 v111, 0xffff0000, v98
	v_lshlrev_b32_e32 v112, 16, v99
	v_and_b32_e32 v113, 0xffff0000, v99
	v_lshlrev_b32_e32 v114, 16, v100
	v_and_b32_e32 v115, 0xffff0000, v100
	v_lshlrev_b32_e32 v116, 16, v101
	v_and_b32_e32 v117, 0xffff0000, v101
	global_load_dwordx4 v[98:101], v1, s[16:17]
	s_add_u32 s16, s16, 0x7e00
	s_addc_u32 s17, s17, 0
	v_pk_mul_f32 v[152:153], v[22:23], v[118:119]
	v_pk_mul_f32 v[154:155], v[24:25], v[120:121]
	v_pk_mul_f32 v[156:157], v[26:27], v[122:123]
	v_pk_mul_f32 v[158:159], v[28:29], v[124:125]
	v_pk_fma_f32 v[152:153], v[30:31], v[126:127], v[152:153]
	v_pk_fma_f32 v[154:155], v[32:33], v[128:129], v[154:155]
	v_pk_fma_f32 v[156:157], v[34:35], v[130:131], v[156:157]
	v_pk_fma_f32 v[158:159], v[36:37], v[132:133], v[158:159]
	v_pk_fma_f32 v[152:153], v[38:39], v[134:135], v[152:153]
	v_pk_fma_f32 v[154:155], v[40:41], v[136:137], v[154:155]
	v_pk_fma_f32 v[156:157], v[42:43], v[138:139], v[156:157]
	v_pk_fma_f32 v[158:159], v[44:45], v[140:141], v[158:159]
	v_pk_fma_f32 v[152:153], v[46:47], v[110:111], v[152:153]
	v_pk_fma_f32 v[154:155], v[48:49], v[112:113], v[154:155]
	v_pk_fma_f32 v[156:157], v[50:51], v[114:115], v[156:157]
	v_pk_fma_f32 v[158:159], v[52:53], v[116:117], v[158:159]
	v_pk_mul_f32 v[8:9], v[152:153], s[12:13]
	v_pk_mul_f32 v[10:11], v[154:155], s[12:13]
	v_pk_mul_f32 v[12:13], v[156:157], s[12:13]
	v_pk_mul_f32 v[14:15], v[158:159], s[12:13]
	v_exp_f32_e32 v8, v8
	v_exp_f32_e32 v9, v9
	v_exp_f32_e32 v10, v10
	v_exp_f32_e32 v11, v11
	v_exp_f32_e32 v12, v12
	v_exp_f32_e32 v13, v13
	v_exp_f32_e32 v14, v14
	v_exp_f32_e32 v15, v15
	v_pk_add_f32 v[8:9], v[8:9], s[14:15]
	v_pk_add_f32 v[10:11], v[10:11], s[14:15]
	v_pk_add_f32 v[12:13], v[12:13], s[14:15]
	v_pk_add_f32 v[14:15], v[14:15], s[14:15]
	v_rcp_f32_e32 v8, v8
	v_rcp_f32_e32 v9, v9
	v_rcp_f32_e32 v10, v10
	v_rcp_f32_e32 v11, v11
	v_rcp_f32_e32 v12, v12
	v_rcp_f32_e32 v13, v13
	v_rcp_f32_e32 v14, v14
	v_rcp_f32_e32 v15, v15
	v_pk_mul_f32 v[152:153], v[152:153], v[8:9]
	v_pk_mul_f32 v[154:155], v[154:155], v[10:11]
	v_pk_mul_f32 v[156:157], v[156:157], v[12:13]
	v_pk_mul_f32 v[158:159], v[158:159], v[14:15]
	v_pk_mul_f32 v[8:9], v[152:153], v[152:153]
	v_pk_fma_f32 v[8:9], v[154:155], v[154:155], v[8:9]
	v_pk_fma_f32 v[8:9], v[156:157], v[156:157], v[8:9]
	v_pk_fma_f32 v[8:9], v[158:159], v[158:159], v[8:9]
	s_nop 0
	v_add_f32_e32 v54, v8, v9
	s_nop 1
	v_add_f32_dpp v54, v54, v54 quad_perm:[1,0,3,2] row_mask:0xf bank_mask:0xf
	s_nop 1
	v_add_f32_dpp v54, v54, v54 quad_perm:[2,3,0,1] row_mask:0xf bank_mask:0xf
	s_nop 1
	v_add_f32_dpp v54, v54, v54 row_half_mirror row_mask:0xf bank_mask:0xf
	s_nop 1
	v_add_f32_dpp v54, v54, v54 row_mirror row_mask:0xf bank_mask:0xf
	v_add_f32_e32 v54, 0x358637bd, v54
	v_rsq_f32_e32 v54, v54
	s_nop 0
	v_mul_f32_e32 v54, 0x3db504f3, v54
	v_pk_mul_f32 v[152:153], v[152:153], v[54:55] op_sel_hi:[1,0]
	v_pk_mul_f32 v[154:155], v[154:155], v[54:55] op_sel_hi:[1,0]
	v_pk_mul_f32 v[156:157], v[156:157], v[54:55] op_sel_hi:[1,0]
	v_pk_mul_f32 v[158:159], v[158:159], v[54:55] op_sel_hi:[1,0]
	v_cvt_pk_bf16_f32 v56, v152, v153
	v_cvt_pk_bf16_f32 v57, v154, v155
	v_cvt_pk_bf16_f32 v58, v156, v157
	v_cvt_pk_bf16_f32 v59, v158, v159
	global_store_dwordx4 v4, v[56:59], s[18:19]
	s_add_u32 s18, s18, 0x800
	s_addc_u32 s19, s19, 0
	s_waitcnt vmcnt(18)
	v_lshlrev_b32_e32 v118, 16, v102
	v_and_b32_e32 v119, 0xffff0000, v102
	v_lshlrev_b32_e32 v120, 16, v103
	v_and_b32_e32 v121, 0xffff0000, v103
	v_lshlrev_b32_e32 v122, 16, v104
	v_and_b32_e32 v123, 0xffff0000, v104
	v_lshlrev_b32_e32 v124, 16, v105
	v_and_b32_e32 v125, 0xffff0000, v105
	global_load_dwordx4 v[102:105], v1, s[16:17]
	s_add_u32 s16, s16, 0x7e00
	s_addc_u32 s17, s17, 0
	v_pk_mul_f32 v[152:153], v[22:23], v[126:127]
	v_pk_mul_f32 v[154:155], v[24:25], v[128:129]
	v_pk_mul_f32 v[156:157], v[26:27], v[130:131]
	v_pk_mul_f32 v[158:159], v[28:29], v[132:133]
	v_pk_fma_f32 v[152:153], v[30:31], v[134:135], v[152:153]
	v_pk_fma_f32 v[154:155], v[32:33], v[136:137], v[154:155]
	v_pk_fma_f32 v[156:157], v[34:35], v[138:139], v[156:157]
	v_pk_fma_f32 v[158:159], v[36:37], v[140:141], v[158:159]
	v_pk_fma_f32 v[152:153], v[38:39], v[110:111], v[152:153]
	v_pk_fma_f32 v[154:155], v[40:41], v[112:113], v[154:155]
	v_pk_fma_f32 v[156:157], v[42:43], v[114:115], v[156:157]
	v_pk_fma_f32 v[158:159], v[44:45], v[116:117], v[158:159]
	v_pk_fma_f32 v[152:153], v[46:47], v[118:119], v[152:153]
	v_pk_fma_f32 v[154:155], v[48:49], v[120:121], v[154:155]
	v_pk_fma_f32 v[156:157], v[50:51], v[122:123], v[156:157]
	v_pk_fma_f32 v[158:159], v[52:53], v[124:125], v[158:159]
	v_pk_mul_f32 v[8:9], v[152:153], s[12:13]
	v_pk_mul_f32 v[10:11], v[154:155], s[12:13]
	v_pk_mul_f32 v[12:13], v[156:157], s[12:13]
	v_pk_mul_f32 v[14:15], v[158:159], s[12:13]
	v_exp_f32_e32 v8, v8
	v_exp_f32_e32 v9, v9
	v_exp_f32_e32 v10, v10
	v_exp_f32_e32 v11, v11
	v_exp_f32_e32 v12, v12
	v_exp_f32_e32 v13, v13
	v_exp_f32_e32 v14, v14
	v_exp_f32_e32 v15, v15
	v_pk_add_f32 v[8:9], v[8:9], s[14:15]
	v_pk_add_f32 v[10:11], v[10:11], s[14:15]
	v_pk_add_f32 v[12:13], v[12:13], s[14:15]
	v_pk_add_f32 v[14:15], v[14:15], s[14:15]
	v_rcp_f32_e32 v8, v8
	v_rcp_f32_e32 v9, v9
	v_rcp_f32_e32 v10, v10
	v_rcp_f32_e32 v11, v11
	v_rcp_f32_e32 v12, v12
	v_rcp_f32_e32 v13, v13
	v_rcp_f32_e32 v14, v14
	v_rcp_f32_e32 v15, v15
	v_pk_mul_f32 v[152:153], v[152:153], v[8:9]
	v_pk_mul_f32 v[154:155], v[154:155], v[10:11]
	v_pk_mul_f32 v[156:157], v[156:157], v[12:13]
	v_pk_mul_f32 v[158:159], v[158:159], v[14:15]
	v_pk_mul_f32 v[8:9], v[152:153], v[152:153]
	v_pk_fma_f32 v[8:9], v[154:155], v[154:155], v[8:9]
	v_pk_fma_f32 v[8:9], v[156:157], v[156:157], v[8:9]
	v_pk_fma_f32 v[8:9], v[158:159], v[158:159], v[8:9]
	s_nop 0
	v_add_f32_e32 v54, v8, v9
	s_nop 1
	v_add_f32_dpp v54, v54, v54 quad_perm:[1,0,3,2] row_mask:0xf bank_mask:0xf
	s_nop 1
	v_add_f32_dpp v54, v54, v54 quad_perm:[2,3,0,1] row_mask:0xf bank_mask:0xf
	s_nop 1
	v_add_f32_dpp v54, v54, v54 row_half_mirror row_mask:0xf bank_mask:0xf
	s_nop 1
	v_add_f32_dpp v54, v54, v54 row_mirror row_mask:0xf bank_mask:0xf
	v_add_f32_e32 v54, 0x358637bd, v54
	v_rsq_f32_e32 v54, v54
	s_nop 0
	v_mul_f32_e32 v54, 0x3db504f3, v54
	v_pk_mul_f32 v[152:153], v[152:153], v[54:55] op_sel_hi:[1,0]
	v_pk_mul_f32 v[154:155], v[154:155], v[54:55] op_sel_hi:[1,0]
	v_pk_mul_f32 v[156:157], v[156:157], v[54:55] op_sel_hi:[1,0]
	v_pk_mul_f32 v[158:159], v[158:159], v[54:55] op_sel_hi:[1,0]
	v_cvt_pk_bf16_f32 v56, v152, v153
	v_cvt_pk_bf16_f32 v57, v154, v155
	v_cvt_pk_bf16_f32 v58, v156, v157
	v_cvt_pk_bf16_f32 v59, v158, v159
	global_store_dwordx4 v4, v[56:59], s[18:19]
	s_add_u32 s18, s18, 0x800
	s_addc_u32 s19, s19, 0
	s_waitcnt vmcnt(18)
; __device__ __forceinline__ unsigned pk2(float lo, float hi) { const f32v2_t v = {lo, hi}; const bf16v2_t b = __builtin_convertvector(v, bf16v2_t); return __builtin_bit_cast(unsigned, b); }
; __device__ __forceinline__ float lo16(unsigned u) { return __uint_as_float(u << 16); }
; __device__ __forceinline__ float hi16(unsigned u) { return __uint_as_float(u & 0xffff0000u); }
; __device__ __forceinline__ float siluf_(float x) { return x * __builtin_amdgcn_rcpf(1.0f + __expf(-x)); }
; __device__ __forceinline__ void prep_dn_load(const bf16_t* proj, const float* cw, int idx, u32x4 (&raw)[4], int& t, int& ch) {
;     if (idx >= 0) { t = idx / 384; const int j = idx - t * 384; ch = j * 8; }
; #pragma unroll
;     for (int k = 0; k < 4; ++k) { const int tt = t - 3 + k; raw[k] = (u32x4){0u, 0u, 0u, 0u};
;         if (tt >= 0) raw[k] = *(const u32x4*)(proj + (size_t)tt * NP + C_DNQ + ch); }
; }
; __device__ __forceinline__ void prep_dn_finish(const float* cw, bf16_t* dq, bf16_t* dk, bf16_t* dv, const u32x4 (&raw)[4], int t, int ch) {
;     float a[8];
; #pragma unroll
;     for (int e = 0; e < 8; ++e) a[e] = 0.f;
; #pragma unroll
;     for (int k = 0; k < 4; ++k) {
;         const f32x4 w0 = *(const f32x4*)(cw + k * 3072 + ch), w1 = *(const f32x4*)(cw + k * 3072 + ch + 4);
;         a[0] += w0[0] * lo16(raw[k].x); a[1] += w0[1] * hi16(raw[k].x); a[2] += w0[2] * lo16(raw[k].y); a[3] += w0[3] * hi16(raw[k].y);
;         a[4] += w1[0] * lo16(raw[k].z); a[5] += w1[1] * hi16(raw[k].z); a[6] += w1[2] * lo16(raw[k].w); a[7] += w1[3] * hi16(raw[k].w); }
;     float ss = 0.f;
; #pragma unroll
;     for (int e = 0; e < 8; ++e) { a[e] = siluf_(a[e]); ss += a[e] * a[e]; }
;     ss += __shfl_xor(ss, 1); ss += __shfl_xor(ss, 2); ss += __shfl_xor(ss, 4); ss += __shfl_xor(ss, 8);
;     float sc = 1.0f;
;     if (ch < 2048) { sc = rsqrtf(ss + EPS); if (ch < 1024) sc *= 0.08838834764831845f; }
;     u32x4 w; w.x = pk2(a[0] * sc, a[1] * sc); w.y = pk2(a[2] * sc, a[3] * sc); w.z = pk2(a[4] * sc, a[5] * sc); w.w = pk2(a[6] * sc, a[7] * sc);
;     bf16_t* dst = (ch < 1024) ? dq : (ch < 2048 ? dk : dv);
;     *(u32x4*)(dst + (size_t)t * 1024 + (ch & 1023)) = w;
; }
	v_lshlrev_b32_e32 v126, 16, v106
	v_and_b32_e32 v127, 0xffff0000, v106
	v_lshlrev_b32_e32 v128, 16, v107
	v_and_b32_e32 v129, 0xffff0000, v107
	v_lshlrev_b32_e32 v130, 16, v108
	v_and_b32_e32 v131, 0xffff0000, v108
	v_lshlrev_b32_e32 v132, 16, v109
	v_and_b32_e32 v133, 0xffff0000, v109
	global_load_dwordx4 v[106:109], v1, s[16:17]
	s_add_u32 s16, s16, 0xad400
	s_addc_u32 s17, s17, 0
	v_pk_mul_f32 v[152:153], v[22:23], v[134:135]
	v_pk_mul_f32 v[154:155], v[24:25], v[136:137]
	v_pk_mul_f32 v[156:157], v[26:27], v[138:139]
	v_pk_mul_f32 v[158:159], v[28:29], v[140:141]
	v_pk_fma_f32 v[152:153], v[30:31], v[110:111], v[152:153]
	v_pk_fma_f32 v[154:155], v[32:33], v[112:113], v[154:155]
	v_pk_fma_f32 v[156:157], v[34:35], v[114:115], v[156:157]
	v_pk_fma_f32 v[158:159], v[36:37], v[116:117], v[158:159]
	v_pk_fma_f32 v[152:153], v[38:39], v[118:119], v[152:153]
	v_pk_fma_f32 v[154:155], v[40:41], v[120:121], v[154:155]
	v_pk_fma_f32 v[156:157], v[42:43], v[122:123], v[156:157]
	v_pk_fma_f32 v[158:159], v[44:45], v[124:125], v[158:159]
	v_pk_fma_f32 v[152:153], v[46:47], v[126:127], v[152:153]
	v_pk_fma_f32 v[154:155], v[48:49], v[128:129], v[154:155]
	v_pk_fma_f32 v[156:157], v[50:51], v[130:131], v[156:157]
	v_pk_fma_f32 v[158:159], v[52:53], v[132:133], v[158:159]
	v_pk_mul_f32 v[8:9], v[152:153], s[12:13]
	v_pk_mul_f32 v[10:11], v[154:155], s[12:13]
	v_pk_mul_f32 v[12:13], v[156:157], s[12:13]
	v_pk_mul_f32 v[14:15], v[158:159], s[12:13]
	v_exp_f32_e32 v8, v8
	v_exp_f32_e32 v9, v9
	v_exp_f32_e32 v10, v10
	v_exp_f32_e32 v11, v11
	v_exp_f32_e32 v12, v12
	v_exp_f32_e32 v13, v13
	v_exp_f32_e32 v14, v14
	v_exp_f32_e32 v15, v15
	v_pk_add_f32 v[8:9], v[8:9], s[14:15]
	v_pk_add_f32 v[10:11], v[10:11], s[14:15]
	v_pk_add_f32 v[12:13], v[12:13], s[14:15]
	v_pk_add_f32 v[14:15], v[14:15], s[14:15]
	v_rcp_f32_e32 v8, v8
	v_rcp_f32_e32 v9, v9
	v_rcp_f32_e32 v10, v10
	v_rcp_f32_e32 v11, v11
	v_rcp_f32_e32 v12, v12
	v_rcp_f32_e32 v13, v13
	v_rcp_f32_e32 v14, v14
	v_rcp_f32_e32 v15, v15
	v_pk_mul_f32 v[152:153], v[152:153], v[8:9]
	v_pk_mul_f32 v[154:155], v[154:155], v[10:11]
	v_pk_mul_f32 v[156:157], v[156:157], v[12:13]
	v_pk_mul_f32 v[158:159], v[158:159], v[14:15]
	v_pk_mul_f32 v[8:9], v[152:153], v[152:153]
	v_pk_fma_f32 v[8:9], v[154:155], v[154:155], v[8:9]
	v_pk_fma_f32 v[8:9], v[156:157], v[156:157], v[8:9]
	v_pk_fma_f32 v[8:9], v[158:159], v[158:159], v[8:9]
	s_nop 0
	v_add_f32_e32 v54, v8, v9
	s_nop 1
	v_add_f32_dpp v54, v54, v54 quad_perm:[1,0,3,2] row_mask:0xf bank_mask:0xf
	s_nop 1
	v_add_f32_dpp v54, v54, v54 quad_perm:[2,3,0,1] row_mask:0xf bank_mask:0xf
	s_nop 1
	v_add_f32_dpp v54, v54, v54 row_half_mirror row_mask:0xf bank_mask:0xf
	s_nop 1
	v_add_f32_dpp v54, v54, v54 row_mirror row_mask:0xf bank_mask:0xf
	v_add_f32_e32 v54, 0x358637bd, v54
	v_rsq_f32_e32 v54, v54
	s_nop 0
	v_mul_f32_e32 v54, 0x3db504f3, v54
	v_pk_mul_f32 v[152:153], v[152:153], v[54:55] op_sel_hi:[1,0]
	v_pk_mul_f32 v[154:155], v[154:155], v[54:55] op_sel_hi:[1,0]
	v_pk_mul_f32 v[156:157], v[156:157], v[54:55] op_sel_hi:[1,0]
	v_pk_mul_f32 v[158:159], v[158:159], v[54:55] op_sel_hi:[1,0]
	v_cvt_pk_bf16_f32 v56, v152, v153
	v_cvt_pk_bf16_f32 v57, v154, v155
	v_cvt_pk_bf16_f32 v58, v156, v157
	v_cvt_pk_bf16_f32 v59, v158, v159
	global_store_dwordx4 v4, v[56:59], s[18:19]
	s_sub_u32 s18, s18, 0x13800
	s_subb_u32 s19, s19, 0
	s_add_u32 vcc_lo, s4, 0x1000
	s_addc_u32 vcc_hi, s5, 0
	global_load_dwordx4 v[22:25], v3, vcc
	global_load_dwordx4 v[26:29], v3, vcc offset:16
	s_add_u32 vcc_lo, s4, 0x4000
	s_addc_u32 vcc_hi, s5, 0
	global_load_dwordx4 v[30:33], v3, vcc
	global_load_dwordx4 v[34:37], v3, vcc offset:16
	s_add_u32 vcc_lo, s4, 0x7000
	s_addc_u32 vcc_hi, s5, 0
	global_load_dwordx4 v[38:41], v3, vcc
	global_load_dwordx4 v[42:45], v3, vcc offset:16
	s_add_u32 vcc_lo, s4, 0xa000
	s_addc_u32 vcc_hi, s5, 0
	global_load_dwordx4 v[46:49], v3, vcc
	global_load_dwordx4 v[50:53], v3, vcc offset:16
	s_waitcnt vmcnt(0)
	s_cmp_lt_i32 s10, 0
	s_cbranch_scc0 .Ldnc2_nz2
	v_mov_b32_e32 v66, 0
	v_mov_b32_e32 v67, 0
	v_mov_b32_e32 v68, 0
	v_mov_b32_e32 v69, 0
	v_mov_b32_e32 v70, 0
	v_mov_b32_e32 v71, 0
	v_mov_b32_e32 v72, 0
	v_mov_b32_e32 v73, 0
	v_mov_b32_e32 v74, 0
	v_mov_b32_e32 v75, 0
	v_mov_b32_e32 v76, 0
	v_mov_b32_e32 v77, 0
; __device__ __forceinline__ unsigned pk2(float lo, float hi) { const f32v2_t v = {lo, hi}; const bf16v2_t b = __builtin_convertvector(v, bf16v2_t); return __builtin_bit_cast(unsigned, b); }
; __device__ __forceinline__ float lo16(unsigned u) { return __uint_as_float(u << 16); }
; __device__ __forceinline__ float hi16(unsigned u) { return __uint_as_float(u & 0xffff0000u); }
; __device__ __forceinline__ float siluf_(float x) { return x * __builtin_amdgcn_rcpf(1.0f + __expf(-x)); }
; __device__ __forceinline__ void prep_dn_load(const bf16_t* proj, const float* cw, int idx, u32x4 (&raw)[4], int& t, int& ch) {
;     if (idx >= 0) { t = idx / 384; const int j = idx - t * 384; ch = j * 8; }
; #pragma unroll
;     for (int k = 0; k < 4; ++k) { const int tt = t - 3 + k; raw[k] = (u32x4){0u, 0u, 0u, 0u};
;         if (tt >= 0) raw[k] = *(const u32x4*)(proj + (size_t)tt * NP + C_DNQ + ch); }
; }
; __device__ __forceinline__ void prep_dn_finish(const float* cw, bf16_t* dq, bf16_t* dk, bf16_t* dv, const u32x4 (&raw)[4], int t, int ch) {
;     float a[8];
; #pragma unroll
;     for (int e = 0; e < 8; ++e) a[e] = 0.f;
; #pragma unroll
;     for (int k = 0; k < 4; ++k) {
;         const f32x4 w0 = *(const f32x4*)(cw + k * 3072 + ch), w1 = *(const f32x4*)(cw + k * 3072 + ch + 4);
;         a[0] += w0[0] * lo16(raw[k].x); a[1] += w0[1] * hi16(raw[k].x); a[2] += w0[2] * lo16(raw[k].y); a[3] += w0[3] * hi16(raw[k].y);
;         a[4] += w1[0] * lo16(raw[k].z); a[5] += w1[1] * hi16(raw[k].z); a[6] += w1[2] * lo16(raw[k].w); a[7] += w1[3] * hi16(raw[k].w); }
;     float ss = 0.f;
; #pragma unroll
;     for (int e = 0; e < 8; ++e) { a[e] = siluf_(a[e]); ss += a[e] * a[e]; }
;     ss += __shfl_xor(ss, 1); ss += __shfl_xor(ss, 2); ss += __shfl_xor(ss, 4); ss += __shfl_xor(ss, 8);
;     float sc = 1.0f;
;     if (ch < 2048) { sc = rsqrtf(ss + EPS); if (ch < 1024) sc *= 0.08838834764831845f; }
;     u32x4 w; w.x = pk2(a[0] * sc, a[1] * sc); w.y = pk2(a[2] * sc, a[3] * sc); w.z = pk2(a[4] * sc, a[5] * sc); w.w = pk2(a[6] * sc, a[7] * sc);
;     bf16_t* dst = (ch < 1024) ? dq : (ch < 2048 ? dk : dv);
;     *(u32x4*)(dst + (size_t)t * 1024 + (ch & 1023)) = w;
; }
.Ldnc2_nz2:
	v_lshlrev_b32_e32 v110, 16, v66
	v_and_b32_e32 v111, 0xffff0000, v66
	v_lshlrev_b32_e32 v112, 16, v67
	v_and_b32_e32 v113, 0xffff0000, v67
	v_lshlrev_b32_e32 v114, 16, v68
	v_and_b32_e32 v115, 0xffff0000, v68
	v_lshlrev_b32_e32 v116, 16, v69
	v_and_b32_e32 v117, 0xffff0000, v69
	v_lshlrev_b32_e32 v118, 16, v70
	v_and_b32_e32 v119, 0xffff0000, v70
	v_lshlrev_b32_e32 v120, 16, v71
	v_and_b32_e32 v121, 0xffff0000, v71
	v_lshlrev_b32_e32 v122, 16, v72
	v_and_b32_e32 v123, 0xffff0000, v72
	v_lshlrev_b32_e32 v124, 16, v73
	v_and_b32_e32 v125, 0xffff0000, v73
	v_lshlrev_b32_e32 v126, 16, v74
	v_and_b32_e32 v127, 0xffff0000, v74
	v_lshlrev_b32_e32 v128, 16, v75
	v_and_b32_e32 v129, 0xffff0000, v75
	v_lshlrev_b32_e32 v130, 16, v76
	v_and_b32_e32 v131, 0xffff0000, v76
	v_lshlrev_b32_e32 v132, 16, v77
	v_and_b32_e32 v133, 0xffff0000, v77
	global_load_dwordx4 v[66:69], v1, s[16:17]
	s_add_u32 s16, s16, 0x7e00
	s_addc_u32 s17, s17, 0
	global_load_dwordx4 v[70:73], v1, s[16:17]
	s_add_u32 s16, s16, 0x7e00
	s_addc_u32 s17, s17, 0
	global_load_dwordx4 v[74:77], v1, s[16:17]
	s_add_u32 s16, s16, 0x7e00
	s_addc_u32 s17, s17, 0
	v_lshlrev_b32_e32 v134, 16, v78
	v_and_b32_e32 v135, 0xffff0000, v78
	v_lshlrev_b32_e32 v136, 16, v79
	v_and_b32_e32 v137, 0xffff0000, v79
	v_lshlrev_b32_e32 v138, 16, v80
	v_and_b32_e32 v139, 0xffff0000, v80
	v_lshlrev_b32_e32 v140, 16, v81
	v_and_b32_e32 v141, 0xffff0000, v81
	global_load_dwordx4 v[78:81], v1, s[16:17]
	s_add_u32 s16, s16, 0x7e00
	s_addc_u32 s17, s17, 0
	v_pk_mul_f32 v[152:153], v[22:23], v[110:111]
	v_pk_mul_f32 v[154:155], v[24:25], v[112:113]
	v_pk_mul_f32 v[156:157], v[26:27], v[114:115]
	v_pk_mul_f32 v[158:159], v[28:29], v[116:117]
	v_pk_fma_f32 v[152:153], v[30:31], v[118:119], v[152:153]
	v_pk_fma_f32 v[154:155], v[32:33], v[120:121], v[154:155]
	v_pk_fma_f32 v[156:157], v[34:35], v[122:123], v[156:157]
	v_pk_fma_f32 v[158:159], v[36:37], v[124:125], v[158:159]
	v_pk_fma_f32 v[152:153], v[38:39], v[126:127], v[152:153]
	v_pk_fma_f32 v[154:155], v[40:41], v[128:129], v[154:155]
	v_pk_fma_f32 v[156:157], v[42:43], v[130:131], v[156:157]
	v_pk_fma_f32 v[158:159], v[44:45], v[132:133], v[158:159]
	v_pk_fma_f32 v[152:153], v[46:47], v[134:135], v[152:153]
	v_pk_fma_f32 v[154:155], v[48:49], v[136:137], v[154:155]
	v_pk_fma_f32 v[156:157], v[50:51], v[138:139], v[156:157]
	v_pk_fma_f32 v[158:159], v[52:53], v[140:141], v[158:159]
	v_pk_mul_f32 v[8:9], v[152:153], s[12:13]
	v_pk_mul_f32 v[10:11], v[154:155], s[12:13]
	v_pk_mul_f32 v[12:13], v[156:157], s[12:13]
	v_pk_mul_f32 v[14:15], v[158:159], s[12:13]
	v_exp_f32_e32 v8, v8
	v_exp_f32_e32 v9, v9
	v_exp_f32_e32 v10, v10
	v_exp_f32_e32 v11, v11
	v_exp_f32_e32 v12, v12
	v_exp_f32_e32 v13, v13
	v_exp_f32_e32 v14, v14
	v_exp_f32_e32 v15, v15
	v_pk_add_f32 v[8:9], v[8:9], s[14:15]
	v_pk_add_f32 v[10:11], v[10:11], s[14:15]
	v_pk_add_f32 v[12:13], v[12:13], s[14:15]
	v_pk_add_f32 v[14:15], v[14:15], s[14:15]
	v_rcp_f32_e32 v8, v8
	v_rcp_f32_e32 v9, v9
	v_rcp_f32_e32 v10, v10
	v_rcp_f32_e32 v11, v11
	v_rcp_f32_e32 v12, v12
	v_rcp_f32_e32 v13, v13
	v_rcp_f32_e32 v14, v14
	v_rcp_f32_e32 v15, v15
	v_pk_mul_f32 v[152:153], v[152:153], v[8:9]
	v_pk_mul_f32 v[154:155], v[154:155], v[10:11]
	v_pk_mul_f32 v[156:157], v[156:157], v[12:13]
	v_pk_mul_f32 v[158:159], v[158:159], v[14:15]
	v_pk_mul_f32 v[8:9], v[152:153], v[152:153]
	v_pk_fma_f32 v[8:9], v[154:155], v[154:155], v[8:9]
	v_pk_fma_f32 v[8:9], v[156:157], v[156:157], v[8:9]
	v_pk_fma_f32 v[8:9], v[158:159], v[158:159], v[8:9]
	s_nop 0
	v_add_f32_e32 v54, v8, v9
	s_nop 1
	v_add_f32_dpp v54, v54, v54 quad_perm:[1,0,3,2] row_mask:0xf bank_mask:0xf
	s_nop 1
	v_add_f32_dpp v54, v54, v54 quad_perm:[2,3,0,1] row_mask:0xf bank_mask:0xf
	s_nop 1
	v_add_f32_dpp v54, v54, v54 row_half_mirror row_mask:0xf bank_mask:0xf
	s_nop 1
	v_add_f32_dpp v54, v54, v54 row_mirror row_mask:0xf bank_mask:0xf
	v_add_f32_e32 v54, 0x358637bd, v54
	v_rsq_f32_e32 v54, v54
	s_nop 0
	v_pk_mul_f32 v[152:153], v[152:153], v[54:55] op_sel_hi:[1,0]
	v_pk_mul_f32 v[154:155], v[154:155], v[54:55] op_sel_hi:[1,0]
	v_pk_mul_f32 v[156:157], v[156:157], v[54:55] op_sel_hi:[1,0]
	v_pk_mul_f32 v[158:159], v[158:159], v[54:55] op_sel_hi:[1,0]
	v_cvt_pk_bf16_f32 v56, v152, v153
	v_cvt_pk_bf16_f32 v57, v154, v155
	v_cvt_pk_bf16_f32 v58, v156, v157
	v_cvt_pk_bf16_f32 v59, v158, v159
	global_store_dwordx4 v5, v[56:59], s[18:19]
	s_add_u32 s18, s18, 0x800
	s_addc_u32 s19, s19, 0
	v_lshlrev_b32_e32 v110, 16, v82
	v_and_b32_e32 v111, 0xffff0000, v82
	v_lshlrev_b32_e32 v112, 16, v83
	v_and_b32_e32 v113, 0xffff0000, v83
	v_lshlrev_b32_e32 v114, 16, v84
	v_and_b32_e32 v115, 0xffff0000, v84
	v_lshlrev_b32_e32 v116, 16, v85
	v_and_b32_e32 v117, 0xffff0000, v85
	global_load_dwordx4 v[82:85], v1, s[16:17]
	s_add_u32 s16, s16, 0x7e00
	s_addc_u32 s17, s17, 0
	v_pk_mul_f32 v[152:153], v[22:23], v[118:119]
	v_pk_mul_f32 v[154:155], v[24:25], v[120:121]
	v_pk_mul_f32 v[156:157], v[26:27], v[122:123]
	v_pk_mul_f32 v[158:159], v[28:29], v[124:125]
	v_pk_fma_f32 v[152:153], v[30:31], v[126:127], v[152:153]
	v_pk_fma_f32 v[154:155], v[32:33], v[128:129], v[154:155]
	v_pk_fma_f32 v[156:157], v[34:35], v[130:131], v[156:157]
	v_pk_fma_f32 v[158:159], v[36:37], v[132:133], v[158:159]
	v_pk_fma_f32 v[152:153], v[38:39], v[134:135], v[152:153]
	v_pk_fma_f32 v[154:155], v[40:41], v[136:137], v[154:155]
	v_pk_fma_f32 v[156:157], v[42:43], v[138:139], v[156:157]
	v_pk_fma_f32 v[158:159], v[44:45], v[140:141], v[158:159]
	v_pk_fma_f32 v[152:153], v[46:47], v[110:111], v[152:153]
	v_pk_fma_f32 v[154:155], v[48:49], v[112:113], v[154:155]
	v_pk_fma_f32 v[156:157], v[50:51], v[114:115], v[156:157]
; __device__ __forceinline__ unsigned pk2(float lo, float hi) { const f32v2_t v = {lo, hi}; const bf16v2_t b = __builtin_convertvector(v, bf16v2_t); return __builtin_bit_cast(unsigned, b); }
; __device__ __forceinline__ float lo16(unsigned u) { return __uint_as_float(u << 16); }
; __device__ __forceinline__ float hi16(unsigned u) { return __uint_as_float(u & 0xffff0000u); }
; __device__ __forceinline__ float siluf_(float x) { return x * __builtin_amdgcn_rcpf(1.0f + __expf(-x)); }
; __device__ __forceinline__ void prep_dn_finish(const float* cw, bf16_t* dq, bf16_t* dk, bf16_t* dv, const u32x4 (&raw)[4], int t, int ch) {
;     float a[8];
; #pragma unroll
;     for (int e = 0; e < 8; ++e) a[e] = 0.f;
; #pragma unroll
;     for (int k = 0; k < 4; ++k) {
;         const f32x4 w0 = *(const f32x4*)(cw + k * 3072 + ch), w1 = *(const f32x4*)(cw + k * 3072 + ch + 4);
;         a[0] += w0[0] * lo16(raw[k].x); a[1] += w0[1] * hi16(raw[k].x); a[2] += w0[2] * lo16(raw[k].y); a[3] += w0[3] * hi16(raw[k].y);
;         a[4] += w1[0] * lo16(raw[k].z); a[5] += w1[1] * hi16(raw[k].z); a[6] += w1[2] * lo16(raw[k].w); a[7] += w1[3] * hi16(raw[k].w); }
;     float ss = 0.f;
; #pragma unroll
;     for (int e = 0; e < 8; ++e) { a[e] = siluf_(a[e]); ss += a[e] * a[e]; }
;     ss += __shfl_xor(ss, 1); ss += __shfl_xor(ss, 2); ss += __shfl_xor(ss, 4); ss += __shfl_xor(ss, 8);
;     float sc = 1.0f;
;     if (ch < 2048) { sc = rsqrtf(ss + EPS); if (ch < 1024) sc *= 0.08838834764831845f; }
;     u32x4 w; w.x = pk2(a[0] * sc, a[1] * sc); w.y = pk2(a[2] * sc, a[3] * sc); w.z = pk2(a[4] * sc, a[5] * sc); w.w = pk2(a[6] * sc, a[7] * sc);
;     bf16_t* dst = (ch < 1024) ? dq : (ch < 2048 ? dk : dv);
;     *(u32x4*)(dst + (size_t)t * 1024 + (ch & 1023)) = w;
; }
	v_pk_fma_f32 v[158:159], v[52:53], v[116:117], v[158:159]
	v_pk_mul_f32 v[8:9], v[152:153], s[12:13]
	v_pk_mul_f32 v[10:11], v[154:155], s[12:13]
	v_pk_mul_f32 v[12:13], v[156:157], s[12:13]
	v_pk_mul_f32 v[14:15], v[158:159], s[12:13]
	v_exp_f32_e32 v8, v8
	v_exp_f32_e32 v9, v9
	v_exp_f32_e32 v10, v10
	v_exp_f32_e32 v11, v11
	v_exp_f32_e32 v12, v12
	v_exp_f32_e32 v13, v13
	v_exp_f32_e32 v14, v14
	v_exp_f32_e32 v15, v15
	v_pk_add_f32 v[8:9], v[8:9], s[14:15]
	v_pk_add_f32 v[10:11], v[10:11], s[14:15]
	v_pk_add_f32 v[12:13], v[12:13], s[14:15]
	v_pk_add_f32 v[14:15], v[14:15], s[14:15]
	v_rcp_f32_e32 v8, v8
	v_rcp_f32_e32 v9, v9
	v_rcp_f32_e32 v10, v10
	v_rcp_f32_e32 v11, v11
	v_rcp_f32_e32 v12, v12
	v_rcp_f32_e32 v13, v13
	v_rcp_f32_e32 v14, v14
	v_rcp_f32_e32 v15, v15
	v_pk_mul_f32 v[152:153], v[152:153], v[8:9]
	v_pk_mul_f32 v[154:155], v[154:155], v[10:11]
	v_pk_mul_f32 v[156:157], v[156:157], v[12:13]
	v_pk_mul_f32 v[158:159], v[158:159], v[14:15]
	v_pk_mul_f32 v[8:9], v[152:153], v[152:153]
	v_pk_fma_f32 v[8:9], v[154:155], v[154:155], v[8:9]
	v_pk_fma_f32 v[8:9], v[156:157], v[156:157], v[8:9]
	v_pk_fma_f32 v[8:9], v[158:159], v[158:159], v[8:9]
	s_nop 0
	v_add_f32_e32 v54, v8, v9
	s_nop 1
	v_add_f32_dpp v54, v54, v54 quad_perm:[1,0,3,2] row_mask:0xf bank_mask:0xf
	s_nop 1
	v_add_f32_dpp v54, v54, v54 quad_perm:[2,3,0,1] row_mask:0xf bank_mask:0xf
	s_nop 1
	v_add_f32_dpp v54, v54, v54 row_half_mirror row_mask:0xf bank_mask:0xf
	s_nop 1
	v_add_f32_dpp v54, v54, v54 row_mirror row_mask:0xf bank_mask:0xf
	v_add_f32_e32 v54, 0x358637bd, v54
	v_rsq_f32_e32 v54, v54
	s_nop 0
	v_pk_mul_f32 v[152:153], v[152:153], v[54:55] op_sel_hi:[1,0]
	v_pk_mul_f32 v[154:155], v[154:155], v[54:55] op_sel_hi:[1,0]
	v_pk_mul_f32 v[156:157], v[156:157], v[54:55] op_sel_hi:[1,0]
	v_pk_mul_f32 v[158:159], v[158:159], v[54:55] op_sel_hi:[1,0]
	v_cvt_pk_bf16_f32 v56, v152, v153
	v_cvt_pk_bf16_f32 v57, v154, v155
	v_cvt_pk_bf16_f32 v58, v156, v157
	v_cvt_pk_bf16_f32 v59, v158, v159
	global_store_dwordx4 v5, v[56:59], s[18:19]
	s_add_u32 s18, s18, 0x800
	s_addc_u32 s19, s19, 0
	v_lshlrev_b32_e32 v118, 16, v86
	v_and_b32_e32 v119, 0xffff0000, v86
	v_lshlrev_b32_e32 v120, 16, v87
	v_and_b32_e32 v121, 0xffff0000, v87
	v_lshlrev_b32_e32 v122, 16, v88
	v_and_b32_e32 v123, 0xffff0000, v88
	v_lshlrev_b32_e32 v124, 16, v89
	v_and_b32_e32 v125, 0xffff0000, v89
	global_load_dwordx4 v[86:89], v1, s[16:17]
	s_add_u32 s16, s16, 0x7e00
	s_addc_u32 s17, s17, 0
	v_pk_mul_f32 v[152:153], v[22:23], v[126:127]
	v_pk_mul_f32 v[154:155], v[24:25], v[128:129]
	v_pk_mul_f32 v[156:157], v[26:27], v[130:131]
	v_pk_mul_f32 v[158:159], v[28:29], v[132:133]
	v_pk_fma_f32 v[152:153], v[30:31], v[134:135], v[152:153]
	v_pk_fma_f32 v[154:155], v[32:33], v[136:137], v[154:155]
	v_pk_fma_f32 v[156:157], v[34:35], v[138:139], v[156:157]
	v_pk_fma_f32 v[158:159], v[36:37], v[140:141], v[158:159]
	v_pk_fma_f32 v[152:153], v[38:39], v[110:111], v[152:153]
	v_pk_fma_f32 v[154:155], v[40:41], v[112:113], v[154:155]
	v_pk_fma_f32 v[156:157], v[42:43], v[114:115], v[156:157]
	v_pk_fma_f32 v[158:159], v[44:45], v[116:117], v[158:159]
	v_pk_fma_f32 v[152:153], v[46:47], v[118:119], v[152:153]
	v_pk_fma_f32 v[154:155], v[48:49], v[120:121], v[154:155]
	v_pk_fma_f32 v[156:157], v[50:51], v[122:123], v[156:157]
	v_pk_fma_f32 v[158:159], v[52:53], v[124:125], v[158:159]
	v_pk_mul_f32 v[8:9], v[152:153], s[12:13]
	v_pk_mul_f32 v[10:11], v[154:155], s[12:13]
	v_pk_mul_f32 v[12:13], v[156:157], s[12:13]
	v_pk_mul_f32 v[14:15], v[158:159], s[12:13]
	v_exp_f32_e32 v8, v8
	v_exp_f32_e32 v9, v9
	v_exp_f32_e32 v10, v10
	v_exp_f32_e32 v11, v11
	v_exp_f32_e32 v12, v12
	v_exp_f32_e32 v13, v13
	v_exp_f32_e32 v14, v14
	v_exp_f32_e32 v15, v15
	v_pk_add_f32 v[8:9], v[8:9], s[14:15]
	v_pk_add_f32 v[10:11], v[10:11], s[14:15]
	v_pk_add_f32 v[12:13], v[12:13], s[14:15]
	v_pk_add_f32 v[14:15], v[14:15], s[14:15]
	v_rcp_f32_e32 v8, v8
	v_rcp_f32_e32 v9, v9
	v_rcp_f32_e32 v10, v10
	v_rcp_f32_e32 v11, v11
	v_rcp_f32_e32 v12, v12
	v_rcp_f32_e32 v13, v13
	v_rcp_f32_e32 v14, v14
	v_rcp_f32_e32 v15, v15
	v_pk_mul_f32 v[152:153], v[152:153], v[8:9]
	v_pk_mul_f32 v[154:155], v[154:155], v[10:11]
	v_pk_mul_f32 v[156:157], v[156:157], v[12:13]
	v_pk_mul_f32 v[158:159], v[158:159], v[14:15]
	v_pk_mul_f32 v[8:9], v[152:153], v[152:153]
	v_pk_fma_f32 v[8:9], v[154:155], v[154:155], v[8:9]
	v_pk_fma_f32 v[8:9], v[156:157], v[156:157], v[8:9]
	v_pk_fma_f32 v[8:9], v[158:159], v[158:159], v[8:9]
	s_nop 0
	v_add_f32_e32 v54, v8, v9
	s_nop 1
	v_add_f32_dpp v54, v54, v54 quad_perm:[1,0,3,2] row_mask:0xf bank_mask:0xf
	s_nop 1
	v_add_f32_dpp v54, v54, v54 quad_perm:[2,3,0,1] row_mask:0xf bank_mask:0xf
	s_nop 1
	v_add_f32_dpp v54, v54, v54 row_half_mirror row_mask:0xf bank_mask:0xf
	s_nop 1
	v_add_f32_dpp v54, v54, v54 row_mirror row_mask:0xf bank_mask:0xf
	v_add_f32_e32 v54, 0x358637bd, v54
	v_rsq_f32_e32 v54, v54
	s_nop 0
	v_pk_mul_f32 v[152:153], v[152:153], v[54:55] op_sel_hi:[1,0]
	v_pk_mul_f32 v[154:155], v[154:155], v[54:55] op_sel_hi:[1,0]
	v_pk_mul_f32 v[156:157], v[156:157], v[54:55] op_sel_hi:[1,0]
	v_pk_mul_f32 v[158:159], v[158:159], v[54:55] op_sel_hi:[1,0]
	v_cvt_pk_bf16_f32 v56, v152, v153
	v_cvt_pk_bf16_f32 v57, v154, v155
	v_cvt_pk_bf16_f32 v58, v156, v157
	v_cvt_pk_bf16_f32 v59, v158, v159
	global_store_dwordx4 v5, v[56:59], s[18:19]
	s_add_u32 s18, s18, 0x800
	s_addc_u32 s19, s19, 0
	v_lshlrev_b32_e32 v126, 16, v90
	v_and_b32_e32 v127, 0xffff0000, v90
	v_lshlrev_b32_e32 v128, 16, v91
	v_and_b32_e32 v129, 0xffff0000, v91
	v_lshlrev_b32_e32 v130, 16, v92
	v_and_b32_e32 v131, 0xffff0000, v92
	v_lshlrev_b32_e32 v132, 16, v93
; __device__ __forceinline__ unsigned pk2(float lo, float hi) { const f32v2_t v = {lo, hi}; const bf16v2_t b = __builtin_convertvector(v, bf16v2_t); return __builtin_bit_cast(unsigned, b); }
; __device__ __forceinline__ float lo16(unsigned u) { return __uint_as_float(u << 16); }
; __device__ __forceinline__ float hi16(unsigned u) { return __uint_as_float(u & 0xffff0000u); }
; __device__ __forceinline__ float siluf_(float x) { return x * __builtin_amdgcn_rcpf(1.0f + __expf(-x)); }
; __device__ __forceinline__ void prep_dn_finish(const float* cw, bf16_t* dq, bf16_t* dk, bf16_t* dv, const u32x4 (&raw)[4], int t, int ch) {
;     float a[8];
; #pragma unroll
;     for (int e = 0; e < 8; ++e) a[e] = 0.f;
; #pragma unroll
;     for (int k = 0; k < 4; ++k) {
;         const f32x4 w0 = *(const f32x4*)(cw + k * 3072 + ch), w1 = *(const f32x4*)(cw + k * 3072 + ch + 4);
;         a[0] += w0[0] * lo16(raw[k].x); a[1] += w0[1] * hi16(raw[k].x); a[2] += w0[2] * lo16(raw[k].y); a[3] += w0[3] * hi16(raw[k].y);
;         a[4] += w1[0] * lo16(raw[k].z); a[5] += w1[1] * hi16(raw[k].z); a[6] += w1[2] * lo16(raw[k].w); a[7] += w1[3] * hi16(raw[k].w); }
;     float ss = 0.f;
; #pragma unroll
;     for (int e = 0; e < 8; ++e) { a[e] = siluf_(a[e]); ss += a[e] * a[e]; }
;     ss += __shfl_xor(ss, 1); ss += __shfl_xor(ss, 2); ss += __shfl_xor(ss, 4); ss += __shfl_xor(ss, 8);
;     float sc = 1.0f;
;     if (ch < 2048) { sc = rsqrtf(ss + EPS); if (ch < 1024) sc *= 0.08838834764831845f; }
;     u32x4 w; w.x = pk2(a[0] * sc, a[1] * sc); w.y = pk2(a[2] * sc, a[3] * sc); w.z = pk2(a[4] * sc, a[5] * sc); w.w = pk2(a[6] * sc, a[7] * sc);
;     bf16_t* dst = (ch < 1024) ? dq : (ch < 2048 ? dk : dv);
;     *(u32x4*)(dst + (size_t)t * 1024 + (ch & 1023)) = w;
; }
	v_and_b32_e32 v133, 0xffff0000, v93
	global_load_dwordx4 v[90:93], v1, s[16:17]
	s_add_u32 s16, s16, 0x7e00
	s_addc_u32 s17, s17, 0
	v_pk_mul_f32 v[152:153], v[22:23], v[134:135]
	v_pk_mul_f32 v[154:155], v[24:25], v[136:137]
	v_pk_mul_f32 v[156:157], v[26:27], v[138:139]
	v_pk_mul_f32 v[158:159], v[28:29], v[140:141]
	v_pk_fma_f32 v[152:153], v[30:31], v[110:111], v[152:153]
	v_pk_fma_f32 v[154:155], v[32:33], v[112:113], v[154:155]
	v_pk_fma_f32 v[156:157], v[34:35], v[114:115], v[156:157]
	v_pk_fma_f32 v[158:159], v[36:37], v[116:117], v[158:159]
	v_pk_fma_f32 v[152:153], v[38:39], v[118:119], v[152:153]
	v_pk_fma_f32 v[154:155], v[40:41], v[120:121], v[154:155]
	v_pk_fma_f32 v[156:157], v[42:43], v[122:123], v[156:157]
	v_pk_fma_f32 v[158:159], v[44:45], v[124:125], v[158:159]
	v_pk_fma_f32 v[152:153], v[46:47], v[126:127], v[152:153]
	v_pk_fma_f32 v[154:155], v[48:49], v[128:129], v[154:155]
	v_pk_fma_f32 v[156:157], v[50:51], v[130:131], v[156:157]
	v_pk_fma_f32 v[158:159], v[52:53], v[132:133], v[158:159]
	v_pk_mul_f32 v[8:9], v[152:153], s[12:13]
	v_pk_mul_f32 v[10:11], v[154:155], s[12:13]
	v_pk_mul_f32 v[12:13], v[156:157], s[12:13]
	v_pk_mul_f32 v[14:15], v[158:159], s[12:13]
	v_exp_f32_e32 v8, v8
	v_exp_f32_e32 v9, v9
	v_exp_f32_e32 v10, v10
	v_exp_f32_e32 v11, v11
	v_exp_f32_e32 v12, v12
	v_exp_f32_e32 v13, v13
	v_exp_f32_e32 v14, v14
	v_exp_f32_e32 v15, v15
	v_pk_add_f32 v[8:9], v[8:9], s[14:15]
	v_pk_add_f32 v[10:11], v[10:11], s[14:15]
	v_pk_add_f32 v[12:13], v[12:13], s[14:15]
	v_pk_add_f32 v[14:15], v[14:15], s[14:15]
	v_rcp_f32_e32 v8, v8
	v_rcp_f32_e32 v9, v9
	v_rcp_f32_e32 v10, v10
	v_rcp_f32_e32 v11, v11
	v_rcp_f32_e32 v12, v12
	v_rcp_f32_e32 v13, v13
	v_rcp_f32_e32 v14, v14
	v_rcp_f32_e32 v15, v15
	v_pk_mul_f32 v[152:153], v[152:153], v[8:9]
	v_pk_mul_f32 v[154:155], v[154:155], v[10:11]
	v_pk_mul_f32 v[156:157], v[156:157], v[12:13]
	v_pk_mul_f32 v[158:159], v[158:159], v[14:15]
	v_pk_mul_f32 v[8:9], v[152:153], v[152:153]
	v_pk_fma_f32 v[8:9], v[154:155], v[154:155], v[8:9]
	v_pk_fma_f32 v[8:9], v[156:157], v[156:157], v[8:9]
	v_pk_fma_f32 v[8:9], v[158:159], v[158:159], v[8:9]
	s_nop 0
	v_add_f32_e32 v54, v8, v9
	s_nop 1
	v_add_f32_dpp v54, v54, v54 quad_perm:[1,0,3,2] row_mask:0xf bank_mask:0xf
	s_nop 1
	v_add_f32_dpp v54, v54, v54 quad_perm:[2,3,0,1] row_mask:0xf bank_mask:0xf
	s_nop 1
	v_add_f32_dpp v54, v54, v54 row_half_mirror row_mask:0xf bank_mask:0xf
	s_nop 1
	v_add_f32_dpp v54, v54, v54 row_mirror row_mask:0xf bank_mask:0xf
	v_add_f32_e32 v54, 0x358637bd, v54
	v_rsq_f32_e32 v54, v54
	s_nop 0
	v_pk_mul_f32 v[152:153], v[152:153], v[54:55] op_sel_hi:[1,0]
	v_pk_mul_f32 v[154:155], v[154:155], v[54:55] op_sel_hi:[1,0]
	v_pk_mul_f32 v[156:157], v[156:157], v[54:55] op_sel_hi:[1,0]
	v_pk_mul_f32 v[158:159], v[158:159], v[54:55] op_sel_hi:[1,0]
	v_cvt_pk_bf16_f32 v56, v152, v153
	v_cvt_pk_bf16_f32 v57, v154, v155
	v_cvt_pk_bf16_f32 v58, v156, v157
	v_cvt_pk_bf16_f32 v59, v158, v159
	global_store_dwordx4 v5, v[56:59], s[18:19]
	s_add_u32 s18, s18, 0x800
	s_addc_u32 s19, s19, 0
	v_lshlrev_b32_e32 v134, 16, v94
	v_and_b32_e32 v135, 0xffff0000, v94
	v_lshlrev_b32_e32 v136, 16, v95
	v_and_b32_e32 v137, 0xffff0000, v95
	v_lshlrev_b32_e32 v138, 16, v96
	v_and_b32_e32 v139, 0xffff0000, v96
	v_lshlrev_b32_e32 v140, 16, v97
	v_and_b32_e32 v141, 0xffff0000, v97
	global_load_dwordx4 v[94:97], v1, s[16:17]
	s_add_u32 s16, s16, 0x7e00
	s_addc_u32 s17, s17, 0
	v_pk_mul_f32 v[152:153], v[22:23], v[110:111]
	v_pk_mul_f32 v[154:155], v[24:25], v[112:113]
	v_pk_mul_f32 v[156:157], v[26:27], v[114:115]
	v_pk_mul_f32 v[158:159], v[28:29], v[116:117]
	v_pk_fma_f32 v[152:153], v[30:31], v[118:119], v[152:153]
	v_pk_fma_f32 v[154:155], v[32:33], v[120:121], v[154:155]
	v_pk_fma_f32 v[156:157], v[34:35], v[122:123], v[156:157]
	v_pk_fma_f32 v[158:159], v[36:37], v[124:125], v[158:159]
	v_pk_fma_f32 v[152:153], v[38:39], v[126:127], v[152:153]
	v_pk_fma_f32 v[154:155], v[40:41], v[128:129], v[154:155]
	v_pk_fma_f32 v[156:157], v[42:43], v[130:131], v[156:157]
	v_pk_fma_f32 v[158:159], v[44:45], v[132:133], v[158:159]
	v_pk_fma_f32 v[152:153], v[46:47], v[134:135], v[152:153]
	v_pk_fma_f32 v[154:155], v[48:49], v[136:137], v[154:155]
	v_pk_fma_f32 v[156:157], v[50:51], v[138:139], v[156:157]
	v_pk_fma_f32 v[158:159], v[52:53], v[140:141], v[158:159]
	v_pk_mul_f32 v[8:9], v[152:153], s[12:13]
	v_pk_mul_f32 v[10:11], v[154:155], s[12:13]
	v_pk_mul_f32 v[12:13], v[156:157], s[12:13]
	v_pk_mul_f32 v[14:15], v[158:159], s[12:13]
	v_exp_f32_e32 v8, v8
	v_exp_f32_e32 v9, v9
	v_exp_f32_e32 v10, v10
	v_exp_f32_e32 v11, v11
	v_exp_f32_e32 v12, v12
	v_exp_f32_e32 v13, v13
	v_exp_f32_e32 v14, v14
	v_exp_f32_e32 v15, v15
	v_pk_add_f32 v[8:9], v[8:9], s[14:15]
	v_pk_add_f32 v[10:11], v[10:11], s[14:15]
	v_pk_add_f32 v[12:13], v[12:13], s[14:15]
	v_pk_add_f32 v[14:15], v[14:15], s[14:15]
	v_rcp_f32_e32 v8, v8
	v_rcp_f32_e32 v9, v9
	v_rcp_f32_e32 v10, v10
	v_rcp_f32_e32 v11, v11
	v_rcp_f32_e32 v12, v12
	v_rcp_f32_e32 v13, v13
	v_rcp_f32_e32 v14, v14
	v_rcp_f32_e32 v15, v15
	v_pk_mul_f32 v[152:153], v[152:153], v[8:9]
	v_pk_mul_f32 v[154:155], v[154:155], v[10:11]
	v_pk_mul_f32 v[156:157], v[156:157], v[12:13]
	v_pk_mul_f32 v[158:159], v[158:159], v[14:15]
	v_pk_mul_f32 v[8:9], v[152:153], v[152:153]
	v_pk_fma_f32 v[8:9], v[154:155], v[154:155], v[8:9]
	v_pk_fma_f32 v[8:9], v[156:157], v[156:157], v[8:9]
	v_pk_fma_f32 v[8:9], v[158:159], v[158:159], v[8:9]
	s_nop 0
	v_add_f32_e32 v54, v8, v9
	s_nop 1
	v_add_f32_dpp v54, v54, v54 quad_perm:[1,0,3,2] row_mask:0xf bank_mask:0xf
	s_nop 1
	v_add_f32_dpp v54, v54, v54 quad_perm:[2,3,0,1] row_mask:0xf bank_mask:0xf
; __device__ __forceinline__ unsigned pk2(float lo, float hi) { const f32v2_t v = {lo, hi}; const bf16v2_t b = __builtin_convertvector(v, bf16v2_t); return __builtin_bit_cast(unsigned, b); }
; __device__ __forceinline__ float lo16(unsigned u) { return __uint_as_float(u << 16); }
; __device__ __forceinline__ float hi16(unsigned u) { return __uint_as_float(u & 0xffff0000u); }
; __device__ __forceinline__ float siluf_(float x) { return x * __builtin_amdgcn_rcpf(1.0f + __expf(-x)); }
; __device__ __forceinline__ void prep_dn_finish(const float* cw, bf16_t* dq, bf16_t* dk, bf16_t* dv, const u32x4 (&raw)[4], int t, int ch) {
;     float a[8];
; #pragma unroll
;     for (int e = 0; e < 8; ++e) a[e] = 0.f;
; #pragma unroll
;     for (int k = 0; k < 4; ++k) {
;         const f32x4 w0 = *(const f32x4*)(cw + k * 3072 + ch), w1 = *(const f32x4*)(cw + k * 3072 + ch + 4);
;         a[0] += w0[0] * lo16(raw[k].x); a[1] += w0[1] * hi16(raw[k].x); a[2] += w0[2] * lo16(raw[k].y); a[3] += w0[3] * hi16(raw[k].y);
;         a[4] += w1[0] * lo16(raw[k].z); a[5] += w1[1] * hi16(raw[k].z); a[6] += w1[2] * lo16(raw[k].w); a[7] += w1[3] * hi16(raw[k].w); }
;     float ss = 0.f;
; #pragma unroll
;     for (int e = 0; e < 8; ++e) { a[e] = siluf_(a[e]); ss += a[e] * a[e]; }
;     ss += __shfl_xor(ss, 1); ss += __shfl_xor(ss, 2); ss += __shfl_xor(ss, 4); ss += __shfl_xor(ss, 8);
;     float sc = 1.0f;
;     if (ch < 2048) { sc = rsqrtf(ss + EPS); if (ch < 1024) sc *= 0.08838834764831845f; }
;     u32x4 w; w.x = pk2(a[0] * sc, a[1] * sc); w.y = pk2(a[2] * sc, a[3] * sc); w.z = pk2(a[4] * sc, a[5] * sc); w.w = pk2(a[6] * sc, a[7] * sc);
;     bf16_t* dst = (ch < 1024) ? dq : (ch < 2048 ? dk : dv);
;     *(u32x4*)(dst + (size_t)t * 1024 + (ch & 1023)) = w;
; }
	s_nop 1
	v_add_f32_dpp v54, v54, v54 row_half_mirror row_mask:0xf bank_mask:0xf
	s_nop 1
	v_add_f32_dpp v54, v54, v54 row_mirror row_mask:0xf bank_mask:0xf
	v_add_f32_e32 v54, 0x358637bd, v54
	v_rsq_f32_e32 v54, v54
	s_nop 0
	v_pk_mul_f32 v[152:153], v[152:153], v[54:55] op_sel_hi:[1,0]
	v_pk_mul_f32 v[154:155], v[154:155], v[54:55] op_sel_hi:[1,0]
	v_pk_mul_f32 v[156:157], v[156:157], v[54:55] op_sel_hi:[1,0]
	v_pk_mul_f32 v[158:159], v[158:159], v[54:55] op_sel_hi:[1,0]
	v_cvt_pk_bf16_f32 v56, v152, v153
	v_cvt_pk_bf16_f32 v57, v154, v155
	v_cvt_pk_bf16_f32 v58, v156, v157
	v_cvt_pk_bf16_f32 v59, v158, v159
	global_store_dwordx4 v5, v[56:59], s[18:19]
	s_add_u32 s18, s18, 0x800
	s_addc_u32 s19, s19, 0
	v_lshlrev_b32_e32 v110, 16, v98
	v_and_b32_e32 v111, 0xffff0000, v98
	v_lshlrev_b32_e32 v112, 16, v99
	v_and_b32_e32 v113, 0xffff0000, v99
	v_lshlrev_b32_e32 v114, 16, v100
	v_and_b32_e32 v115, 0xffff0000, v100
	v_lshlrev_b32_e32 v116, 16, v101
	v_and_b32_e32 v117, 0xffff0000, v101
	global_load_dwordx4 v[98:101], v1, s[16:17]
	s_add_u32 s16, s16, 0x7e00
	s_addc_u32 s17, s17, 0
	v_pk_mul_f32 v[152:153], v[22:23], v[118:119]
	v_pk_mul_f32 v[154:155], v[24:25], v[120:121]
	v_pk_mul_f32 v[156:157], v[26:27], v[122:123]
	v_pk_mul_f32 v[158:159], v[28:29], v[124:125]
	v_pk_fma_f32 v[152:153], v[30:31], v[126:127], v[152:153]
	v_pk_fma_f32 v[154:155], v[32:33], v[128:129], v[154:155]
	v_pk_fma_f32 v[156:157], v[34:35], v[130:131], v[156:157]
	v_pk_fma_f32 v[158:159], v[36:37], v[132:133], v[158:159]
	v_pk_fma_f32 v[152:153], v[38:39], v[134:135], v[152:153]
	v_pk_fma_f32 v[154:155], v[40:41], v[136:137], v[154:155]
	v_pk_fma_f32 v[156:157], v[42:43], v[138:139], v[156:157]
	v_pk_fma_f32 v[158:159], v[44:45], v[140:141], v[158:159]
	v_pk_fma_f32 v[152:153], v[46:47], v[110:111], v[152:153]
	v_pk_fma_f32 v[154:155], v[48:49], v[112:113], v[154:155]
	v_pk_fma_f32 v[156:157], v[50:51], v[114:115], v[156:157]
	v_pk_fma_f32 v[158:159], v[52:53], v[116:117], v[158:159]
	v_pk_mul_f32 v[8:9], v[152:153], s[12:13]
	v_pk_mul_f32 v[10:11], v[154:155], s[12:13]
	v_pk_mul_f32 v[12:13], v[156:157], s[12:13]
	v_pk_mul_f32 v[14:15], v[158:159], s[12:13]
	v_exp_f32_e32 v8, v8
	v_exp_f32_e32 v9, v9
	v_exp_f32_e32 v10, v10
	v_exp_f32_e32 v11, v11
	v_exp_f32_e32 v12, v12
	v_exp_f32_e32 v13, v13
	v_exp_f32_e32 v14, v14
	v_exp_f32_e32 v15, v15
	v_pk_add_f32 v[8:9], v[8:9], s[14:15]
	v_pk_add_f32 v[10:11], v[10:11], s[14:15]
	v_pk_add_f32 v[12:13], v[12:13], s[14:15]
	v_pk_add_f32 v[14:15], v[14:15], s[14:15]
	v_rcp_f32_e32 v8, v8
	v_rcp_f32_e32 v9, v9
	v_rcp_f32_e32 v10, v10
	v_rcp_f32_e32 v11, v11
	v_rcp_f32_e32 v12, v12
	v_rcp_f32_e32 v13, v13
	v_rcp_f32_e32 v14, v14
	v_rcp_f32_e32 v15, v15
	v_pk_mul_f32 v[152:153], v[152:153], v[8:9]
	v_pk_mul_f32 v[154:155], v[154:155], v[10:11]
	v_pk_mul_f32 v[156:157], v[156:157], v[12:13]
	v_pk_mul_f32 v[158:159], v[158:159], v[14:15]
	v_pk_mul_f32 v[8:9], v[152:153], v[152:153]
	v_pk_fma_f32 v[8:9], v[154:155], v[154:155], v[8:9]
	v_pk_fma_f32 v[8:9], v[156:157], v[156:157], v[8:9]
	v_pk_fma_f32 v[8:9], v[158:159], v[158:159], v[8:9]
	s_nop 0
	v_add_f32_e32 v54, v8, v9
	s_nop 1
	v_add_f32_dpp v54, v54, v54 quad_perm:[1,0,3,2] row_mask:0xf bank_mask:0xf
	s_nop 1
	v_add_f32_dpp v54, v54, v54 quad_perm:[2,3,0,1] row_mask:0xf bank_mask:0xf
	s_nop 1
	v_add_f32_dpp v54, v54, v54 row_half_mirror row_mask:0xf bank_mask:0xf
	s_nop 1
	v_add_f32_dpp v54, v54, v54 row_mirror row_mask:0xf bank_mask:0xf
	v_add_f32_e32 v54, 0x358637bd, v54
	v_rsq_f32_e32 v54, v54
	s_nop 0
	v_pk_mul_f32 v[152:153], v[152:153], v[54:55] op_sel_hi:[1,0]
	v_pk_mul_f32 v[154:155], v[154:155], v[54:55] op_sel_hi:[1,0]
	v_pk_mul_f32 v[156:157], v[156:157], v[54:55] op_sel_hi:[1,0]
	v_pk_mul_f32 v[158:159], v[158:159], v[54:55] op_sel_hi:[1,0]
	v_cvt_pk_bf16_f32 v56, v152, v153
	v_cvt_pk_bf16_f32 v57, v154, v155
	v_cvt_pk_bf16_f32 v58, v156, v157
	v_cvt_pk_bf16_f32 v59, v158, v159
	global_store_dwordx4 v5, v[56:59], s[18:19]
	s_add_u32 s18, s18, 0x800
	s_addc_u32 s19, s19, 0
	v_lshlrev_b32_e32 v118, 16, v102
	v_and_b32_e32 v119, 0xffff0000, v102
	v_lshlrev_b32_e32 v120, 16, v103
	v_and_b32_e32 v121, 0xffff0000, v103
	v_lshlrev_b32_e32 v122, 16, v104
	v_and_b32_e32 v123, 0xffff0000, v104
	v_lshlrev_b32_e32 v124, 16, v105
	v_and_b32_e32 v125, 0xffff0000, v105
	global_load_dwordx4 v[102:105], v1, s[16:17]
	s_add_u32 s16, s16, 0x7e00
	s_addc_u32 s17, s17, 0
	v_pk_mul_f32 v[152:153], v[22:23], v[126:127]
	v_pk_mul_f32 v[154:155], v[24:25], v[128:129]
	v_pk_mul_f32 v[156:157], v[26:27], v[130:131]
	v_pk_mul_f32 v[158:159], v[28:29], v[132:133]
	v_pk_fma_f32 v[152:153], v[30:31], v[134:135], v[152:153]
	v_pk_fma_f32 v[154:155], v[32:33], v[136:137], v[154:155]
	v_pk_fma_f32 v[156:157], v[34:35], v[138:139], v[156:157]
	v_pk_fma_f32 v[158:159], v[36:37], v[140:141], v[158:159]
	v_pk_fma_f32 v[152:153], v[38:39], v[110:111], v[152:153]
	v_pk_fma_f32 v[154:155], v[40:41], v[112:113], v[154:155]
	v_pk_fma_f32 v[156:157], v[42:43], v[114:115], v[156:157]
	v_pk_fma_f32 v[158:159], v[44:45], v[116:117], v[158:159]
	v_pk_fma_f32 v[152:153], v[46:47], v[118:119], v[152:153]
	v_pk_fma_f32 v[154:155], v[48:49], v[120:121], v[154:155]
	v_pk_fma_f32 v[156:157], v[50:51], v[122:123], v[156:157]
	v_pk_fma_f32 v[158:159], v[52:53], v[124:125], v[158:159]
	v_pk_mul_f32 v[8:9], v[152:153], s[12:13]
	v_pk_mul_f32 v[10:11], v[154:155], s[12:13]
	v_pk_mul_f32 v[12:13], v[156:157], s[12:13]
	v_pk_mul_f32 v[14:15], v[158:159], s[12:13]
	v_exp_f32_e32 v8, v8
	v_exp_f32_e32 v9, v9
	v_exp_f32_e32 v10, v10
	v_exp_f32_e32 v11, v11
	v_exp_f32_e32 v12, v12
	v_exp_f32_e32 v13, v13
	v_exp_f32_e32 v14, v14
; __device__ __forceinline__ unsigned pk2(float lo, float hi) { const f32v2_t v = {lo, hi}; const bf16v2_t b = __builtin_convertvector(v, bf16v2_t); return __builtin_bit_cast(unsigned, b); }
; __device__ __forceinline__ float lo16(unsigned u) { return __uint_as_float(u << 16); }
; __device__ __forceinline__ float hi16(unsigned u) { return __uint_as_float(u & 0xffff0000u); }
; __device__ __forceinline__ float siluf_(float x) { return x * __builtin_amdgcn_rcpf(1.0f + __expf(-x)); }
; __device__ __forceinline__ void prep_dn_load(const bf16_t* proj, const float* cw, int idx, u32x4 (&raw)[4], int& t, int& ch) {
;     if (idx >= 0) { t = idx / 384; const int j = idx - t * 384; ch = j * 8; }
; #pragma unroll
;     for (int k = 0; k < 4; ++k) { const int tt = t - 3 + k; raw[k] = (u32x4){0u, 0u, 0u, 0u};
;         if (tt >= 0) raw[k] = *(const u32x4*)(proj + (size_t)tt * NP + C_DNQ + ch); }
; }
; __device__ __forceinline__ void prep_dn_finish(const float* cw, bf16_t* dq, bf16_t* dk, bf16_t* dv, const u32x4 (&raw)[4], int t, int ch) {
;     float a[8];
; #pragma unroll
;     for (int e = 0; e < 8; ++e) a[e] = 0.f;
; #pragma unroll
;     for (int k = 0; k < 4; ++k) {
;         const f32x4 w0 = *(const f32x4*)(cw + k * 3072 + ch), w1 = *(const f32x4*)(cw + k * 3072 + ch + 4);
;         a[0] += w0[0] * lo16(raw[k].x); a[1] += w0[1] * hi16(raw[k].x); a[2] += w0[2] * lo16(raw[k].y); a[3] += w0[3] * hi16(raw[k].y);
;         a[4] += w1[0] * lo16(raw[k].z); a[5] += w1[1] * hi16(raw[k].z); a[6] += w1[2] * lo16(raw[k].w); a[7] += w1[3] * hi16(raw[k].w); }
;     float ss = 0.f;
; #pragma unroll
;     for (int e = 0; e < 8; ++e) { a[e] = siluf_(a[e]); ss += a[e] * a[e]; }
;     ss += __shfl_xor(ss, 1); ss += __shfl_xor(ss, 2); ss += __shfl_xor(ss, 4); ss += __shfl_xor(ss, 8);
;     float sc = 1.0f;
;     if (ch < 2048) { sc = rsqrtf(ss + EPS); if (ch < 1024) sc *= 0.08838834764831845f; }
;     u32x4 w; w.x = pk2(a[0] * sc, a[1] * sc); w.y = pk2(a[2] * sc, a[3] * sc); w.z = pk2(a[4] * sc, a[5] * sc); w.w = pk2(a[6] * sc, a[7] * sc);
;     bf16_t* dst = (ch < 1024) ? dq : (ch < 2048 ? dk : dv);
;     *(u32x4*)(dst + (size_t)t * 1024 + (ch & 1023)) = w;
; }
	v_exp_f32_e32 v15, v15
	v_pk_add_f32 v[8:9], v[8:9], s[14:15]
	v_pk_add_f32 v[10:11], v[10:11], s[14:15]
	v_pk_add_f32 v[12:13], v[12:13], s[14:15]
	v_pk_add_f32 v[14:15], v[14:15], s[14:15]
	v_rcp_f32_e32 v8, v8
	v_rcp_f32_e32 v9, v9
	v_rcp_f32_e32 v10, v10
	v_rcp_f32_e32 v11, v11
	v_rcp_f32_e32 v12, v12
	v_rcp_f32_e32 v13, v13
	v_rcp_f32_e32 v14, v14
	v_rcp_f32_e32 v15, v15
	v_pk_mul_f32 v[152:153], v[152:153], v[8:9]
	v_pk_mul_f32 v[154:155], v[154:155], v[10:11]
	v_pk_mul_f32 v[156:157], v[156:157], v[12:13]
	v_pk_mul_f32 v[158:159], v[158:159], v[14:15]
	v_pk_mul_f32 v[8:9], v[152:153], v[152:153]
	v_pk_fma_f32 v[8:9], v[154:155], v[154:155], v[8:9]
	v_pk_fma_f32 v[8:9], v[156:157], v[156:157], v[8:9]
	v_pk_fma_f32 v[8:9], v[158:159], v[158:159], v[8:9]
	s_nop 0
	v_add_f32_e32 v54, v8, v9
	s_nop 1
	v_add_f32_dpp v54, v54, v54 quad_perm:[1,0,3,2] row_mask:0xf bank_mask:0xf
	s_nop 1
	v_add_f32_dpp v54, v54, v54 quad_perm:[2,3,0,1] row_mask:0xf bank_mask:0xf
	s_nop 1
	v_add_f32_dpp v54, v54, v54 row_half_mirror row_mask:0xf bank_mask:0xf
	s_nop 1
	v_add_f32_dpp v54, v54, v54 row_mirror row_mask:0xf bank_mask:0xf
	v_add_f32_e32 v54, 0x358637bd, v54
	v_rsq_f32_e32 v54, v54
	s_nop 0
	v_pk_mul_f32 v[152:153], v[152:153], v[54:55] op_sel_hi:[1,0]
	v_pk_mul_f32 v[154:155], v[154:155], v[54:55] op_sel_hi:[1,0]
	v_pk_mul_f32 v[156:157], v[156:157], v[54:55] op_sel_hi:[1,0]
	v_pk_mul_f32 v[158:159], v[158:159], v[54:55] op_sel_hi:[1,0]
	v_cvt_pk_bf16_f32 v56, v152, v153
	v_cvt_pk_bf16_f32 v57, v154, v155
	v_cvt_pk_bf16_f32 v58, v156, v157
	v_cvt_pk_bf16_f32 v59, v158, v159
	global_store_dwordx4 v5, v[56:59], s[18:19]
	s_add_u32 s18, s18, 0x800
	s_addc_u32 s19, s19, 0
	v_lshlrev_b32_e32 v126, 16, v106
	v_and_b32_e32 v127, 0xffff0000, v106
	v_lshlrev_b32_e32 v128, 16, v107
	v_and_b32_e32 v129, 0xffff0000, v107
	v_lshlrev_b32_e32 v130, 16, v108
	v_and_b32_e32 v131, 0xffff0000, v108
	v_lshlrev_b32_e32 v132, 16, v109
	v_and_b32_e32 v133, 0xffff0000, v109
	global_load_dwordx4 v[106:109], v1, s[16:17]
	s_sub_u32 s16, s16, 0x14ac00
	s_subb_u32 s17, s17, 0
	v_pk_mul_f32 v[152:153], v[22:23], v[134:135]
	v_pk_mul_f32 v[154:155], v[24:25], v[136:137]
	v_pk_mul_f32 v[156:157], v[26:27], v[138:139]
	v_pk_mul_f32 v[158:159], v[28:29], v[140:141]
	v_pk_fma_f32 v[152:153], v[30:31], v[110:111], v[152:153]
	v_pk_fma_f32 v[154:155], v[32:33], v[112:113], v[154:155]
	v_pk_fma_f32 v[156:157], v[34:35], v[114:115], v[156:157]
	v_pk_fma_f32 v[158:159], v[36:37], v[116:117], v[158:159]
	v_pk_fma_f32 v[152:153], v[38:39], v[118:119], v[152:153]
	v_pk_fma_f32 v[154:155], v[40:41], v[120:121], v[154:155]
	v_pk_fma_f32 v[156:157], v[42:43], v[122:123], v[156:157]
	v_pk_fma_f32 v[158:159], v[44:45], v[124:125], v[158:159]
	v_pk_fma_f32 v[152:153], v[46:47], v[126:127], v[152:153]
	v_pk_fma_f32 v[154:155], v[48:49], v[128:129], v[154:155]
	v_pk_fma_f32 v[156:157], v[50:51], v[130:131], v[156:157]
	v_pk_fma_f32 v[158:159], v[52:53], v[132:133], v[158:159]
	v_pk_mul_f32 v[8:9], v[152:153], s[12:13]
	v_pk_mul_f32 v[10:11], v[154:155], s[12:13]
	v_pk_mul_f32 v[12:13], v[156:157], s[12:13]
	v_pk_mul_f32 v[14:15], v[158:159], s[12:13]
	v_exp_f32_e32 v8, v8
	v_exp_f32_e32 v9, v9
	v_exp_f32_e32 v10, v10
	v_exp_f32_e32 v11, v11
	v_exp_f32_e32 v12, v12
	v_exp_f32_e32 v13, v13
	v_exp_f32_e32 v14, v14
	v_exp_f32_e32 v15, v15
	v_pk_add_f32 v[8:9], v[8:9], s[14:15]
	v_pk_add_f32 v[10:11], v[10:11], s[14:15]
	v_pk_add_f32 v[12:13], v[12:13], s[14:15]
	v_pk_add_f32 v[14:15], v[14:15], s[14:15]
	v_rcp_f32_e32 v8, v8
	v_rcp_f32_e32 v9, v9
	v_rcp_f32_e32 v10, v10
	v_rcp_f32_e32 v11, v11
	v_rcp_f32_e32 v12, v12
	v_rcp_f32_e32 v13, v13
	v_rcp_f32_e32 v14, v14
	v_rcp_f32_e32 v15, v15
	v_pk_mul_f32 v[152:153], v[152:153], v[8:9]
	v_pk_mul_f32 v[154:155], v[154:155], v[10:11]
	v_pk_mul_f32 v[156:157], v[156:157], v[12:13]
	v_pk_mul_f32 v[158:159], v[158:159], v[14:15]
	v_pk_mul_f32 v[8:9], v[152:153], v[152:153]
	v_pk_fma_f32 v[8:9], v[154:155], v[154:155], v[8:9]
	v_pk_fma_f32 v[8:9], v[156:157], v[156:157], v[8:9]
	v_pk_fma_f32 v[8:9], v[158:159], v[158:159], v[8:9]
	s_nop 0
	v_add_f32_e32 v54, v8, v9
	s_nop 1
	v_add_f32_dpp v54, v54, v54 quad_perm:[1,0,3,2] row_mask:0xf bank_mask:0xf
	s_nop 1
	v_add_f32_dpp v54, v54, v54 quad_perm:[2,3,0,1] row_mask:0xf bank_mask:0xf
	s_nop 1
	v_add_f32_dpp v54, v54, v54 row_half_mirror row_mask:0xf bank_mask:0xf
	s_nop 1
	v_add_f32_dpp v54, v54, v54 row_mirror row_mask:0xf bank_mask:0xf
	v_add_f32_e32 v54, 0x358637bd, v54
	v_rsq_f32_e32 v54, v54
	s_nop 0
	v_pk_mul_f32 v[152:153], v[152:153], v[54:55] op_sel_hi:[1,0]
	v_pk_mul_f32 v[154:155], v[154:155], v[54:55] op_sel_hi:[1,0]
	v_pk_mul_f32 v[156:157], v[156:157], v[54:55] op_sel_hi:[1,0]
	v_pk_mul_f32 v[158:159], v[158:159], v[54:55] op_sel_hi:[1,0]
	v_cvt_pk_bf16_f32 v56, v152, v153
	v_cvt_pk_bf16_f32 v57, v154, v155
	v_cvt_pk_bf16_f32 v58, v156, v157
	v_cvt_pk_bf16_f32 v59, v158, v159
	global_store_dwordx4 v5, v[56:59], s[18:19]
	s_add_u32 s18, s18, 0xc800
	s_addc_u32 s19, s19, 0
	s_waitcnt vmcnt(16)
	v_lshlrev_b32_e32 v110, 16, v66
	v_and_b32_e32 v111, 0xffff0000, v66
	v_lshlrev_b32_e32 v112, 16, v67
	v_and_b32_e32 v113, 0xffff0000, v67
	v_lshlrev_b32_e32 v114, 16, v68
	v_and_b32_e32 v115, 0xffff0000, v68
	v_lshlrev_b32_e32 v116, 16, v69
	v_and_b32_e32 v117, 0xffff0000, v69
	v_lshlrev_b32_e32 v118, 16, v70
	v_and_b32_e32 v119, 0xffff0000, v70
	v_lshlrev_b32_e32 v120, 16, v71
	v_and_b32_e32 v121, 0xffff0000, v71
	v_lshlrev_b32_e32 v122, 16, v72
	v_and_b32_e32 v123, 0xffff0000, v72
	v_lshlrev_b32_e32 v124, 16, v73
	v_and_b32_e32 v125, 0xffff0000, v73
	v_lshlrev_b32_e32 v126, 16, v74
	v_and_b32_e32 v127, 0xffff0000, v74
	v_lshlrev_b32_e32 v128, 16, v75
	v_and_b32_e32 v129, 0xffff0000, v75
	v_lshlrev_b32_e32 v130, 16, v76
	v_and_b32_e32 v131, 0xffff0000, v76
	v_lshlrev_b32_e32 v132, 16, v77
	v_and_b32_e32 v133, 0xffff0000, v77
	global_load_dwordx4 v[66:69], v2, s[16:17]
	s_add_u32 s16, s16, 0x7e00
	s_addc_u32 s17, s17, 0
	global_load_dwordx4 v[70:73], v2, s[16:17]
	s_add_u32 s16, s16, 0x7e00
	s_addc_u32 s17, s17, 0
	global_load_dwordx4 v[74:77], v2, s[16:17]
	s_add_u32 s16, s16, 0x7e00
	s_addc_u32 s17, s17, 0
	s_waitcnt vmcnt(18)
; __device__ __forceinline__ unsigned pk2(float lo, float hi) { const f32v2_t v = {lo, hi}; const bf16v2_t b = __builtin_convertvector(v, bf16v2_t); return __builtin_bit_cast(unsigned, b); }
; __device__ __forceinline__ float lo16(unsigned u) { return __uint_as_float(u << 16); }
; __device__ __forceinline__ float hi16(unsigned u) { return __uint_as_float(u & 0xffff0000u); }
; __device__ __forceinline__ float siluf_(float x) { return x * __builtin_amdgcn_rcpf(1.0f + __expf(-x)); }
; __device__ __forceinline__ void prep_dn_finish(const float* cw, bf16_t* dq, bf16_t* dk, bf16_t* dv, const u32x4 (&raw)[4], int t, int ch) {
;     float a[8];
; #pragma unroll
;     for (int e = 0; e < 8; ++e) a[e] = 0.f;
; #pragma unroll
;     for (int k = 0; k < 4; ++k) {
;         const f32x4 w0 = *(const f32x4*)(cw + k * 3072 + ch), w1 = *(const f32x4*)(cw + k * 3072 + ch + 4);
;         a[0] += w0[0] * lo16(raw[k].x); a[1] += w0[1] * hi16(raw[k].x); a[2] += w0[2] * lo16(raw[k].y); a[3] += w0[3] * hi16(raw[k].y);
;         a[4] += w1[0] * lo16(raw[k].z); a[5] += w1[1] * hi16(raw[k].z); a[6] += w1[2] * lo16(raw[k].w); a[7] += w1[3] * hi16(raw[k].w); }
;     float ss = 0.f;
; #pragma unroll
;     for (int e = 0; e < 8; ++e) { a[e] = siluf_(a[e]); ss += a[e] * a[e]; }
;     ss += __shfl_xor(ss, 1); ss += __shfl_xor(ss, 2); ss += __shfl_xor(ss, 4); ss += __shfl_xor(ss, 8);
;     float sc = 1.0f;
;     if (ch < 2048) { sc = rsqrtf(ss + EPS); if (ch < 1024) sc *= 0.08838834764831845f; }
;     u32x4 w; w.x = pk2(a[0] * sc, a[1] * sc); w.y = pk2(a[2] * sc, a[3] * sc); w.z = pk2(a[4] * sc, a[5] * sc); w.w = pk2(a[6] * sc, a[7] * sc);
;     bf16_t* dst = (ch < 1024) ? dq : (ch < 2048 ? dk : dv);
;     *(u32x4*)(dst + (size_t)t * 1024 + (ch & 1023)) = w;
; }
	v_lshlrev_b32_e32 v134, 16, v78
	v_and_b32_e32 v135, 0xffff0000, v78
	v_lshlrev_b32_e32 v136, 16, v79
	v_and_b32_e32 v137, 0xffff0000, v79
	v_lshlrev_b32_e32 v138, 16, v80
	v_and_b32_e32 v139, 0xffff0000, v80
	v_lshlrev_b32_e32 v140, 16, v81
	v_and_b32_e32 v141, 0xffff0000, v81
	global_load_dwordx4 v[78:81], v2, s[16:17]
	s_add_u32 s16, s16, 0x7e00
	s_addc_u32 s17, s17, 0
	v_pk_mul_f32 v[152:153], v[22:23], v[110:111]
	v_pk_mul_f32 v[154:155], v[24:25], v[112:113]
	v_pk_mul_f32 v[156:157], v[26:27], v[114:115]
	v_pk_mul_f32 v[158:159], v[28:29], v[116:117]
	v_pk_fma_f32 v[152:153], v[30:31], v[118:119], v[152:153]
	v_pk_fma_f32 v[154:155], v[32:33], v[120:121], v[154:155]
	v_pk_fma_f32 v[156:157], v[34:35], v[122:123], v[156:157]
	v_pk_fma_f32 v[158:159], v[36:37], v[124:125], v[158:159]
	v_pk_fma_f32 v[152:153], v[38:39], v[126:127], v[152:153]
	v_pk_fma_f32 v[154:155], v[40:41], v[128:129], v[154:155]
	v_pk_fma_f32 v[156:157], v[42:43], v[130:131], v[156:157]
	v_pk_fma_f32 v[158:159], v[44:45], v[132:133], v[158:159]
	v_pk_fma_f32 v[152:153], v[46:47], v[134:135], v[152:153]
	v_pk_fma_f32 v[154:155], v[48:49], v[136:137], v[154:155]
	v_pk_fma_f32 v[156:157], v[50:51], v[138:139], v[156:157]
	v_pk_fma_f32 v[158:159], v[52:53], v[140:141], v[158:159]
	v_pk_mul_f32 v[8:9], v[152:153], s[12:13]
	v_pk_mul_f32 v[10:11], v[154:155], s[12:13]
	v_pk_mul_f32 v[12:13], v[156:157], s[12:13]
	v_pk_mul_f32 v[14:15], v[158:159], s[12:13]
	v_exp_f32_e32 v8, v8
	v_exp_f32_e32 v9, v9
	v_exp_f32_e32 v10, v10
	v_exp_f32_e32 v11, v11
	v_exp_f32_e32 v12, v12
	v_exp_f32_e32 v13, v13
	v_exp_f32_e32 v14, v14
	v_exp_f32_e32 v15, v15
	v_pk_add_f32 v[8:9], v[8:9], s[14:15]
	v_pk_add_f32 v[10:11], v[10:11], s[14:15]
	v_pk_add_f32 v[12:13], v[12:13], s[14:15]
	v_pk_add_f32 v[14:15], v[14:15], s[14:15]
	v_rcp_f32_e32 v8, v8
	v_rcp_f32_e32 v9, v9
	v_rcp_f32_e32 v10, v10
	v_rcp_f32_e32 v11, v11
	v_rcp_f32_e32 v12, v12
	v_rcp_f32_e32 v13, v13
	v_rcp_f32_e32 v14, v14
	v_rcp_f32_e32 v15, v15
	v_pk_mul_f32 v[152:153], v[152:153], v[8:9]
	v_pk_mul_f32 v[154:155], v[154:155], v[10:11]
	v_pk_mul_f32 v[156:157], v[156:157], v[12:13]
	v_pk_mul_f32 v[158:159], v[158:159], v[14:15]
	v_pk_mul_f32 v[8:9], v[152:153], v[152:153]
	v_pk_fma_f32 v[8:9], v[154:155], v[154:155], v[8:9]
	v_pk_fma_f32 v[8:9], v[156:157], v[156:157], v[8:9]
	v_pk_fma_f32 v[8:9], v[158:159], v[158:159], v[8:9]
	s_nop 0
	v_add_f32_e32 v54, v8, v9
	s_nop 1
	v_add_f32_dpp v54, v54, v54 quad_perm:[1,0,3,2] row_mask:0xf bank_mask:0xf
	s_nop 1
	v_add_f32_dpp v54, v54, v54 quad_perm:[2,3,0,1] row_mask:0xf bank_mask:0xf
	s_nop 1
	v_add_f32_dpp v54, v54, v54 row_half_mirror row_mask:0xf bank_mask:0xf
	s_nop 1
	v_add_f32_dpp v54, v54, v54 row_mirror row_mask:0xf bank_mask:0xf
	v_add_f32_e32 v54, 0x358637bd, v54
	v_rsq_f32_e32 v54, v54
	s_nop 0
	v_pk_mul_f32 v[152:153], v[152:153], v[54:55] op_sel_hi:[1,0]
	v_pk_mul_f32 v[154:155], v[154:155], v[54:55] op_sel_hi:[1,0]
	v_pk_mul_f32 v[156:157], v[156:157], v[54:55] op_sel_hi:[1,0]
	v_pk_mul_f32 v[158:159], v[158:159], v[54:55] op_sel_hi:[1,0]
	v_cvt_pk_bf16_f32 v56, v152, v153
	v_cvt_pk_bf16_f32 v57, v154, v155
	v_cvt_pk_bf16_f32 v58, v156, v157
	v_cvt_pk_bf16_f32 v59, v158, v159
	global_store_dwordx4 v5, v[56:59], s[18:19]
	s_add_u32 s18, s18, 0x800
	s_addc_u32 s19, s19, 0
	s_waitcnt vmcnt(18)
	v_lshlrev_b32_e32 v110, 16, v82
	v_and_b32_e32 v111, 0xffff0000, v82
	v_lshlrev_b32_e32 v112, 16, v83
	v_and_b32_e32 v113, 0xffff0000, v83
	v_lshlrev_b32_e32 v114, 16, v84
	v_and_b32_e32 v115, 0xffff0000, v84
	v_lshlrev_b32_e32 v116, 16, v85
	v_and_b32_e32 v117, 0xffff0000, v85
	global_load_dwordx4 v[82:85], v2, s[16:17]
	s_add_u32 s16, s16, 0x7e00
	s_addc_u32 s17, s17, 0
	v_pk_mul_f32 v[152:153], v[22:23], v[118:119]
	v_pk_mul_f32 v[154:155], v[24:25], v[120:121]
	v_pk_mul_f32 v[156:157], v[26:27], v[122:123]
	v_pk_mul_f32 v[158:159], v[28:29], v[124:125]
	v_pk_fma_f32 v[152:153], v[30:31], v[126:127], v[152:153]
	v_pk_fma_f32 v[154:155], v[32:33], v[128:129], v[154:155]
	v_pk_fma_f32 v[156:157], v[34:35], v[130:131], v[156:157]
	v_pk_fma_f32 v[158:159], v[36:37], v[132:133], v[158:159]
	v_pk_fma_f32 v[152:153], v[38:39], v[134:135], v[152:153]
	v_pk_fma_f32 v[154:155], v[40:41], v[136:137], v[154:155]
	v_pk_fma_f32 v[156:157], v[42:43], v[138:139], v[156:157]
	v_pk_fma_f32 v[158:159], v[44:45], v[140:141], v[158:159]
	v_pk_fma_f32 v[152:153], v[46:47], v[110:111], v[152:153]
	v_pk_fma_f32 v[154:155], v[48:49], v[112:113], v[154:155]
	v_pk_fma_f32 v[156:157], v[50:51], v[114:115], v[156:157]
	v_pk_fma_f32 v[158:159], v[52:53], v[116:117], v[158:159]
	v_pk_mul_f32 v[8:9], v[152:153], s[12:13]
	v_pk_mul_f32 v[10:11], v[154:155], s[12:13]
	v_pk_mul_f32 v[12:13], v[156:157], s[12:13]
	v_pk_mul_f32 v[14:15], v[158:159], s[12:13]
	v_exp_f32_e32 v8, v8
	v_exp_f32_e32 v9, v9
	v_exp_f32_e32 v10, v10
	v_exp_f32_e32 v11, v11
	v_exp_f32_e32 v12, v12
	v_exp_f32_e32 v13, v13
	v_exp_f32_e32 v14, v14
	v_exp_f32_e32 v15, v15
	v_pk_add_f32 v[8:9], v[8:9], s[14:15]
	v_pk_add_f32 v[10:11], v[10:11], s[14:15]
	v_pk_add_f32 v[12:13], v[12:13], s[14:15]
	v_pk_add_f32 v[14:15], v[14:15], s[14:15]
	v_rcp_f32_e32 v8, v8
	v_rcp_f32_e32 v9, v9
	v_rcp_f32_e32 v10, v10
	v_rcp_f32_e32 v11, v11
	v_rcp_f32_e32 v12, v12
	v_rcp_f32_e32 v13, v13
	v_rcp_f32_e32 v14, v14
	v_rcp_f32_e32 v15, v15
	v_pk_mul_f32 v[152:153], v[152:153], v[8:9]
	v_pk_mul_f32 v[154:155], v[154:155], v[10:11]
	v_pk_mul_f32 v[156:157], v[156:157], v[12:13]
	v_pk_mul_f32 v[158:159], v[158:159], v[14:15]
	v_pk_mul_f32 v[8:9], v[152:153], v[152:153]
	v_pk_fma_f32 v[8:9], v[154:155], v[154:155], v[8:9]
	v_pk_fma_f32 v[8:9], v[156:157], v[156:157], v[8:9]
	v_pk_fma_f32 v[8:9], v[158:159], v[158:159], v[8:9]
	s_nop 0
	v_add_f32_e32 v54, v8, v9
	s_nop 1
	v_add_f32_dpp v54, v54, v54 quad_perm:[1,0,3,2] row_mask:0xf bank_mask:0xf
	s_nop 1
	v_add_f32_dpp v54, v54, v54 quad_perm:[2,3,0,1] row_mask:0xf bank_mask:0xf
	s_nop 1
	v_add_f32_dpp v54, v54, v54 row_half_mirror row_mask:0xf bank_mask:0xf
	s_nop 1
	v_add_f32_dpp v54, v54, v54 row_mirror row_mask:0xf bank_mask:0xf
	v_add_f32_e32 v54, 0x358637bd, v54
	v_rsq_f32_e32 v54, v54
	s_nop 0
	v_pk_mul_f32 v[152:153], v[152:153], v[54:55] op_sel_hi:[1,0]
	v_pk_mul_f32 v[154:155], v[154:155], v[54:55] op_sel_hi:[1,0]
	v_pk_mul_f32 v[156:157], v[156:157], v[54:55] op_sel_hi:[1,0]
	v_pk_mul_f32 v[158:159], v[158:159], v[54:55] op_sel_hi:[1,0]
	v_cvt_pk_bf16_f32 v56, v152, v153
	v_cvt_pk_bf16_f32 v57, v154, v155
	v_cvt_pk_bf16_f32 v58, v156, v157
	v_cvt_pk_bf16_f32 v59, v158, v159
	global_store_dwordx4 v5, v[56:59], s[18:19]
	s_add_u32 s18, s18, 0x800
	s_addc_u32 s19, s19, 0
	s_waitcnt vmcnt(18)
; __device__ __forceinline__ unsigned pk2(float lo, float hi) { const f32v2_t v = {lo, hi}; const bf16v2_t b = __builtin_convertvector(v, bf16v2_t); return __builtin_bit_cast(unsigned, b); }
; __device__ __forceinline__ float lo16(unsigned u) { return __uint_as_float(u << 16); }
; __device__ __forceinline__ float hi16(unsigned u) { return __uint_as_float(u & 0xffff0000u); }
; __device__ __forceinline__ float siluf_(float x) { return x * __builtin_amdgcn_rcpf(1.0f + __expf(-x)); }
; __device__ __forceinline__ void prep_dn_finish(const float* cw, bf16_t* dq, bf16_t* dk, bf16_t* dv, const u32x4 (&raw)[4], int t, int ch) {
;     float a[8];
; #pragma unroll
;     for (int e = 0; e < 8; ++e) a[e] = 0.f;
; #pragma unroll
;     for (int k = 0; k < 4; ++k) {
;         const f32x4 w0 = *(const f32x4*)(cw + k * 3072 + ch), w1 = *(const f32x4*)(cw + k * 3072 + ch + 4);
;         a[0] += w0[0] * lo16(raw[k].x); a[1] += w0[1] * hi16(raw[k].x); a[2] += w0[2] * lo16(raw[k].y); a[3] += w0[3] * hi16(raw[k].y);
;         a[4] += w1[0] * lo16(raw[k].z); a[5] += w1[1] * hi16(raw[k].z); a[6] += w1[2] * lo16(raw[k].w); a[7] += w1[3] * hi16(raw[k].w); }
;     float ss = 0.f;
; #pragma unroll
;     for (int e = 0; e < 8; ++e) { a[e] = siluf_(a[e]); ss += a[e] * a[e]; }
;     ss += __shfl_xor(ss, 1); ss += __shfl_xor(ss, 2); ss += __shfl_xor(ss, 4); ss += __shfl_xor(ss, 8);
;     float sc = 1.0f;
;     if (ch < 2048) { sc = rsqrtf(ss + EPS); if (ch < 1024) sc *= 0.08838834764831845f; }
;     u32x4 w; w.x = pk2(a[0] * sc, a[1] * sc); w.y = pk2(a[2] * sc, a[3] * sc); w.z = pk2(a[4] * sc, a[5] * sc); w.w = pk2(a[6] * sc, a[7] * sc);
;     bf16_t* dst = (ch < 1024) ? dq : (ch < 2048 ? dk : dv);
;     *(u32x4*)(dst + (size_t)t * 1024 + (ch & 1023)) = w;
; }
	v_lshlrev_b32_e32 v118, 16, v86
	v_and_b32_e32 v119, 0xffff0000, v86
	v_lshlrev_b32_e32 v120, 16, v87
	v_and_b32_e32 v121, 0xffff0000, v87
	v_lshlrev_b32_e32 v122, 16, v88
	v_and_b32_e32 v123, 0xffff0000, v88
	v_lshlrev_b32_e32 v124, 16, v89
	v_and_b32_e32 v125, 0xffff0000, v89
	global_load_dwordx4 v[86:89], v2, s[16:17]
	s_add_u32 s16, s16, 0x7e00
	s_addc_u32 s17, s17, 0
	v_pk_mul_f32 v[152:153], v[22:23], v[126:127]
	v_pk_mul_f32 v[154:155], v[24:25], v[128:129]
	v_pk_mul_f32 v[156:157], v[26:27], v[130:131]
	v_pk_mul_f32 v[158:159], v[28:29], v[132:133]
	v_pk_fma_f32 v[152:153], v[30:31], v[134:135], v[152:153]
	v_pk_fma_f32 v[154:155], v[32:33], v[136:137], v[154:155]
	v_pk_fma_f32 v[156:157], v[34:35], v[138:139], v[156:157]
	v_pk_fma_f32 v[158:159], v[36:37], v[140:141], v[158:159]
	v_pk_fma_f32 v[152:153], v[38:39], v[110:111], v[152:153]
	v_pk_fma_f32 v[154:155], v[40:41], v[112:113], v[154:155]
	v_pk_fma_f32 v[156:157], v[42:43], v[114:115], v[156:157]
	v_pk_fma_f32 v[158:159], v[44:45], v[116:117], v[158:159]
	v_pk_fma_f32 v[152:153], v[46:47], v[118:119], v[152:153]
	v_pk_fma_f32 v[154:155], v[48:49], v[120:121], v[154:155]
	v_pk_fma_f32 v[156:157], v[50:51], v[122:123], v[156:157]
	v_pk_fma_f32 v[158:159], v[52:53], v[124:125], v[158:159]
	v_pk_mul_f32 v[8:9], v[152:153], s[12:13]
	v_pk_mul_f32 v[10:11], v[154:155], s[12:13]
	v_pk_mul_f32 v[12:13], v[156:157], s[12:13]
	v_pk_mul_f32 v[14:15], v[158:159], s[12:13]
	v_exp_f32_e32 v8, v8
	v_exp_f32_e32 v9, v9
	v_exp_f32_e32 v10, v10
	v_exp_f32_e32 v11, v11
	v_exp_f32_e32 v12, v12
	v_exp_f32_e32 v13, v13
	v_exp_f32_e32 v14, v14
	v_exp_f32_e32 v15, v15
	v_pk_add_f32 v[8:9], v[8:9], s[14:15]
	v_pk_add_f32 v[10:11], v[10:11], s[14:15]
	v_pk_add_f32 v[12:13], v[12:13], s[14:15]
	v_pk_add_f32 v[14:15], v[14:15], s[14:15]
	v_rcp_f32_e32 v8, v8
	v_rcp_f32_e32 v9, v9
	v_rcp_f32_e32 v10, v10
	v_rcp_f32_e32 v11, v11
	v_rcp_f32_e32 v12, v12
	v_rcp_f32_e32 v13, v13
	v_rcp_f32_e32 v14, v14
	v_rcp_f32_e32 v15, v15
	v_pk_mul_f32 v[152:153], v[152:153], v[8:9]
	v_pk_mul_f32 v[154:155], v[154:155], v[10:11]
	v_pk_mul_f32 v[156:157], v[156:157], v[12:13]
	v_pk_mul_f32 v[158:159], v[158:159], v[14:15]
	v_pk_mul_f32 v[8:9], v[152:153], v[152:153]
	v_pk_fma_f32 v[8:9], v[154:155], v[154:155], v[8:9]
	v_pk_fma_f32 v[8:9], v[156:157], v[156:157], v[8:9]
	v_pk_fma_f32 v[8:9], v[158:159], v[158:159], v[8:9]
	s_nop 0
	v_add_f32_e32 v54, v8, v9
	s_nop 1
	v_add_f32_dpp v54, v54, v54 quad_perm:[1,0,3,2] row_mask:0xf bank_mask:0xf
	s_nop 1
	v_add_f32_dpp v54, v54, v54 quad_perm:[2,3,0,1] row_mask:0xf bank_mask:0xf
	s_nop 1
	v_add_f32_dpp v54, v54, v54 row_half_mirror row_mask:0xf bank_mask:0xf
	s_nop 1
	v_add_f32_dpp v54, v54, v54 row_mirror row_mask:0xf bank_mask:0xf
	v_add_f32_e32 v54, 0x358637bd, v54
	v_rsq_f32_e32 v54, v54
	s_nop 0
	v_pk_mul_f32 v[152:153], v[152:153], v[54:55] op_sel_hi:[1,0]
	v_pk_mul_f32 v[154:155], v[154:155], v[54:55] op_sel_hi:[1,0]
	v_pk_mul_f32 v[156:157], v[156:157], v[54:55] op_sel_hi:[1,0]
	v_pk_mul_f32 v[158:159], v[158:159], v[54:55] op_sel_hi:[1,0]
	v_cvt_pk_bf16_f32 v56, v152, v153
	v_cvt_pk_bf16_f32 v57, v154, v155
	v_cvt_pk_bf16_f32 v58, v156, v157
	v_cvt_pk_bf16_f32 v59, v158, v159
	global_store_dwordx4 v5, v[56:59], s[18:19]
	s_add_u32 s18, s18, 0x800
	s_addc_u32 s19, s19, 0
	s_waitcnt vmcnt(18)
	v_lshlrev_b32_e32 v126, 16, v90
	v_and_b32_e32 v127, 0xffff0000, v90
	v_lshlrev_b32_e32 v128, 16, v91
	v_and_b32_e32 v129, 0xffff0000, v91
	v_lshlrev_b32_e32 v130, 16, v92
	v_and_b32_e32 v131, 0xffff0000, v92
	v_lshlrev_b32_e32 v132, 16, v93
	v_and_b32_e32 v133, 0xffff0000, v93
	global_load_dwordx4 v[90:93], v2, s[16:17]
	s_add_u32 s16, s16, 0x7e00
	s_addc_u32 s17, s17, 0
	v_pk_mul_f32 v[152:153], v[22:23], v[134:135]
	v_pk_mul_f32 v[154:155], v[24:25], v[136:137]
	v_pk_mul_f32 v[156:157], v[26:27], v[138:139]
	v_pk_mul_f32 v[158:159], v[28:29], v[140:141]
	v_pk_fma_f32 v[152:153], v[30:31], v[110:111], v[152:153]
	v_pk_fma_f32 v[154:155], v[32:33], v[112:113], v[154:155]
	v_pk_fma_f32 v[156:157], v[34:35], v[114:115], v[156:157]
	v_pk_fma_f32 v[158:159], v[36:37], v[116:117], v[158:159]
	v_pk_fma_f32 v[152:153], v[38:39], v[118:119], v[152:153]
	v_pk_fma_f32 v[154:155], v[40:41], v[120:121], v[154:155]
	v_pk_fma_f32 v[156:157], v[42:43], v[122:123], v[156:157]
	v_pk_fma_f32 v[158:159], v[44:45], v[124:125], v[158:159]
	v_pk_fma_f32 v[152:153], v[46:47], v[126:127], v[152:153]
	v_pk_fma_f32 v[154:155], v[48:49], v[128:129], v[154:155]
	v_pk_fma_f32 v[156:157], v[50:51], v[130:131], v[156:157]
	v_pk_fma_f32 v[158:159], v[52:53], v[132:133], v[158:159]
	v_pk_mul_f32 v[8:9], v[152:153], s[12:13]
	v_pk_mul_f32 v[10:11], v[154:155], s[12:13]
	v_pk_mul_f32 v[12:13], v[156:157], s[12:13]
	v_pk_mul_f32 v[14:15], v[158:159], s[12:13]
	v_exp_f32_e32 v8, v8
	v_exp_f32_e32 v9, v9
	v_exp_f32_e32 v10, v10
	v_exp_f32_e32 v11, v11
	v_exp_f32_e32 v12, v12
	v_exp_f32_e32 v13, v13
	v_exp_f32_e32 v14, v14
	v_exp_f32_e32 v15, v15
	v_pk_add_f32 v[8:9], v[8:9], s[14:15]
	v_pk_add_f32 v[10:11], v[10:11], s[14:15]
	v_pk_add_f32 v[12:13], v[12:13], s[14:15]
	v_pk_add_f32 v[14:15], v[14:15], s[14:15]
	v_rcp_f32_e32 v8, v8
	v_rcp_f32_e32 v9, v9
	v_rcp_f32_e32 v10, v10
	v_rcp_f32_e32 v11, v11
	v_rcp_f32_e32 v12, v12
	v_rcp_f32_e32 v13, v13
	v_rcp_f32_e32 v14, v14
	v_rcp_f32_e32 v15, v15
	v_pk_mul_f32 v[152:153], v[152:153], v[8:9]
	v_pk_mul_f32 v[154:155], v[154:155], v[10:11]
	v_pk_mul_f32 v[156:157], v[156:157], v[12:13]
	v_pk_mul_f32 v[158:159], v[158:159], v[14:15]
	v_pk_mul_f32 v[8:9], v[152:153], v[152:153]
	v_pk_fma_f32 v[8:9], v[154:155], v[154:155], v[8:9]
	v_pk_fma_f32 v[8:9], v[156:157], v[156:157], v[8:9]
	v_pk_fma_f32 v[8:9], v[158:159], v[158:159], v[8:9]
	s_nop 0
	v_add_f32_e32 v54, v8, v9
	s_nop 1
	v_add_f32_dpp v54, v54, v54 quad_perm:[1,0,3,2] row_mask:0xf bank_mask:0xf
	s_nop 1
	v_add_f32_dpp v54, v54, v54 quad_perm:[2,3,0,1] row_mask:0xf bank_mask:0xf
	s_nop 1
	v_add_f32_dpp v54, v54, v54 row_half_mirror row_mask:0xf bank_mask:0xf
	s_nop 1
	v_add_f32_dpp v54, v54, v54 row_mirror row_mask:0xf bank_mask:0xf
	v_add_f32_e32 v54, 0x358637bd, v54
	v_rsq_f32_e32 v54, v54
	s_nop 0
	v_pk_mul_f32 v[152:153], v[152:153], v[54:55] op_sel_hi:[1,0]
	v_pk_mul_f32 v[154:155], v[154:155], v[54:55] op_sel_hi:[1,0]
	v_pk_mul_f32 v[156:157], v[156:157], v[54:55] op_sel_hi:[1,0]
	v_pk_mul_f32 v[158:159], v[158:159], v[54:55] op_sel_hi:[1,0]
	v_cvt_pk_bf16_f32 v56, v152, v153
	v_cvt_pk_bf16_f32 v57, v154, v155
	v_cvt_pk_bf16_f32 v58, v156, v157
	v_cvt_pk_bf16_f32 v59, v158, v159
	global_store_dwordx4 v5, v[56:59], s[18:19]
	s_add_u32 s18, s18, 0x800
	s_addc_u32 s19, s19, 0
	s_waitcnt vmcnt(18)
; __device__ __forceinline__ unsigned pk2(float lo, float hi) { const f32v2_t v = {lo, hi}; const bf16v2_t b = __builtin_convertvector(v, bf16v2_t); return __builtin_bit_cast(unsigned, b); }
; __device__ __forceinline__ float lo16(unsigned u) { return __uint_as_float(u << 16); }
; __device__ __forceinline__ float hi16(unsigned u) { return __uint_as_float(u & 0xffff0000u); }
; __device__ __forceinline__ float siluf_(float x) { return x * __builtin_amdgcn_rcpf(1.0f + __expf(-x)); }
; __device__ __forceinline__ void prep_dn_finish(const float* cw, bf16_t* dq, bf16_t* dk, bf16_t* dv, const u32x4 (&raw)[4], int t, int ch) {
;     float a[8];
; #pragma unroll
;     for (int e = 0; e < 8; ++e) a[e] = 0.f;
; #pragma unroll
;     for (int k = 0; k < 4; ++k) {
;         const f32x4 w0 = *(const f32x4*)(cw + k * 3072 + ch), w1 = *(const f32x4*)(cw + k * 3072 + ch + 4);
;         a[0] += w0[0] * lo16(raw[k].x); a[1] += w0[1] * hi16(raw[k].x); a[2] += w0[2] * lo16(raw[k].y); a[3] += w0[3] * hi16(raw[k].y);
;         a[4] += w1[0] * lo16(raw[k].z); a[5] += w1[1] * hi16(raw[k].z); a[6] += w1[2] * lo16(raw[k].w); a[7] += w1[3] * hi16(raw[k].w); }
;     float ss = 0.f;
; #pragma unroll
;     for (int e = 0; e < 8; ++e) { a[e] = siluf_(a[e]); ss += a[e] * a[e]; }
;     ss += __shfl_xor(ss, 1); ss += __shfl_xor(ss, 2); ss += __shfl_xor(ss, 4); ss += __shfl_xor(ss, 8);
;     float sc = 1.0f;
;     if (ch < 2048) { sc = rsqrtf(ss + EPS); if (ch < 1024) sc *= 0.08838834764831845f; }
;     u32x4 w; w.x = pk2(a[0] * sc, a[1] * sc); w.y = pk2(a[2] * sc, a[3] * sc); w.z = pk2(a[4] * sc, a[5] * sc); w.w = pk2(a[6] * sc, a[7] * sc);
;     bf16_t* dst = (ch < 1024) ? dq : (ch < 2048 ? dk : dv);
;     *(u32x4*)(dst + (size_t)t * 1024 + (ch & 1023)) = w;
; }
	v_lshlrev_b32_e32 v134, 16, v94
	v_and_b32_e32 v135, 0xffff0000, v94
	v_lshlrev_b32_e32 v136, 16, v95
	v_and_b32_e32 v137, 0xffff0000, v95
	v_lshlrev_b32_e32 v138, 16, v96
	v_and_b32_e32 v139, 0xffff0000, v96
	v_lshlrev_b32_e32 v140, 16, v97
	v_and_b32_e32 v141, 0xffff0000, v97
	global_load_dwordx4 v[94:97], v2, s[16:17]
	s_add_u32 s16, s16, 0x7e00
	s_addc_u32 s17, s17, 0
	v_pk_mul_f32 v[152:153], v[22:23], v[110:111]
	v_pk_mul_f32 v[154:155], v[24:25], v[112:113]
	v_pk_mul_f32 v[156:157], v[26:27], v[114:115]
	v_pk_mul_f32 v[158:159], v[28:29], v[116:117]
	v_pk_fma_f32 v[152:153], v[30:31], v[118:119], v[152:153]
	v_pk_fma_f32 v[154:155], v[32:33], v[120:121], v[154:155]
	v_pk_fma_f32 v[156:157], v[34:35], v[122:123], v[156:157]
	v_pk_fma_f32 v[158:159], v[36:37], v[124:125], v[158:159]
	v_pk_fma_f32 v[152:153], v[38:39], v[126:127], v[152:153]
	v_pk_fma_f32 v[154:155], v[40:41], v[128:129], v[154:155]
	v_pk_fma_f32 v[156:157], v[42:43], v[130:131], v[156:157]
	v_pk_fma_f32 v[158:159], v[44:45], v[132:133], v[158:159]
	v_pk_fma_f32 v[152:153], v[46:47], v[134:135], v[152:153]
	v_pk_fma_f32 v[154:155], v[48:49], v[136:137], v[154:155]
	v_pk_fma_f32 v[156:157], v[50:51], v[138:139], v[156:157]
	v_pk_fma_f32 v[158:159], v[52:53], v[140:141], v[158:159]
	v_pk_mul_f32 v[8:9], v[152:153], s[12:13]
	v_pk_mul_f32 v[10:11], v[154:155], s[12:13]
	v_pk_mul_f32 v[12:13], v[156:157], s[12:13]
	v_pk_mul_f32 v[14:15], v[158:159], s[12:13]
	v_exp_f32_e32 v8, v8
	v_exp_f32_e32 v9, v9
	v_exp_f32_e32 v10, v10
	v_exp_f32_e32 v11, v11
	v_exp_f32_e32 v12, v12
	v_exp_f32_e32 v13, v13
	v_exp_f32_e32 v14, v14
	v_exp_f32_e32 v15, v15
	v_pk_add_f32 v[8:9], v[8:9], s[14:15]
	v_pk_add_f32 v[10:11], v[10:11], s[14:15]
	v_pk_add_f32 v[12:13], v[12:13], s[14:15]
	v_pk_add_f32 v[14:15], v[14:15], s[14:15]
	v_rcp_f32_e32 v8, v8
	v_rcp_f32_e32 v9, v9
	v_rcp_f32_e32 v10, v10
	v_rcp_f32_e32 v11, v11
	v_rcp_f32_e32 v12, v12
	v_rcp_f32_e32 v13, v13
	v_rcp_f32_e32 v14, v14
	v_rcp_f32_e32 v15, v15
	v_pk_mul_f32 v[152:153], v[152:153], v[8:9]
	v_pk_mul_f32 v[154:155], v[154:155], v[10:11]
	v_pk_mul_f32 v[156:157], v[156:157], v[12:13]
	v_pk_mul_f32 v[158:159], v[158:159], v[14:15]
	v_pk_mul_f32 v[8:9], v[152:153], v[152:153]
	v_pk_fma_f32 v[8:9], v[154:155], v[154:155], v[8:9]
	v_pk_fma_f32 v[8:9], v[156:157], v[156:157], v[8:9]
	v_pk_fma_f32 v[8:9], v[158:159], v[158:159], v[8:9]
	s_nop 0
	v_add_f32_e32 v54, v8, v9
	s_nop 1
	v_add_f32_dpp v54, v54, v54 quad_perm:[1,0,3,2] row_mask:0xf bank_mask:0xf
	s_nop 1
	v_add_f32_dpp v54, v54, v54 quad_perm:[2,3,0,1] row_mask:0xf bank_mask:0xf
	s_nop 1
	v_add_f32_dpp v54, v54, v54 row_half_mirror row_mask:0xf bank_mask:0xf
	s_nop 1
	v_add_f32_dpp v54, v54, v54 row_mirror row_mask:0xf bank_mask:0xf
	v_add_f32_e32 v54, 0x358637bd, v54
	v_rsq_f32_e32 v54, v54
	s_nop 0
	v_pk_mul_f32 v[152:153], v[152:153], v[54:55] op_sel_hi:[1,0]
	v_pk_mul_f32 v[154:155], v[154:155], v[54:55] op_sel_hi:[1,0]
	v_pk_mul_f32 v[156:157], v[156:157], v[54:55] op_sel_hi:[1,0]
	v_pk_mul_f32 v[158:159], v[158:159], v[54:55] op_sel_hi:[1,0]
	v_cvt_pk_bf16_f32 v56, v152, v153
	v_cvt_pk_bf16_f32 v57, v154, v155
	v_cvt_pk_bf16_f32 v58, v156, v157
	v_cvt_pk_bf16_f32 v59, v158, v159
	global_store_dwordx4 v5, v[56:59], s[18:19]
	s_add_u32 s18, s18, 0x800
	s_addc_u32 s19, s19, 0
	s_waitcnt vmcnt(18)
	v_lshlrev_b32_e32 v110, 16, v98
	v_and_b32_e32 v111, 0xffff0000, v98
	v_lshlrev_b32_e32 v112, 16, v99
	v_and_b32_e32 v113, 0xffff0000, v99
	v_lshlrev_b32_e32 v114, 16, v100
	v_and_b32_e32 v115, 0xffff0000, v100
	v_lshlrev_b32_e32 v116, 16, v101
	v_and_b32_e32 v117, 0xffff0000, v101
	global_load_dwordx4 v[98:101], v2, s[16:17]
	s_add_u32 s16, s16, 0x7e00
	s_addc_u32 s17, s17, 0
	v_pk_mul_f32 v[152:153], v[22:23], v[118:119]
	v_pk_mul_f32 v[154:155], v[24:25], v[120:121]
	v_pk_mul_f32 v[156:157], v[26:27], v[122:123]
	v_pk_mul_f32 v[158:159], v[28:29], v[124:125]
	v_pk_fma_f32 v[152:153], v[30:31], v[126:127], v[152:153]
	v_pk_fma_f32 v[154:155], v[32:33], v[128:129], v[154:155]
	v_pk_fma_f32 v[156:157], v[34:35], v[130:131], v[156:157]
	v_pk_fma_f32 v[158:159], v[36:37], v[132:133], v[158:159]
	v_pk_fma_f32 v[152:153], v[38:39], v[134:135], v[152:153]
	v_pk_fma_f32 v[154:155], v[40:41], v[136:137], v[154:155]
	v_pk_fma_f32 v[156:157], v[42:43], v[138:139], v[156:157]
	v_pk_fma_f32 v[158:159], v[44:45], v[140:141], v[158:159]
	v_pk_fma_f32 v[152:153], v[46:47], v[110:111], v[152:153]
	v_pk_fma_f32 v[154:155], v[48:49], v[112:113], v[154:155]
	v_pk_fma_f32 v[156:157], v[50:51], v[114:115], v[156:157]
	v_pk_fma_f32 v[158:159], v[52:53], v[116:117], v[158:159]
	v_pk_mul_f32 v[8:9], v[152:153], s[12:13]
	v_pk_mul_f32 v[10:11], v[154:155], s[12:13]
	v_pk_mul_f32 v[12:13], v[156:157], s[12:13]
	v_pk_mul_f32 v[14:15], v[158:159], s[12:13]
	v_exp_f32_e32 v8, v8
	v_exp_f32_e32 v9, v9
	v_exp_f32_e32 v10, v10
	v_exp_f32_e32 v11, v11
	v_exp_f32_e32 v12, v12
	v_exp_f32_e32 v13, v13
	v_exp_f32_e32 v14, v14
	v_exp_f32_e32 v15, v15
	v_pk_add_f32 v[8:9], v[8:9], s[14:15]
	v_pk_add_f32 v[10:11], v[10:11], s[14:15]
	v_pk_add_f32 v[12:13], v[12:13], s[14:15]
	v_pk_add_f32 v[14:15], v[14:15], s[14:15]
	v_rcp_f32_e32 v8, v8
	v_rcp_f32_e32 v9, v9
	v_rcp_f32_e32 v10, v10
	v_rcp_f32_e32 v11, v11
	v_rcp_f32_e32 v12, v12
	v_rcp_f32_e32 v13, v13
	v_rcp_f32_e32 v14, v14
	v_rcp_f32_e32 v15, v15
	v_pk_mul_f32 v[152:153], v[152:153], v[8:9]
	v_pk_mul_f32 v[154:155], v[154:155], v[10:11]
	v_pk_mul_f32 v[156:157], v[156:157], v[12:13]
	v_pk_mul_f32 v[158:159], v[158:159], v[14:15]
	v_pk_mul_f32 v[8:9], v[152:153], v[152:153]
	v_pk_fma_f32 v[8:9], v[154:155], v[154:155], v[8:9]
	v_pk_fma_f32 v[8:9], v[156:157], v[156:157], v[8:9]
	v_pk_fma_f32 v[8:9], v[158:159], v[158:159], v[8:9]
	s_nop 0
	v_add_f32_e32 v54, v8, v9
	s_nop 1
	v_add_f32_dpp v54, v54, v54 quad_perm:[1,0,3,2] row_mask:0xf bank_mask:0xf
	s_nop 1
	v_add_f32_dpp v54, v54, v54 quad_perm:[2,3,0,1] row_mask:0xf bank_mask:0xf
	s_nop 1
	v_add_f32_dpp v54, v54, v54 row_half_mirror row_mask:0xf bank_mask:0xf
	s_nop 1
	v_add_f32_dpp v54, v54, v54 row_mirror row_mask:0xf bank_mask:0xf
	v_add_f32_e32 v54, 0x358637bd, v54
	v_rsq_f32_e32 v54, v54
	s_nop 0
	v_pk_mul_f32 v[152:153], v[152:153], v[54:55] op_sel_hi:[1,0]
	v_pk_mul_f32 v[154:155], v[154:155], v[54:55] op_sel_hi:[1,0]
	v_pk_mul_f32 v[156:157], v[156:157], v[54:55] op_sel_hi:[1,0]
	v_pk_mul_f32 v[158:159], v[158:159], v[54:55] op_sel_hi:[1,0]
	v_cvt_pk_bf16_f32 v56, v152, v153
	v_cvt_pk_bf16_f32 v57, v154, v155
	v_cvt_pk_bf16_f32 v58, v156, v157
	v_cvt_pk_bf16_f32 v59, v158, v159
	global_store_dwordx4 v5, v[56:59], s[18:19]
	s_add_u32 s18, s18, 0x800
	s_addc_u32 s19, s19, 0
	s_waitcnt vmcnt(18)
; __device__ __forceinline__ unsigned pk2(float lo, float hi) { const f32v2_t v = {lo, hi}; const bf16v2_t b = __builtin_convertvector(v, bf16v2_t); return __builtin_bit_cast(unsigned, b); }
; __device__ __forceinline__ float lo16(unsigned u) { return __uint_as_float(u << 16); }
; __device__ __forceinline__ float hi16(unsigned u) { return __uint_as_float(u & 0xffff0000u); }
; __device__ __forceinline__ float siluf_(float x) { return x * __builtin_amdgcn_rcpf(1.0f + __expf(-x)); }
; __device__ __forceinline__ void prep_dn_finish(const float* cw, bf16_t* dq, bf16_t* dk, bf16_t* dv, const u32x4 (&raw)[4], int t, int ch) {
;     float a[8];
; #pragma unroll
;     for (int e = 0; e < 8; ++e) a[e] = 0.f;
; #pragma unroll
;     for (int k = 0; k < 4; ++k) {
;         const f32x4 w0 = *(const f32x4*)(cw + k * 3072 + ch), w1 = *(const f32x4*)(cw + k * 3072 + ch + 4);
;         a[0] += w0[0] * lo16(raw[k].x); a[1] += w0[1] * hi16(raw[k].x); a[2] += w0[2] * lo16(raw[k].y); a[3] += w0[3] * hi16(raw[k].y);
;         a[4] += w1[0] * lo16(raw[k].z); a[5] += w1[1] * hi16(raw[k].z); a[6] += w1[2] * lo16(raw[k].w); a[7] += w1[3] * hi16(raw[k].w); }
;     float ss = 0.f;
; #pragma unroll
;     for (int e = 0; e < 8; ++e) { a[e] = siluf_(a[e]); ss += a[e] * a[e]; }
;     ss += __shfl_xor(ss, 1); ss += __shfl_xor(ss, 2); ss += __shfl_xor(ss, 4); ss += __shfl_xor(ss, 8);
;     float sc = 1.0f;
;     if (ch < 2048) { sc = rsqrtf(ss + EPS); if (ch < 1024) sc *= 0.08838834764831845f; }
;     u32x4 w; w.x = pk2(a[0] * sc, a[1] * sc); w.y = pk2(a[2] * sc, a[3] * sc); w.z = pk2(a[4] * sc, a[5] * sc); w.w = pk2(a[6] * sc, a[7] * sc);
;     bf16_t* dst = (ch < 1024) ? dq : (ch < 2048 ? dk : dv);
;     *(u32x4*)(dst + (size_t)t * 1024 + (ch & 1023)) = w;
; }
	v_lshlrev_b32_e32 v118, 16, v102
	v_and_b32_e32 v119, 0xffff0000, v102
	v_lshlrev_b32_e32 v120, 16, v103
	v_and_b32_e32 v121, 0xffff0000, v103
	v_lshlrev_b32_e32 v122, 16, v104
	v_and_b32_e32 v123, 0xffff0000, v104
	v_lshlrev_b32_e32 v124, 16, v105
	v_and_b32_e32 v125, 0xffff0000, v105
	global_load_dwordx4 v[102:105], v2, s[16:17]
	s_add_u32 s16, s16, 0x7e00
	s_addc_u32 s17, s17, 0
	v_pk_mul_f32 v[152:153], v[22:23], v[126:127]
	v_pk_mul_f32 v[154:155], v[24:25], v[128:129]
	v_pk_mul_f32 v[156:157], v[26:27], v[130:131]
	v_pk_mul_f32 v[158:159], v[28:29], v[132:133]
	v_pk_fma_f32 v[152:153], v[30:31], v[134:135], v[152:153]
	v_pk_fma_f32 v[154:155], v[32:33], v[136:137], v[154:155]
	v_pk_fma_f32 v[156:157], v[34:35], v[138:139], v[156:157]
	v_pk_fma_f32 v[158:159], v[36:37], v[140:141], v[158:159]
	v_pk_fma_f32 v[152:153], v[38:39], v[110:111], v[152:153]
	v_pk_fma_f32 v[154:155], v[40:41], v[112:113], v[154:155]
	v_pk_fma_f32 v[156:157], v[42:43], v[114:115], v[156:157]
	v_pk_fma_f32 v[158:159], v[44:45], v[116:117], v[158:159]
	v_pk_fma_f32 v[152:153], v[46:47], v[118:119], v[152:153]
	v_pk_fma_f32 v[154:155], v[48:49], v[120:121], v[154:155]
	v_pk_fma_f32 v[156:157], v[50:51], v[122:123], v[156:157]
	v_pk_fma_f32 v[158:159], v[52:53], v[124:125], v[158:159]
	v_pk_mul_f32 v[8:9], v[152:153], s[12:13]
	v_pk_mul_f32 v[10:11], v[154:155], s[12:13]
	v_pk_mul_f32 v[12:13], v[156:157], s[12:13]
	v_pk_mul_f32 v[14:15], v[158:159], s[12:13]
	v_exp_f32_e32 v8, v8
	v_exp_f32_e32 v9, v9
	v_exp_f32_e32 v10, v10
	v_exp_f32_e32 v11, v11
	v_exp_f32_e32 v12, v12
	v_exp_f32_e32 v13, v13
	v_exp_f32_e32 v14, v14
	v_exp_f32_e32 v15, v15
	v_pk_add_f32 v[8:9], v[8:9], s[14:15]
	v_pk_add_f32 v[10:11], v[10:11], s[14:15]
	v_pk_add_f32 v[12:13], v[12:13], s[14:15]
	v_pk_add_f32 v[14:15], v[14:15], s[14:15]
	v_rcp_f32_e32 v8, v8
	v_rcp_f32_e32 v9, v9
	v_rcp_f32_e32 v10, v10
	v_rcp_f32_e32 v11, v11
	v_rcp_f32_e32 v12, v12
	v_rcp_f32_e32 v13, v13
	v_rcp_f32_e32 v14, v14
	v_rcp_f32_e32 v15, v15
	v_pk_mul_f32 v[152:153], v[152:153], v[8:9]
	v_pk_mul_f32 v[154:155], v[154:155], v[10:11]
	v_pk_mul_f32 v[156:157], v[156:157], v[12:13]
	v_pk_mul_f32 v[158:159], v[158:159], v[14:15]
	v_pk_mul_f32 v[8:9], v[152:153], v[152:153]
	v_pk_fma_f32 v[8:9], v[154:155], v[154:155], v[8:9]
	v_pk_fma_f32 v[8:9], v[156:157], v[156:157], v[8:9]
	v_pk_fma_f32 v[8:9], v[158:159], v[158:159], v[8:9]
	s_nop 0
	v_add_f32_e32 v54, v8, v9
	s_nop 1
	v_add_f32_dpp v54, v54, v54 quad_perm:[1,0,3,2] row_mask:0xf bank_mask:0xf
	s_nop 1
	v_add_f32_dpp v54, v54, v54 quad_perm:[2,3,0,1] row_mask:0xf bank_mask:0xf
	s_nop 1
	v_add_f32_dpp v54, v54, v54 row_half_mirror row_mask:0xf bank_mask:0xf
	s_nop 1
	v_add_f32_dpp v54, v54, v54 row_mirror row_mask:0xf bank_mask:0xf
	v_add_f32_e32 v54, 0x358637bd, v54
	v_rsq_f32_e32 v54, v54
	s_nop 0
	v_pk_mul_f32 v[152:153], v[152:153], v[54:55] op_sel_hi:[1,0]
	v_pk_mul_f32 v[154:155], v[154:155], v[54:55] op_sel_hi:[1,0]
	v_pk_mul_f32 v[156:157], v[156:157], v[54:55] op_sel_hi:[1,0]
	v_pk_mul_f32 v[158:159], v[158:159], v[54:55] op_sel_hi:[1,0]
	v_cvt_pk_bf16_f32 v56, v152, v153
	v_cvt_pk_bf16_f32 v57, v154, v155
	v_cvt_pk_bf16_f32 v58, v156, v157
	v_cvt_pk_bf16_f32 v59, v158, v159
	global_store_dwordx4 v5, v[56:59], s[18:19]
	s_add_u32 s18, s18, 0x800
	s_addc_u32 s19, s19, 0
	s_waitcnt vmcnt(18)
	v_lshlrev_b32_e32 v126, 16, v106
	v_and_b32_e32 v127, 0xffff0000, v106
	v_lshlrev_b32_e32 v128, 16, v107
	v_and_b32_e32 v129, 0xffff0000, v107
	v_lshlrev_b32_e32 v130, 16, v108
	v_and_b32_e32 v131, 0xffff0000, v108
	v_lshlrev_b32_e32 v132, 16, v109
	v_and_b32_e32 v133, 0xffff0000, v109
	global_load_dwordx4 v[106:109], v2, s[16:17]
	s_add_u32 s16, s16, 0xad400
	s_addc_u32 s17, s17, 0
	v_pk_mul_f32 v[152:153], v[22:23], v[134:135]
	v_pk_mul_f32 v[154:155], v[24:25], v[136:137]
	v_pk_mul_f32 v[156:157], v[26:27], v[138:139]
	v_pk_mul_f32 v[158:159], v[28:29], v[140:141]
	v_pk_fma_f32 v[152:153], v[30:31], v[110:111], v[152:153]
	v_pk_fma_f32 v[154:155], v[32:33], v[112:113], v[154:155]
	v_pk_fma_f32 v[156:157], v[34:35], v[114:115], v[156:157]
	v_pk_fma_f32 v[158:159], v[36:37], v[116:117], v[158:159]
	v_pk_fma_f32 v[152:153], v[38:39], v[118:119], v[152:153]
	v_pk_fma_f32 v[154:155], v[40:41], v[120:121], v[154:155]
	v_pk_fma_f32 v[156:157], v[42:43], v[122:123], v[156:157]
	v_pk_fma_f32 v[158:159], v[44:45], v[124:125], v[158:159]
	v_pk_fma_f32 v[152:153], v[46:47], v[126:127], v[152:153]
	v_pk_fma_f32 v[154:155], v[48:49], v[128:129], v[154:155]
	v_pk_fma_f32 v[156:157], v[50:51], v[130:131], v[156:157]
	v_pk_fma_f32 v[158:159], v[52:53], v[132:133], v[158:159]
	v_pk_mul_f32 v[8:9], v[152:153], s[12:13]
	v_pk_mul_f32 v[10:11], v[154:155], s[12:13]
	v_pk_mul_f32 v[12:13], v[156:157], s[12:13]
	v_pk_mul_f32 v[14:15], v[158:159], s[12:13]
	v_exp_f32_e32 v8, v8
	v_exp_f32_e32 v9, v9
	v_exp_f32_e32 v10, v10
	v_exp_f32_e32 v11, v11
	v_exp_f32_e32 v12, v12
	v_exp_f32_e32 v13, v13
	v_exp_f32_e32 v14, v14
	v_exp_f32_e32 v15, v15
	v_pk_add_f32 v[8:9], v[8:9], s[14:15]
	v_pk_add_f32 v[10:11], v[10:11], s[14:15]
	v_pk_add_f32 v[12:13], v[12:13], s[14:15]
	v_pk_add_f32 v[14:15], v[14:15], s[14:15]
	v_rcp_f32_e32 v8, v8
	v_rcp_f32_e32 v9, v9
	v_rcp_f32_e32 v10, v10
	v_rcp_f32_e32 v11, v11
	v_rcp_f32_e32 v12, v12
	v_rcp_f32_e32 v13, v13
	v_rcp_f32_e32 v14, v14
	v_rcp_f32_e32 v15, v15
	v_pk_mul_f32 v[152:153], v[152:153], v[8:9]
	v_pk_mul_f32 v[154:155], v[154:155], v[10:11]
	v_pk_mul_f32 v[156:157], v[156:157], v[12:13]
	v_pk_mul_f32 v[158:159], v[158:159], v[14:15]
	v_pk_mul_f32 v[8:9], v[152:153], v[152:153]
	v_pk_fma_f32 v[8:9], v[154:155], v[154:155], v[8:9]
; __device__ __forceinline__ unsigned pk2(float lo, float hi) { const f32v2_t v = {lo, hi}; const bf16v2_t b = __builtin_convertvector(v, bf16v2_t); return __builtin_bit_cast(unsigned, b); }
; __device__ __forceinline__ float lo16(unsigned u) { return __uint_as_float(u << 16); }
; __device__ __forceinline__ float hi16(unsigned u) { return __uint_as_float(u & 0xffff0000u); }
; __device__ __forceinline__ float siluf_(float x) { return x * __builtin_amdgcn_rcpf(1.0f + __expf(-x)); }
; __device__ __forceinline__ void prep_dn_load(const bf16_t* proj, const float* cw, int idx, u32x4 (&raw)[4], int& t, int& ch) {
;     if (idx >= 0) { t = idx / 384; const int j = idx - t * 384; ch = j * 8; }
; #pragma unroll
;     for (int k = 0; k < 4; ++k) { const int tt = t - 3 + k; raw[k] = (u32x4){0u, 0u, 0u, 0u};
;         if (tt >= 0) raw[k] = *(const u32x4*)(proj + (size_t)tt * NP + C_DNQ + ch); }
; }
; __device__ __forceinline__ void prep_dn_finish(const float* cw, bf16_t* dq, bf16_t* dk, bf16_t* dv, const u32x4 (&raw)[4], int t, int ch) {
;     float a[8];
; #pragma unroll
;     for (int e = 0; e < 8; ++e) a[e] = 0.f;
; #pragma unroll
;     for (int k = 0; k < 4; ++k) {
;         const f32x4 w0 = *(const f32x4*)(cw + k * 3072 + ch), w1 = *(const f32x4*)(cw + k * 3072 + ch + 4);
;         a[0] += w0[0] * lo16(raw[k].x); a[1] += w0[1] * hi16(raw[k].x); a[2] += w0[2] * lo16(raw[k].y); a[3] += w0[3] * hi16(raw[k].y);
;         a[4] += w1[0] * lo16(raw[k].z); a[5] += w1[1] * hi16(raw[k].z); a[6] += w1[2] * lo16(raw[k].w); a[7] += w1[3] * hi16(raw[k].w); }
;     float ss = 0.f;
; #pragma unroll
;     for (int e = 0; e < 8; ++e) { a[e] = siluf_(a[e]); ss += a[e] * a[e]; }
;     ss += __shfl_xor(ss, 1); ss += __shfl_xor(ss, 2); ss += __shfl_xor(ss, 4); ss += __shfl_xor(ss, 8);
;     float sc = 1.0f;
;     if (ch < 2048) { sc = rsqrtf(ss + EPS); if (ch < 1024) sc *= 0.08838834764831845f; }
;     u32x4 w; w.x = pk2(a[0] * sc, a[1] * sc); w.y = pk2(a[2] * sc, a[3] * sc); w.z = pk2(a[4] * sc, a[5] * sc); w.w = pk2(a[6] * sc, a[7] * sc);
;     bf16_t* dst = (ch < 1024) ? dq : (ch < 2048 ? dk : dv);
;     *(u32x4*)(dst + (size_t)t * 1024 + (ch & 1023)) = w;
; }
	v_pk_fma_f32 v[8:9], v[156:157], v[156:157], v[8:9]
	v_pk_fma_f32 v[8:9], v[158:159], v[158:159], v[8:9]
	s_nop 0
	v_add_f32_e32 v54, v8, v9
	s_nop 1
	v_add_f32_dpp v54, v54, v54 quad_perm:[1,0,3,2] row_mask:0xf bank_mask:0xf
	s_nop 1
	v_add_f32_dpp v54, v54, v54 quad_perm:[2,3,0,1] row_mask:0xf bank_mask:0xf
	s_nop 1
	v_add_f32_dpp v54, v54, v54 row_half_mirror row_mask:0xf bank_mask:0xf
	s_nop 1
	v_add_f32_dpp v54, v54, v54 row_mirror row_mask:0xf bank_mask:0xf
	v_add_f32_e32 v54, 0x358637bd, v54
	v_rsq_f32_e32 v54, v54
	s_nop 0
	v_pk_mul_f32 v[152:153], v[152:153], v[54:55] op_sel_hi:[1,0]
	v_pk_mul_f32 v[154:155], v[154:155], v[54:55] op_sel_hi:[1,0]
	v_pk_mul_f32 v[156:157], v[156:157], v[54:55] op_sel_hi:[1,0]
	v_pk_mul_f32 v[158:159], v[158:159], v[54:55] op_sel_hi:[1,0]
	v_cvt_pk_bf16_f32 v56, v152, v153
	v_cvt_pk_bf16_f32 v57, v154, v155
	v_cvt_pk_bf16_f32 v58, v156, v157
	v_cvt_pk_bf16_f32 v59, v158, v159
	global_store_dwordx4 v5, v[56:59], s[18:19]
	s_sub_u32 s18, s18, 0x13800
	s_subb_u32 s19, s19, 0
	s_add_u32 vcc_lo, s4, 0x2000
	s_addc_u32 vcc_hi, s5, 0
	global_load_dwordx4 v[22:25], v3, vcc
	global_load_dwordx4 v[26:29], v3, vcc offset:16
	s_add_u32 vcc_lo, s4, 0x5000
	s_addc_u32 vcc_hi, s5, 0
	global_load_dwordx4 v[30:33], v3, vcc
	global_load_dwordx4 v[34:37], v3, vcc offset:16
	s_add_u32 vcc_lo, s4, 0x8000
	s_addc_u32 vcc_hi, s5, 0
	global_load_dwordx4 v[38:41], v3, vcc
	global_load_dwordx4 v[42:45], v3, vcc offset:16
	s_add_u32 vcc_lo, s4, 0xb000
	s_addc_u32 vcc_hi, s5, 0
	global_load_dwordx4 v[46:49], v3, vcc
	global_load_dwordx4 v[50:53], v3, vcc offset:16
	s_waitcnt vmcnt(0)
	s_cmp_lt_i32 s10, 0
	s_cbranch_scc0 .Ldnc2_nz4
	v_mov_b32_e32 v66, 0
	v_mov_b32_e32 v67, 0
	v_mov_b32_e32 v68, 0
	v_mov_b32_e32 v69, 0
	v_mov_b32_e32 v70, 0
	v_mov_b32_e32 v71, 0
	v_mov_b32_e32 v72, 0
	v_mov_b32_e32 v73, 0
	v_mov_b32_e32 v74, 0
	v_mov_b32_e32 v75, 0
	v_mov_b32_e32 v76, 0
	v_mov_b32_e32 v77, 0
.Ldnc2_nz4:
	v_lshlrev_b32_e32 v110, 16, v66
	v_and_b32_e32 v111, 0xffff0000, v66
	v_lshlrev_b32_e32 v112, 16, v67
	v_and_b32_e32 v113, 0xffff0000, v67
	v_lshlrev_b32_e32 v114, 16, v68
	v_and_b32_e32 v115, 0xffff0000, v68
	v_lshlrev_b32_e32 v116, 16, v69
	v_and_b32_e32 v117, 0xffff0000, v69
	v_lshlrev_b32_e32 v118, 16, v70
	v_and_b32_e32 v119, 0xffff0000, v70
	v_lshlrev_b32_e32 v120, 16, v71
	v_and_b32_e32 v121, 0xffff0000, v71
	v_lshlrev_b32_e32 v122, 16, v72
	v_and_b32_e32 v123, 0xffff0000, v72
	v_lshlrev_b32_e32 v124, 16, v73
	v_and_b32_e32 v125, 0xffff0000, v73
	v_lshlrev_b32_e32 v126, 16, v74
	v_and_b32_e32 v127, 0xffff0000, v74
	v_lshlrev_b32_e32 v128, 16, v75
	v_and_b32_e32 v129, 0xffff0000, v75
	v_lshlrev_b32_e32 v130, 16, v76
	v_and_b32_e32 v131, 0xffff0000, v76
	v_lshlrev_b32_e32 v132, 16, v77
	v_and_b32_e32 v133, 0xffff0000, v77
	global_load_dwordx4 v[66:69], v2, s[16:17]
	s_add_u32 s16, s16, 0x7e00
	s_addc_u32 s17, s17, 0
	global_load_dwordx4 v[70:73], v2, s[16:17]
	s_add_u32 s16, s16, 0x7e00
	s_addc_u32 s17, s17, 0
	global_load_dwordx4 v[74:77], v2, s[16:17]
	s_add_u32 s16, s16, 0x7e00
	s_addc_u32 s17, s17, 0
	v_lshlrev_b32_e32 v134, 16, v78
	v_and_b32_e32 v135, 0xffff0000, v78
	v_lshlrev_b32_e32 v136, 16, v79
	v_and_b32_e32 v137, 0xffff0000, v79
	v_lshlrev_b32_e32 v138, 16, v80
	v_and_b32_e32 v139, 0xffff0000, v80
	v_lshlrev_b32_e32 v140, 16, v81
	v_and_b32_e32 v141, 0xffff0000, v81
	global_load_dwordx4 v[78:81], v2, s[16:17]
	s_add_u32 s16, s16, 0x7e00
	s_addc_u32 s17, s17, 0
	v_pk_mul_f32 v[152:153], v[22:23], v[110:111]
	v_pk_mul_f32 v[154:155], v[24:25], v[112:113]
	v_pk_mul_f32 v[156:157], v[26:27], v[114:115]
	v_pk_mul_f32 v[158:159], v[28:29], v[116:117]
	v_pk_fma_f32 v[152:153], v[30:31], v[118:119], v[152:153]
	v_pk_fma_f32 v[154:155], v[32:33], v[120:121], v[154:155]
	v_pk_fma_f32 v[156:157], v[34:35], v[122:123], v[156:157]
	v_pk_fma_f32 v[158:159], v[36:37], v[124:125], v[158:159]
	v_pk_fma_f32 v[152:153], v[38:39], v[126:127], v[152:153]
	v_pk_fma_f32 v[154:155], v[40:41], v[128:129], v[154:155]
	v_pk_fma_f32 v[156:157], v[42:43], v[130:131], v[156:157]
	v_pk_fma_f32 v[158:159], v[44:45], v[132:133], v[158:159]
	v_pk_fma_f32 v[152:153], v[46:47], v[134:135], v[152:153]
	v_pk_fma_f32 v[154:155], v[48:49], v[136:137], v[154:155]
	v_pk_fma_f32 v[156:157], v[50:51], v[138:139], v[156:157]
	v_pk_fma_f32 v[158:159], v[52:53], v[140:141], v[158:159]
	v_pk_mul_f32 v[8:9], v[152:153], s[12:13]
	v_pk_mul_f32 v[10:11], v[154:155], s[12:13]
	v_pk_mul_f32 v[12:13], v[156:157], s[12:13]
	v_pk_mul_f32 v[14:15], v[158:159], s[12:13]
	v_exp_f32_e32 v8, v8
	v_exp_f32_e32 v9, v9
	v_exp_f32_e32 v10, v10
	v_exp_f32_e32 v11, v11
	v_exp_f32_e32 v12, v12
	v_exp_f32_e32 v13, v13
	v_exp_f32_e32 v14, v14
	v_exp_f32_e32 v15, v15
	v_pk_add_f32 v[8:9], v[8:9], s[14:15]
	v_pk_add_f32 v[10:11], v[10:11], s[14:15]
	v_pk_add_f32 v[12:13], v[12:13], s[14:15]
	v_pk_add_f32 v[14:15], v[14:15], s[14:15]
	v_rcp_f32_e32 v8, v8
	v_rcp_f32_e32 v9, v9
	v_rcp_f32_e32 v10, v10
	v_rcp_f32_e32 v11, v11
	v_rcp_f32_e32 v12, v12
	v_rcp_f32_e32 v13, v13
	v_rcp_f32_e32 v14, v14
	v_rcp_f32_e32 v15, v15
	v_pk_mul_f32 v[152:153], v[152:153], v[8:9]
	v_pk_mul_f32 v[154:155], v[154:155], v[10:11]
	v_pk_mul_f32 v[156:157], v[156:157], v[12:13]
	v_pk_mul_f32 v[158:159], v[158:159], v[14:15]
	v_cvt_pk_bf16_f32 v56, v152, v153
	v_cvt_pk_bf16_f32 v57, v154, v155
	v_cvt_pk_bf16_f32 v58, v156, v157
	v_cvt_pk_bf16_f32 v59, v158, v159
	global_store_dwordx4 v6, v[56:59], s[18:19]
	s_add_u32 s18, s18, 0x800
	s_addc_u32 s19, s19, 0
	v_lshlrev_b32_e32 v110, 16, v82
	v_and_b32_e32 v111, 0xffff0000, v82
	v_lshlrev_b32_e32 v112, 16, v83
	v_and_b32_e32 v113, 0xffff0000, v83
; __device__ __forceinline__ unsigned pk2(float lo, float hi) { const f32v2_t v = {lo, hi}; const bf16v2_t b = __builtin_convertvector(v, bf16v2_t); return __builtin_bit_cast(unsigned, b); }
; __device__ __forceinline__ float lo16(unsigned u) { return __uint_as_float(u << 16); }
; __device__ __forceinline__ float hi16(unsigned u) { return __uint_as_float(u & 0xffff0000u); }
; __device__ __forceinline__ float siluf_(float x) { return x * __builtin_amdgcn_rcpf(1.0f + __expf(-x)); }
; __device__ __forceinline__ void prep_dn_load(const bf16_t* proj, const float* cw, int idx, u32x4 (&raw)[4], int& t, int& ch) {
;     ...
;     for (int k = 0; k < 4; ++k) { const int tt = t - 3 + k; raw[k] = (u32x4){0u, 0u, 0u, 0u};
;         if (tt >= 0) raw[k] = *(const u32x4*)(proj + (size_t)tt * NP + C_DNQ + ch); }
; }
; __device__ __forceinline__ void prep_dn_finish(const float* cw, bf16_t* dq, bf16_t* dk, bf16_t* dv, const u32x4 (&raw)[4], int t, int ch) {
;     float a[8];
; #pragma unroll
;     for (int e = 0; e < 8; ++e) a[e] = 0.f;
; #pragma unroll
;     for (int k = 0; k < 4; ++k) {
;         const f32x4 w0 = *(const f32x4*)(cw + k * 3072 + ch), w1 = *(const f32x4*)(cw + k * 3072 + ch + 4);
;         a[0] += w0[0] * lo16(raw[k].x); a[1] += w0[1] * hi16(raw[k].x); a[2] += w0[2] * lo16(raw[k].y); a[3] += w0[3] * hi16(raw[k].y);
;         a[4] += w1[0] * lo16(raw[k].z); a[5] += w1[1] * hi16(raw[k].z); a[6] += w1[2] * lo16(raw[k].w); a[7] += w1[3] * hi16(raw[k].w); }
;     float ss = 0.f;
; #pragma unroll
;     for (int e = 0; e < 8; ++e) { a[e] = siluf_(a[e]); ss += a[e] * a[e]; }
;     ss += __shfl_xor(ss, 1); ss += __shfl_xor(ss, 2); ss += __shfl_xor(ss, 4); ss += __shfl_xor(ss, 8);
;     float sc = 1.0f;
;     if (ch < 2048) { sc = rsqrtf(ss + EPS); if (ch < 1024) sc *= 0.08838834764831845f; }
;     u32x4 w; w.x = pk2(a[0] * sc, a[1] * sc); w.y = pk2(a[2] * sc, a[3] * sc); w.z = pk2(a[4] * sc, a[5] * sc); w.w = pk2(a[6] * sc, a[7] * sc);
;     bf16_t* dst = (ch < 1024) ? dq : (ch < 2048 ? dk : dv);
;     *(u32x4*)(dst + (size_t)t * 1024 + (ch & 1023)) = w;
	v_lshlrev_b32_e32 v114, 16, v84
	v_and_b32_e32 v115, 0xffff0000, v84
	v_lshlrev_b32_e32 v116, 16, v85
	v_and_b32_e32 v117, 0xffff0000, v85
	global_load_dwordx4 v[82:85], v2, s[16:17]
	s_add_u32 s16, s16, 0x7e00
	s_addc_u32 s17, s17, 0
	v_pk_mul_f32 v[152:153], v[22:23], v[118:119]
	v_pk_mul_f32 v[154:155], v[24:25], v[120:121]
	v_pk_mul_f32 v[156:157], v[26:27], v[122:123]
	v_pk_mul_f32 v[158:159], v[28:29], v[124:125]
	v_pk_fma_f32 v[152:153], v[30:31], v[126:127], v[152:153]
	v_pk_fma_f32 v[154:155], v[32:33], v[128:129], v[154:155]
	v_pk_fma_f32 v[156:157], v[34:35], v[130:131], v[156:157]
	v_pk_fma_f32 v[158:159], v[36:37], v[132:133], v[158:159]
	v_pk_fma_f32 v[152:153], v[38:39], v[134:135], v[152:153]
	v_pk_fma_f32 v[154:155], v[40:41], v[136:137], v[154:155]
	v_pk_fma_f32 v[156:157], v[42:43], v[138:139], v[156:157]
	v_pk_fma_f32 v[158:159], v[44:45], v[140:141], v[158:159]
	v_pk_fma_f32 v[152:153], v[46:47], v[110:111], v[152:153]
	v_pk_fma_f32 v[154:155], v[48:49], v[112:113], v[154:155]
	v_pk_fma_f32 v[156:157], v[50:51], v[114:115], v[156:157]
	v_pk_fma_f32 v[158:159], v[52:53], v[116:117], v[158:159]
	v_pk_mul_f32 v[8:9], v[152:153], s[12:13]
	v_pk_mul_f32 v[10:11], v[154:155], s[12:13]
	v_pk_mul_f32 v[12:13], v[156:157], s[12:13]
	v_pk_mul_f32 v[14:15], v[158:159], s[12:13]
	v_exp_f32_e32 v8, v8
	v_exp_f32_e32 v9, v9
	v_exp_f32_e32 v10, v10
	v_exp_f32_e32 v11, v11
	v_exp_f32_e32 v12, v12
	v_exp_f32_e32 v13, v13
	v_exp_f32_e32 v14, v14
	v_exp_f32_e32 v15, v15
	v_pk_add_f32 v[8:9], v[8:9], s[14:15]
	v_pk_add_f32 v[10:11], v[10:11], s[14:15]
	v_pk_add_f32 v[12:13], v[12:13], s[14:15]
	v_pk_add_f32 v[14:15], v[14:15], s[14:15]
	v_rcp_f32_e32 v8, v8
	v_rcp_f32_e32 v9, v9
	v_rcp_f32_e32 v10, v10
	v_rcp_f32_e32 v11, v11
	v_rcp_f32_e32 v12, v12
	v_rcp_f32_e32 v13, v13
	v_rcp_f32_e32 v14, v14
	v_rcp_f32_e32 v15, v15
	v_pk_mul_f32 v[152:153], v[152:153], v[8:9]
	v_pk_mul_f32 v[154:155], v[154:155], v[10:11]
	v_pk_mul_f32 v[156:157], v[156:157], v[12:13]
	v_pk_mul_f32 v[158:159], v[158:159], v[14:15]
	v_cvt_pk_bf16_f32 v56, v152, v153
	v_cvt_pk_bf16_f32 v57, v154, v155
	v_cvt_pk_bf16_f32 v58, v156, v157
	v_cvt_pk_bf16_f32 v59, v158, v159
	global_store_dwordx4 v6, v[56:59], s[18:19]
	s_add_u32 s18, s18, 0x800
	s_addc_u32 s19, s19, 0
	v_lshlrev_b32_e32 v118, 16, v86
	v_and_b32_e32 v119, 0xffff0000, v86
	v_lshlrev_b32_e32 v120, 16, v87
	v_and_b32_e32 v121, 0xffff0000, v87
	v_lshlrev_b32_e32 v122, 16, v88
	v_and_b32_e32 v123, 0xffff0000, v88
	v_lshlrev_b32_e32 v124, 16, v89
	v_and_b32_e32 v125, 0xffff0000, v89
	global_load_dwordx4 v[86:89], v2, s[16:17]
	s_add_u32 s16, s16, 0x7e00
	s_addc_u32 s17, s17, 0
	v_pk_mul_f32 v[152:153], v[22:23], v[126:127]
	v_pk_mul_f32 v[154:155], v[24:25], v[128:129]
	v_pk_mul_f32 v[156:157], v[26:27], v[130:131]
	v_pk_mul_f32 v[158:159], v[28:29], v[132:133]
	v_pk_fma_f32 v[152:153], v[30:31], v[134:135], v[152:153]
	v_pk_fma_f32 v[154:155], v[32:33], v[136:137], v[154:155]
	v_pk_fma_f32 v[156:157], v[34:35], v[138:139], v[156:157]
	v_pk_fma_f32 v[158:159], v[36:37], v[140:141], v[158:159]
	v_pk_fma_f32 v[152:153], v[38:39], v[110:111], v[152:153]
	v_pk_fma_f32 v[154:155], v[40:41], v[112:113], v[154:155]
	v_pk_fma_f32 v[156:157], v[42:43], v[114:115], v[156:157]
	v_pk_fma_f32 v[158:159], v[44:45], v[116:117], v[158:159]
	v_pk_fma_f32 v[152:153], v[46:47], v[118:119], v[152:153]
	v_pk_fma_f32 v[154:155], v[48:49], v[120:121], v[154:155]
	v_pk_fma_f32 v[156:157], v[50:51], v[122:123], v[156:157]
	v_pk_fma_f32 v[158:159], v[52:53], v[124:125], v[158:159]
	v_pk_mul_f32 v[8:9], v[152:153], s[12:13]
	v_pk_mul_f32 v[10:11], v[154:155], s[12:13]
	v_pk_mul_f32 v[12:13], v[156:157], s[12:13]
	v_pk_mul_f32 v[14:15], v[158:159], s[12:13]
	v_exp_f32_e32 v8, v8
	v_exp_f32_e32 v9, v9
	v_exp_f32_e32 v10, v10
	v_exp_f32_e32 v11, v11
	v_exp_f32_e32 v12, v12
	v_exp_f32_e32 v13, v13
	v_exp_f32_e32 v14, v14
	v_exp_f32_e32 v15, v15
	v_pk_add_f32 v[8:9], v[8:9], s[14:15]
	v_pk_add_f32 v[10:11], v[10:11], s[14:15]
	v_pk_add_f32 v[12:13], v[12:13], s[14:15]
	v_pk_add_f32 v[14:15], v[14:15], s[14:15]
	v_rcp_f32_e32 v8, v8
	v_rcp_f32_e32 v9, v9
	v_rcp_f32_e32 v10, v10
	v_rcp_f32_e32 v11, v11
	v_rcp_f32_e32 v12, v12
	v_rcp_f32_e32 v13, v13
	v_rcp_f32_e32 v14, v14
	v_rcp_f32_e32 v15, v15
	v_pk_mul_f32 v[152:153], v[152:153], v[8:9]
	v_pk_mul_f32 v[154:155], v[154:155], v[10:11]
	v_pk_mul_f32 v[156:157], v[156:157], v[12:13]
	v_pk_mul_f32 v[158:159], v[158:159], v[14:15]
	v_cvt_pk_bf16_f32 v56, v152, v153
	v_cvt_pk_bf16_f32 v57, v154, v155
	v_cvt_pk_bf16_f32 v58, v156, v157
	v_cvt_pk_bf16_f32 v59, v158, v159
	global_store_dwordx4 v6, v[56:59], s[18:19]
	s_add_u32 s18, s18, 0x800
	s_addc_u32 s19, s19, 0
	v_lshlrev_b32_e32 v126, 16, v90
	v_and_b32_e32 v127, 0xffff0000, v90
	v_lshlrev_b32_e32 v128, 16, v91
	v_and_b32_e32 v129, 0xffff0000, v91
	v_lshlrev_b32_e32 v130, 16, v92
	v_and_b32_e32 v131, 0xffff0000, v92
	v_lshlrev_b32_e32 v132, 16, v93
	v_and_b32_e32 v133, 0xffff0000, v93
	global_load_dwordx4 v[90:93], v2, s[16:17]
	s_add_u32 s16, s16, 0x7e00
	s_addc_u32 s17, s17, 0
	v_pk_mul_f32 v[152:153], v[22:23], v[134:135]
	v_pk_mul_f32 v[154:155], v[24:25], v[136:137]
	v_pk_mul_f32 v[156:157], v[26:27], v[138:139]
	v_pk_mul_f32 v[158:159], v[28:29], v[140:141]
	v_pk_fma_f32 v[152:153], v[30:31], v[110:111], v[152:153]
	v_pk_fma_f32 v[154:155], v[32:33], v[112:113], v[154:155]
	v_pk_fma_f32 v[156:157], v[34:35], v[114:115], v[156:157]
	v_pk_fma_f32 v[158:159], v[36:37], v[116:117], v[158:159]
	v_pk_fma_f32 v[152:153], v[38:39], v[118:119], v[152:153]
	v_pk_fma_f32 v[154:155], v[40:41], v[120:121], v[154:155]
	v_pk_fma_f32 v[156:157], v[42:43], v[122:123], v[156:157]
; __device__ __forceinline__ unsigned pk2(float lo, float hi) { const f32v2_t v = {lo, hi}; const bf16v2_t b = __builtin_convertvector(v, bf16v2_t); return __builtin_bit_cast(unsigned, b); }
; __device__ __forceinline__ float lo16(unsigned u) { return __uint_as_float(u << 16); }
; __device__ __forceinline__ float hi16(unsigned u) { return __uint_as_float(u & 0xffff0000u); }
; __device__ __forceinline__ float siluf_(float x) { return x * __builtin_amdgcn_rcpf(1.0f + __expf(-x)); }
; __device__ __forceinline__ void prep_dn_load(const bf16_t* proj, const float* cw, int idx, u32x4 (&raw)[4], int& t, int& ch) {
;     ...
;     for (int k = 0; k < 4; ++k) { const int tt = t - 3 + k; raw[k] = (u32x4){0u, 0u, 0u, 0u};
;         if (tt >= 0) raw[k] = *(const u32x4*)(proj + (size_t)tt * NP + C_DNQ + ch); }
; }
; __device__ __forceinline__ void prep_dn_finish(const float* cw, bf16_t* dq, bf16_t* dk, bf16_t* dv, const u32x4 (&raw)[4], int t, int ch) {
;     float a[8];
; #pragma unroll
;     for (int e = 0; e < 8; ++e) a[e] = 0.f;
; #pragma unroll
;     for (int k = 0; k < 4; ++k) {
;         const f32x4 w0 = *(const f32x4*)(cw + k * 3072 + ch), w1 = *(const f32x4*)(cw + k * 3072 + ch + 4);
;         a[0] += w0[0] * lo16(raw[k].x); a[1] += w0[1] * hi16(raw[k].x); a[2] += w0[2] * lo16(raw[k].y); a[3] += w0[3] * hi16(raw[k].y);
;         a[4] += w1[0] * lo16(raw[k].z); a[5] += w1[1] * hi16(raw[k].z); a[6] += w1[2] * lo16(raw[k].w); a[7] += w1[3] * hi16(raw[k].w); }
;     float ss = 0.f;
; #pragma unroll
;     for (int e = 0; e < 8; ++e) { a[e] = siluf_(a[e]); ss += a[e] * a[e]; }
;     ss += __shfl_xor(ss, 1); ss += __shfl_xor(ss, 2); ss += __shfl_xor(ss, 4); ss += __shfl_xor(ss, 8);
;     float sc = 1.0f;
;     if (ch < 2048) { sc = rsqrtf(ss + EPS); if (ch < 1024) sc *= 0.08838834764831845f; }
;     u32x4 w; w.x = pk2(a[0] * sc, a[1] * sc); w.y = pk2(a[2] * sc, a[3] * sc); w.z = pk2(a[4] * sc, a[5] * sc); w.w = pk2(a[6] * sc, a[7] * sc);
;     bf16_t* dst = (ch < 1024) ? dq : (ch < 2048 ? dk : dv);
;     *(u32x4*)(dst + (size_t)t * 1024 + (ch & 1023)) = w;
	v_pk_fma_f32 v[158:159], v[44:45], v[124:125], v[158:159]
	v_pk_fma_f32 v[152:153], v[46:47], v[126:127], v[152:153]
	v_pk_fma_f32 v[154:155], v[48:49], v[128:129], v[154:155]
	v_pk_fma_f32 v[156:157], v[50:51], v[130:131], v[156:157]
	v_pk_fma_f32 v[158:159], v[52:53], v[132:133], v[158:159]
	v_pk_mul_f32 v[8:9], v[152:153], s[12:13]
	v_pk_mul_f32 v[10:11], v[154:155], s[12:13]
	v_pk_mul_f32 v[12:13], v[156:157], s[12:13]
	v_pk_mul_f32 v[14:15], v[158:159], s[12:13]
	v_exp_f32_e32 v8, v8
	v_exp_f32_e32 v9, v9
	v_exp_f32_e32 v10, v10
	v_exp_f32_e32 v11, v11
	v_exp_f32_e32 v12, v12
	v_exp_f32_e32 v13, v13
	v_exp_f32_e32 v14, v14
	v_exp_f32_e32 v15, v15
	v_pk_add_f32 v[8:9], v[8:9], s[14:15]
	v_pk_add_f32 v[10:11], v[10:11], s[14:15]
	v_pk_add_f32 v[12:13], v[12:13], s[14:15]
	v_pk_add_f32 v[14:15], v[14:15], s[14:15]
	v_rcp_f32_e32 v8, v8
	v_rcp_f32_e32 v9, v9
	v_rcp_f32_e32 v10, v10
	v_rcp_f32_e32 v11, v11
	v_rcp_f32_e32 v12, v12
	v_rcp_f32_e32 v13, v13
	v_rcp_f32_e32 v14, v14
	v_rcp_f32_e32 v15, v15
	v_pk_mul_f32 v[152:153], v[152:153], v[8:9]
	v_pk_mul_f32 v[154:155], v[154:155], v[10:11]
	v_pk_mul_f32 v[156:157], v[156:157], v[12:13]
	v_pk_mul_f32 v[158:159], v[158:159], v[14:15]
	v_cvt_pk_bf16_f32 v56, v152, v153
	v_cvt_pk_bf16_f32 v57, v154, v155
	v_cvt_pk_bf16_f32 v58, v156, v157
	v_cvt_pk_bf16_f32 v59, v158, v159
	global_store_dwordx4 v6, v[56:59], s[18:19]
	s_add_u32 s18, s18, 0x800
	s_addc_u32 s19, s19, 0
	v_lshlrev_b32_e32 v134, 16, v94
	v_and_b32_e32 v135, 0xffff0000, v94
	v_lshlrev_b32_e32 v136, 16, v95
	v_and_b32_e32 v137, 0xffff0000, v95
	v_lshlrev_b32_e32 v138, 16, v96
	v_and_b32_e32 v139, 0xffff0000, v96
	v_lshlrev_b32_e32 v140, 16, v97
	v_and_b32_e32 v141, 0xffff0000, v97
	global_load_dwordx4 v[94:97], v2, s[16:17]
	s_add_u32 s16, s16, 0x7e00
	s_addc_u32 s17, s17, 0
	v_pk_mul_f32 v[152:153], v[22:23], v[110:111]
	v_pk_mul_f32 v[154:155], v[24:25], v[112:113]
	v_pk_mul_f32 v[156:157], v[26:27], v[114:115]
	v_pk_mul_f32 v[158:159], v[28:29], v[116:117]
	v_pk_fma_f32 v[152:153], v[30:31], v[118:119], v[152:153]
	v_pk_fma_f32 v[154:155], v[32:33], v[120:121], v[154:155]
	v_pk_fma_f32 v[156:157], v[34:35], v[122:123], v[156:157]
	v_pk_fma_f32 v[158:159], v[36:37], v[124:125], v[158:159]
	v_pk_fma_f32 v[152:153], v[38:39], v[126:127], v[152:153]
	v_pk_fma_f32 v[154:155], v[40:41], v[128:129], v[154:155]
	v_pk_fma_f32 v[156:157], v[42:43], v[130:131], v[156:157]
	v_pk_fma_f32 v[158:159], v[44:45], v[132:133], v[158:159]
	v_pk_fma_f32 v[152:153], v[46:47], v[134:135], v[152:153]
	v_pk_fma_f32 v[154:155], v[48:49], v[136:137], v[154:155]
	v_pk_fma_f32 v[156:157], v[50:51], v[138:139], v[156:157]
	v_pk_fma_f32 v[158:159], v[52:53], v[140:141], v[158:159]
	v_pk_mul_f32 v[8:9], v[152:153], s[12:13]
	v_pk_mul_f32 v[10:11], v[154:155], s[12:13]
	v_pk_mul_f32 v[12:13], v[156:157], s[12:13]
	v_pk_mul_f32 v[14:15], v[158:159], s[12:13]
	v_exp_f32_e32 v8, v8
	v_exp_f32_e32 v9, v9
	v_exp_f32_e32 v10, v10
	v_exp_f32_e32 v11, v11
	v_exp_f32_e32 v12, v12
	v_exp_f32_e32 v13, v13
	v_exp_f32_e32 v14, v14
	v_exp_f32_e32 v15, v15
	v_pk_add_f32 v[8:9], v[8:9], s[14:15]
	v_pk_add_f32 v[10:11], v[10:11], s[14:15]
	v_pk_add_f32 v[12:13], v[12:13], s[14:15]
	v_pk_add_f32 v[14:15], v[14:15], s[14:15]
	v_rcp_f32_e32 v8, v8
	v_rcp_f32_e32 v9, v9
	v_rcp_f32_e32 v10, v10
	v_rcp_f32_e32 v11, v11
	v_rcp_f32_e32 v12, v12
	v_rcp_f32_e32 v13, v13
	v_rcp_f32_e32 v14, v14
	v_rcp_f32_e32 v15, v15
	v_pk_mul_f32 v[152:153], v[152:153], v[8:9]
	v_pk_mul_f32 v[154:155], v[154:155], v[10:11]
	v_pk_mul_f32 v[156:157], v[156:157], v[12:13]
	v_pk_mul_f32 v[158:159], v[158:159], v[14:15]
	v_cvt_pk_bf16_f32 v56, v152, v153
	v_cvt_pk_bf16_f32 v57, v154, v155
	v_cvt_pk_bf16_f32 v58, v156, v157
	v_cvt_pk_bf16_f32 v59, v158, v159
	global_store_dwordx4 v6, v[56:59], s[18:19]
	s_add_u32 s18, s18, 0x800
	s_addc_u32 s19, s19, 0
	v_lshlrev_b32_e32 v110, 16, v98
	v_and_b32_e32 v111, 0xffff0000, v98
	v_lshlrev_b32_e32 v112, 16, v99
	v_and_b32_e32 v113, 0xffff0000, v99
	v_lshlrev_b32_e32 v114, 16, v100
	v_and_b32_e32 v115, 0xffff0000, v100
	v_lshlrev_b32_e32 v116, 16, v101
	v_and_b32_e32 v117, 0xffff0000, v101
	global_load_dwordx4 v[98:101], v2, s[16:17]
	s_add_u32 s16, s16, 0x7e00
	s_addc_u32 s17, s17, 0
	v_pk_mul_f32 v[152:153], v[22:23], v[118:119]
	v_pk_mul_f32 v[154:155], v[24:25], v[120:121]
	v_pk_mul_f32 v[156:157], v[26:27], v[122:123]
	v_pk_mul_f32 v[158:159], v[28:29], v[124:125]
	v_pk_fma_f32 v[152:153], v[30:31], v[126:127], v[152:153]
	v_pk_fma_f32 v[154:155], v[32:33], v[128:129], v[154:155]
	v_pk_fma_f32 v[156:157], v[34:35], v[130:131], v[156:157]
	v_pk_fma_f32 v[158:159], v[36:37], v[132:133], v[158:159]
	v_pk_fma_f32 v[152:153], v[38:39], v[134:135], v[152:153]
	v_pk_fma_f32 v[154:155], v[40:41], v[136:137], v[154:155]
	v_pk_fma_f32 v[156:157], v[42:43], v[138:139], v[156:157]
	v_pk_fma_f32 v[158:159], v[44:45], v[140:141], v[158:159]
	v_pk_fma_f32 v[152:153], v[46:47], v[110:111], v[152:153]
	v_pk_fma_f32 v[154:155], v[48:49], v[112:113], v[154:155]
	v_pk_fma_f32 v[156:157], v[50:51], v[114:115], v[156:157]
	v_pk_fma_f32 v[158:159], v[52:53], v[116:117], v[158:159]
	v_pk_mul_f32 v[8:9], v[152:153], s[12:13]
	v_pk_mul_f32 v[10:11], v[154:155], s[12:13]
	v_pk_mul_f32 v[12:13], v[156:157], s[12:13]
	v_pk_mul_f32 v[14:15], v[158:159], s[12:13]
	v_exp_f32_e32 v8, v8
	v_exp_f32_e32 v9, v9
	v_exp_f32_e32 v10, v10
	v_exp_f32_e32 v11, v11
	v_exp_f32_e32 v12, v12
	v_exp_f32_e32 v13, v13
	v_exp_f32_e32 v14, v14
	v_exp_f32_e32 v15, v15
	v_pk_add_f32 v[8:9], v[8:9], s[14:15]
	v_pk_add_f32 v[10:11], v[10:11], s[14:15]
	v_pk_add_f32 v[12:13], v[12:13], s[14:15]
; __device__ __forceinline__ unsigned pk2(float lo, float hi) { const f32v2_t v = {lo, hi}; const bf16v2_t b = __builtin_convertvector(v, bf16v2_t); return __builtin_bit_cast(unsigned, b); }
; __device__ __forceinline__ float lo16(unsigned u) { return __uint_as_float(u << 16); }
; __device__ __forceinline__ float hi16(unsigned u) { return __uint_as_float(u & 0xffff0000u); }
; __device__ __forceinline__ float siluf_(float x) { return x * __builtin_amdgcn_rcpf(1.0f + __expf(-x)); }
; __device__ __forceinline__ void prep_dn_load(const bf16_t* proj, const float* cw, int idx, u32x4 (&raw)[4], int& t, int& ch) {
;     ...
;     for (int k = 0; k < 4; ++k) { const int tt = t - 3 + k; raw[k] = (u32x4){0u, 0u, 0u, 0u};
;         if (tt >= 0) raw[k] = *(const u32x4*)(proj + (size_t)tt * NP + C_DNQ + ch); }
; }
; __device__ __forceinline__ void prep_dn_finish(const float* cw, bf16_t* dq, bf16_t* dk, bf16_t* dv, const u32x4 (&raw)[4], int t, int ch) {
;     float a[8];
; #pragma unroll
;     for (int e = 0; e < 8; ++e) a[e] = 0.f;
; #pragma unroll
;     for (int k = 0; k < 4; ++k) {
;         const f32x4 w0 = *(const f32x4*)(cw + k * 3072 + ch), w1 = *(const f32x4*)(cw + k * 3072 + ch + 4);
;         a[0] += w0[0] * lo16(raw[k].x); a[1] += w0[1] * hi16(raw[k].x); a[2] += w0[2] * lo16(raw[k].y); a[3] += w0[3] * hi16(raw[k].y);
;         a[4] += w1[0] * lo16(raw[k].z); a[5] += w1[1] * hi16(raw[k].z); a[6] += w1[2] * lo16(raw[k].w); a[7] += w1[3] * hi16(raw[k].w); }
;     float ss = 0.f;
; #pragma unroll
;     for (int e = 0; e < 8; ++e) { a[e] = siluf_(a[e]); ss += a[e] * a[e]; }
;     ss += __shfl_xor(ss, 1); ss += __shfl_xor(ss, 2); ss += __shfl_xor(ss, 4); ss += __shfl_xor(ss, 8);
;     float sc = 1.0f;
;     if (ch < 2048) { sc = rsqrtf(ss + EPS); if (ch < 1024) sc *= 0.08838834764831845f; }
;     u32x4 w; w.x = pk2(a[0] * sc, a[1] * sc); w.y = pk2(a[2] * sc, a[3] * sc); w.z = pk2(a[4] * sc, a[5] * sc); w.w = pk2(a[6] * sc, a[7] * sc);
;     bf16_t* dst = (ch < 1024) ? dq : (ch < 2048 ? dk : dv);
;     *(u32x4*)(dst + (size_t)t * 1024 + (ch & 1023)) = w;
	v_pk_add_f32 v[14:15], v[14:15], s[14:15]
	v_rcp_f32_e32 v8, v8
	v_rcp_f32_e32 v9, v9
	v_rcp_f32_e32 v10, v10
	v_rcp_f32_e32 v11, v11
	v_rcp_f32_e32 v12, v12
	v_rcp_f32_e32 v13, v13
	v_rcp_f32_e32 v14, v14
	v_rcp_f32_e32 v15, v15
	v_pk_mul_f32 v[152:153], v[152:153], v[8:9]
	v_pk_mul_f32 v[154:155], v[154:155], v[10:11]
	v_pk_mul_f32 v[156:157], v[156:157], v[12:13]
	v_pk_mul_f32 v[158:159], v[158:159], v[14:15]
	v_cvt_pk_bf16_f32 v56, v152, v153
	v_cvt_pk_bf16_f32 v57, v154, v155
	v_cvt_pk_bf16_f32 v58, v156, v157
	v_cvt_pk_bf16_f32 v59, v158, v159
	global_store_dwordx4 v6, v[56:59], s[18:19]
	s_add_u32 s18, s18, 0x800
	s_addc_u32 s19, s19, 0
	v_lshlrev_b32_e32 v118, 16, v102
	v_and_b32_e32 v119, 0xffff0000, v102
	v_lshlrev_b32_e32 v120, 16, v103
	v_and_b32_e32 v121, 0xffff0000, v103
	v_lshlrev_b32_e32 v122, 16, v104
	v_and_b32_e32 v123, 0xffff0000, v104
	v_lshlrev_b32_e32 v124, 16, v105
	v_and_b32_e32 v125, 0xffff0000, v105
	global_load_dwordx4 v[102:105], v2, s[16:17]
	s_add_u32 s16, s16, 0x7e00
	s_addc_u32 s17, s17, 0
	v_pk_mul_f32 v[152:153], v[22:23], v[126:127]
	v_pk_mul_f32 v[154:155], v[24:25], v[128:129]
	v_pk_mul_f32 v[156:157], v[26:27], v[130:131]
	v_pk_mul_f32 v[158:159], v[28:29], v[132:133]
	v_pk_fma_f32 v[152:153], v[30:31], v[134:135], v[152:153]
	v_pk_fma_f32 v[154:155], v[32:33], v[136:137], v[154:155]
	v_pk_fma_f32 v[156:157], v[34:35], v[138:139], v[156:157]
	v_pk_fma_f32 v[158:159], v[36:37], v[140:141], v[158:159]
	v_pk_fma_f32 v[152:153], v[38:39], v[110:111], v[152:153]
	v_pk_fma_f32 v[154:155], v[40:41], v[112:113], v[154:155]
	v_pk_fma_f32 v[156:157], v[42:43], v[114:115], v[156:157]
	v_pk_fma_f32 v[158:159], v[44:45], v[116:117], v[158:159]
	v_pk_fma_f32 v[152:153], v[46:47], v[118:119], v[152:153]
	v_pk_fma_f32 v[154:155], v[48:49], v[120:121], v[154:155]
	v_pk_fma_f32 v[156:157], v[50:51], v[122:123], v[156:157]
	v_pk_fma_f32 v[158:159], v[52:53], v[124:125], v[158:159]
	v_pk_mul_f32 v[8:9], v[152:153], s[12:13]
	v_pk_mul_f32 v[10:11], v[154:155], s[12:13]
	v_pk_mul_f32 v[12:13], v[156:157], s[12:13]
	v_pk_mul_f32 v[14:15], v[158:159], s[12:13]
	v_exp_f32_e32 v8, v8
	v_exp_f32_e32 v9, v9
	v_exp_f32_e32 v10, v10
	v_exp_f32_e32 v11, v11
	v_exp_f32_e32 v12, v12
	v_exp_f32_e32 v13, v13
	v_exp_f32_e32 v14, v14
	v_exp_f32_e32 v15, v15
	v_pk_add_f32 v[8:9], v[8:9], s[14:15]
	v_pk_add_f32 v[10:11], v[10:11], s[14:15]
	v_pk_add_f32 v[12:13], v[12:13], s[14:15]
	v_pk_add_f32 v[14:15], v[14:15], s[14:15]
	v_rcp_f32_e32 v8, v8
	v_rcp_f32_e32 v9, v9
	v_rcp_f32_e32 v10, v10
	v_rcp_f32_e32 v11, v11
	v_rcp_f32_e32 v12, v12
	v_rcp_f32_e32 v13, v13
	v_rcp_f32_e32 v14, v14
	v_rcp_f32_e32 v15, v15
	v_pk_mul_f32 v[152:153], v[152:153], v[8:9]
	v_pk_mul_f32 v[154:155], v[154:155], v[10:11]
	v_pk_mul_f32 v[156:157], v[156:157], v[12:13]
	v_pk_mul_f32 v[158:159], v[158:159], v[14:15]
	v_cvt_pk_bf16_f32 v56, v152, v153
	v_cvt_pk_bf16_f32 v57, v154, v155
	v_cvt_pk_bf16_f32 v58, v156, v157
	v_cvt_pk_bf16_f32 v59, v158, v159
	global_store_dwordx4 v6, v[56:59], s[18:19]
	s_add_u32 s18, s18, 0x800
	s_addc_u32 s19, s19, 0
	v_lshlrev_b32_e32 v126, 16, v106
	v_and_b32_e32 v127, 0xffff0000, v106
	v_lshlrev_b32_e32 v128, 16, v107
	v_and_b32_e32 v129, 0xffff0000, v107
	v_lshlrev_b32_e32 v130, 16, v108
	v_and_b32_e32 v131, 0xffff0000, v108
	v_lshlrev_b32_e32 v132, 16, v109
	v_and_b32_e32 v133, 0xffff0000, v109
	global_load_dwordx4 v[106:109], v2, s[16:17]
	v_pk_mul_f32 v[152:153], v[22:23], v[134:135]
	v_pk_mul_f32 v[154:155], v[24:25], v[136:137]
	v_pk_mul_f32 v[156:157], v[26:27], v[138:139]
	v_pk_mul_f32 v[158:159], v[28:29], v[140:141]
	v_pk_fma_f32 v[152:153], v[30:31], v[110:111], v[152:153]
	v_pk_fma_f32 v[154:155], v[32:33], v[112:113], v[154:155]
	v_pk_fma_f32 v[156:157], v[34:35], v[114:115], v[156:157]
	v_pk_fma_f32 v[158:159], v[36:37], v[116:117], v[158:159]
	v_pk_fma_f32 v[152:153], v[38:39], v[118:119], v[152:153]
	v_pk_fma_f32 v[154:155], v[40:41], v[120:121], v[154:155]
	v_pk_fma_f32 v[156:157], v[42:43], v[122:123], v[156:157]
	v_pk_fma_f32 v[158:159], v[44:45], v[124:125], v[158:159]
	v_pk_fma_f32 v[152:153], v[46:47], v[126:127], v[152:153]
	v_pk_fma_f32 v[154:155], v[48:49], v[128:129], v[154:155]
	v_pk_fma_f32 v[156:157], v[50:51], v[130:131], v[156:157]
	v_pk_fma_f32 v[158:159], v[52:53], v[132:133], v[158:159]
	v_pk_mul_f32 v[8:9], v[152:153], s[12:13]
	v_pk_mul_f32 v[10:11], v[154:155], s[12:13]
	v_pk_mul_f32 v[12:13], v[156:157], s[12:13]
	v_pk_mul_f32 v[14:15], v[158:159], s[12:13]
	v_exp_f32_e32 v8, v8
	v_exp_f32_e32 v9, v9
	v_exp_f32_e32 v10, v10
	v_exp_f32_e32 v11, v11
	v_exp_f32_e32 v12, v12
	v_exp_f32_e32 v13, v13
	v_exp_f32_e32 v14, v14
	v_exp_f32_e32 v15, v15
	v_pk_add_f32 v[8:9], v[8:9], s[14:15]
	v_pk_add_f32 v[10:11], v[10:11], s[14:15]
	v_pk_add_f32 v[12:13], v[12:13], s[14:15]
	v_pk_add_f32 v[14:15], v[14:15], s[14:15]
	v_rcp_f32_e32 v8, v8
	v_rcp_f32_e32 v9, v9
	v_rcp_f32_e32 v10, v10
	v_rcp_f32_e32 v11, v11
	v_rcp_f32_e32 v12, v12
	v_rcp_f32_e32 v13, v13
	v_rcp_f32_e32 v14, v14
	v_rcp_f32_e32 v15, v15
	v_pk_mul_f32 v[152:153], v[152:153], v[8:9]
	v_pk_mul_f32 v[154:155], v[154:155], v[10:11]
	v_pk_mul_f32 v[156:157], v[156:157], v[12:13]
	v_pk_mul_f32 v[158:159], v[158:159], v[14:15]
	v_cvt_pk_bf16_f32 v56, v152, v153
	v_cvt_pk_bf16_f32 v57, v154, v155
	v_cvt_pk_bf16_f32 v58, v156, v157
	v_cvt_pk_bf16_f32 v59, v158, v159
	global_store_dwordx4 v6, v[56:59], s[18:19]
	s_add_u32 s18, s18, 0xc800
	s_addc_u32 s19, s19, 0
	s_waitcnt vmcnt(16)
; __device__ __forceinline__ unsigned pk2(float lo, float hi) { const f32v2_t v = {lo, hi}; const bf16v2_t b = __builtin_convertvector(v, bf16v2_t); return __builtin_bit_cast(unsigned, b); }
; __device__ __forceinline__ float lo16(unsigned u) { return __uint_as_float(u << 16); }
; __device__ __forceinline__ float hi16(unsigned u) { return __uint_as_float(u & 0xffff0000u); }
; __device__ __forceinline__ float siluf_(float x) { return x * __builtin_amdgcn_rcpf(1.0f + __expf(-x)); }
; __device__ __forceinline__ void prep_dn_load(const bf16_t* proj, const float* cw, int idx, u32x4 (&raw)[4], int& t, int& ch) {
;     ...
;     for (int k = 0; k < 4; ++k) { const int tt = t - 3 + k; raw[k] = (u32x4){0u, 0u, 0u, 0u};
;         if (tt >= 0) raw[k] = *(const u32x4*)(proj + (size_t)tt * NP + C_DNQ + ch); }
; }
; __device__ __forceinline__ void prep_dn_finish(const float* cw, bf16_t* dq, bf16_t* dk, bf16_t* dv, const u32x4 (&raw)[4], int t, int ch) {
;     float a[8];
; #pragma unroll
;     for (int e = 0; e < 8; ++e) a[e] = 0.f;
; #pragma unroll
;     for (int k = 0; k < 4; ++k) {
;         const f32x4 w0 = *(const f32x4*)(cw + k * 3072 + ch), w1 = *(const f32x4*)(cw + k * 3072 + ch + 4);
;         a[0] += w0[0] * lo16(raw[k].x); a[1] += w0[1] * hi16(raw[k].x); a[2] += w0[2] * lo16(raw[k].y); a[3] += w0[3] * hi16(raw[k].y);
;         a[4] += w1[0] * lo16(raw[k].z); a[5] += w1[1] * hi16(raw[k].z); a[6] += w1[2] * lo16(raw[k].w); a[7] += w1[3] * hi16(raw[k].w); }
;     float ss = 0.f;
; #pragma unroll
;     for (int e = 0; e < 8; ++e) { a[e] = siluf_(a[e]); ss += a[e] * a[e]; }
;     ss += __shfl_xor(ss, 1); ss += __shfl_xor(ss, 2); ss += __shfl_xor(ss, 4); ss += __shfl_xor(ss, 8);
;     float sc = 1.0f;
;     if (ch < 2048) { sc = rsqrtf(ss + EPS); if (ch < 1024) sc *= 0.08838834764831845f; }
;     u32x4 w; w.x = pk2(a[0] * sc, a[1] * sc); w.y = pk2(a[2] * sc, a[3] * sc); w.z = pk2(a[4] * sc, a[5] * sc); w.w = pk2(a[6] * sc, a[7] * sc);
;     bf16_t* dst = (ch < 1024) ? dq : (ch < 2048 ? dk : dv);
;     *(u32x4*)(dst + (size_t)t * 1024 + (ch & 1023)) = w;
	v_lshlrev_b32_e32 v110, 16, v66
	v_and_b32_e32 v111, 0xffff0000, v66
	v_lshlrev_b32_e32 v112, 16, v67
	v_and_b32_e32 v113, 0xffff0000, v67
	v_lshlrev_b32_e32 v114, 16, v68
	v_and_b32_e32 v115, 0xffff0000, v68
	v_lshlrev_b32_e32 v116, 16, v69
	v_and_b32_e32 v117, 0xffff0000, v69
	v_lshlrev_b32_e32 v118, 16, v70
	v_and_b32_e32 v119, 0xffff0000, v70
	v_lshlrev_b32_e32 v120, 16, v71
	v_and_b32_e32 v121, 0xffff0000, v71
	v_lshlrev_b32_e32 v122, 16, v72
	v_and_b32_e32 v123, 0xffff0000, v72
	v_lshlrev_b32_e32 v124, 16, v73
	v_and_b32_e32 v125, 0xffff0000, v73
	v_lshlrev_b32_e32 v126, 16, v74
	v_and_b32_e32 v127, 0xffff0000, v74
	v_lshlrev_b32_e32 v128, 16, v75
	v_and_b32_e32 v129, 0xffff0000, v75
	v_lshlrev_b32_e32 v130, 16, v76
	v_and_b32_e32 v131, 0xffff0000, v76
	v_lshlrev_b32_e32 v132, 16, v77
	v_and_b32_e32 v133, 0xffff0000, v77
	s_waitcnt vmcnt(15)
	v_lshlrev_b32_e32 v134, 16, v78
	v_and_b32_e32 v135, 0xffff0000, v78
	v_lshlrev_b32_e32 v136, 16, v79
	v_and_b32_e32 v137, 0xffff0000, v79
	v_lshlrev_b32_e32 v138, 16, v80
	v_and_b32_e32 v139, 0xffff0000, v80
	v_lshlrev_b32_e32 v140, 16, v81
	v_and_b32_e32 v141, 0xffff0000, v81
	v_pk_mul_f32 v[152:153], v[22:23], v[110:111]
	v_pk_mul_f32 v[154:155], v[24:25], v[112:113]
	v_pk_mul_f32 v[156:157], v[26:27], v[114:115]
	v_pk_mul_f32 v[158:159], v[28:29], v[116:117]
	v_pk_fma_f32 v[152:153], v[30:31], v[118:119], v[152:153]
	v_pk_fma_f32 v[154:155], v[32:33], v[120:121], v[154:155]
	v_pk_fma_f32 v[156:157], v[34:35], v[122:123], v[156:157]
	v_pk_fma_f32 v[158:159], v[36:37], v[124:125], v[158:159]
	v_pk_fma_f32 v[152:153], v[38:39], v[126:127], v[152:153]
	v_pk_fma_f32 v[154:155], v[40:41], v[128:129], v[154:155]
	v_pk_fma_f32 v[156:157], v[42:43], v[130:131], v[156:157]
	v_pk_fma_f32 v[158:159], v[44:45], v[132:133], v[158:159]
	v_pk_fma_f32 v[152:153], v[46:47], v[134:135], v[152:153]
	v_pk_fma_f32 v[154:155], v[48:49], v[136:137], v[154:155]
	v_pk_fma_f32 v[156:157], v[50:51], v[138:139], v[156:157]
	v_pk_fma_f32 v[158:159], v[52:53], v[140:141], v[158:159]
	v_pk_mul_f32 v[8:9], v[152:153], s[12:13]
	v_pk_mul_f32 v[10:11], v[154:155], s[12:13]
	v_pk_mul_f32 v[12:13], v[156:157], s[12:13]
	v_pk_mul_f32 v[14:15], v[158:159], s[12:13]
	v_exp_f32_e32 v8, v8
	v_exp_f32_e32 v9, v9
	v_exp_f32_e32 v10, v10
	v_exp_f32_e32 v11, v11
	v_exp_f32_e32 v12, v12
	v_exp_f32_e32 v13, v13
	v_exp_f32_e32 v14, v14
	v_exp_f32_e32 v15, v15
	v_pk_add_f32 v[8:9], v[8:9], s[14:15]
	v_pk_add_f32 v[10:11], v[10:11], s[14:15]
	v_pk_add_f32 v[12:13], v[12:13], s[14:15]
	v_pk_add_f32 v[14:15], v[14:15], s[14:15]
	v_rcp_f32_e32 v8, v8
	v_rcp_f32_e32 v9, v9
	v_rcp_f32_e32 v10, v10
	v_rcp_f32_e32 v11, v11
	v_rcp_f32_e32 v12, v12
	v_rcp_f32_e32 v13, v13
	v_rcp_f32_e32 v14, v14
	v_rcp_f32_e32 v15, v15
	v_pk_mul_f32 v[152:153], v[152:153], v[8:9]
	v_pk_mul_f32 v[154:155], v[154:155], v[10:11]
	v_pk_mul_f32 v[156:157], v[156:157], v[12:13]
	v_pk_mul_f32 v[158:159], v[158:159], v[14:15]
	v_cvt_pk_bf16_f32 v56, v152, v153
	v_cvt_pk_bf16_f32 v57, v154, v155
	v_cvt_pk_bf16_f32 v58, v156, v157
	v_cvt_pk_bf16_f32 v59, v158, v159
	global_store_dwordx4 v6, v[56:59], s[18:19]
	s_add_u32 s18, s18, 0x800
	s_addc_u32 s19, s19, 0
	s_waitcnt vmcnt(14)
	v_lshlrev_b32_e32 v110, 16, v82
	v_and_b32_e32 v111, 0xffff0000, v82
	v_lshlrev_b32_e32 v112, 16, v83
	v_and_b32_e32 v113, 0xffff0000, v83
	v_lshlrev_b32_e32 v114, 16, v84
	v_and_b32_e32 v115, 0xffff0000, v84
	v_lshlrev_b32_e32 v116, 16, v85
	v_and_b32_e32 v117, 0xffff0000, v85
	v_pk_mul_f32 v[152:153], v[22:23], v[118:119]
	v_pk_mul_f32 v[154:155], v[24:25], v[120:121]
	v_pk_mul_f32 v[156:157], v[26:27], v[122:123]
	v_pk_mul_f32 v[158:159], v[28:29], v[124:125]
	v_pk_fma_f32 v[152:153], v[30:31], v[126:127], v[152:153]
	v_pk_fma_f32 v[154:155], v[32:33], v[128:129], v[154:155]
	v_pk_fma_f32 v[156:157], v[34:35], v[130:131], v[156:157]
	v_pk_fma_f32 v[158:159], v[36:37], v[132:133], v[158:159]
	v_pk_fma_f32 v[152:153], v[38:39], v[134:135], v[152:153]
	v_pk_fma_f32 v[154:155], v[40:41], v[136:137], v[154:155]
	v_pk_fma_f32 v[156:157], v[42:43], v[138:139], v[156:157]
	v_pk_fma_f32 v[158:159], v[44:45], v[140:141], v[158:159]
	v_pk_fma_f32 v[152:153], v[46:47], v[110:111], v[152:153]
	v_pk_fma_f32 v[154:155], v[48:49], v[112:113], v[154:155]
	v_pk_fma_f32 v[156:157], v[50:51], v[114:115], v[156:157]
	v_pk_fma_f32 v[158:159], v[52:53], v[116:117], v[158:159]
	v_pk_mul_f32 v[8:9], v[152:153], s[12:13]
	v_pk_mul_f32 v[10:11], v[154:155], s[12:13]
	v_pk_mul_f32 v[12:13], v[156:157], s[12:13]
	v_pk_mul_f32 v[14:15], v[158:159], s[12:13]
	v_exp_f32_e32 v8, v8
	v_exp_f32_e32 v9, v9
	v_exp_f32_e32 v10, v10
	v_exp_f32_e32 v11, v11
	v_exp_f32_e32 v12, v12
	v_exp_f32_e32 v13, v13
	v_exp_f32_e32 v14, v14
	v_exp_f32_e32 v15, v15
	v_pk_add_f32 v[8:9], v[8:9], s[14:15]
	v_pk_add_f32 v[10:11], v[10:11], s[14:15]
	v_pk_add_f32 v[12:13], v[12:13], s[14:15]
	v_pk_add_f32 v[14:15], v[14:15], s[14:15]
	v_rcp_f32_e32 v8, v8
	v_rcp_f32_e32 v9, v9
	v_rcp_f32_e32 v10, v10
	v_rcp_f32_e32 v11, v11
	v_rcp_f32_e32 v12, v12
	v_rcp_f32_e32 v13, v13
	v_rcp_f32_e32 v14, v14
	v_rcp_f32_e32 v15, v15
	v_pk_mul_f32 v[152:153], v[152:153], v[8:9]
	v_pk_mul_f32 v[154:155], v[154:155], v[10:11]
	v_pk_mul_f32 v[156:157], v[156:157], v[12:13]
	v_pk_mul_f32 v[158:159], v[158:159], v[14:15]
	v_cvt_pk_bf16_f32 v56, v152, v153
	v_cvt_pk_bf16_f32 v57, v154, v155
	v_cvt_pk_bf16_f32 v58, v156, v157
	v_cvt_pk_bf16_f32 v59, v158, v159
	global_store_dwordx4 v6, v[56:59], s[18:19]
	s_add_u32 s18, s18, 0x800
	s_addc_u32 s19, s19, 0
	s_waitcnt vmcnt(13)
; __device__ __forceinline__ unsigned pk2(float lo, float hi) { const f32v2_t v = {lo, hi}; const bf16v2_t b = __builtin_convertvector(v, bf16v2_t); return __builtin_bit_cast(unsigned, b); }
; __device__ __forceinline__ float lo16(unsigned u) { return __uint_as_float(u << 16); }
; __device__ __forceinline__ float hi16(unsigned u) { return __uint_as_float(u & 0xffff0000u); }
; __device__ __forceinline__ float siluf_(float x) { return x * __builtin_amdgcn_rcpf(1.0f + __expf(-x)); }
; __device__ __forceinline__ void prep_dn_load(const bf16_t* proj, const float* cw, int idx, u32x4 (&raw)[4], int& t, int& ch) {
;     ...
;     for (int k = 0; k < 4; ++k) { const int tt = t - 3 + k; raw[k] = (u32x4){0u, 0u, 0u, 0u};
;         if (tt >= 0) raw[k] = *(const u32x4*)(proj + (size_t)tt * NP + C_DNQ + ch); }
; }
; __device__ __forceinline__ void prep_dn_finish(const float* cw, bf16_t* dq, bf16_t* dk, bf16_t* dv, const u32x4 (&raw)[4], int t, int ch) {
;     float a[8];
; #pragma unroll
;     for (int e = 0; e < 8; ++e) a[e] = 0.f;
; #pragma unroll
;     for (int k = 0; k < 4; ++k) {
;         const f32x4 w0 = *(const f32x4*)(cw + k * 3072 + ch), w1 = *(const f32x4*)(cw + k * 3072 + ch + 4);
;         a[0] += w0[0] * lo16(raw[k].x); a[1] += w0[1] * hi16(raw[k].x); a[2] += w0[2] * lo16(raw[k].y); a[3] += w0[3] * hi16(raw[k].y);
;         a[4] += w1[0] * lo16(raw[k].z); a[5] += w1[1] * hi16(raw[k].z); a[6] += w1[2] * lo16(raw[k].w); a[7] += w1[3] * hi16(raw[k].w); }
;     float ss = 0.f;
; #pragma unroll
;     for (int e = 0; e < 8; ++e) { a[e] = siluf_(a[e]); ss += a[e] * a[e]; }
;     ss += __shfl_xor(ss, 1); ss += __shfl_xor(ss, 2); ss += __shfl_xor(ss, 4); ss += __shfl_xor(ss, 8);
;     float sc = 1.0f;
;     if (ch < 2048) { sc = rsqrtf(ss + EPS); if (ch < 1024) sc *= 0.08838834764831845f; }
;     u32x4 w; w.x = pk2(a[0] * sc, a[1] * sc); w.y = pk2(a[2] * sc, a[3] * sc); w.z = pk2(a[4] * sc, a[5] * sc); w.w = pk2(a[6] * sc, a[7] * sc);
;     bf16_t* dst = (ch < 1024) ? dq : (ch < 2048 ? dk : dv);
;     *(u32x4*)(dst + (size_t)t * 1024 + (ch & 1023)) = w;
	v_lshlrev_b32_e32 v118, 16, v86
	v_and_b32_e32 v119, 0xffff0000, v86
	v_lshlrev_b32_e32 v120, 16, v87
	v_and_b32_e32 v121, 0xffff0000, v87
	v_lshlrev_b32_e32 v122, 16, v88
	v_and_b32_e32 v123, 0xffff0000, v88
	v_lshlrev_b32_e32 v124, 16, v89
	v_and_b32_e32 v125, 0xffff0000, v89
	v_pk_mul_f32 v[152:153], v[22:23], v[126:127]
	v_pk_mul_f32 v[154:155], v[24:25], v[128:129]
	v_pk_mul_f32 v[156:157], v[26:27], v[130:131]
	v_pk_mul_f32 v[158:159], v[28:29], v[132:133]
	v_pk_fma_f32 v[152:153], v[30:31], v[134:135], v[152:153]
	v_pk_fma_f32 v[154:155], v[32:33], v[136:137], v[154:155]
	v_pk_fma_f32 v[156:157], v[34:35], v[138:139], v[156:157]
	v_pk_fma_f32 v[158:159], v[36:37], v[140:141], v[158:159]
	v_pk_fma_f32 v[152:153], v[38:39], v[110:111], v[152:153]
	v_pk_fma_f32 v[154:155], v[40:41], v[112:113], v[154:155]
	v_pk_fma_f32 v[156:157], v[42:43], v[114:115], v[156:157]
	v_pk_fma_f32 v[158:159], v[44:45], v[116:117], v[158:159]
	v_pk_fma_f32 v[152:153], v[46:47], v[118:119], v[152:153]
	v_pk_fma_f32 v[154:155], v[48:49], v[120:121], v[154:155]
	v_pk_fma_f32 v[156:157], v[50:51], v[122:123], v[156:157]
	v_pk_fma_f32 v[158:159], v[52:53], v[124:125], v[158:159]
	v_pk_mul_f32 v[8:9], v[152:153], s[12:13]
	v_pk_mul_f32 v[10:11], v[154:155], s[12:13]
	v_pk_mul_f32 v[12:13], v[156:157], s[12:13]
	v_pk_mul_f32 v[14:15], v[158:159], s[12:13]
	v_exp_f32_e32 v8, v8
	v_exp_f32_e32 v9, v9
	v_exp_f32_e32 v10, v10
	v_exp_f32_e32 v11, v11
	v_exp_f32_e32 v12, v12
	v_exp_f32_e32 v13, v13
	v_exp_f32_e32 v14, v14
	v_exp_f32_e32 v15, v15
	v_pk_add_f32 v[8:9], v[8:9], s[14:15]
	v_pk_add_f32 v[10:11], v[10:11], s[14:15]
	v_pk_add_f32 v[12:13], v[12:13], s[14:15]
	v_pk_add_f32 v[14:15], v[14:15], s[14:15]
	v_rcp_f32_e32 v8, v8
	v_rcp_f32_e32 v9, v9
	v_rcp_f32_e32 v10, v10
	v_rcp_f32_e32 v11, v11
	v_rcp_f32_e32 v12, v12
	v_rcp_f32_e32 v13, v13
	v_rcp_f32_e32 v14, v14
	v_rcp_f32_e32 v15, v15
	v_pk_mul_f32 v[152:153], v[152:153], v[8:9]
	v_pk_mul_f32 v[154:155], v[154:155], v[10:11]
	v_pk_mul_f32 v[156:157], v[156:157], v[12:13]
	v_pk_mul_f32 v[158:159], v[158:159], v[14:15]
	v_cvt_pk_bf16_f32 v56, v152, v153
	v_cvt_pk_bf16_f32 v57, v154, v155
	v_cvt_pk_bf16_f32 v58, v156, v157
	v_cvt_pk_bf16_f32 v59, v158, v159
	global_store_dwordx4 v6, v[56:59], s[18:19]
	s_add_u32 s18, s18, 0x800
	s_addc_u32 s19, s19, 0
	s_waitcnt vmcnt(12)
	v_lshlrev_b32_e32 v126, 16, v90
	v_and_b32_e32 v127, 0xffff0000, v90
	v_lshlrev_b32_e32 v128, 16, v91
	v_and_b32_e32 v129, 0xffff0000, v91
	v_lshlrev_b32_e32 v130, 16, v92
	v_and_b32_e32 v131, 0xffff0000, v92
	v_lshlrev_b32_e32 v132, 16, v93
	v_and_b32_e32 v133, 0xffff0000, v93
	v_pk_mul_f32 v[152:153], v[22:23], v[134:135]
	v_pk_mul_f32 v[154:155], v[24:25], v[136:137]
	v_pk_mul_f32 v[156:157], v[26:27], v[138:139]
	v_pk_mul_f32 v[158:159], v[28:29], v[140:141]
	v_pk_fma_f32 v[152:153], v[30:31], v[110:111], v[152:153]
	v_pk_fma_f32 v[154:155], v[32:33], v[112:113], v[154:155]
	v_pk_fma_f32 v[156:157], v[34:35], v[114:115], v[156:157]
	v_pk_fma_f32 v[158:159], v[36:37], v[116:117], v[158:159]
	v_pk_fma_f32 v[152:153], v[38:39], v[118:119], v[152:153]
	v_pk_fma_f32 v[154:155], v[40:41], v[120:121], v[154:155]
	v_pk_fma_f32 v[156:157], v[42:43], v[122:123], v[156:157]
	v_pk_fma_f32 v[158:159], v[44:45], v[124:125], v[158:159]
	v_pk_fma_f32 v[152:153], v[46:47], v[126:127], v[152:153]
	v_pk_fma_f32 v[154:155], v[48:49], v[128:129], v[154:155]
	v_pk_fma_f32 v[156:157], v[50:51], v[130:131], v[156:157]
	v_pk_fma_f32 v[158:159], v[52:53], v[132:133], v[158:159]
	v_pk_mul_f32 v[8:9], v[152:153], s[12:13]
	v_pk_mul_f32 v[10:11], v[154:155], s[12:13]
	v_pk_mul_f32 v[12:13], v[156:157], s[12:13]
	v_pk_mul_f32 v[14:15], v[158:159], s[12:13]
	v_exp_f32_e32 v8, v8
	v_exp_f32_e32 v9, v9
	v_exp_f32_e32 v10, v10
	v_exp_f32_e32 v11, v11
	v_exp_f32_e32 v12, v12
	v_exp_f32_e32 v13, v13
	v_exp_f32_e32 v14, v14
	v_exp_f32_e32 v15, v15
	v_pk_add_f32 v[8:9], v[8:9], s[14:15]
	v_pk_add_f32 v[10:11], v[10:11], s[14:15]
	v_pk_add_f32 v[12:13], v[12:13], s[14:15]
	v_pk_add_f32 v[14:15], v[14:15], s[14:15]
	v_rcp_f32_e32 v8, v8
	v_rcp_f32_e32 v9, v9
	v_rcp_f32_e32 v10, v10
	v_rcp_f32_e32 v11, v11
	v_rcp_f32_e32 v12, v12
	v_rcp_f32_e32 v13, v13
	v_rcp_f32_e32 v14, v14
	v_rcp_f32_e32 v15, v15
	v_pk_mul_f32 v[152:153], v[152:153], v[8:9]
	v_pk_mul_f32 v[154:155], v[154:155], v[10:11]
	v_pk_mul_f32 v[156:157], v[156:157], v[12:13]
	v_pk_mul_f32 v[158:159], v[158:159], v[14:15]
	v_cvt_pk_bf16_f32 v56, v152, v153
	v_cvt_pk_bf16_f32 v57, v154, v155
	v_cvt_pk_bf16_f32 v58, v156, v157
	v_cvt_pk_bf16_f32 v59, v158, v159
	global_store_dwordx4 v6, v[56:59], s[18:19]
	s_add_u32 s18, s18, 0x800
	s_addc_u32 s19, s19, 0
	s_waitcnt vmcnt(11)
; __device__ __forceinline__ unsigned pk2(float lo, float hi) { const f32v2_t v = {lo, hi}; const bf16v2_t b = __builtin_convertvector(v, bf16v2_t); return __builtin_bit_cast(unsigned, b); }
; __device__ __forceinline__ float lo16(unsigned u) { return __uint_as_float(u << 16); }
; __device__ __forceinline__ float hi16(unsigned u) { return __uint_as_float(u & 0xffff0000u); }
; __device__ __forceinline__ float siluf_(float x) { return x * __builtin_amdgcn_rcpf(1.0f + __expf(-x)); }
; __device__ __forceinline__ void prep_dn_load(const bf16_t* proj, const float* cw, int idx, u32x4 (&raw)[4], int& t, int& ch) {
;     ...
;     for (int k = 0; k < 4; ++k) { const int tt = t - 3 + k; raw[k] = (u32x4){0u, 0u, 0u, 0u};
;         if (tt >= 0) raw[k] = *(const u32x4*)(proj + (size_t)tt * NP + C_DNQ + ch); }
; }
; __device__ __forceinline__ void prep_dn_finish(const float* cw, bf16_t* dq, bf16_t* dk, bf16_t* dv, const u32x4 (&raw)[4], int t, int ch) {
;     float a[8];
; #pragma unroll
;     for (int e = 0; e < 8; ++e) a[e] = 0.f;
; #pragma unroll
;     for (int k = 0; k < 4; ++k) {
;         const f32x4 w0 = *(const f32x4*)(cw + k * 3072 + ch), w1 = *(const f32x4*)(cw + k * 3072 + ch + 4);
;         a[0] += w0[0] * lo16(raw[k].x); a[1] += w0[1] * hi16(raw[k].x); a[2] += w0[2] * lo16(raw[k].y); a[3] += w0[3] * hi16(raw[k].y);
;         a[4] += w1[0] * lo16(raw[k].z); a[5] += w1[1] * hi16(raw[k].z); a[6] += w1[2] * lo16(raw[k].w); a[7] += w1[3] * hi16(raw[k].w); }
;     float ss = 0.f;
; #pragma unroll
;     for (int e = 0; e < 8; ++e) { a[e] = siluf_(a[e]); ss += a[e] * a[e]; }
;     ss += __shfl_xor(ss, 1); ss += __shfl_xor(ss, 2); ss += __shfl_xor(ss, 4); ss += __shfl_xor(ss, 8);
;     float sc = 1.0f;
;     if (ch < 2048) { sc = rsqrtf(ss + EPS); if (ch < 1024) sc *= 0.08838834764831845f; }
;     u32x4 w; w.x = pk2(a[0] * sc, a[1] * sc); w.y = pk2(a[2] * sc, a[3] * sc); w.z = pk2(a[4] * sc, a[5] * sc); w.w = pk2(a[6] * sc, a[7] * sc);
;     bf16_t* dst = (ch < 1024) ? dq : (ch < 2048 ? dk : dv);
;     *(u32x4*)(dst + (size_t)t * 1024 + (ch & 1023)) = w;
	v_lshlrev_b32_e32 v134, 16, v94
	v_and_b32_e32 v135, 0xffff0000, v94
	v_lshlrev_b32_e32 v136, 16, v95
	v_and_b32_e32 v137, 0xffff0000, v95
	v_lshlrev_b32_e32 v138, 16, v96
	v_and_b32_e32 v139, 0xffff0000, v96
	v_lshlrev_b32_e32 v140, 16, v97
	v_and_b32_e32 v141, 0xffff0000, v97
	v_pk_mul_f32 v[152:153], v[22:23], v[110:111]
	v_pk_mul_f32 v[154:155], v[24:25], v[112:113]
	v_pk_mul_f32 v[156:157], v[26:27], v[114:115]
	v_pk_mul_f32 v[158:159], v[28:29], v[116:117]
	v_pk_fma_f32 v[152:153], v[30:31], v[118:119], v[152:153]
	v_pk_fma_f32 v[154:155], v[32:33], v[120:121], v[154:155]
	v_pk_fma_f32 v[156:157], v[34:35], v[122:123], v[156:157]
	v_pk_fma_f32 v[158:159], v[36:37], v[124:125], v[158:159]
	v_pk_fma_f32 v[152:153], v[38:39], v[126:127], v[152:153]
	v_pk_fma_f32 v[154:155], v[40:41], v[128:129], v[154:155]
	v_pk_fma_f32 v[156:157], v[42:43], v[130:131], v[156:157]
	v_pk_fma_f32 v[158:159], v[44:45], v[132:133], v[158:159]
	v_pk_fma_f32 v[152:153], v[46:47], v[134:135], v[152:153]
	v_pk_fma_f32 v[154:155], v[48:49], v[136:137], v[154:155]
	v_pk_fma_f32 v[156:157], v[50:51], v[138:139], v[156:157]
	v_pk_fma_f32 v[158:159], v[52:53], v[140:141], v[158:159]
	v_pk_mul_f32 v[8:9], v[152:153], s[12:13]
	v_pk_mul_f32 v[10:11], v[154:155], s[12:13]
	v_pk_mul_f32 v[12:13], v[156:157], s[12:13]
	v_pk_mul_f32 v[14:15], v[158:159], s[12:13]
	v_exp_f32_e32 v8, v8
	v_exp_f32_e32 v9, v9
	v_exp_f32_e32 v10, v10
	v_exp_f32_e32 v11, v11
	v_exp_f32_e32 v12, v12
	v_exp_f32_e32 v13, v13
	v_exp_f32_e32 v14, v14
	v_exp_f32_e32 v15, v15
	v_pk_add_f32 v[8:9], v[8:9], s[14:15]
	v_pk_add_f32 v[10:11], v[10:11], s[14:15]
	v_pk_add_f32 v[12:13], v[12:13], s[14:15]
	v_pk_add_f32 v[14:15], v[14:15], s[14:15]
	v_rcp_f32_e32 v8, v8
	v_rcp_f32_e32 v9, v9
	v_rcp_f32_e32 v10, v10
	v_rcp_f32_e32 v11, v11
	v_rcp_f32_e32 v12, v12
	v_rcp_f32_e32 v13, v13
	v_rcp_f32_e32 v14, v14
	v_rcp_f32_e32 v15, v15
	v_pk_mul_f32 v[152:153], v[152:153], v[8:9]
	v_pk_mul_f32 v[154:155], v[154:155], v[10:11]
	v_pk_mul_f32 v[156:157], v[156:157], v[12:13]
	v_pk_mul_f32 v[158:159], v[158:159], v[14:15]
	v_cvt_pk_bf16_f32 v56, v152, v153
	v_cvt_pk_bf16_f32 v57, v154, v155
	v_cvt_pk_bf16_f32 v58, v156, v157
	v_cvt_pk_bf16_f32 v59, v158, v159
	global_store_dwordx4 v6, v[56:59], s[18:19]
	s_add_u32 s18, s18, 0x800
	s_addc_u32 s19, s19, 0
	s_waitcnt vmcnt(10)
	v_lshlrev_b32_e32 v110, 16, v98
	v_and_b32_e32 v111, 0xffff0000, v98
	v_lshlrev_b32_e32 v112, 16, v99
	v_and_b32_e32 v113, 0xffff0000, v99
	v_lshlrev_b32_e32 v114, 16, v100
	v_and_b32_e32 v115, 0xffff0000, v100
	v_lshlrev_b32_e32 v116, 16, v101
	v_and_b32_e32 v117, 0xffff0000, v101
	v_pk_mul_f32 v[152:153], v[22:23], v[118:119]
	v_pk_mul_f32 v[154:155], v[24:25], v[120:121]
	v_pk_mul_f32 v[156:157], v[26:27], v[122:123]
	v_pk_mul_f32 v[158:159], v[28:29], v[124:125]
	v_pk_fma_f32 v[152:153], v[30:31], v[126:127], v[152:153]
	v_pk_fma_f32 v[154:155], v[32:33], v[128:129], v[154:155]
	v_pk_fma_f32 v[156:157], v[34:35], v[130:131], v[156:157]
	v_pk_fma_f32 v[158:159], v[36:37], v[132:133], v[158:159]
	v_pk_fma_f32 v[152:153], v[38:39], v[134:135], v[152:153]
	v_pk_fma_f32 v[154:155], v[40:41], v[136:137], v[154:155]
	v_pk_fma_f32 v[156:157], v[42:43], v[138:139], v[156:157]
	v_pk_fma_f32 v[158:159], v[44:45], v[140:141], v[158:159]
	v_pk_fma_f32 v[152:153], v[46:47], v[110:111], v[152:153]
	v_pk_fma_f32 v[154:155], v[48:49], v[112:113], v[154:155]
	v_pk_fma_f32 v[156:157], v[50:51], v[114:115], v[156:157]
	v_pk_fma_f32 v[158:159], v[52:53], v[116:117], v[158:159]
	v_pk_mul_f32 v[8:9], v[152:153], s[12:13]
	v_pk_mul_f32 v[10:11], v[154:155], s[12:13]
	v_pk_mul_f32 v[12:13], v[156:157], s[12:13]
	v_pk_mul_f32 v[14:15], v[158:159], s[12:13]
	v_exp_f32_e32 v8, v8
	v_exp_f32_e32 v9, v9
	v_exp_f32_e32 v10, v10
	v_exp_f32_e32 v11, v11
	v_exp_f32_e32 v12, v12
	v_exp_f32_e32 v13, v13
	v_exp_f32_e32 v14, v14
	v_exp_f32_e32 v15, v15
	v_pk_add_f32 v[8:9], v[8:9], s[14:15]
	v_pk_add_f32 v[10:11], v[10:11], s[14:15]
	v_pk_add_f32 v[12:13], v[12:13], s[14:15]
	v_pk_add_f32 v[14:15], v[14:15], s[14:15]
	v_rcp_f32_e32 v8, v8
	v_rcp_f32_e32 v9, v9
	v_rcp_f32_e32 v10, v10
	v_rcp_f32_e32 v11, v11
	v_rcp_f32_e32 v12, v12
	v_rcp_f32_e32 v13, v13
	v_rcp_f32_e32 v14, v14
	v_rcp_f32_e32 v15, v15
	v_pk_mul_f32 v[152:153], v[152:153], v[8:9]
	v_pk_mul_f32 v[154:155], v[154:155], v[10:11]
	v_pk_mul_f32 v[156:157], v[156:157], v[12:13]
	v_pk_mul_f32 v[158:159], v[158:159], v[14:15]
	v_cvt_pk_bf16_f32 v56, v152, v153
	v_cvt_pk_bf16_f32 v57, v154, v155
	v_cvt_pk_bf16_f32 v58, v156, v157
	v_cvt_pk_bf16_f32 v59, v158, v159
	global_store_dwordx4 v6, v[56:59], s[18:19]
	s_add_u32 s18, s18, 0x800
	s_addc_u32 s19, s19, 0
	s_waitcnt vmcnt(9)
; __device__ __forceinline__ unsigned pk2(float lo, float hi) { const f32v2_t v = {lo, hi}; const bf16v2_t b = __builtin_convertvector(v, bf16v2_t); return __builtin_bit_cast(unsigned, b); }
; __device__ __forceinline__ float lo16(unsigned u) { return __uint_as_float(u << 16); }
; __device__ __forceinline__ float hi16(unsigned u) { return __uint_as_float(u & 0xffff0000u); }
; __device__ __forceinline__ float siluf_(float x) { return x * __builtin_amdgcn_rcpf(1.0f + __expf(-x)); }
; __device__ __forceinline__ void prep_dn_load(const bf16_t* proj, const float* cw, int idx, u32x4 (&raw)[4], int& t, int& ch) {
;     ...
;     for (int k = 0; k < 4; ++k) { const int tt = t - 3 + k; raw[k] = (u32x4){0u, 0u, 0u, 0u};
;         if (tt >= 0) raw[k] = *(const u32x4*)(proj + (size_t)tt * NP + C_DNQ + ch); }
; }
; __device__ __forceinline__ void prep_dn_finish(const float* cw, bf16_t* dq, bf16_t* dk, bf16_t* dv, const u32x4 (&raw)[4], int t, int ch) {
;     float a[8];
; #pragma unroll
;     for (int e = 0; e < 8; ++e) a[e] = 0.f;
; #pragma unroll
;     for (int k = 0; k < 4; ++k) {
;         const f32x4 w0 = *(const f32x4*)(cw + k * 3072 + ch), w1 = *(const f32x4*)(cw + k * 3072 + ch + 4);
;         a[0] += w0[0] * lo16(raw[k].x); a[1] += w0[1] * hi16(raw[k].x); a[2] += w0[2] * lo16(raw[k].y); a[3] += w0[3] * hi16(raw[k].y);
;         a[4] += w1[0] * lo16(raw[k].z); a[5] += w1[1] * hi16(raw[k].z); a[6] += w1[2] * lo16(raw[k].w); a[7] += w1[3] * hi16(raw[k].w); }
;     float ss = 0.f;
; #pragma unroll
;     for (int e = 0; e < 8; ++e) { a[e] = siluf_(a[e]); ss += a[e] * a[e]; }
;     ss += __shfl_xor(ss, 1); ss += __shfl_xor(ss, 2); ss += __shfl_xor(ss, 4); ss += __shfl_xor(ss, 8);
;     float sc = 1.0f;
;     if (ch < 2048) { sc = rsqrtf(ss + EPS); if (ch < 1024) sc *= 0.08838834764831845f; }
;     u32x4 w; w.x = pk2(a[0] * sc, a[1] * sc); w.y = pk2(a[2] * sc, a[3] * sc); w.z = pk2(a[4] * sc, a[5] * sc); w.w = pk2(a[6] * sc, a[7] * sc);
;     bf16_t* dst = (ch < 1024) ? dq : (ch < 2048 ? dk : dv);
;     *(u32x4*)(dst + (size_t)t * 1024 + (ch & 1023)) = w;
	v_lshlrev_b32_e32 v118, 16, v102
	v_and_b32_e32 v119, 0xffff0000, v102
	v_lshlrev_b32_e32 v120, 16, v103
	v_and_b32_e32 v121, 0xffff0000, v103
	v_lshlrev_b32_e32 v122, 16, v104
	v_and_b32_e32 v123, 0xffff0000, v104
	v_lshlrev_b32_e32 v124, 16, v105
	v_and_b32_e32 v125, 0xffff0000, v105
	v_pk_mul_f32 v[152:153], v[22:23], v[126:127]
	v_pk_mul_f32 v[154:155], v[24:25], v[128:129]
	v_pk_mul_f32 v[156:157], v[26:27], v[130:131]
	v_pk_mul_f32 v[158:159], v[28:29], v[132:133]
	v_pk_fma_f32 v[152:153], v[30:31], v[134:135], v[152:153]
	v_pk_fma_f32 v[154:155], v[32:33], v[136:137], v[154:155]
	v_pk_fma_f32 v[156:157], v[34:35], v[138:139], v[156:157]
	v_pk_fma_f32 v[158:159], v[36:37], v[140:141], v[158:159]
	v_pk_fma_f32 v[152:153], v[38:39], v[110:111], v[152:153]
	v_pk_fma_f32 v[154:155], v[40:41], v[112:113], v[154:155]
	v_pk_fma_f32 v[156:157], v[42:43], v[114:115], v[156:157]
	v_pk_fma_f32 v[158:159], v[44:45], v[116:117], v[158:159]
	v_pk_fma_f32 v[152:153], v[46:47], v[118:119], v[152:153]
	v_pk_fma_f32 v[154:155], v[48:49], v[120:121], v[154:155]
	v_pk_fma_f32 v[156:157], v[50:51], v[122:123], v[156:157]
	v_pk_fma_f32 v[158:159], v[52:53], v[124:125], v[158:159]
	v_pk_mul_f32 v[8:9], v[152:153], s[12:13]
	v_pk_mul_f32 v[10:11], v[154:155], s[12:13]
	v_pk_mul_f32 v[12:13], v[156:157], s[12:13]
	v_pk_mul_f32 v[14:15], v[158:159], s[12:13]
	v_exp_f32_e32 v8, v8
	v_exp_f32_e32 v9, v9
	v_exp_f32_e32 v10, v10
	v_exp_f32_e32 v11, v11
	v_exp_f32_e32 v12, v12
	v_exp_f32_e32 v13, v13
	v_exp_f32_e32 v14, v14
	v_exp_f32_e32 v15, v15
	v_pk_add_f32 v[8:9], v[8:9], s[14:15]
	v_pk_add_f32 v[10:11], v[10:11], s[14:15]
	v_pk_add_f32 v[12:13], v[12:13], s[14:15]
	v_pk_add_f32 v[14:15], v[14:15], s[14:15]
	v_rcp_f32_e32 v8, v8
	v_rcp_f32_e32 v9, v9
	v_rcp_f32_e32 v10, v10
	v_rcp_f32_e32 v11, v11
	v_rcp_f32_e32 v12, v12
	v_rcp_f32_e32 v13, v13
	v_rcp_f32_e32 v14, v14
	v_rcp_f32_e32 v15, v15
	v_pk_mul_f32 v[152:153], v[152:153], v[8:9]
	v_pk_mul_f32 v[154:155], v[154:155], v[10:11]
	v_pk_mul_f32 v[156:157], v[156:157], v[12:13]
	v_pk_mul_f32 v[158:159], v[158:159], v[14:15]
	v_cvt_pk_bf16_f32 v56, v152, v153
	v_cvt_pk_bf16_f32 v57, v154, v155
	v_cvt_pk_bf16_f32 v58, v156, v157
	v_cvt_pk_bf16_f32 v59, v158, v159
	global_store_dwordx4 v6, v[56:59], s[18:19]
	s_add_u32 s18, s18, 0x800
	s_addc_u32 s19, s19, 0
	s_waitcnt vmcnt(8)
	v_lshlrev_b32_e32 v126, 16, v106
	v_and_b32_e32 v127, 0xffff0000, v106
	v_lshlrev_b32_e32 v128, 16, v107
	v_and_b32_e32 v129, 0xffff0000, v107
	v_lshlrev_b32_e32 v130, 16, v108
	v_and_b32_e32 v131, 0xffff0000, v108
	v_lshlrev_b32_e32 v132, 16, v109
	v_and_b32_e32 v133, 0xffff0000, v109
	v_pk_mul_f32 v[152:153], v[22:23], v[134:135]
	v_pk_mul_f32 v[154:155], v[24:25], v[136:137]
	v_pk_mul_f32 v[156:157], v[26:27], v[138:139]
	v_pk_mul_f32 v[158:159], v[28:29], v[140:141]
	v_pk_fma_f32 v[152:153], v[30:31], v[110:111], v[152:153]
	v_pk_fma_f32 v[154:155], v[32:33], v[112:113], v[154:155]
	v_pk_fma_f32 v[156:157], v[34:35], v[114:115], v[156:157]
	v_pk_fma_f32 v[158:159], v[36:37], v[116:117], v[158:159]
	v_pk_fma_f32 v[152:153], v[38:39], v[118:119], v[152:153]
	v_pk_fma_f32 v[154:155], v[40:41], v[120:121], v[154:155]
	v_pk_fma_f32 v[156:157], v[42:43], v[122:123], v[156:157]
	v_pk_fma_f32 v[158:159], v[44:45], v[124:125], v[158:159]
	v_pk_fma_f32 v[152:153], v[46:47], v[126:127], v[152:153]
	v_pk_fma_f32 v[154:155], v[48:49], v[128:129], v[154:155]
	v_pk_fma_f32 v[156:157], v[50:51], v[130:131], v[156:157]
	v_pk_fma_f32 v[158:159], v[52:53], v[132:133], v[158:159]
	v_pk_mul_f32 v[8:9], v[152:153], s[12:13]
	v_pk_mul_f32 v[10:11], v[154:155], s[12:13]
	v_pk_mul_f32 v[12:13], v[156:157], s[12:13]
	v_pk_mul_f32 v[14:15], v[158:159], s[12:13]
	v_exp_f32_e32 v8, v8
	v_exp_f32_e32 v9, v9
	v_exp_f32_e32 v10, v10
	v_exp_f32_e32 v11, v11
	v_exp_f32_e32 v12, v12
	v_exp_f32_e32 v13, v13
	v_exp_f32_e32 v14, v14
	v_exp_f32_e32 v15, v15
	v_pk_add_f32 v[8:9], v[8:9], s[14:15]
	v_pk_add_f32 v[10:11], v[10:11], s[14:15]
	v_pk_add_f32 v[12:13], v[12:13], s[14:15]
	v_pk_add_f32 v[14:15], v[14:15], s[14:15]
	v_rcp_f32_e32 v8, v8
	v_rcp_f32_e32 v9, v9
	v_rcp_f32_e32 v10, v10
	v_rcp_f32_e32 v11, v11
	v_rcp_f32_e32 v12, v12
	v_rcp_f32_e32 v13, v13
	v_rcp_f32_e32 v14, v14
	v_rcp_f32_e32 v15, v15
	v_pk_mul_f32 v[152:153], v[152:153], v[8:9]
	v_pk_mul_f32 v[154:155], v[154:155], v[10:11]
	v_pk_mul_f32 v[156:157], v[156:157], v[12:13]
	v_pk_mul_f32 v[158:159], v[158:159], v[14:15]
	v_cvt_pk_bf16_f32 v56, v152, v153
	v_cvt_pk_bf16_f32 v57, v154, v155
	v_cvt_pk_bf16_f32 v58, v156, v157
	v_cvt_pk_bf16_f32 v59, v158, v159
	global_store_dwordx4 v6, v[56:59], s[18:19]
	s_waitcnt vmcnt(0)
	s_mov_b64 exec, 0
